# RWKV scan: y=S.r dot chain fused from scalar mul/fmac pairs into packed f32 ops (bitwise identical); per-head parameters kept in AGPRs instead of re-read from LDS every chunk; attention epilogue gate
# speedup vs baseline: 1.3306x; 1.0108x over previous
; DI void scan_item(const Params& p, int L, int c, int item, char* smem, bool dry) {
;     ...
;   auto load_raw = [&](int tc) {
;     const int lr = b * 4096 + tc * 32 + tt;
;     const int s = c * 4096 + tc * 32 + tt;
;     const u16* cur = U + (size_t)lr * LDU_R;
;     const u16* prv = (s == 0) ? (BND + (size_t)4 * SHIFTW) : ((s == 4096 && c == 1) ? (BND + (size_t)b * SHIFTW) : (cur - LDU_R));
;     Rr_c = *(const uint4*)(cur + R_R + head * 64 + cs * 8);  Rr_p = *(const uint4*)(prv + R_R + head * 64 + cs * 8);
;     Rk_c = *(const uint4*)(cur + R_K + head * 64 + cs * 8);  Rk_p = *(const uint4*)(prv + R_K + head * 64 + cs * 8);
;     Rw_c = *(const uint4*)(cur + R_WD + cs * 8);             Rw_p = *(const uint4*)(prv + R_WD + cs * 8);
;     Ra_c = *(const uint4*)(cur + R_AD + cs * 8);             Ra_p = *(const uint4*)(prv + R_AD + cs * 8);
;     const int vo = R_V + head * 64 + 32 * half + c4 * 8;
;     Rv_c = *(const uint4*)(cur + vo);                        Rv_p = *(const uint4*)(prv + vo);
;   };
;   uint4 d_y = zero4, d_v = zero4; float d_sm = 0.f, d_sq = 0.f; int d_lr = -1;
;   auto flush_out = [&]() {
;     if (cs < 4 && !dry && d_lr >= 0) {
;       const size_t o = (size_t)d_lr * 1536 + head * 64 + 32 * half + cs * 8;
;       *(uint4*)(YR + o) = d_y;
;       *(uint4*)(BV + o) = d_v;
;       if (cs == 0) {
;         float* stp = ST + ((size_t)(d_lr * 24 + head) * 2 + half) * 2;
;         stp[0] = d_sm; stp[1] = d_sq;
;       }
;     }
;   };
;   float rm[8], km[8];
;   auto prep1 = [&](float* Vst) {
;     float cu[8], pv[8], t8[8];
;     unpack8(Rr_c, cu); unpack8(Rr_p, pv);
; #pragma unroll
;     for (int e = 0; e < 8; ++e) rm[e] = cu[e] + (pv[e] - cu[e]) * PRM[0 * 64 + cs * 8 + e];
;     unpack8(Rk_c, cu); unpack8(Rk_p, pv);
; #pragma unroll
;     for (int e = 0; e < 8; ++e) km[e] = cu[e] + (pv[e] - cu[e]) * PRM[1 * 64 + cs * 8 + e];
;     unpack8(Rw_c, cu); unpack8(Rw_p, pv);
; #pragma unroll
;     for (int e = 0; e < 8; ++e) {
;       float xw = cu[e] + (pv[e] - cu[e]) * PRM[2 * 64 + cs * 8 + e];
;       float ee = ex2(xw * 2.8853900817779268f);
;       t8[e] = 1.f - 2.f * frcp(ee + 1.f);
;     }
;     *(uint4*)(A1 + (0 * 32 + tt) * 72 + cs * 8) = pack8(t8);
;     unpack8(Ra_c, cu); unpack8(Ra_p, pv);
; #pragma unroll
;     for (int e = 0; e < 8; ++e) t8[e] = cu[e] + (pv[e] - cu[e]) * PRM[3 * 64 + cs * 8 + e];
.LBB0_151:
	s_or_saveexec_b64 s[6:7], s[6:7]
	v_mov_b64_e32 v[66:67], s[14:15]
	s_xor_b64 exec, exec, s[6:7]
	v_cmp_ne_u32_e32 vcc, 0, v41
	s_andn2_b64 s[12:13], s[12:13], exec
	s_and_b64 s[14:15], vcc, exec
	v_mov_b64_e32 v[66:67], s[96:97]
	s_or_b64 s[12:13], s[12:13], s[14:15]
	s_or_b64 exec, exec, s[6:7]
	v_add_u32_e32 v42, s23, v40
	v_mov_b64_e32 v[40:41], s[2:3]
	v_mad_i64_i32 v[68:69], s[6:7], v42, s66, v[40:41]
	s_and_saveexec_b64 s[6:7], s[12:13]
	s_movk_i32 s12, 0xc700
	s_mov_b32 s13, -1
	v_lshl_add_u64 v[66:67], v[68:69], 0, s[12:13]
	s_or_b64 exec, exec, s[6:7]
	v_lshlrev_b32_e32 v40, 16, v36
	v_and_b32_e32 v41, 0xffff0000, v36
	v_lshlrev_b32_e32 v44, 16, v32
	v_and_b32_e32 v45, 0xffff0000, v32
	v_lshlrev_b32_e32 v36, 16, v37
	v_and_b32_e32 v37, 0xffff0000, v37
	v_lshlrev_b32_e32 v32, 16, v33
	v_and_b32_e32 v33, 0xffff0000, v33
	v_pk_add_f32 v[44:45], v[44:45], v[40:41] neg_lo:[0,1] neg_hi:[0,1]
	v_lshlrev_b32_e32 v42, 16, v38
	v_and_b32_e32 v43, 0xffff0000, v38
	v_lshlrev_b32_e32 v46, 16, v34
	v_and_b32_e32 v47, 0xffff0000, v34
	v_pk_fma_f32 v[56:57], v[44:45], v[28:29], v[40:41]
	v_pk_add_f32 v[28:29], v[32:33], v[36:37] neg_lo:[0,1] neg_hi:[0,1]
	v_lshlrev_b32_e32 v38, 16, v39
	v_and_b32_e32 v39, 0xffff0000, v39
	v_lshlrev_b32_e32 v34, 16, v35
	v_and_b32_e32 v35, 0xffff0000, v35
	v_pk_fma_f32 v[58:59], v[28:29], v[30:31], v[36:37]
	v_pk_add_f32 v[28:29], v[46:47], v[42:43] neg_lo:[0,1] neg_hi:[0,1]
	v_lshlrev_b32_e32 v78, 16, v26
	v_pk_fma_f32 v[60:61], v[28:29], v[16:17], v[42:43]
	v_pk_add_f32 v[16:17], v[34:35], v[38:39] neg_lo:[0,1] neg_hi:[0,1]
	v_and_b32_e32 v79, 0xffff0000, v26
	v_pk_fma_f32 v[62:63], v[16:17], v[18:19], v[38:39]
	v_lshlrev_b32_e32 v16, 16, v24
	v_and_b32_e32 v17, 0xffff0000, v24
	v_lshlrev_b32_e32 v18, 16, v25
	v_and_b32_e32 v19, 0xffff0000, v25
	v_lshlrev_b32_e32 v24, 16, v20
	v_and_b32_e32 v25, 0xffff0000, v20
	v_lshlrev_b32_e32 v86, 16, v27
	v_and_b32_e32 v87, 0xffff0000, v27
	v_lshlrev_b32_e32 v20, 16, v21
	v_and_b32_e32 v21, 0xffff0000, v21
	v_lshlrev_b32_e32 v26, 16, v22
	v_and_b32_e32 v27, 0xffff0000, v22
	v_lshlrev_b32_e32 v80, 16, v23
	v_and_b32_e32 v81, 0xffff0000, v23
	v_pk_add_f32 v[22:23], v[24:25], v[16:17] neg_lo:[0,1] neg_hi:[0,1]
	s_movk_i32 s6, 0x2000
	v_pk_fma_f32 v[64:65], v[22:23], v[4:5], v[16:17]
	v_pk_add_f32 v[4:5], v[20:21], v[18:19] neg_lo:[0,1] neg_hi:[0,1]
	v_lshl_add_u64 v[16:17], v[68:69], 0, s[10:11]
	v_pk_fma_f32 v[4:5], v[4:5], v[6:7], v[18:19]
	v_lshl_add_u64 v[16:17], v[16:17], 0, v[198:199]
	v_lshl_add_u64 v[18:19], v[66:67], 0, s[10:11]
	v_lshl_add_u64 v[18:19], v[18:19], 0, v[198:199]
	global_load_dwordx4 v[48:51], v[16:17], off
	global_load_dwordx4 v[40:43], v[16:17], off offset:3072
	global_load_dwordx4 v[52:55], v[18:19], off
	global_load_dwordx4 v[44:47], v[18:19], off offset:3072
	v_lshl_add_u64 v[16:17], v[68:69], 0, v[198:199]
	v_add_co_u32_e32 v16, vcc, s6, v16
	v_lshl_add_u64 v[18:19], v[66:67], 0, v[198:199]
	s_nop 0
	v_addc_co_u32_e32 v17, vcc, 0, v17, vcc
	v_add_co_u32_e32 v18, vcc, s6, v18
	v_lshl_add_u64 v[20:21], v[66:67], 0, v[100:101]
	v_lshl_or_b32 v66, v71, 8, v136
	v_pk_add_f32 v[6:7], v[26:27], v[78:79] neg_lo:[0,1] neg_hi:[0,1]
	v_addc_co_u32_e32 v19, vcc, 0, v19, vcc
	global_load_dwordx4 v[32:35], v[16:17], off offset:1024
	global_load_dwordx4 v[24:27], v[16:17], off offset:1152
	global_load_dwordx4 v[36:39], v[18:19], off offset:1024
	global_load_dwordx4 v[28:31], v[18:19], off offset:1152
	v_lshl_add_u64 v[16:17], v[68:69], 0, v[100:101]
	v_add_u32_e32 v145, 0x20780, v66
	global_load_dwordx4 v[16:19], v[16:17], off
	v_pk_fma_f32 v[0:1], v[6:7], v[0:1], v[78:79]
	global_load_dwordx4 v[20:23], v[20:21], off
	s_waitcnt lgkmcnt(0)
	s_barrier
	ds_read_b128 v[66:69], v145
	ds_read_b128 v[74:77], v137 offset:1024
	v_pk_add_f32 v[6:7], v[80:81], v[86:87] neg_lo:[0,1] neg_hi:[0,1]
	ds_read_b128 v[78:81], v137 offset:1040
	ds_read_b128 v[82:85], v137 offset:2064
	v_pk_fma_f32 v[2:3], v[6:7], v[2:3], v[86:87]
	ds_read_b128 v[86:89], v145 offset:16
	ds_read_b128 v[90:93], v145 offset:8192
	ds_read_b128 v[102:105], v145 offset:8208
	s_waitcnt lgkmcnt(5)
	v_add_f32_e32 v66, v66, v74
	v_mul_f32_e32 v66, 0xbfb8aa3b, v66
	ds_read_b128 v[106:109], v137 offset:1280
	v_exp_f32_e32 v66, v66
	v_add_f32_e32 v7, v67, v75
	ds_read_b128 v[110:113], v137 offset:1296
	v_mul_f32_e32 v7, 0xbfb8aa3b, v7
	v_add_f32_e32 v6, 1.0, v66
	s_waitcnt lgkmcnt(1)
	v_add_f32_e32 v66, v90, v106
	v_mul_f32_e32 v66, 0xbfb8aa3b, v66
	v_exp_f32_e32 v66, v66
	v_add_f32_e32 v67, v91, v107
	v_mul_f32_e32 v67, 0xbfb8aa3b, v67
	v_exp_f32_e32 v67, v67
	v_add_f32_e32 v66, 1.0, v66
	v_rcp_f32_e32 v90, v66
	v_add_f32_e32 v66, v68, v76
	v_mul_f32_e32 v66, 0xbfb8aa3b, v66
	v_add_f32_e32 v67, 1.0, v67
	v_exp_f32_e32 v66, v66
	v_rcp_f32_e32 v91, v67
	v_add_f32_e32 v67, v69, v77
	v_mul_f32_e32 v67, 0xbfb8aa3b, v67
	v_exp_f32_e32 v67, v67
	v_add_f32_e32 v66, 1.0, v66
	v_add_f32_e32 v68, v92, v108
	v_rcp_f32_e32 v66, v66
	v_mul_f32_e32 v68, 0xbfb8aa3b, v68
	v_exp_f32_e32 v68, v68
	v_add_f32_e32 v67, 1.0, v67
	v_rcp_f32_e32 v67, v67
	v_mul_f32_e32 v66, 0xbf60023a, v66
	v_exp_f32_e32 v92, v66
	v_add_f32_e32 v66, 1.0, v68
	v_rcp_f32_e32 v94, v66
	v_mul_f32_e32 v66, 0xbf60023a, v67
	v_add_f32_e32 v67, v86, v78
	v_mul_f32_e32 v67, 0xbfb8aa3b, v67
	v_exp_f32_e32 v67, v67
	v_add_f32_e32 v68, v93, v109
	v_mul_f32_e32 v68, 0xbfb8aa3b, v68
	v_exp_f32_e32 v68, v68
	v_add_f32_e32 v67, 1.0, v67
	v_rcp_f32_e32 v67, v67
	v_exp_f32_e32 v93, v66
	v_add_f32_e32 v66, 1.0, v68
	v_rcp_f32_e32 v95, v66
	v_mul_f32_e32 v66, 0xbf60023a, v67
	v_add_f32_e32 v67, v87, v79
	v_mul_f32_e32 v67, 0xbfb8aa3b, v67
	v_exp_f32_e32 v67, v67
	s_waitcnt lgkmcnt(0)
; DI float ex2(float x) { return __builtin_amdgcn_exp2f(x); }
; DI float fexp(float x) { return __builtin_amdgcn_exp2f(x * 1.4426950408889634f); }
; DI void scan_item(const Params& p, int L, int c, int item, char* smem, bool dry) {
;     ...
;     float dec[8], kk[8], av[8], kp[8];
;     float ssq = 0.f, bon = 0.f;
; #pragma unroll
;     for (int e = 0; e < 8; ++e) {
;       const int ch = cs * 8 + e;
;       const float sg = frcp(1.f + fexp(-(lw[e] + PRM[4 * 64 + ch])));
;       dec[e] = ex2(-0.8750340f * sg);
;       float a = frcp(1.f + fexp(-(la[e] + PRM[5 * 64 + ch])));
;       av[e] = a;
;       kk[e] = km[e] * PRM[6 * 64 + ch];
;       ssq += kk[e] * kk[e];
;       kp[e] = km[e] * (1.f + (a - 1.f) * PRM[7 * 64 + ch]);
;       bon += rm[e] * kp[e] * PRM[8 * 64 + ch];
;     }
;     ssq = red8(ssq); bon = red8(bon);
;     const float inv = fminf(__builtin_amdgcn_rsqf(ssq), 1e12f);
;     float nk[8], bb[8];
; #pragma unroll
;     for (int e = 0; e < 8; ++e) { float kn = kk[e] * inv; nk[e] = -kn; bb[e] = kn * av[e]; }
;     float* pa = PA + tt * 320 + cs * 8;
;     *(float4*)(pa) = make_float4(dec[0], dec[1], dec[2], dec[3]); *(float4*)(pa + 4) = make_float4(dec[4], dec[5], dec[6], dec[7]);
;     *(float4*)(pa + 64) = make_float4(nk[0], nk[1], nk[2], nk[3]); *(float4*)(pa + 68) = make_float4(nk[4], nk[5], nk[6], nk[7]);
;     *(float4*)(pa + 128) = make_float4(bb[0], bb[1], bb[2], bb[3]); *(float4*)(pa + 132) = make_float4(bb[4], bb[5], bb[6], bb[7]);
;     *(float4*)(pa + 192) = make_float4(kp[0], kp[1], kp[2], kp[3]); *(float4*)(pa + 196) = make_float4(kp[4], kp[5], kp[6], kp[7]);
;     *(float4*)(pa + 256) = make_float4(rm[0], rm[1], rm[2], rm[3]); *(float4*)(pa + 260) = make_float4(rm[4], rm[5], rm[6], rm[7]);
;     BON[tt] = bon;
;     ...
;   load_raw(0);
;   prep1(Vstb);
;   __syncthreads();
;   prep3();
;   load_raw(1);
;   __syncthreads();
;   prep4(PAb, BONb);
;   __syncthreads();
;   int v3 = 0;
;   for (int tc = 0; tc < 128; ++tc) {
;     const int lr = b * 4096 + tc * 32 + tt;
;     const int v3n = (v3 == 2) ? 0 : v3 + 1;
;     float* PAc = PAb + (tc & 1) * 10240;        float* PAn = PAb + ((tc + 1) & 1) * 10240;
;     float* Vc = Vstb + v3 * 1024;               float* Vn = Vstb + v3n * 1024;
;     float* Bc = BONb + v3 * 32;                 float* Bn = BONb + v3n * 32;
;     float* Yc = Ystb + (tc & 1) * 1024;
;     step_load(PAc, Vc, 0);
	v_add_f32_e32 v68, v102, v110
	v_mul_f32_e32 v68, 0xbfb8aa3b, v68
	v_exp_f32_e32 v68, v68
	v_add_f32_e32 v67, 1.0, v67
	v_rcp_f32_e32 v67, v67
	v_exp_f32_e32 v78, v66
	v_add_f32_e32 v66, 1.0, v68
	v_rcp_f32_e32 v86, v66
	v_mul_f32_e32 v66, 0xbf60023a, v67
	v_add_f32_e32 v67, v88, v80
	v_mul_f32_e32 v67, 0xbfb8aa3b, v67
	v_exp_f32_e32 v67, v67
	v_add_f32_e32 v68, v103, v111
	v_mul_f32_e32 v68, 0xbfb8aa3b, v68
	v_exp_f32_e32 v68, v68
	v_add_f32_e32 v67, 1.0, v67
	v_rcp_f32_e32 v67, v67
	v_exp_f32_e32 v79, v66
	v_add_f32_e32 v66, 1.0, v68
	v_rcp_f32_e32 v87, v66
	v_mul_f32_e32 v66, 0xbf60023a, v67
	v_add_f32_e32 v67, v104, v112
	v_mul_f32_e32 v67, 0xbfb8aa3b, v67
	v_add_f32_e32 v68, v89, v81
	v_exp_f32_e32 v67, v67
	v_mul_f32_e32 v68, 0xbfb8aa3b, v68
	v_exp_f32_e32 v68, v68
	v_exp_f32_e32 v80, v66
	v_add_f32_e32 v66, 1.0, v67
	v_rcp_f32_e32 v88, v66
	v_add_f32_e32 v66, 1.0, v68
	v_rcp_f32_e32 v73, v66
	v_add_f32_e32 v66, v105, v113
	v_mul_f32_e32 v66, 0xbfb8aa3b, v66
	v_exp_f32_e32 v74, v66
	ds_read_b128 v[66:69], v137 offset:1536
	v_mul_f32_e32 v73, 0xbf60023a, v73
	v_exp_f32_e32 v81, v73
	v_add_f32_e32 v73, 1.0, v74
	ds_read_b128 v[74:77], v137 offset:1552
	s_waitcnt lgkmcnt(1)
	v_pk_mul_f32 v[66:67], v[64:65], v[66:67]
	v_pk_mul_f32 v[68:69], v[4:5], v[68:69]
	v_pk_mul_f32 v[102:103], v[66:67], v[66:67]
	v_pk_mul_f32 v[104:105], v[68:69], v[68:69]
	v_add_f32_e32 v89, v102, v103
	s_waitcnt lgkmcnt(0)
	v_pk_mul_f32 v[74:75], v[0:1], v[74:75]
	v_add_f32_e32 v89, v89, v104
	v_pk_mul_f32 v[106:107], v[74:75], v[74:75]
	v_add_f32_e32 v89, v89, v105
	v_pk_mul_f32 v[76:77], v[2:3], v[76:77]
	v_add_f32_e32 v89, v89, v106
	v_pk_mul_f32 v[108:109], v[76:77], v[76:77]
	v_add_f32_e32 v89, v89, v107
	v_add_f32_e32 v89, v89, v108
	v_add_f32_e32 v89, v89, v109
	v_exp_f32_e32 v7, v7
	v_rcp_f32_e32 v6, v6
	v_add_f32_dpp v89, v89, v89 quad_perm:[1,0,3,2] row_mask:0xf bank_mask:0xf bound_ctrl:1
	s_movk_i32 s6, 0x500
	v_add_f32_e32 v7, 1.0, v7
	v_add_f32_dpp v89, v89, v89 quad_perm:[2,3,0,1] row_mask:0xf bank_mask:0xf bound_ctrl:1
	v_rcp_f32_e32 v7, v7
	v_mul_f32_e32 v6, 0xbf60023a, v6
	v_add_f32_dpp v89, v89, v89 row_half_mirror row_mask:0xf bank_mask:0xf bound_ctrl:1
	v_rsq_f32_e32 v102, v89
	v_mul_f32_e32 v7, 0xbf60023a, v7
	v_exp_f32_e32 v6, v6
	v_exp_f32_e32 v7, v7
	v_min_f32_e32 v102, 0x5368d4a5, v102
	v_pk_mul_f32 v[104:105], v[66:67], v[102:103] op_sel_hi:[1,0] neg_lo:[0,1] neg_hi:[0,1]
	v_pk_mul_f32 v[106:107], v[68:69], v[102:103] op_sel_hi:[1,0] neg_lo:[0,1] neg_hi:[0,1]
	ds_read_b128 v[66:69], v137 offset:2048
	ds_read_b64 v[108:109], v137 offset:1792
	v_rcp_f32_e32 v89, v73
	v_mul_lo_u32 v73, v71, s6
	v_pk_mul_f32 v[74:75], v[74:75], v[102:103] op_sel_hi:[1,0] neg_lo:[0,1] neg_hi:[0,1]
	v_pk_mul_f32 v[76:77], v[76:77], v[102:103] op_sel_hi:[1,0] neg_lo:[0,1] neg_hi:[0,1]
	v_pk_mul_f32 v[102:103], v[90:91], v[104:105] neg_lo:[0,1] neg_hi:[0,1]
	v_pk_add_f32 v[90:91], v[90:91], -1.0 op_sel_hi:[1,0]
	v_or_b32_e32 v146, v136, v73
	s_waitcnt lgkmcnt(0)
	v_pk_fma_f32 v[90:91], v[108:109], v[90:91], 1.0 op_sel_hi:[1,1,0]
	v_pk_mul_f32 v[110:111], v[94:95], v[106:107] neg_lo:[0,1] neg_hi:[0,1]
	v_pk_mul_f32 v[64:65], v[64:65], v[90:91]
	ds_write_b64 v146, v[6:7]
	ds_write_b64 v146, v[104:105] offset:256
	ds_write_b64 v146, v[102:103] offset:512
	ds_write_b64 v146, v[64:65] offset:768
	ds_read_b64 v[6:7], v137 offset:1800
	v_pk_mul_f32 v[90:91], v[56:57], v[64:65]
	v_pk_add_f32 v[64:65], v[94:95], -1.0 op_sel_hi:[1,0]
	v_fma_f32 v66, v66, v90, 0
	v_fmac_f32_e32 v66, v67, v91
	s_waitcnt lgkmcnt(0)
	v_pk_fma_f32 v[6:7], v[6:7], v[64:65], 1.0 op_sel_hi:[1,1,0]
	v_pk_mul_f32 v[112:113], v[86:87], v[74:75] neg_lo:[0,1] neg_hi:[0,1]
	v_pk_mul_f32 v[4:5], v[4:5], v[6:7]
	ds_write_b64 v146, v[92:93] offset:8
	ds_write_b64 v146, v[106:107] offset:264
	ds_write_b64 v146, v[110:111] offset:520
	ds_write_b64 v146, v[4:5] offset:776
	ds_read_b64 v[6:7], v137 offset:1808
	v_pk_mul_f32 v[4:5], v[58:59], v[4:5]
	v_readlane_b32 s6, v255, 18
	v_fmac_f32_e32 v66, v68, v4
	v_fmac_f32_e32 v66, v69, v5
	v_pk_add_f32 v[4:5], v[86:87], -1.0 op_sel_hi:[1,0]
	v_cmp_lt_u32_e32 vcc, 3, v70
	s_waitcnt lgkmcnt(0)
	v_pk_fma_f32 v[4:5], v[6:7], v[4:5], 1.0 op_sel_hi:[1,1,0]
	v_readlane_b32 s7, v255, 19
	v_pk_mul_f32 v[0:1], v[0:1], v[4:5]
	ds_write_b64 v146, v[78:79] offset:16
	ds_write_b64 v146, v[74:75] offset:272
	ds_write_b64 v146, v[112:113] offset:528
	ds_write_b64 v146, v[0:1] offset:784
	ds_read_b64 v[4:5], v137 offset:1816
	v_pk_mul_f32 v[0:1], v[60:61], v[0:1]
	s_or_b64 s[16:17], s[6:7], vcc
	v_fmac_f32_e32 v66, v82, v0
	v_fmac_f32_e32 v66, v83, v1
	v_pk_add_f32 v[0:1], v[88:89], -1.0 op_sel_hi:[1,0]
	s_add_u32 s12, s40, s22
	s_waitcnt lgkmcnt(0)
	v_pk_fma_f32 v[0:1], v[4:5], v[0:1], 1.0 op_sel_hi:[1,1,0]
	s_addc_u32 s13, s41, s20
	v_pk_mul_f32 v[0:1], v[2:3], v[0:1]
	s_lshl_b32 s20, s18, 3
	v_pk_mul_f32 v[2:3], v[62:63], v[0:1]
	v_readlane_b32 s14, v252, 56
	v_fmac_f32_e32 v66, v84, v2
	v_fmac_f32_e32 v66, v85, v3
	v_pk_mul_f32 v[114:115], v[88:89], v[76:77] neg_lo:[0,1] neg_hi:[0,1]
	ds_write_b64 v146, v[80:81] offset:24
	ds_write_b64 v146, v[76:77] offset:280
	ds_write_b64 v146, v[114:115] offset:536
	v_add_f32_dpp v2, v66, v66 quad_perm:[1,0,3,2] row_mask:0xf bank_mask:0xf bound_ctrl:1
	ds_write_b64 v146, v[0:1] offset:792
	ds_write_b128 v146, v[56:59] offset:1024
	ds_write_b128 v146, v[60:63] offset:1040
	v_add_f32_dpp v2, v2, v2 quad_perm:[2,3,0,1] row_mask:0xf bank_mask:0xf bound_ctrl:1
	v_mov_b32_e32 v0, 0x19a00
	v_readlane_b32 s15, v252, 57
	s_add_u32 s14, s14, s20
	v_mov_b32_e32 v104, 0
	v_add_f32_dpp v2, v2, v2 row_half_mirror row_mask:0xf bank_mask:0xf bound_ctrl:1
	v_lshl_add_u32 v147, v71, 2, v0
	s_addc_u32 s15, s15, 0
	s_or_b32 s0, s0, s19
	v_readlane_b32 s18, v255, 14
	s_mov_b32 s30, 1
	s_mov_b32 s29, 0
	ds_write_b32 v147, v2
	v_cmp_eq_u32_e64 s[6:7], 0, v70
	v_lshl_add_u64 v[102:103], s[0:1], 0, v[98:99]
	v_add_u32_e32 v99, s18, v71
	v_mov_b32_e32 v152, -1
	s_xor_b64 s[16:17], s[16:17], -1
	v_lshlrev_b32_e32 v148, 2, v72
	s_mov_b32 s31, 0
	v_mov_b32_e32 v105, v104
	v_mov_b32_e32 v4, v104
	v_mov_b32_e32 v5, v104
	v_mov_b32_e32 v6, v104
	v_mov_b32_e32 v7, v104
	v_mov_b32_e32 v0, v104
	v_mov_b32_e32 v1, v104
	v_mov_b32_e32 v2, v104
	v_mov_b32_e32 v3, v104
	ds_read_b128 v[236:239], v137 offset:512
	s_waitcnt lgkmcnt(0)
; DI float ex2(float x) { return __builtin_amdgcn_exp2f(x); }
; DI float frcp(float x) { return __builtin_amdgcn_rcpf(x); }
; DI uint4 pack8(const float* f) { uint4 v; v.x = pack2(f[0], f[1]); v.y = pack2(f[2], f[3]); v.z = pack2(f[4], f[5]); v.w = pack2(f[6], f[7]); return v; }
; DI void scan_item(const Params& p, int L, int c, int item, char* smem, bool dry) {
;     ...
;   auto prep1 = [&](float* Vst) {
;     float cu[8], pv[8], t8[8];
;     unpack8(Rr_c, cu); unpack8(Rr_p, pv);
; #pragma unroll
;     for (int e = 0; e < 8; ++e) rm[e] = cu[e] + (pv[e] - cu[e]) * PRM[0 * 64 + cs * 8 + e];
;     unpack8(Rk_c, cu); unpack8(Rk_p, pv);
; #pragma unroll
;     for (int e = 0; e < 8; ++e) km[e] = cu[e] + (pv[e] - cu[e]) * PRM[1 * 64 + cs * 8 + e];
;     unpack8(Rw_c, cu); unpack8(Rw_p, pv);
; #pragma unroll
;     for (int e = 0; e < 8; ++e) {
;       float xw = cu[e] + (pv[e] - cu[e]) * PRM[2 * 64 + cs * 8 + e];
;       float ee = ex2(xw * 2.8853900817779268f);
;       t8[e] = 1.f - 2.f * frcp(ee + 1.f);
;     }
;     *(uint4*)(A1 + (0 * 32 + tt) * 72 + cs * 8) = pack8(t8);
;     ...
;   auto step_load = [&](const float* PA, const float* Vst, int t) {
;     const float* pa = PA + t * 320 + ks * 8;
;     d0 = *(const float4*)(pa); d1 = *(const float4*)(pa + 4);
;     n0 = *(const float4*)(pa + 64); n1 = *(const float4*)(pa + 68);
;     b0 = *(const float4*)(pa + 128); b1 = *(const float4*)(pa + 132);
;     k0 = *(const float4*)(pa + 192); k1 = *(const float4*)(pa + 196);
;     r0 = *(const float4*)(pa + 256); r1 = *(const float4*)(pa + 260);
;     vv = Vst[t * 32 + row32];
	v_accvgpr_write_b32 a16, v236
	v_accvgpr_write_b32 a17, v237
	v_accvgpr_write_b32 a18, v238
	v_accvgpr_write_b32 a19, v239
	ds_read_b128 v[236:239], v137 offset:528
	s_waitcnt lgkmcnt(0)
	v_accvgpr_write_b32 a20, v236
	v_accvgpr_write_b32 a21, v237
	v_accvgpr_write_b32 a22, v238
	v_accvgpr_write_b32 a23, v239
	ds_read_b128 v[236:239], v137 offset:256
	s_waitcnt lgkmcnt(0)
	v_accvgpr_write_b32 a24, v236
	v_accvgpr_write_b32 a25, v237
	v_accvgpr_write_b32 a26, v238
	v_accvgpr_write_b32 a27, v239
	ds_read_b128 v[236:239], v137 offset:272
	s_waitcnt lgkmcnt(0)
	v_accvgpr_write_b32 a28, v236
	v_accvgpr_write_b32 a29, v237
	v_accvgpr_write_b32 a30, v238
	v_accvgpr_write_b32 a31, v239
	ds_read_b128 v[236:239], v137
	s_waitcnt lgkmcnt(0)
	v_accvgpr_write_b32 a32, v236
	v_accvgpr_write_b32 a33, v237
	v_accvgpr_write_b32 a34, v238
	v_accvgpr_write_b32 a35, v239
	ds_read_b64 v[236:237], v137 offset:16
	s_waitcnt lgkmcnt(0)
	v_accvgpr_write_b32 a36, v236
	v_accvgpr_write_b32 a37, v237
	ds_read_b64 v[236:237], v137 offset:768
	s_waitcnt lgkmcnt(0)
	v_accvgpr_write_b32 a38, v236
	v_accvgpr_write_b32 a39, v237
	ds_read_b64 v[236:237], v137 offset:784
	s_waitcnt lgkmcnt(0)
	v_accvgpr_write_b32 a40, v236
	v_accvgpr_write_b32 a41, v237
	ds_read_b64 v[236:237], v137 offset:24
	s_waitcnt lgkmcnt(0)
	v_accvgpr_write_b32 a42, v236
	v_accvgpr_write_b32 a43, v237
	ds_read_b64 v[236:237], v137 offset:776
	s_waitcnt lgkmcnt(0)
	v_accvgpr_write_b32 a44, v236
	v_accvgpr_write_b32 a45, v237
	ds_read_b64 v[236:237], v137 offset:792
	s_waitcnt lgkmcnt(0)
	v_accvgpr_write_b32 a46, v236
	v_accvgpr_write_b32 a47, v237
	ds_read_b128 v[236:239], v143 offset:2304
	s_waitcnt lgkmcnt(0)
	v_accvgpr_write_b32 a48, v236
	v_accvgpr_write_b32 a49, v237
	v_accvgpr_write_b32 a50, v238
	v_accvgpr_write_b32 a51, v239
	ds_read_b128 v[236:239], v143 offset:2320
	s_waitcnt lgkmcnt(0)
	v_accvgpr_write_b32 a52, v236
	v_accvgpr_write_b32 a53, v237
	v_accvgpr_write_b32 a54, v238
	v_accvgpr_write_b32 a55, v239
	ds_read_b128 v[236:239], v137 offset:1024
	s_waitcnt lgkmcnt(0)
	v_accvgpr_write_b32 a56, v236
	v_accvgpr_write_b32 a57, v237
	v_accvgpr_write_b32 a58, v238
	v_accvgpr_write_b32 a59, v239
	ds_read_b128 v[236:239], v137 offset:1040
	s_waitcnt lgkmcnt(0)
	v_accvgpr_write_b32 a60, v236
	v_accvgpr_write_b32 a61, v237
	v_accvgpr_write_b32 a62, v238
	v_accvgpr_write_b32 a63, v239
	ds_read_b128 v[236:239], v137 offset:1536
	s_waitcnt lgkmcnt(0)
	v_accvgpr_write_b32 a64, v236
	v_accvgpr_write_b32 a65, v237
	v_accvgpr_write_b32 a66, v238
	v_accvgpr_write_b32 a67, v239
	ds_read_b128 v[236:239], v137 offset:1280
	s_waitcnt lgkmcnt(0)
	v_accvgpr_write_b32 a68, v236
	v_accvgpr_write_b32 a69, v237
	v_accvgpr_write_b32 a70, v238
	v_accvgpr_write_b32 a71, v239
	ds_read_b128 v[236:239], v137 offset:1552
	s_waitcnt lgkmcnt(0)
	v_accvgpr_write_b32 a72, v236
	v_accvgpr_write_b32 a73, v237
	v_accvgpr_write_b32 a74, v238
	v_accvgpr_write_b32 a75, v239
	ds_read_b128 v[236:239], v137 offset:1296
	s_waitcnt lgkmcnt(0)
	v_accvgpr_write_b32 a76, v236
	v_accvgpr_write_b32 a77, v237
	v_accvgpr_write_b32 a78, v238
	v_accvgpr_write_b32 a79, v239
	ds_read_b128 v[236:239], v137 offset:1792
	s_waitcnt lgkmcnt(0)
	v_accvgpr_write_b32 a80, v236
	v_accvgpr_write_b32 a81, v237
	v_accvgpr_write_b32 a82, v238
	v_accvgpr_write_b32 a83, v239
	ds_read_b128 v[236:239], v137 offset:2048
	s_waitcnt lgkmcnt(0)
	v_accvgpr_write_b32 a84, v236
	v_accvgpr_write_b32 a85, v237
	v_accvgpr_write_b32 a86, v238
	v_accvgpr_write_b32 a87, v239
	ds_read_b128 v[236:239], v137 offset:1808
	s_waitcnt lgkmcnt(0)
	v_accvgpr_write_b32 a88, v236
	v_accvgpr_write_b32 a89, v237
	v_accvgpr_write_b32 a90, v238
	v_accvgpr_write_b32 a91, v239
	ds_read_b128 v[236:239], v137 offset:2064
	s_waitcnt lgkmcnt(0)
	v_accvgpr_write_b32 a92, v236
	v_accvgpr_write_b32 a93, v237
	v_accvgpr_write_b32 a94, v238
	v_accvgpr_write_b32 a95, v239
	s_waitcnt lgkmcnt(0)
	s_barrier
.LBB0_156:
	s_add_i32 s18, s30, -1
	s_add_i32 s19, s31, 1
	s_cmp_lg_u32 s31, 2
	s_cselect_b32 s34, s19, 0
	s_and_b32 s19, s18, 1
	s_mul_i32 s22, s19, 0xa000
	v_or_b32_e32 v149, s22, v136
	ds_read_b128 v[64:67], v149
	ds_read_b128 v[76:79], v149 offset:16
	ds_read_b128 v[92:95], v149 offset:256
	ds_read_b128 v[88:91], v149 offset:272
	ds_read_b128 v[68:71], v149 offset:512
	ds_read_b128 v[80:83], v149 offset:528
	ds_read_b128 v[72:75], v149 offset:768
	ds_read_b128 v[84:87], v149 offset:784
	ds_read_b128 v[60:63], v149 offset:1024
	ds_read_b128 v[56:59], v149 offset:1040
	v_accvgpr_read_b32 v126, a16
	v_accvgpr_read_b32 v127, a17
	v_accvgpr_read_b32 v128, a18
	v_accvgpr_read_b32 v129, a19
	s_waitcnt vmcnt(9)
	v_lshlrev_b32_e32 v112, 16, v48
	v_and_b32_e32 v113, 0xffff0000, v48
	v_lshlrev_b32_e32 v110, 16, v49
	v_and_b32_e32 v111, 0xffff0000, v49
	v_lshlrev_b32_e32 v108, 16, v50
	v_and_b32_e32 v109, 0xffff0000, v50
	v_lshlrev_b32_e32 v48, 16, v51
	v_and_b32_e32 v49, 0xffff0000, v51
	s_waitcnt vmcnt(7)
	v_lshlrev_b32_e32 v116, 16, v52
	v_and_b32_e32 v117, 0xffff0000, v52
	v_lshlrev_b32_e32 v114, 16, v53
	v_and_b32_e32 v115, 0xffff0000, v53
	v_lshlrev_b32_e32 v52, 16, v54
	v_and_b32_e32 v53, 0xffff0000, v54
	v_lshlrev_b32_e32 v50, 16, v55
	v_and_b32_e32 v51, 0xffff0000, v55
	v_lshlrev_b32_e32 v120, 16, v40
	v_and_b32_e32 v121, 0xffff0000, v40
	v_lshlrev_b32_e32 v118, 16, v41
	v_and_b32_e32 v119, 0xffff0000, v41
	v_lshlrev_b32_e32 v54, 16, v42
	v_and_b32_e32 v55, 0xffff0000, v42
	v_lshlrev_b32_e32 v40, 16, v43
	v_and_b32_e32 v41, 0xffff0000, v43
	s_waitcnt vmcnt(6)
; DI float ex2(float x) { return __builtin_amdgcn_exp2f(x); }
; DI float frcp(float x) { return __builtin_amdgcn_rcpf(x); }
; DI float red8(float x) { x += dppf(x, 0); x += dppf(x, 1); x += dppf(x, 2); return x; }
; DI uint4 pack8(const float* f) { uint4 v; v.x = pack2(f[0], f[1]); v.y = pack2(f[2], f[3]); v.z = pack2(f[4], f[5]); v.w = pack2(f[6], f[7]); return v; }
; DI void scan_item(const Params& p, int L, int c, int item, char* smem, bool dry) {
;     ...
;   auto prep1 = [&](float* Vst) {
;     float cu[8], pv[8], t8[8];
;     unpack8(Rr_c, cu); unpack8(Rr_p, pv);
; #pragma unroll
;     for (int e = 0; e < 8; ++e) rm[e] = cu[e] + (pv[e] - cu[e]) * PRM[0 * 64 + cs * 8 + e];
;     unpack8(Rk_c, cu); unpack8(Rk_p, pv);
; #pragma unroll
;     for (int e = 0; e < 8; ++e) km[e] = cu[e] + (pv[e] - cu[e]) * PRM[1 * 64 + cs * 8 + e];
;     unpack8(Rw_c, cu); unpack8(Rw_p, pv);
; #pragma unroll
;     for (int e = 0; e < 8; ++e) {
;       float xw = cu[e] + (pv[e] - cu[e]) * PRM[2 * 64 + cs * 8 + e];
;       float ee = ex2(xw * 2.8853900817779268f);
;       t8[e] = 1.f - 2.f * frcp(ee + 1.f);
;     }
;     *(uint4*)(A1 + (0 * 32 + tt) * 72 + cs * 8) = pack8(t8);
;     unpack8(Ra_c, cu); unpack8(Ra_p, pv);
; #pragma unroll
;     for (int e = 0; e < 8; ++e) t8[e] = cu[e] + (pv[e] - cu[e]) * PRM[3 * 64 + cs * 8 + e];
;     *(uint4*)(A1 + (1 * 32 + tt) * 72 + cs * 8) = pack8(t8);
;     unpack8(Rv_c, cu); unpack8(Rv_p, pv);
;     float v8[8];
; #pragma unroll
;     for (int e = 0; e < 8; ++e) v8[e] = cu[e] + (pv[e] - cu[e]) * PRM[9 * 64 + c4 * 8 + e];
;     *(float4*)(Vst + tt * 32 + c4 * 8) = make_float4(v8[0], v8[1], v8[2], v8[3]);
;     *(float4*)(Vst + tt * 32 + c4 * 8 + 4) = make_float4(v8[4], v8[5], v8[6], v8[7]);
;   };
;     ...
;       float sa0 = S[0] * n0.x, sa1 = S[1] * n0.y;
;       sa0 = fmaf(S[2], n0.z, sa0); sa1 = fmaf(S[3], n0.w, sa1);
;       sa0 = fmaf(S[4], n1.x, sa0); sa1 = fmaf(S[5], n1.y, sa1);
;       sa0 = fmaf(S[6], n1.z, sa0); sa1 = fmaf(S[7], n1.w, sa1);
;       float sa = red8(sa0 + sa1);
	v_lshlrev_b32_e32 v124, 16, v44
	v_and_b32_e32 v125, 0xffff0000, v44
	v_lshlrev_b32_e32 v122, 16, v45
	v_and_b32_e32 v123, 0xffff0000, v45
	v_lshlrev_b32_e32 v44, 16, v46
	v_and_b32_e32 v45, 0xffff0000, v46
	v_lshlrev_b32_e32 v42, 16, v47
	v_and_b32_e32 v43, 0xffff0000, v47
	s_waitcnt vmcnt(5)
	v_lshlrev_b32_e32 v46, 16, v32
	s_waitcnt vmcnt(3)
	v_lshlrev_b32_e32 v47, 16, v36
	v_and_b32_e32 v32, 0xffff0000, v32
	v_and_b32_e32 v36, 0xffff0000, v36
	v_sub_f32_e32 v36, v36, v32
	v_fmac_f32_e32 v32, v36, v127
	v_mul_f32_e32 v32, 0x4038aa3b, v32
	v_exp_f32_e32 v32, v32
	v_sub_f32_e32 v47, v47, v46
	v_fmac_f32_e32 v46, v47, v126
	v_lshlrev_b32_e32 v36, 16, v37
	v_add_f32_e32 v32, 1.0, v32
	v_rcp_f32_e32 v47, v32
	v_lshlrev_b32_e32 v32, 16, v33
	v_sub_f32_e32 v36, v36, v32
	v_fmac_f32_e32 v32, v36, v128
	v_and_b32_e32 v33, 0xffff0000, v33
	v_and_b32_e32 v36, 0xffff0000, v37
	v_sub_f32_e32 v36, v36, v33
	v_fmac_f32_e32 v33, v36, v129
	v_accvgpr_read_b32 v126, a20
	v_accvgpr_read_b32 v127, a21
	v_accvgpr_read_b32 v128, a22
	v_accvgpr_read_b32 v129, a23
	v_lshlrev_b32_e32 v36, 16, v34
	v_lshlrev_b32_e32 v37, 16, v38
	v_sub_f32_e32 v37, v37, v36
	v_and_b32_e32 v34, 0xffff0000, v34
	v_fmac_f32_e32 v36, v37, v126
	v_and_b32_e32 v37, 0xffff0000, v38
	v_sub_f32_e32 v37, v37, v34
	v_fmac_f32_e32 v34, v37, v127
	v_mul_f32_e32 v34, 0x4038aa3b, v34
	v_exp_f32_e32 v34, v34
	v_lshlrev_b32_e32 v38, 16, v39
	v_mul_f32_e32 v32, 0x4038aa3b, v32
	v_mul_f32_e32 v33, 0x4038aa3b, v33
	v_add_f32_e32 v34, 1.0, v34
	v_rcp_f32_e32 v37, v34
	v_lshlrev_b32_e32 v34, 16, v35
	v_sub_f32_e32 v38, v38, v34
	v_fmac_f32_e32 v34, v38, v128
	v_and_b32_e32 v35, 0xffff0000, v35
	v_and_b32_e32 v38, 0xffff0000, v39
	v_sub_f32_e32 v38, v38, v35
	v_fmac_f32_e32 v35, v38, v129
	v_mul_f32_e32 v36, 0x4038aa3b, v36
	v_mul_f32_e32 v34, 0x4038aa3b, v34
	v_mul_f32_e32 v35, 0x4038aa3b, v35
	v_exp_f32_e32 v32, v32
	v_exp_f32_e32 v33, v33
	v_exp_f32_e32 v36, v36
	v_exp_f32_e32 v34, v34
	v_exp_f32_e32 v35, v35
	s_waitcnt vmcnt(1)
	v_lshlrev_b32_e32 v130, 16, v16
	v_and_b32_e32 v131, 0xffff0000, v16
	v_lshlrev_b32_e32 v126, 16, v17
	v_and_b32_e32 v127, 0xffff0000, v17
	s_waitcnt lgkmcnt(7)
	v_pk_mul_f32 v[16:17], v[8:9], v[92:93]
	v_add_f32_e32 v32, 1.0, v32
	v_add_f32_e32 v33, 1.0, v33
	v_add_f32_e32 v36, 1.0, v36
	v_add_f32_e32 v34, 1.0, v34
	v_add_f32_e32 v35, 1.0, v35
	v_pk_fma_f32 v[16:17], v[10:11], v[94:95], v[16:17]
	v_rcp_f32_e32 v32, v32
	v_rcp_f32_e32 v33, v33
	v_rcp_f32_e32 v36, v36
	v_rcp_f32_e32 v34, v34
	v_rcp_f32_e32 v35, v35
	s_waitcnt lgkmcnt(6)
	v_pk_fma_f32 v[16:17], v[12:13], v[88:89], v[16:17]
	v_pk_fma_f32 v[32:33], v[32:33], 2.0, 1.0 op_sel_hi:[1,0,0] neg_lo:[1,0,0] neg_hi:[1,0,0]
	v_pk_fma_f32 v[16:17], v[14:15], v[90:91], v[16:17]
	v_pk_fma_f32 v[36:37], v[36:37], 2.0, 1.0 op_sel_hi:[1,0,0] neg_lo:[1,0,0] neg_hi:[1,0,0]
	v_add_f32_e32 v16, v16, v17
	v_pk_fma_f32 v[34:35], v[34:35], 2.0, 1.0 op_sel_hi:[1,0,0] neg_lo:[1,0,0] neg_hi:[1,0,0]
	v_cvt_pk_bf16_f32 v129, v32, v33
	v_add_f32_dpp v16, v16, v16 quad_perm:[1,0,3,2] row_mask:0xf bank_mask:0xf bound_ctrl:1
	v_cvt_pk_bf16_f32 v154, v36, v37
	v_cvt_pk_bf16_f32 v155, v34, v35
	v_add_f32_dpp v16, v16, v16 quad_perm:[2,3,0,1] row_mask:0xf bank_mask:0xf bound_ctrl:1
	v_lshlrev_b32_e32 v36, 16, v18
	v_and_b32_e32 v37, 0xffff0000, v18
	v_lshlrev_b32_e32 v34, 16, v19
	v_and_b32_e32 v35, 0xffff0000, v19
	v_add_f32_dpp v32, v16, v16 row_half_mirror row_mask:0xf bank_mask:0xf bound_ctrl:1
	v_accvgpr_read_b32 v16, a24
	v_accvgpr_read_b32 v17, a25
	v_accvgpr_read_b32 v18, a26
	v_accvgpr_read_b32 v19, a27
	v_mul_f32_e32 v46, 0x4038aa3b, v46
	v_exp_f32_e32 v46, v46
	s_waitcnt vmcnt(0)
	v_lshlrev_b32_e32 v156, 16, v20
	v_and_b32_e32 v157, 0xffff0000, v20
	v_lshlrev_b32_e32 v132, 16, v21
	v_and_b32_e32 v133, 0xffff0000, v21
	v_pk_add_f32 v[20:21], v[124:125], v[120:121] neg_lo:[0,1] neg_hi:[0,1]
	s_bitcmp1_b32 s30, 0
	v_pk_fma_f32 v[94:95], v[20:21], v[16:17], v[120:121]
	v_pk_add_f32 v[16:17], v[122:123], v[118:119] neg_lo:[0,1] neg_hi:[0,1]
	v_add_f32_e32 v46, 1.0, v46
	v_pk_fma_f32 v[92:93], v[16:17], v[18:19], v[118:119]
	v_accvgpr_read_b32 v16, a28
	v_accvgpr_read_b32 v17, a29
	v_accvgpr_read_b32 v18, a30
	v_accvgpr_read_b32 v19, a31
	s_cselect_b32 s18, 0xa000, 0
	s_lshl_b32 s35, s31, 12
	v_rcp_f32_e32 v46, v46
	s_add_i32 s35, s35, 0x14000
	v_lshlrev_b32_e32 v107, 2, v134
	v_pk_add_f32 v[20:21], v[44:45], v[54:55] neg_lo:[0,1] neg_hi:[0,1]
	v_add_u32_e32 v150, s35, v107
	v_pk_fma_f32 v[90:91], v[20:21], v[16:17], v[54:55]
	v_pk_add_f32 v[16:17], v[42:43], v[40:41] neg_lo:[0,1] neg_hi:[0,1]
	ds_read_b32 v106, v150
	v_pk_fma_f32 v[88:89], v[16:17], v[18:19], v[40:41]
	v_accvgpr_read_b32 v16, a32
	v_accvgpr_read_b32 v17, a33
	v_accvgpr_read_b32 v18, a34
	v_accvgpr_read_b32 v19, a35
	v_accvgpr_read_b32 v40, a36
	v_accvgpr_read_b32 v41, a37
	v_pk_fma_f32 v[46:47], v[46:47], 2.0, 1.0 op_sel_hi:[1,0,0] neg_lo:[1,0,0] neg_hi:[1,0,0]
	v_pk_add_f32 v[20:21], v[116:117], v[112:113] neg_lo:[0,1] neg_hi:[0,1]
	v_cvt_pk_bf16_f32 v128, v46, v47
	ds_write_b64 v138, v[128:129]
	v_pk_fma_f32 v[20:21], v[20:21], v[16:17], v[112:113]
	v_pk_add_f32 v[16:17], v[114:115], v[110:111] neg_lo:[0,1] neg_hi:[0,1]
	v_accvgpr_read_b32 v42, a38
	v_accvgpr_read_b32 v43, a39
	v_accvgpr_read_b32 v44, a40
	v_accvgpr_read_b32 v45, a41
	v_lshlrev_b32_e32 v46, 16, v22
	v_and_b32_e32 v47, 0xffff0000, v22
	v_lshlrev_b32_e32 v38, 16, v23
	v_and_b32_e32 v39, 0xffff0000, v23
	v_pk_fma_f32 v[22:23], v[16:17], v[18:19], v[110:111]
	v_pk_add_f32 v[16:17], v[52:53], v[108:109] neg_lo:[0,1] neg_hi:[0,1]
	v_lshlrev_b32_e32 v18, 16, v24
	v_pk_fma_f32 v[16:17], v[16:17], v[40:41], v[108:109]
; DI void scan_item(const Params& p, int L, int c, int item, char* smem, bool dry) {
;     ...
;     unpack8(Ra_c, cu); unpack8(Ra_p, pv);
; #pragma unroll
;     for (int e = 0; e < 8; ++e) t8[e] = cu[e] + (pv[e] - cu[e]) * PRM[3 * 64 + cs * 8 + e];
;     *(uint4*)(A1 + (1 * 32 + tt) * 72 + cs * 8) = pack8(t8);
;     unpack8(Rv_c, cu); unpack8(Rv_p, pv);
;     float v8[8];
; #pragma unroll
;     for (int e = 0; e < 8; ++e) v8[e] = cu[e] + (pv[e] - cu[e]) * PRM[9 * 64 + c4 * 8 + e];
;     *(float4*)(Vst + tt * 32 + c4 * 8) = make_float4(v8[0], v8[1], v8[2], v8[3]);
;     *(float4*)(Vst + tt * 32 + c4 * 8 + 4) = make_float4(v8[4], v8[5], v8[6], v8[7]);
;     ...
;   auto steps8 = [&](const float* PA, const float* Vst, float* Yst, int t0) {
; #pragma unroll
;     for (int t8 = 0; t8 < 8; ++t8) {
;       const int t = t0 + t8;
;       const float* pa = PA + (t + 1) * 320 + ks * 8;
;       const float4 xd0 = *(const float4*)(pa), xd1 = *(const float4*)(pa + 4);
;       const float4 xn0 = *(const float4*)(pa + 64), xn1 = *(const float4*)(pa + 68);
;       const float4 xb0 = *(const float4*)(pa + 128), xb1 = *(const float4*)(pa + 132);
;       const float4 xk0 = *(const float4*)(pa + 192), xk1 = *(const float4*)(pa + 196);
;       const float4 xr0 = *(const float4*)(pa + 256), xr1 = *(const float4*)(pa + 260);
;       const float xvv = Vst[(t + 1) * 32 + row32];
;       float sa0 = S[0] * n0.x, sa1 = S[1] * n0.y;
;       sa0 = fmaf(S[2], n0.z, sa0); sa1 = fmaf(S[3], n0.w, sa1);
;       sa0 = fmaf(S[4], n1.x, sa0); sa1 = fmaf(S[5], n1.y, sa1);
;       sa0 = fmaf(S[6], n1.z, sa0); sa1 = fmaf(S[7], n1.w, sa1);
;       float sa = red8(sa0 + sa1);
;       S[0] = fmaf(sa, b0.x, fmaf(S[0], d0.x, vv * k0.x)); S[1] = fmaf(sa, b0.y, fmaf(S[1], d0.y, vv * k0.y));
;       S[2] = fmaf(sa, b0.z, fmaf(S[2], d0.z, vv * k0.z)); S[3] = fmaf(sa, b0.w, fmaf(S[3], d0.w, vv * k0.w));
;       S[4] = fmaf(sa, b1.x, fmaf(S[4], d1.x, vv * k1.x)); S[5] = fmaf(sa, b1.y, fmaf(S[5], d1.y, vv * k1.y));
;       S[6] = fmaf(sa, b1.z, fmaf(S[6], d1.z, vv * k1.z)); S[7] = fmaf(sa, b1.w, fmaf(S[7], d1.w, vv * k1.w));
;       float y0 = S[0] * r0.x, y1 = S[1] * r0.y;
;       y0 = fmaf(S[2], r0.z, y0); y1 = fmaf(S[3], r0.w, y1);
;       y0 = fmaf(S[4], r1.x, y0); y1 = fmaf(S[5], r1.y, y1);
;       y0 = fmaf(S[6], r1.z, y0); y1 = fmaf(S[7], r1.w, y1);
;       float y = red8(y0 + y1);
;       Yst[t * 32 + row32] = y;
	v_and_b32_e32 v19, 0xffff0000, v24
	v_lshlrev_b32_e32 v40, 16, v28
	v_and_b32_e32 v41, 0xffff0000, v28
	v_pk_add_f32 v[40:41], v[40:41], v[18:19] neg_lo:[0,1] neg_hi:[0,1]
	v_lshlrev_b32_e32 v24, 16, v25
	v_pk_fma_f32 v[18:19], v[40:41], v[42:43], v[18:19]
	v_lshlrev_b32_e32 v40, 16, v26
	v_and_b32_e32 v41, 0xffff0000, v26
	v_lshlrev_b32_e32 v42, 16, v30
	v_and_b32_e32 v43, 0xffff0000, v30
	v_pk_add_f32 v[42:43], v[42:43], v[40:41] neg_lo:[0,1] neg_hi:[0,1]
	v_cvt_pk_bf16_f32 v18, v18, v19
	v_pk_fma_f32 v[40:41], v[42:43], v[44:45], v[40:41]
	ds_write_b32 v138, v18 offset:4608
	v_cvt_pk_bf16_f32 v30, v40, v41
	v_accvgpr_read_b32 v40, a42
	v_accvgpr_read_b32 v41, a43
	v_pk_add_f32 v[18:19], v[50:51], v[48:49] neg_lo:[0,1] neg_hi:[0,1]
	ds_write_b64 v138, v[154:155] offset:8
	v_and_b32_e32 v25, 0xffff0000, v25
	v_lshlrev_b32_e32 v28, 16, v29
	v_pk_fma_f32 v[18:19], v[18:19], v[40:41], v[48:49]
	v_accvgpr_read_b32 v40, a44
	v_accvgpr_read_b32 v41, a45
	v_accvgpr_read_b32 v42, a46
	v_accvgpr_read_b32 v43, a47
	v_and_b32_e32 v29, 0xffff0000, v29
	v_pk_add_f32 v[28:29], v[28:29], v[24:25] neg_lo:[0,1] neg_hi:[0,1]
	v_lshlrev_b32_e32 v26, 16, v27
	v_pk_fma_f32 v[24:25], v[28:29], v[40:41], v[24:25]
	v_and_b32_e32 v27, 0xffff0000, v27
	v_lshlrev_b32_e32 v28, 16, v31
	v_and_b32_e32 v29, 0xffff0000, v31
	v_pk_add_f32 v[28:29], v[28:29], v[26:27] neg_lo:[0,1] neg_hi:[0,1]
	v_cvt_pk_bf16_f32 v24, v24, v25
	v_pk_fma_f32 v[26:27], v[28:29], v[42:43], v[26:27]
	v_pk_add_f32 v[40:41], v[156:157], v[130:131] neg_lo:[0,1] neg_hi:[0,1]
	v_cvt_pk_bf16_f32 v25, v26, v27
	ds_write_b32 v138, v25 offset:4620
	v_add_u32_e32 v25, 0x1204, v138
	ds_write2_b32 v25, v24, v30 offset1:1
	v_accvgpr_read_b32 v24, a48
	v_accvgpr_read_b32 v25, a49
	v_accvgpr_read_b32 v26, a50
	v_accvgpr_read_b32 v27, a51
	v_accvgpr_read_b32 v28, a52
	v_accvgpr_read_b32 v29, a53
	v_accvgpr_read_b32 v30, a54
	v_accvgpr_read_b32 v31, a55
	v_lshl_add_u32 v33, s34, 12, v140
	s_waitcnt lgkmcnt(5)
	v_pk_mul_f32 v[54:55], v[86:87], v[106:107] op_sel_hi:[1,0]
	s_lshl_b32 s36, s19, 12
	v_pk_fma_f32 v[24:25], v[40:41], v[24:25], v[130:131]
	v_pk_add_f32 v[40:41], v[132:133], v[126:127] neg_lo:[0,1] neg_hi:[0,1]
	v_pk_fma_f32 v[14:15], v[14:15], v[78:79], v[54:55]
	v_pk_fma_f32 v[26:27], v[40:41], v[26:27], v[126:127]
	ds_write_b128 v33, v[24:27]
	v_pk_add_f32 v[24:25], v[46:47], v[36:37] neg_lo:[0,1] neg_hi:[0,1]
	v_pk_add_f32 v[26:27], v[38:39], v[34:35] neg_lo:[0,1] neg_hi:[0,1]
	v_pk_fma_f32 v[24:25], v[24:25], v[28:29], v[36:37]
	v_pk_fma_f32 v[26:27], v[26:27], v[30:31], v[34:35]
	ds_write_b128 v33, v[24:27] offset:16
	ds_read_b128 v[24:27], v149 offset:1280
	ds_read_b128 v[28:31], v149 offset:1296
	ds_read_b128 v[34:37], v149 offset:1536
	ds_read_b128 v[38:41], v149 offset:1552
	ds_read_b128 v[42:45], v149 offset:1792
	ds_read_b128 v[46:49], v149 offset:1808
	ds_read_b128 v[50:53], v149 offset:2048
	ds_read_b128 v[108:111], v149 offset:2064
	ds_read_b128 v[112:115], v149 offset:2304
	ds_read_b128 v[116:119], v149 offset:2320
	ds_read2_b32 v[120:121], v150 offset0:32 offset1:64
	v_pk_fma_f32 v[78:79], v[32:33], v[82:83], v[14:15] op_sel_hi:[0,1,1]
	s_add_i32 s36, s36, 0x17000
	v_add_u32_e32 v151, s36, v107
	v_add_u32_e32 v153, s18, v146
	s_waitcnt lgkmcnt(0)
	v_pk_mul_f32 v[14:15], v[110:111], v[120:121] op_sel_hi:[1,0]
	s_mov_b64 s[18:19], 0
	v_pk_fma_f32 v[82:83], v[78:79], v[30:31], v[14:15]
	v_pk_mul_f32 v[14:15], v[84:85], v[106:107] op_sel_hi:[1,0]
	s_nop 0
	v_pk_fma_f32 v[12:13], v[12:13], v[76:77], v[14:15]
	s_nop 0
	v_pk_fma_f32 v[76:77], v[32:33], v[80:81], v[12:13] op_sel_hi:[0,1,1]
	v_pk_mul_f32 v[12:13], v[108:109], v[120:121] op_sel_hi:[1,0]
	s_nop 0
	v_pk_fma_f32 v[80:81], v[76:77], v[28:29], v[12:13]
	v_pk_mul_f32 v[12:13], v[74:75], v[106:107] op_sel_hi:[1,0]
	s_nop 0
	v_pk_fma_f32 v[10:11], v[10:11], v[66:67], v[12:13]
	s_nop 0
	v_pk_fma_f32 v[74:75], v[32:33], v[70:71], v[10:11] op_sel_hi:[0,1,1]
	v_pk_mul_f32 v[10:11], v[52:53], v[120:121] op_sel_hi:[1,0]
	s_nop 0
	v_pk_fma_f32 v[84:85], v[74:75], v[26:27], v[10:11]
	v_pk_mul_f32 v[10:11], v[72:73], v[106:107] op_sel_hi:[1,0]
	s_nop 0
	v_pk_fma_f32 v[8:9], v[8:9], v[64:65], v[10:11]
	s_nop 0
	v_pk_fma_f32 v[32:33], v[32:33], v[68:69], v[8:9] op_sel_hi:[0,1,1]
	v_pk_mul_f32 v[10:11], v[60:61], v[32:33]
	v_pk_mul_f32 v[8:9], v[50:51], v[120:121] op_sel_hi:[1,0]
	v_pk_fma_f32 v[86:87], v[32:33], v[24:25], v[8:9]
	v_pk_fma_f32 v[10:11], v[74:75], v[62:63], v[10:11]
	v_pk_mul_f32 v[32:33], v[34:35], v[32:33]
	v_pk_fma_f32 v[10:11], v[76:77], v[56:57], v[10:11]
	v_pk_fma_f32 v[32:33], v[74:75], v[36:37], v[32:33]
	v_pk_fma_f32 v[10:11], v[78:79], v[58:59], v[10:11]
	v_pk_fma_f32 v[32:33], v[76:77], v[38:39], v[32:33]
	v_add_f32_e32 v8, v10, v11
	v_pk_fma_f32 v[32:33], v[78:79], v[40:41], v[32:33]
	s_nop 0
	v_add_f32_dpp v8, v8, v8 quad_perm:[1,0,3,2] row_mask:0xf bank_mask:0xf bound_ctrl:1
	v_add_f32_e32 v32, v33, v32
	s_nop 0
	v_add_f32_dpp v8, v8, v8 quad_perm:[2,3,0,1] row_mask:0xf bank_mask:0xf bound_ctrl:1
	v_add_f32_dpp v32, v32, v32 quad_perm:[1,0,3,2] row_mask:0xf bank_mask:0xf bound_ctrl:1
	s_nop 0
	v_add_f32_dpp v8, v8, v8 row_half_mirror row_mask:0xf bank_mask:0xf bound_ctrl:1
	v_add_f32_dpp v32, v32, v32 quad_perm:[2,3,0,1] row_mask:0xf bank_mask:0xf bound_ctrl:1
	ds_write_b32 v151, v8
	ds_read_b128 v[8:11], v149 offset:2560
	ds_read_b128 v[12:15], v149 offset:2576
	ds_read_b128 v[24:27], v149 offset:2816
	ds_read_b128 v[28:31], v149 offset:2832
	ds_read_b128 v[50:53], v149 offset:3072
	ds_read_b128 v[54:57], v149 offset:3088
	ds_read_b128 v[58:61], v149 offset:3328
	ds_read_b128 v[62:65], v149 offset:3344
	ds_read_b128 v[66:69], v149 offset:3584
	ds_read_b128 v[70:73], v149 offset:3600
	v_add_f32_dpp v32, v32, v32 row_half_mirror row_mask:0xf bank_mask:0xf bound_ctrl:1
	v_pk_fma_f32 v[86:87], v[32:33], v[42:43], v[86:87] op_sel_hi:[0,1,1]
	v_pk_fma_f32 v[122:123], v[32:33], v[44:45], v[84:85] op_sel_hi:[0,1,1]
	s_waitcnt lgkmcnt(7)
; DI float red8(float x) { x += dppf(x, 0); x += dppf(x, 1); x += dppf(x, 2); return x; }
; DI void scan_item(const Params& p, int L, int c, int item, char* smem, bool dry) {
;     ...
;   auto steps8 = [&](const float* PA, const float* Vst, float* Yst, int t0) {
; #pragma unroll
;     for (int t8 = 0; t8 < 8; ++t8) {
;       const int t = t0 + t8;
;       const float* pa = PA + (t + 1) * 320 + ks * 8;
;       const float4 xd0 = *(const float4*)(pa), xd1 = *(const float4*)(pa + 4);
;       const float4 xn0 = *(const float4*)(pa + 64), xn1 = *(const float4*)(pa + 68);
;       const float4 xb0 = *(const float4*)(pa + 128), xb1 = *(const float4*)(pa + 132);
;       const float4 xk0 = *(const float4*)(pa + 192), xk1 = *(const float4*)(pa + 196);
;       const float4 xr0 = *(const float4*)(pa + 256), xr1 = *(const float4*)(pa + 260);
;       const float xvv = Vst[(t + 1) * 32 + row32];
;       float sa0 = S[0] * n0.x, sa1 = S[1] * n0.y;
;       sa0 = fmaf(S[2], n0.z, sa0); sa1 = fmaf(S[3], n0.w, sa1);
;       sa0 = fmaf(S[4], n1.x, sa0); sa1 = fmaf(S[5], n1.y, sa1);
;       sa0 = fmaf(S[6], n1.z, sa0); sa1 = fmaf(S[7], n1.w, sa1);
;       float sa = red8(sa0 + sa1);
;       S[0] = fmaf(sa, b0.x, fmaf(S[0], d0.x, vv * k0.x)); S[1] = fmaf(sa, b0.y, fmaf(S[1], d0.y, vv * k0.y));
;       S[2] = fmaf(sa, b0.z, fmaf(S[2], d0.z, vv * k0.z)); S[3] = fmaf(sa, b0.w, fmaf(S[3], d0.w, vv * k0.w));
;       S[4] = fmaf(sa, b1.x, fmaf(S[4], d1.x, vv * k1.x)); S[5] = fmaf(sa, b1.y, fmaf(S[5], d1.y, vv * k1.y));
;       S[6] = fmaf(sa, b1.z, fmaf(S[6], d1.z, vv * k1.z)); S[7] = fmaf(sa, b1.w, fmaf(S[7], d1.w, vv * k1.w));
;       float y0 = S[0] * r0.x, y1 = S[1] * r0.y;
;       y0 = fmaf(S[2], r0.z, y0); y1 = fmaf(S[3], r0.w, y1);
;       y0 = fmaf(S[4], r1.x, y0); y1 = fmaf(S[5], r1.y, y1);
;       y0 = fmaf(S[6], r1.z, y0); y1 = fmaf(S[7], r1.w, y1);
;       float y = red8(y0 + y1);
;       Yst[t * 32 + row32] = y;
;       d0 = xd0; d1 = xd1; n0 = xn0; n1 = xn1; b0 = xb0; b1 = xb1; k0 = xk0; k1 = xk1; r0 = xr0; r1 = xr1; vv = xvv;
	v_pk_mul_f32 v[24:25], v[24:25], v[86:87]
	v_pk_fma_f32 v[124:125], v[32:33], v[46:47], v[80:81] op_sel_hi:[0,1,1]
	v_pk_fma_f32 v[24:25], v[122:123], v[26:27], v[24:25]
	v_pk_fma_f32 v[48:49], v[32:33], v[48:49], v[82:83] op_sel_hi:[0,1,1]
	v_pk_mul_f32 v[32:33], v[112:113], v[86:87]
	s_waitcnt lgkmcnt(6)
	v_pk_fma_f32 v[24:25], v[124:125], v[28:29], v[24:25]
	v_pk_fma_f32 v[32:33], v[122:123], v[114:115], v[32:33]
	v_pk_fma_f32 v[24:25], v[48:49], v[30:31], v[24:25]
	v_pk_fma_f32 v[32:33], v[124:125], v[116:117], v[32:33]
	v_add_f32_e32 v24, v25, v24
	v_pk_fma_f32 v[32:33], v[48:49], v[118:119], v[32:33]
	s_nop 0
	v_add_f32_dpp v24, v24, v24 quad_perm:[1,0,3,2] row_mask:0xf bank_mask:0xf bound_ctrl:1
	v_mov_b32_e32 v26, v121
	v_add_f32_e32 v32, v32, v33
	v_add_f32_dpp v24, v24, v24 quad_perm:[2,3,0,1] row_mask:0xf bank_mask:0xf bound_ctrl:1
	s_waitcnt lgkmcnt(3)
	v_pk_mul_f32 v[28:29], v[58:59], v[26:27] op_sel_hi:[1,0]
	v_add_f32_dpp v32, v32, v32 quad_perm:[1,0,3,2] row_mask:0xf bank_mask:0xf bound_ctrl:1
	v_add_f32_dpp v24, v24, v24 row_half_mirror row_mask:0xf bank_mask:0xf bound_ctrl:1
	v_pk_fma_f32 v[8:9], v[86:87], v[8:9], v[28:29]
	v_add_f32_dpp v32, v32, v32 quad_perm:[2,3,0,1] row_mask:0xf bank_mask:0xf bound_ctrl:1
	v_pk_fma_f32 v[86:87], v[24:25], v[50:51], v[8:9] op_sel_hi:[0,1,1]
	v_pk_mul_f32 v[8:9], v[60:61], v[26:27] op_sel_hi:[1,0]
	v_add_f32_dpp v32, v32, v32 row_half_mirror row_mask:0xf bank_mask:0xf bound_ctrl:1
	v_pk_fma_f32 v[8:9], v[122:123], v[10:11], v[8:9]
	ds_write_b32 v151, v32 offset:128
	v_pk_fma_f32 v[120:121], v[24:25], v[52:53], v[8:9] op_sel_hi:[0,1,1]
	s_waitcnt lgkmcnt(3)
	v_pk_mul_f32 v[8:9], v[62:63], v[26:27] op_sel_hi:[1,0]
	ds_read_b128 v[32:35], v149 offset:3840
	ds_read_b128 v[36:39], v149 offset:3856
	ds_read_b128 v[40:43], v149 offset:4096
	ds_read_b128 v[44:47], v149 offset:4112
	ds_read_b128 v[74:77], v149 offset:4352
	ds_read_b128 v[78:81], v149 offset:4368
	ds_read_b128 v[82:85], v149 offset:4608
	ds_read_b128 v[106:109], v149 offset:4624
	ds_read_b128 v[110:113], v149 offset:4864
	ds_read_b128 v[114:117], v149 offset:4880
	ds_read2_b32 v[118:119], v150 offset0:96 offset1:128
	v_pk_fma_f32 v[8:9], v[124:125], v[12:13], v[8:9]
	s_waitcnt lgkmcnt(8)
	v_pk_mul_f32 v[40:41], v[40:41], v[86:87]
	v_pk_fma_f32 v[122:123], v[24:25], v[54:55], v[8:9] op_sel_hi:[0,1,1]
	v_pk_mul_f32 v[8:9], v[64:65], v[26:27] op_sel_hi:[1,0]
	v_pk_fma_f32 v[40:41], v[120:121], v[42:43], v[40:41]
	v_pk_fma_f32 v[8:9], v[48:49], v[14:15], v[8:9]
	s_waitcnt lgkmcnt(7)
	v_pk_fma_f32 v[40:41], v[122:123], v[44:45], v[40:41]
	v_pk_fma_f32 v[124:125], v[24:25], v[56:57], v[8:9] op_sel_hi:[0,1,1]
	v_pk_fma_f32 v[40:41], v[124:125], v[46:47], v[40:41]
	v_add_f32_e32 v40, v41, v40
	v_pk_mul_f32 v[8:9], v[66:67], v[86:87]
	s_waitcnt lgkmcnt(0)
	v_pk_mul_f32 v[42:43], v[82:83], v[118:119] op_sel_hi:[1,0]
	v_add_f32_dpp v40, v40, v40 quad_perm:[1,0,3,2] row_mask:0xf bank_mask:0xf bound_ctrl:1
	v_pk_fma_f32 v[8:9], v[120:121], v[68:69], v[8:9]
	s_nop 0
	v_add_f32_dpp v40, v40, v40 quad_perm:[2,3,0,1] row_mask:0xf bank_mask:0xf bound_ctrl:1
	v_pk_fma_f32 v[32:33], v[86:87], v[32:33], v[42:43]
	s_nop 0
	v_add_f32_dpp v40, v40, v40 row_half_mirror row_mask:0xf bank_mask:0xf bound_ctrl:1
	v_pk_fma_f32 v[8:9], v[122:123], v[70:71], v[8:9]
	v_pk_fma_f32 v[126:127], v[40:41], v[74:75], v[32:33] op_sel_hi:[0,1,1]
	v_pk_mul_f32 v[32:33], v[84:85], v[118:119] op_sel_hi:[1,0]
	v_pk_fma_f32 v[8:9], v[124:125], v[72:73], v[8:9]
	v_pk_fma_f32 v[32:33], v[120:121], v[34:35], v[32:33]
	v_add_f32_e32 v8, v8, v9
	v_pk_fma_f32 v[120:121], v[40:41], v[76:77], v[32:33] op_sel_hi:[0,1,1]
	v_pk_mul_f32 v[32:33], v[106:107], v[118:119] op_sel_hi:[1,0]
	v_add_f32_dpp v8, v8, v8 quad_perm:[1,0,3,2] row_mask:0xf bank_mask:0xf bound_ctrl:1
	v_pk_fma_f32 v[32:33], v[122:123], v[36:37], v[32:33]
	s_nop 0
	v_add_f32_dpp v8, v8, v8 quad_perm:[2,3,0,1] row_mask:0xf bank_mask:0xf bound_ctrl:1
	v_pk_fma_f32 v[122:123], v[40:41], v[78:79], v[32:33] op_sel_hi:[0,1,1]
	v_pk_mul_f32 v[32:33], v[108:109], v[118:119] op_sel_hi:[1,0]
	v_add_f32_dpp v8, v8, v8 row_half_mirror row_mask:0xf bank_mask:0xf bound_ctrl:1
	v_pk_fma_f32 v[32:33], v[124:125], v[38:39], v[32:33]
	ds_write_b32 v151, v8 offset:256
	v_pk_fma_f32 v[124:125], v[40:41], v[80:81], v[32:33] op_sel_hi:[0,1,1]
	v_pk_mul_f32 v[32:33], v[110:111], v[126:127]
	ds_read_b128 v[8:11], v149 offset:5120
	ds_read_b128 v[12:15], v149 offset:5136
	ds_read_b128 v[24:27], v149 offset:5376
	ds_read_b128 v[28:31], v149 offset:5392
	ds_read_b128 v[48:51], v149 offset:5632
	ds_read_b128 v[52:55], v149 offset:5648
	ds_read_b128 v[56:59], v149 offset:5888
	ds_read_b128 v[60:63], v149 offset:5904
	ds_read_b128 v[64:67], v149 offset:6144
	ds_read_b128 v[68:71], v149 offset:6160
	v_pk_fma_f32 v[32:33], v[120:121], v[112:113], v[32:33]
	v_pk_fma_f32 v[32:33], v[122:123], v[114:115], v[32:33]
	s_waitcnt lgkmcnt(7)
	v_pk_mul_f32 v[24:25], v[24:25], v[126:127]
	v_pk_fma_f32 v[32:33], v[124:125], v[116:117], v[32:33]
	v_pk_fma_f32 v[24:25], v[120:121], v[26:27], v[24:25]
	v_add_f32_e32 v32, v32, v33
	s_waitcnt lgkmcnt(6)
	v_pk_fma_f32 v[24:25], v[122:123], v[28:29], v[24:25]
	v_mov_b32_e32 v26, v119
	v_add_f32_dpp v32, v32, v32 quad_perm:[1,0,3,2] row_mask:0xf bank_mask:0xf bound_ctrl:1
	v_pk_fma_f32 v[24:25], v[124:125], v[30:31], v[24:25]
	s_waitcnt lgkmcnt(3)
; DI float red8(float x) { x += dppf(x, 0); x += dppf(x, 1); x += dppf(x, 2); return x; }
; DI void scan_item(const Params& p, int L, int c, int item, char* smem, bool dry) {
;     ...
;   auto steps8 = [&](const float* PA, const float* Vst, float* Yst, int t0) {
; #pragma unroll
;     for (int t8 = 0; t8 < 8; ++t8) {
;       const int t = t0 + t8;
;       const float* pa = PA + (t + 1) * 320 + ks * 8;
;       const float4 xd0 = *(const float4*)(pa), xd1 = *(const float4*)(pa + 4);
;       const float4 xn0 = *(const float4*)(pa + 64), xn1 = *(const float4*)(pa + 68);
;       const float4 xb0 = *(const float4*)(pa + 128), xb1 = *(const float4*)(pa + 132);
;       const float4 xk0 = *(const float4*)(pa + 192), xk1 = *(const float4*)(pa + 196);
;       const float4 xr0 = *(const float4*)(pa + 256), xr1 = *(const float4*)(pa + 260);
;       const float xvv = Vst[(t + 1) * 32 + row32];
;       float sa0 = S[0] * n0.x, sa1 = S[1] * n0.y;
;       sa0 = fmaf(S[2], n0.z, sa0); sa1 = fmaf(S[3], n0.w, sa1);
;       sa0 = fmaf(S[4], n1.x, sa0); sa1 = fmaf(S[5], n1.y, sa1);
;       sa0 = fmaf(S[6], n1.z, sa0); sa1 = fmaf(S[7], n1.w, sa1);
;       float sa = red8(sa0 + sa1);
;       S[0] = fmaf(sa, b0.x, fmaf(S[0], d0.x, vv * k0.x)); S[1] = fmaf(sa, b0.y, fmaf(S[1], d0.y, vv * k0.y));
;       S[2] = fmaf(sa, b0.z, fmaf(S[2], d0.z, vv * k0.z)); S[3] = fmaf(sa, b0.w, fmaf(S[3], d0.w, vv * k0.w));
;       S[4] = fmaf(sa, b1.x, fmaf(S[4], d1.x, vv * k1.x)); S[5] = fmaf(sa, b1.y, fmaf(S[5], d1.y, vv * k1.y));
;       S[6] = fmaf(sa, b1.z, fmaf(S[6], d1.z, vv * k1.z)); S[7] = fmaf(sa, b1.w, fmaf(S[7], d1.w, vv * k1.w));
;       float y0 = S[0] * r0.x, y1 = S[1] * r0.y;
;       y0 = fmaf(S[2], r0.z, y0); y1 = fmaf(S[3], r0.w, y1);
;       y0 = fmaf(S[4], r1.x, y0); y1 = fmaf(S[5], r1.y, y1);
;       y0 = fmaf(S[6], r1.z, y0); y1 = fmaf(S[7], r1.w, y1);
;       float y = red8(y0 + y1);
;       Yst[t * 32 + row32] = y;
;       d0 = xd0; d1 = xd1; n0 = xn0; n1 = xn1; b0 = xb0; b1 = xb1; k0 = xk0; k1 = xk1; r0 = xr0; r1 = xr1; vv = xvv;
	v_pk_mul_f32 v[28:29], v[56:57], v[26:27] op_sel_hi:[1,0]
	v_add_f32_dpp v32, v32, v32 quad_perm:[2,3,0,1] row_mask:0xf bank_mask:0xf bound_ctrl:1
	v_add_f32_e32 v24, v25, v24
	v_pk_fma_f32 v[8:9], v[126:127], v[8:9], v[28:29]
	v_add_f32_dpp v32, v32, v32 row_half_mirror row_mask:0xf bank_mask:0xf bound_ctrl:1
	v_add_f32_dpp v24, v24, v24 quad_perm:[1,0,3,2] row_mask:0xf bank_mask:0xf bound_ctrl:1
	ds_write_b32 v151, v32 offset:384
	ds_read_b128 v[32:35], v149 offset:6400
	ds_read_b128 v[36:39], v149 offset:6416
	ds_read_b128 v[40:43], v149 offset:6656
	ds_read_b128 v[44:47], v149 offset:6672
	ds_read_b128 v[72:75], v149 offset:6912
	ds_read_b128 v[76:79], v149 offset:6928
	ds_read_b128 v[80:83], v149 offset:7168
	ds_read_b128 v[84:87], v149 offset:7184
	ds_read_b128 v[106:109], v149 offset:7424
	ds_read_b128 v[110:113], v149 offset:7440
	ds_read2_b32 v[128:129], v150 offset0:160 offset1:192
	v_add_f32_dpp v24, v24, v24 quad_perm:[2,3,0,1] row_mask:0xf bank_mask:0xf bound_ctrl:1
	v_pk_mul_f32 v[28:29], v[58:59], v[26:27] op_sel_hi:[1,0]
	s_nop 0
	v_add_f32_dpp v24, v24, v24 row_half_mirror row_mask:0xf bank_mask:0xf bound_ctrl:1
	v_pk_fma_f32 v[8:9], v[24:25], v[48:49], v[8:9] op_sel_hi:[0,1,1]
	v_pk_fma_f32 v[10:11], v[120:121], v[10:11], v[28:29]
	s_waitcnt lgkmcnt(13)
	v_mul_f32_e32 v25, v64, v8
	v_pk_mul_f32 v[28:29], v[60:61], v[26:27] op_sel_hi:[1,0]
	v_pk_fma_f32 v[114:115], v[24:25], v[50:51], v[10:11] op_sel_hi:[0,1,1]
	v_pk_fma_f32 v[12:13], v[122:123], v[12:13], v[28:29]
	v_pk_mul_f32 v[26:27], v[62:63], v[26:27] op_sel_hi:[1,0]
	v_fmac_f32_e32 v25, v114, v66
	v_pk_fma_f32 v[14:15], v[124:125], v[14:15], v[26:27]
	v_mul_f32_e32 v28, v65, v9
	s_waitcnt lgkmcnt(0)
	v_pk_mul_f32 v[26:27], v[80:81], v[128:129] op_sel_hi:[1,0]
	v_pk_fma_f32 v[116:117], v[24:25], v[52:53], v[12:13] op_sel_hi:[0,1,1]
	v_pk_fma_f32 v[80:81], v[8:9], v[32:33], v[26:27]
	v_pk_mul_f32 v[10:11], v[82:83], v[128:129] op_sel_hi:[1,0]
	v_fmac_f32_e32 v28, v115, v67
	v_fmac_f32_e32 v25, v116, v68
	v_pk_mul_f32 v[8:9], v[40:41], v[8:9]
	v_pk_fma_f32 v[82:83], v[114:115], v[34:35], v[10:11]
	v_pk_mul_f32 v[10:11], v[84:85], v[128:129] op_sel_hi:[1,0]
	v_fmac_f32_e32 v28, v117, v69
	v_pk_fma_f32 v[14:15], v[24:25], v[54:55], v[14:15] op_sel_hi:[0,1,1]
	v_pk_fma_f32 v[8:9], v[114:115], v[42:43], v[8:9]
	v_pk_fma_f32 v[84:85], v[116:117], v[36:37], v[10:11]
	v_pk_mul_f32 v[10:11], v[86:87], v[128:129] op_sel_hi:[1,0]
	v_fmac_f32_e32 v25, v14, v70
	v_fmac_f32_e32 v28, v15, v71
	v_pk_fma_f32 v[8:9], v[116:117], v[44:45], v[8:9]
	v_pk_fma_f32 v[68:69], v[14:15], v[38:39], v[10:11]
	v_add_f32_e32 v10, v25, v28
	v_pk_fma_f32 v[8:9], v[14:15], v[46:47], v[8:9]
	v_add_u32_e32 v128, 0x400, v150
	v_add_f32_dpp v10, v10, v10 quad_perm:[1,0,3,2] row_mask:0xf bank_mask:0xf bound_ctrl:1
	v_add_f32_e32 v8, v9, v8
	s_nop 0
	v_add_f32_dpp v10, v10, v10 quad_perm:[2,3,0,1] row_mask:0xf bank_mask:0xf bound_ctrl:1
	v_add_f32_dpp v8, v8, v8 quad_perm:[1,0,3,2] row_mask:0xf bank_mask:0xf bound_ctrl:1
	s_nop 0
	v_add_f32_dpp v10, v10, v10 row_half_mirror row_mask:0xf bank_mask:0xf bound_ctrl:1
	v_add_f32_dpp v8, v8, v8 quad_perm:[2,3,0,1] row_mask:0xf bank_mask:0xf bound_ctrl:1
	ds_write_b32 v151, v10 offset:512
	ds_read_b128 v[10:13], v149 offset:7680
	ds_read_b128 v[24:27], v149 offset:7696
	ds_read_b128 v[28:31], v149 offset:7936
	ds_read_b128 v[32:35], v149 offset:7952
	ds_read_b128 v[36:39], v149 offset:8192
	ds_read_b128 v[48:51], v149 offset:8208
	ds_read_b128 v[52:55], v149 offset:8448
	ds_read_b128 v[56:59], v149 offset:8464
	ds_read_b128 v[60:63], v149 offset:8704
	ds_read_b128 v[64:67], v149 offset:8720
	v_add_f32_dpp v8, v8, v8 row_half_mirror row_mask:0xf bank_mask:0xf bound_ctrl:1
	v_pk_fma_f32 v[14:15], v[8:9], v[72:73], v[80:81] op_sel_hi:[0,1,1]
	v_pk_fma_f32 v[118:119], v[8:9], v[74:75], v[82:83] op_sel_hi:[0,1,1]
	s_waitcnt lgkmcnt(7)
	v_pk_mul_f32 v[28:29], v[28:29], v[14:15]
	v_pk_fma_f32 v[120:121], v[8:9], v[76:77], v[84:85] op_sel_hi:[0,1,1]
	v_pk_fma_f32 v[28:29], v[118:119], v[30:31], v[28:29]
	v_pk_fma_f32 v[122:123], v[8:9], v[78:79], v[68:69] op_sel_hi:[0,1,1]
	v_pk_mul_f32 v[8:9], v[106:107], v[14:15]
	s_waitcnt lgkmcnt(6)
	v_pk_fma_f32 v[28:29], v[120:121], v[32:33], v[28:29]
	v_pk_fma_f32 v[8:9], v[118:119], v[108:109], v[8:9]
	v_pk_fma_f32 v[28:29], v[122:123], v[34:35], v[28:29]
	v_pk_fma_f32 v[8:9], v[120:121], v[110:111], v[8:9]
	v_add_f32_e32 v28, v29, v28
	v_pk_fma_f32 v[8:9], v[122:123], v[112:113], v[8:9]
	s_nop 0
	v_add_f32_dpp v28, v28, v28 quad_perm:[1,0,3,2] row_mask:0xf bank_mask:0xf bound_ctrl:1
	v_mov_b32_e32 v30, v129
	v_add_f32_e32 v8, v8, v9
	v_add_f32_dpp v28, v28, v28 quad_perm:[2,3,0,1] row_mask:0xf bank_mask:0xf bound_ctrl:1
	s_waitcnt lgkmcnt(3)
	v_pk_mul_f32 v[32:33], v[52:53], v[30:31] op_sel_hi:[1,0]
	v_add_f32_dpp v8, v8, v8 quad_perm:[1,0,3,2] row_mask:0xf bank_mask:0xf bound_ctrl:1
	v_add_f32_dpp v28, v28, v28 row_half_mirror row_mask:0xf bank_mask:0xf bound_ctrl:1
	v_pk_fma_f32 v[10:11], v[14:15], v[10:11], v[32:33]
	v_add_f32_dpp v8, v8, v8 quad_perm:[2,3,0,1] row_mask:0xf bank_mask:0xf bound_ctrl:1
	v_pk_fma_f32 v[14:15], v[28:29], v[36:37], v[10:11] op_sel_hi:[0,1,1]
	v_pk_mul_f32 v[10:11], v[54:55], v[30:31] op_sel_hi:[1,0]
	v_add_f32_dpp v8, v8, v8 row_half_mirror row_mask:0xf bank_mask:0xf bound_ctrl:1
	v_pk_fma_f32 v[10:11], v[118:119], v[12:13], v[10:11]
	ds_write_b32 v151, v8 offset:640
	v_pk_fma_f32 v[118:119], v[28:29], v[38:39], v[10:11] op_sel_hi:[0,1,1]
	s_waitcnt lgkmcnt(3)
; DI void scan_item(const Params& p, int L, int c, int item, char* smem, bool dry) {
;     ...
;   auto prep3 = [&]() {
;     const int arr = w >> 1, nt = w & 1;
;     f32x16 acc;
; #pragma unroll
;     for (int e = 0; e < 16; ++e) acc[e] = 0.f;
; #pragma unroll
;     for (int k4 = 0; k4 < 4; ++k4) {
;       bf16x8 a = *(const bf16x8*)(A1 + (arr * 32 + r) * 72 + 16 * k4 + 8 * h);
;       bf16x8 bw = *(const bf16x8*)(W2t + (arr * 64 + 32 * nt + r) * 72 + 16 * k4 + 8 * h);
;       acc = MFMA32(a, bw, acc);
;     }
; #pragma unroll
;     ...
;   auto steps8 = [&](const float* PA, const float* Vst, float* Yst, int t0) {
; #pragma unroll
;     for (int t8 = 0; t8 < 8; ++t8) {
;       const int t = t0 + t8;
;       const float* pa = PA + (t + 1) * 320 + ks * 8;
;       const float4 xd0 = *(const float4*)(pa), xd1 = *(const float4*)(pa + 4);
;       const float4 xn0 = *(const float4*)(pa + 64), xn1 = *(const float4*)(pa + 68);
;       const float4 xb0 = *(const float4*)(pa + 128), xb1 = *(const float4*)(pa + 132);
;       const float4 xk0 = *(const float4*)(pa + 192), xk1 = *(const float4*)(pa + 196);
;       const float4 xr0 = *(const float4*)(pa + 256), xr1 = *(const float4*)(pa + 260);
;       const float xvv = Vst[(t + 1) * 32 + row32];
;       float sa0 = S[0] * n0.x, sa1 = S[1] * n0.y;
;       sa0 = fmaf(S[2], n0.z, sa0); sa1 = fmaf(S[3], n0.w, sa1);
;       sa0 = fmaf(S[4], n1.x, sa0); sa1 = fmaf(S[5], n1.y, sa1);
;       sa0 = fmaf(S[6], n1.z, sa0); sa1 = fmaf(S[7], n1.w, sa1);
;       float sa = red8(sa0 + sa1);
;       S[0] = fmaf(sa, b0.x, fmaf(S[0], d0.x, vv * k0.x)); S[1] = fmaf(sa, b0.y, fmaf(S[1], d0.y, vv * k0.y));
;       S[2] = fmaf(sa, b0.z, fmaf(S[2], d0.z, vv * k0.z)); S[3] = fmaf(sa, b0.w, fmaf(S[3], d0.w, vv * k0.w));
;       S[4] = fmaf(sa, b1.x, fmaf(S[4], d1.x, vv * k1.x)); S[5] = fmaf(sa, b1.y, fmaf(S[5], d1.y, vv * k1.y));
;       S[6] = fmaf(sa, b1.z, fmaf(S[6], d1.z, vv * k1.z)); S[7] = fmaf(sa, b1.w, fmaf(S[7], d1.w, vv * k1.w));
;       float y0 = S[0] * r0.x, y1 = S[1] * r0.y;
;       y0 = fmaf(S[2], r0.z, y0); y1 = fmaf(S[3], r0.w, y1);
;       y0 = fmaf(S[4], r1.x, y0); y1 = fmaf(S[5], r1.y, y1);
;       y0 = fmaf(S[6], r1.z, y0); y1 = fmaf(S[7], r1.w, y1);
;       float y = red8(y0 + y1);
;       Yst[t * 32 + row32] = y;
;       d0 = xd0; d1 = xd1; n0 = xn0; n1 = xn1; b0 = xb0; b1 = xb1; k0 = xk0; k1 = xk1; r0 = xr0; r1 = xr1; vv = xvv;
	v_pk_mul_f32 v[10:11], v[56:57], v[30:31] op_sel_hi:[1,0]
	ds_read_b128 v[40:43], v149 offset:8960
	ds_read_b128 v[44:47], v149 offset:8976
	ds_read_b128 v[68:71], v149 offset:9216
	ds_read_b128 v[72:75], v149 offset:9232
	ds_read_b128 v[76:79], v149 offset:9472
	ds_read_b128 v[80:83], v149 offset:9488
	ds_read_b128 v[84:87], v149 offset:9728
	ds_read_b128 v[106:109], v149 offset:9744
	ds_read_b128 v[110:113], v149 offset:9984
	ds_read_b128 v[114:117], v149 offset:10000
	v_add_u32_e32 v8, 0x200, v150
	v_pk_fma_f32 v[10:11], v[120:121], v[24:25], v[10:11]
	ds_read2_b32 v[8:9], v8 offset0:96 offset1:128
	v_pk_fma_f32 v[120:121], v[28:29], v[48:49], v[10:11] op_sel_hi:[0,1,1]
	v_pk_mul_f32 v[10:11], v[58:59], v[30:31] op_sel_hi:[1,0]
	s_waitcnt lgkmcnt(8)
	v_pk_mul_f32 v[68:69], v[68:69], v[14:15]
	v_pk_fma_f32 v[10:11], v[122:123], v[26:27], v[10:11]
	v_pk_fma_f32 v[68:69], v[118:119], v[70:71], v[68:69]
	v_pk_fma_f32 v[122:123], v[28:29], v[50:51], v[10:11] op_sel_hi:[0,1,1]
	s_waitcnt lgkmcnt(7)
	v_pk_fma_f32 v[68:69], v[120:121], v[72:73], v[68:69]
	s_waitcnt lgkmcnt(0)
	v_pk_mul_f32 v[70:71], v[84:85], v[8:9] op_sel_hi:[1,0]
	v_pk_fma_f32 v[68:69], v[122:123], v[74:75], v[68:69]
	v_add_f32_e32 v68, v69, v68
	v_pk_mul_f32 v[10:11], v[60:61], v[14:15]
	v_pk_fma_f32 v[14:15], v[14:15], v[40:41], v[70:71]
	v_add_f32_dpp v68, v68, v68 quad_perm:[1,0,3,2] row_mask:0xf bank_mask:0xf bound_ctrl:1
	v_pk_mul_f32 v[40:41], v[86:87], v[8:9] op_sel_hi:[1,0]
	s_nop 0
	v_add_f32_dpp v68, v68, v68 quad_perm:[2,3,0,1] row_mask:0xf bank_mask:0xf bound_ctrl:1
	v_pk_fma_f32 v[40:41], v[118:119], v[42:43], v[40:41]
	v_pk_fma_f32 v[10:11], v[118:119], v[62:63], v[10:11]
	v_add_f32_dpp v68, v68, v68 row_half_mirror row_mask:0xf bank_mask:0xf bound_ctrl:1
	v_pk_fma_f32 v[118:119], v[68:69], v[78:79], v[40:41] op_sel_hi:[0,1,1]
	v_pk_mul_f32 v[40:41], v[106:107], v[8:9] op_sel_hi:[1,0]
	v_pk_fma_f32 v[40:41], v[120:121], v[44:45], v[40:41]
	v_pk_fma_f32 v[10:11], v[120:121], v[64:65], v[10:11]
	v_pk_fma_f32 v[120:121], v[68:69], v[80:81], v[40:41] op_sel_hi:[0,1,1]
	v_pk_mul_f32 v[40:41], v[108:109], v[8:9] op_sel_hi:[1,0]
	v_pk_fma_f32 v[14:15], v[68:69], v[76:77], v[14:15] op_sel_hi:[0,1,1]
	v_pk_fma_f32 v[40:41], v[122:123], v[46:47], v[40:41]
	v_pk_fma_f32 v[10:11], v[122:123], v[66:67], v[10:11]
	v_pk_fma_f32 v[122:123], v[68:69], v[82:83], v[40:41] op_sel_hi:[0,1,1]
	v_mul_f32_e32 v8, v110, v14
	v_mul_f32_e32 v40, v111, v15
	v_fmac_f32_e32 v8, v118, v112
	v_fmac_f32_e32 v40, v119, v113
	v_fmac_f32_e32 v8, v120, v114
	v_fmac_f32_e32 v40, v121, v115
	v_add_f32_e32 v10, v10, v11
	v_fmac_f32_e32 v8, v122, v116
	v_fmac_f32_e32 v40, v123, v117
	v_add_f32_dpp v10, v10, v10 quad_perm:[1,0,3,2] row_mask:0xf bank_mask:0xf bound_ctrl:1
	v_add_f32_e32 v8, v8, v40
	s_nop 0
	v_add_f32_dpp v10, v10, v10 quad_perm:[2,3,0,1] row_mask:0xf bank_mask:0xf bound_ctrl:1
	v_add_f32_dpp v8, v8, v8 quad_perm:[1,0,3,2] row_mask:0xf bank_mask:0xf bound_ctrl:1
	s_nop 0
	v_add_f32_dpp v10, v10, v10 row_half_mirror row_mask:0xf bank_mask:0xf bound_ctrl:1
	v_add_f32_dpp v8, v8, v8 quad_perm:[2,3,0,1] row_mask:0xf bank_mask:0xf bound_ctrl:1
	ds_write_b32 v151, v10 offset:768
	ds_read_b128 v[10:13], v149 offset:10240
	ds_read_b128 v[24:27], v149 offset:10256
	ds_read_b128 v[28:31], v149 offset:10496
	ds_read_b128 v[32:35], v149 offset:10512
	ds_read_b128 v[36:39], v149 offset:10752
	ds_read_b128 v[48:51], v149 offset:10768
	ds_read_b128 v[52:55], v149 offset:11008
	ds_read_b128 v[56:59], v149 offset:11024
	ds_read_b128 v[60:63], v149 offset:11264
	ds_read_b128 v[64:67], v149 offset:11280
	v_add_f32_dpp v8, v8, v8 row_half_mirror row_mask:0xf bank_mask:0xf bound_ctrl:1
	ds_write_b32 v151, v8 offset:896
	s_waitcnt lgkmcnt(0)
	s_barrier
	ds_read_b128 v[40:43], v141
	ds_read_b128 v[44:47], v141 offset:32
	ds_read_b128 v[68:71], v142
	ds_read_b128 v[72:75], v142 offset:32
	s_waitcnt lgkmcnt(1)
	v_mfma_f32_32x32x16_bf16 a[0:15], v[40:43], v[68:71], 0
	v_mul_f32_e64 v28, v28, v14
	v_mul_f32_e64 v29, v29, v15
	v_fma_f32 v28, v118, v30, v28
	v_fma_f32 v29, v119, v31, v29
	v_fma_f32 v28, v120, v32, v28
	v_fma_f32 v29, v121, v33, v29
	v_pk_fma_f32 v[28:29], v[122:123], v[34:35], v[28:29]
	s_waitcnt lgkmcnt(0)
	v_mfma_f32_32x32x16_bf16 a[0:15], v[44:47], v[72:75], a[0:15]
	ds_read_b128 v[40:43], v141 offset:64
	ds_read_b128 v[44:47], v142 offset:64
	v_add_f32_e32 v8, v28, v29
	v_mov_b32_e32 v28, v9
	v_mul_f32_e64 v30, v52, v28
	v_mul_f32_e64 v31, v53, v28
	v_add_f32_dpp v8, v8, v8 quad_perm:[1,0,3,2] row_mask:0xf bank_mask:0xf bound_ctrl:1
	v_pk_fma_f32 v[10:11], v[14:15], v[10:11], v[30:31]
	s_waitcnt lgkmcnt(0)
	v_mfma_f32_32x32x16_bf16 a[0:15], v[40:43], v[44:47], a[0:15]
	ds_read_b128 v[40:43], v141 offset:96
	ds_read_b128 v[44:47], v142 offset:96
	v_add_f32_dpp v8, v8, v8 quad_perm:[2,3,0,1] row_mask:0xf bank_mask:0xf bound_ctrl:1
	s_nop 1
	v_add_f32_dpp v8, v8, v8 row_half_mirror row_mask:0xf bank_mask:0xf bound_ctrl:1
	v_fma_f32 v126, v8, v36, v10
	v_fma_f32 v127, v8, v37, v11
	v_pk_mul_f32 v[10:11], v[54:55], v[28:29] op_sel_hi:[1,0]
	s_waitcnt lgkmcnt(0)
; DI void scan_item(const Params& p, int L, int c, int item, char* smem, bool dry) {
;     ...
;   auto prep3 = [&]() {
;     const int arr = w >> 1, nt = w & 1;
;     f32x16 acc;
; #pragma unroll
;     for (int e = 0; e < 16; ++e) acc[e] = 0.f;
; #pragma unroll
;     for (int k4 = 0; k4 < 4; ++k4) {
;       bf16x8 a = *(const bf16x8*)(A1 + (arr * 32 + r) * 72 + 16 * k4 + 8 * h);
;       bf16x8 bw = *(const bf16x8*)(W2t + (arr * 64 + 32 * nt + r) * 72 + 16 * k4 + 8 * h);
;       acc = MFMA32(a, bw, acc);
;     }
; #pragma unroll
;     for (int e = 0; e < 16; ++e) LO[(arr * 32 + crow(e, h)) * 64 + 32 * nt + r] = acc[e];
;   };
;     ...
;   auto steps8 = [&](const float* PA, const float* Vst, float* Yst, int t0) {
; #pragma unroll
;     for (int t8 = 0; t8 < 8; ++t8) {
;       const int t = t0 + t8;
;       const float* pa = PA + (t + 1) * 320 + ks * 8;
;       const float4 xd0 = *(const float4*)(pa), xd1 = *(const float4*)(pa + 4);
;       const float4 xn0 = *(const float4*)(pa + 64), xn1 = *(const float4*)(pa + 68);
;       const float4 xb0 = *(const float4*)(pa + 128), xb1 = *(const float4*)(pa + 132);
;       const float4 xk0 = *(const float4*)(pa + 192), xk1 = *(const float4*)(pa + 196);
;       const float4 xr0 = *(const float4*)(pa + 256), xr1 = *(const float4*)(pa + 260);
;       const float xvv = Vst[(t + 1) * 32 + row32];
;       float sa0 = S[0] * n0.x, sa1 = S[1] * n0.y;
;       sa0 = fmaf(S[2], n0.z, sa0); sa1 = fmaf(S[3], n0.w, sa1);
;       sa0 = fmaf(S[4], n1.x, sa0); sa1 = fmaf(S[5], n1.y, sa1);
;       sa0 = fmaf(S[6], n1.z, sa0); sa1 = fmaf(S[7], n1.w, sa1);
;       float sa = red8(sa0 + sa1);
;       S[0] = fmaf(sa, b0.x, fmaf(S[0], d0.x, vv * k0.x)); S[1] = fmaf(sa, b0.y, fmaf(S[1], d0.y, vv * k0.y));
;       S[2] = fmaf(sa, b0.z, fmaf(S[2], d0.z, vv * k0.z)); S[3] = fmaf(sa, b0.w, fmaf(S[3], d0.w, vv * k0.w));
;       S[4] = fmaf(sa, b1.x, fmaf(S[4], d1.x, vv * k1.x)); S[5] = fmaf(sa, b1.y, fmaf(S[5], d1.y, vv * k1.y));
;       S[6] = fmaf(sa, b1.z, fmaf(S[6], d1.z, vv * k1.z)); S[7] = fmaf(sa, b1.w, fmaf(S[7], d1.w, vv * k1.w));
;       float y0 = S[0] * r0.x, y1 = S[1] * r0.y;
;       y0 = fmaf(S[2], r0.z, y0); y1 = fmaf(S[3], r0.w, y1);
;       y0 = fmaf(S[4], r1.x, y0); y1 = fmaf(S[5], r1.y, y1);
;       y0 = fmaf(S[6], r1.z, y0); y1 = fmaf(S[7], r1.w, y1);
;       float y = red8(y0 + y1);
;       Yst[t * 32 + row32] = y;
	v_mfma_f32_32x32x16_bf16 a[0:15], v[40:43], v[44:47], a[0:15]
	v_fma_f32 v10, v118, v12, v10
	v_fma_f32 v11, v119, v13, v11
	s_nop 9
	ds_write_b32 v144, a0
	ds_write_b32 v144, a1 offset:256
	ds_write_b32 v144, a2 offset:512
	ds_write_b32 v144, a3 offset:768
	ds_write_b32 v144, a4 offset:2048
	ds_write_b32 v144, a5 offset:2304
	ds_write_b32 v144, a6 offset:2560
	ds_write_b32 v144, a7 offset:2816
	ds_write_b32 v144, a8 offset:4096
	ds_write_b32 v144, a9 offset:4352
	ds_write_b32 v144, a10 offset:4608
	ds_write_b32 v144, a11 offset:4864
	ds_write_b32 v144, a12 offset:6144
	ds_write_b32 v144, a13 offset:6400
	ds_write_b32 v144, a14 offset:6656
	ds_write_b32 v144, a15 offset:6912
	v_pk_fma_f32 v[118:119], v[8:9], v[38:39], v[10:11] op_sel_hi:[0,1,1]
	v_pk_mul_f32 v[10:11], v[56:57], v[28:29] op_sel_hi:[1,0]
	ds_read_b128 v[40:43], v149 offset:11520
	ds_read_b128 v[44:47], v149 offset:11536
	ds_read_b128 v[68:71], v149 offset:11776
	ds_read_b128 v[72:75], v149 offset:11792
	ds_read_b128 v[76:79], v149 offset:12032
	ds_read_b128 v[80:83], v149 offset:12048
	ds_read_b128 v[84:87], v149 offset:12288
	ds_read_b128 v[106:109], v149 offset:12304
	ds_read_b128 v[110:113], v149 offset:12544
	ds_read_b128 v[114:117], v149 offset:12560
	v_pk_fma_f32 v[10:11], v[120:121], v[24:25], v[10:11]
	ds_read2_b32 v[124:125], v128 offset0:32 offset1:64
	v_pk_fma_f32 v[120:121], v[8:9], v[48:49], v[10:11] op_sel_hi:[0,1,1]
	v_pk_mul_f32 v[10:11], v[58:59], v[28:29] op_sel_hi:[1,0]
	s_nop 0
	v_pk_fma_f32 v[10:11], v[122:123], v[26:27], v[10:11]
	s_nop 0
	v_pk_fma_f32 v[122:123], v[8:9], v[50:51], v[10:11] op_sel_hi:[0,1,1]
	v_pk_mul_f32 v[8:9], v[60:61], v[126:127]
	v_pk_fma_f32 v[8:9], v[118:119], v[62:63], v[8:9]
	v_pk_fma_f32 v[8:9], v[120:121], v[64:65], v[8:9]
	s_waitcnt lgkmcnt(8)
	v_pk_mul_f32 v[64:65], v[68:69], v[126:127]
	v_pk_fma_f32 v[64:65], v[118:119], v[70:71], v[64:65]
	v_pk_fma_f32 v[8:9], v[122:123], v[66:67], v[8:9]
	s_waitcnt lgkmcnt(7)
	v_pk_fma_f32 v[64:65], v[120:121], v[72:73], v[64:65]
	s_waitcnt lgkmcnt(0)
	v_pk_mul_f32 v[66:67], v[84:85], v[124:125] op_sel_hi:[1,0]
	v_pk_fma_f32 v[64:65], v[122:123], v[74:75], v[64:65]
	v_pk_fma_f32 v[40:41], v[126:127], v[40:41], v[66:67]
	v_add_f32_e32 v64, v65, v64
	v_add_f32_e32 v8, v8, v9
	s_nop 0
	v_add_f32_dpp v64, v64, v64 quad_perm:[1,0,3,2] row_mask:0xf bank_mask:0xf bound_ctrl:1
	v_add_f32_dpp v8, v8, v8 quad_perm:[1,0,3,2] row_mask:0xf bank_mask:0xf bound_ctrl:1
	s_nop 0
	v_add_f32_dpp v64, v64, v64 quad_perm:[2,3,0,1] row_mask:0xf bank_mask:0xf bound_ctrl:1
	v_add_f32_dpp v8, v8, v8 quad_perm:[2,3,0,1] row_mask:0xf bank_mask:0xf bound_ctrl:1
	s_nop 0
	v_add_f32_dpp v64, v64, v64 row_half_mirror row_mask:0xf bank_mask:0xf bound_ctrl:1
	v_pk_fma_f32 v[126:127], v[64:65], v[76:77], v[40:41] op_sel_hi:[0,1,1]
	v_pk_mul_f32 v[40:41], v[86:87], v[124:125] op_sel_hi:[1,0]
	v_add_f32_dpp v8, v8, v8 row_half_mirror row_mask:0xf bank_mask:0xf bound_ctrl:1
	v_pk_fma_f32 v[40:41], v[118:119], v[42:43], v[40:41]
	ds_write_b32 v151, v8 offset:1024
	v_pk_fma_f32 v[118:119], v[64:65], v[78:79], v[40:41] op_sel_hi:[0,1,1]
	v_pk_mul_f32 v[40:41], v[106:107], v[124:125] op_sel_hi:[1,0]
	ds_read_b128 v[8:11], v149 offset:12800
	ds_read_b128 v[12:15], v149 offset:12816
	ds_read_b128 v[24:27], v149 offset:13056
	ds_read_b128 v[28:31], v149 offset:13072
	ds_read_b128 v[32:35], v149 offset:13312
	ds_read_b128 v[36:39], v149 offset:13328
	ds_read_b128 v[48:51], v149 offset:13568
	ds_read_b128 v[52:55], v149 offset:13584
	ds_read_b128 v[56:59], v149 offset:13824
	ds_read_b128 v[60:63], v149 offset:13840
	v_pk_fma_f32 v[40:41], v[120:121], v[44:45], v[40:41]
	s_waitcnt lgkmcnt(7)
	v_pk_mul_f32 v[24:25], v[24:25], v[126:127]
	v_pk_fma_f32 v[120:121], v[64:65], v[80:81], v[40:41] op_sel_hi:[0,1,1]
	v_pk_mul_f32 v[40:41], v[108:109], v[124:125] op_sel_hi:[1,0]
	v_pk_fma_f32 v[24:25], v[118:119], v[26:27], v[24:25]
	v_pk_fma_f32 v[40:41], v[122:123], v[46:47], v[40:41]
	s_waitcnt lgkmcnt(6)
	v_pk_fma_f32 v[24:25], v[120:121], v[28:29], v[24:25]
	v_pk_fma_f32 v[122:123], v[64:65], v[82:83], v[40:41] op_sel_hi:[0,1,1]
	v_pk_mul_f32 v[40:41], v[110:111], v[126:127]
	v_pk_fma_f32 v[40:41], v[118:119], v[112:113], v[40:41]
	v_pk_fma_f32 v[40:41], v[120:121], v[114:115], v[40:41]
	v_pk_fma_f32 v[40:41], v[122:123], v[116:117], v[40:41]
	v_add_f32_e32 v40, v40, v41
	v_pk_fma_f32 v[24:25], v[122:123], v[30:31], v[24:25]
	v_mov_b32_e32 v26, v125
	v_add_f32_dpp v40, v40, v40 quad_perm:[1,0,3,2] row_mask:0xf bank_mask:0xf bound_ctrl:1
	v_add_f32_e32 v24, v25, v24
	s_waitcnt lgkmcnt(3)
	v_pk_mul_f32 v[28:29], v[48:49], v[26:27] op_sel_hi:[1,0]
	v_add_f32_dpp v40, v40, v40 quad_perm:[2,3,0,1] row_mask:0xf bank_mask:0xf bound_ctrl:1
	v_add_f32_dpp v24, v24, v24 quad_perm:[1,0,3,2] row_mask:0xf bank_mask:0xf bound_ctrl:1
	v_pk_mul_f32 v[30:31], v[50:51], v[26:27] op_sel_hi:[1,0]
	v_add_f32_dpp v40, v40, v40 row_half_mirror row_mask:0xf bank_mask:0xf bound_ctrl:1
	ds_write_b32 v151, v40 offset:1152
	ds_read_b128 v[40:43], v149 offset:14080
	ds_read_b128 v[44:47], v149 offset:14096
	ds_read_b128 v[64:67], v149 offset:14336
	ds_read_b128 v[68:71], v149 offset:14352
	ds_read_b128 v[72:75], v149 offset:14592
	ds_read_b128 v[76:79], v149 offset:14608
	ds_read_b128 v[80:83], v149 offset:14848
	ds_read_b128 v[84:87], v149 offset:14864
	ds_read_b128 v[106:109], v149 offset:15104
	ds_read_b128 v[110:113], v149 offset:15120
	ds_read2_b32 v[114:115], v128 offset0:96 offset1:128
	v_add_f32_dpp v24, v24, v24 quad_perm:[2,3,0,1] row_mask:0xf bank_mask:0xf bound_ctrl:1
	s_waitcnt lgkmcnt(14)
; DI float red8(float x) { x += dppf(x, 0); x += dppf(x, 1); x += dppf(x, 2); return x; }
; DI void scan_item(const Params& p, int L, int c, int item, char* smem, bool dry) {
;     ...
;   auto steps8 = [&](const float* PA, const float* Vst, float* Yst, int t0) {
; #pragma unroll
;     for (int t8 = 0; t8 < 8; ++t8) {
;       const int t = t0 + t8;
;       const float* pa = PA + (t + 1) * 320 + ks * 8;
;       const float4 xd0 = *(const float4*)(pa), xd1 = *(const float4*)(pa + 4);
;       const float4 xn0 = *(const float4*)(pa + 64), xn1 = *(const float4*)(pa + 68);
;       const float4 xb0 = *(const float4*)(pa + 128), xb1 = *(const float4*)(pa + 132);
;       const float4 xk0 = *(const float4*)(pa + 192), xk1 = *(const float4*)(pa + 196);
;       const float4 xr0 = *(const float4*)(pa + 256), xr1 = *(const float4*)(pa + 260);
;       const float xvv = Vst[(t + 1) * 32 + row32];
;       float sa0 = S[0] * n0.x, sa1 = S[1] * n0.y;
;       sa0 = fmaf(S[2], n0.z, sa0); sa1 = fmaf(S[3], n0.w, sa1);
;       sa0 = fmaf(S[4], n1.x, sa0); sa1 = fmaf(S[5], n1.y, sa1);
;       sa0 = fmaf(S[6], n1.z, sa0); sa1 = fmaf(S[7], n1.w, sa1);
;       float sa = red8(sa0 + sa1);
;       S[0] = fmaf(sa, b0.x, fmaf(S[0], d0.x, vv * k0.x)); S[1] = fmaf(sa, b0.y, fmaf(S[1], d0.y, vv * k0.y));
;       S[2] = fmaf(sa, b0.z, fmaf(S[2], d0.z, vv * k0.z)); S[3] = fmaf(sa, b0.w, fmaf(S[3], d0.w, vv * k0.w));
;       S[4] = fmaf(sa, b1.x, fmaf(S[4], d1.x, vv * k1.x)); S[5] = fmaf(sa, b1.y, fmaf(S[5], d1.y, vv * k1.y));
;       S[6] = fmaf(sa, b1.z, fmaf(S[6], d1.z, vv * k1.z)); S[7] = fmaf(sa, b1.w, fmaf(S[7], d1.w, vv * k1.w));
;       float y0 = S[0] * r0.x, y1 = S[1] * r0.y;
;       y0 = fmaf(S[2], r0.z, y0); y1 = fmaf(S[3], r0.w, y1);
;       y0 = fmaf(S[4], r1.x, y0); y1 = fmaf(S[5], r1.y, y1);
;       y0 = fmaf(S[6], r1.z, y0); y1 = fmaf(S[7], r1.w, y1);
;       float y = red8(y0 + y1);
;       Yst[t * 32 + row32] = y;
;       d0 = xd0; d1 = xd1; n0 = xn0; n1 = xn1; b0 = xb0; b1 = xb1; k0 = xk0; k1 = xk1; r0 = xr0; r1 = xr1; vv = xvv;
	v_pk_mul_f32 v[48:49], v[52:53], v[26:27] op_sel_hi:[1,0]
	v_pk_mul_f32 v[26:27], v[54:55], v[26:27] op_sel_hi:[1,0]
	v_add_f32_dpp v24, v24, v24 row_half_mirror row_mask:0xf bank_mask:0xf bound_ctrl:1
	v_pk_fma_f32 v[10:11], v[118:119], v[10:11], v[30:31]
	v_pk_fma_f32 v[8:9], v[126:127], v[8:9], v[28:29]
	v_pk_fma_f32 v[14:15], v[122:123], v[14:15], v[26:27]
	v_pk_fma_f32 v[118:119], v[24:25], v[34:35], v[10:11] op_sel_hi:[0,1,1]
	s_waitcnt lgkmcnt(0)
	v_pk_mul_f32 v[10:11], v[82:83], v[114:115] op_sel_hi:[1,0]
	v_pk_fma_f32 v[122:123], v[24:25], v[32:33], v[8:9] op_sel_hi:[0,1,1]
	v_pk_fma_f32 v[12:13], v[120:121], v[12:13], v[48:49]
	v_pk_fma_f32 v[82:83], v[118:119], v[42:43], v[10:11]
	v_pk_mul_f32 v[10:11], v[56:57], v[122:123]
	v_pk_fma_f32 v[120:121], v[24:25], v[36:37], v[12:13] op_sel_hi:[0,1,1]
	v_pk_fma_f32 v[10:11], v[118:119], v[58:59], v[10:11]
	v_pk_mul_f32 v[58:59], v[64:65], v[122:123]
	v_pk_fma_f32 v[116:117], v[24:25], v[38:39], v[14:15] op_sel_hi:[0,1,1]
	v_pk_fma_f32 v[10:11], v[120:121], v[60:61], v[10:11]
	v_pk_fma_f32 v[58:59], v[118:119], v[66:67], v[58:59]
	v_pk_mul_f32 v[8:9], v[80:81], v[114:115] op_sel_hi:[1,0]
	v_pk_fma_f32 v[10:11], v[116:117], v[62:63], v[10:11]
	v_pk_fma_f32 v[58:59], v[120:121], v[68:69], v[58:59]
	v_pk_fma_f32 v[56:57], v[122:123], v[40:41], v[8:9]
	v_add_f32_e32 v8, v10, v11
	v_pk_fma_f32 v[58:59], v[116:117], v[70:71], v[58:59]
	v_pk_mul_f32 v[14:15], v[86:87], v[114:115] op_sel_hi:[1,0]
	v_add_f32_dpp v8, v8, v8 quad_perm:[1,0,3,2] row_mask:0xf bank_mask:0xf bound_ctrl:1
	v_add_f32_e32 v58, v59, v58
	v_pk_mul_f32 v[12:13], v[84:85], v[114:115] op_sel_hi:[1,0]
	v_add_f32_dpp v8, v8, v8 quad_perm:[2,3,0,1] row_mask:0xf bank_mask:0xf bound_ctrl:1
	v_add_f32_dpp v58, v58, v58 quad_perm:[1,0,3,2] row_mask:0xf bank_mask:0xf bound_ctrl:1
	v_pk_fma_f32 v[86:87], v[116:117], v[46:47], v[14:15]
	v_add_f32_dpp v8, v8, v8 row_half_mirror row_mask:0xf bank_mask:0xf bound_ctrl:1
	v_add_f32_dpp v58, v58, v58 quad_perm:[2,3,0,1] row_mask:0xf bank_mask:0xf bound_ctrl:1
	ds_write_b32 v151, v8 offset:1280
	v_pk_fma_f32 v[84:85], v[120:121], v[44:45], v[12:13]
	v_add_f32_dpp v58, v58, v58 row_half_mirror row_mask:0xf bank_mask:0xf bound_ctrl:1
	ds_read_b128 v[8:11], v149 offset:15360
	ds_read_b128 v[12:15], v149 offset:15376
	ds_read_b128 v[24:27], v149 offset:15616
	ds_read_b128 v[28:31], v149 offset:15632
	ds_read_b128 v[32:35], v149 offset:15872
	ds_read_b128 v[36:39], v149 offset:15888
	ds_read_b128 v[40:43], v149 offset:16128
	ds_read_b128 v[44:47], v149 offset:16144
	ds_read_b128 v[48:51], v149 offset:16384
	ds_read_b128 v[52:55], v149 offset:16400
	v_pk_fma_f32 v[116:117], v[58:59], v[72:73], v[56:57] op_sel_hi:[0,1,1]
	v_pk_fma_f32 v[118:119], v[58:59], v[74:75], v[82:83] op_sel_hi:[0,1,1]
	s_waitcnt lgkmcnt(7)
	v_pk_mul_f32 v[24:25], v[24:25], v[116:117]
	v_pk_fma_f32 v[120:121], v[58:59], v[76:77], v[84:85] op_sel_hi:[0,1,1]
	v_pk_fma_f32 v[24:25], v[118:119], v[26:27], v[24:25]
	v_pk_fma_f32 v[122:123], v[58:59], v[78:79], v[86:87] op_sel_hi:[0,1,1]
	v_pk_mul_f32 v[56:57], v[106:107], v[116:117]
	s_waitcnt lgkmcnt(6)
	v_pk_fma_f32 v[24:25], v[120:121], v[28:29], v[24:25]
	v_pk_fma_f32 v[56:57], v[118:119], v[108:109], v[56:57]
	v_pk_fma_f32 v[24:25], v[122:123], v[30:31], v[24:25]
	v_pk_fma_f32 v[56:57], v[120:121], v[110:111], v[56:57]
	v_add_f32_e32 v24, v25, v24
	v_pk_fma_f32 v[56:57], v[122:123], v[112:113], v[56:57]
	s_nop 0
	v_add_f32_dpp v24, v24, v24 quad_perm:[1,0,3,2] row_mask:0xf bank_mask:0xf bound_ctrl:1
	v_mov_b32_e32 v26, v115
	v_add_f32_e32 v56, v56, v57
	v_add_f32_dpp v24, v24, v24 quad_perm:[2,3,0,1] row_mask:0xf bank_mask:0xf bound_ctrl:1
	s_waitcnt lgkmcnt(3)
	v_pk_mul_f32 v[28:29], v[40:41], v[26:27] op_sel_hi:[1,0]
	v_add_f32_dpp v56, v56, v56 quad_perm:[1,0,3,2] row_mask:0xf bank_mask:0xf bound_ctrl:1
	v_add_f32_dpp v24, v24, v24 row_half_mirror row_mask:0xf bank_mask:0xf bound_ctrl:1
	v_pk_fma_f32 v[8:9], v[116:117], v[8:9], v[28:29]
	v_add_f32_dpp v56, v56, v56 quad_perm:[2,3,0,1] row_mask:0xf bank_mask:0xf bound_ctrl:1
	v_pk_fma_f32 v[114:115], v[24:25], v[32:33], v[8:9] op_sel_hi:[0,1,1]
	v_pk_mul_f32 v[8:9], v[42:43], v[26:27] op_sel_hi:[1,0]
	v_add_f32_dpp v56, v56, v56 row_half_mirror row_mask:0xf bank_mask:0xf bound_ctrl:1
	v_pk_fma_f32 v[8:9], v[118:119], v[10:11], v[8:9]
	ds_write_b32 v151, v56 offset:1408
	v_pk_fma_f32 v[116:117], v[24:25], v[34:35], v[8:9] op_sel_hi:[0,1,1]
	s_waitcnt lgkmcnt(3)
	v_pk_mul_f32 v[8:9], v[44:45], v[26:27] op_sel_hi:[1,0]
	ds_read_b128 v[56:59], v149 offset:16640
	ds_read_b128 v[60:63], v149 offset:16656
	ds_read_b128 v[64:67], v149 offset:16896
	ds_read_b128 v[68:71], v149 offset:16912
	ds_read_b128 v[72:75], v149 offset:17152
	ds_read_b128 v[76:79], v149 offset:17168
	ds_read_b128 v[80:83], v149 offset:17408
	ds_read_b128 v[84:87], v149 offset:17424
	ds_read_b128 v[106:109], v149 offset:17664
	ds_read_b128 v[110:113], v149 offset:17680
	ds_read2_b32 v[124:125], v128 offset0:160 offset1:192
	v_pk_fma_f32 v[8:9], v[120:121], v[12:13], v[8:9]
	s_waitcnt lgkmcnt(8)
	v_pk_mul_f32 v[64:65], v[64:65], v[114:115]
	v_pk_fma_f32 v[118:119], v[24:25], v[36:37], v[8:9] op_sel_hi:[0,1,1]
	v_pk_mul_f32 v[8:9], v[46:47], v[26:27] op_sel_hi:[1,0]
	v_pk_fma_f32 v[64:65], v[116:117], v[66:67], v[64:65]
	v_pk_fma_f32 v[8:9], v[122:123], v[14:15], v[8:9]
	s_waitcnt lgkmcnt(7)
; DI float red8(float x) { x += dppf(x, 0); x += dppf(x, 1); x += dppf(x, 2); return x; }
; DI void scan_item(const Params& p, int L, int c, int item, char* smem, bool dry) {
;     ...
;   auto steps8 = [&](const float* PA, const float* Vst, float* Yst, int t0) {
; #pragma unroll
;     for (int t8 = 0; t8 < 8; ++t8) {
;       const int t = t0 + t8;
;       const float* pa = PA + (t + 1) * 320 + ks * 8;
;       const float4 xd0 = *(const float4*)(pa), xd1 = *(const float4*)(pa + 4);
;       const float4 xn0 = *(const float4*)(pa + 64), xn1 = *(const float4*)(pa + 68);
;       const float4 xb0 = *(const float4*)(pa + 128), xb1 = *(const float4*)(pa + 132);
;       const float4 xk0 = *(const float4*)(pa + 192), xk1 = *(const float4*)(pa + 196);
;       const float4 xr0 = *(const float4*)(pa + 256), xr1 = *(const float4*)(pa + 260);
;       const float xvv = Vst[(t + 1) * 32 + row32];
;       float sa0 = S[0] * n0.x, sa1 = S[1] * n0.y;
;       sa0 = fmaf(S[2], n0.z, sa0); sa1 = fmaf(S[3], n0.w, sa1);
;       sa0 = fmaf(S[4], n1.x, sa0); sa1 = fmaf(S[5], n1.y, sa1);
;       sa0 = fmaf(S[6], n1.z, sa0); sa1 = fmaf(S[7], n1.w, sa1);
;       float sa = red8(sa0 + sa1);
;       S[0] = fmaf(sa, b0.x, fmaf(S[0], d0.x, vv * k0.x)); S[1] = fmaf(sa, b0.y, fmaf(S[1], d0.y, vv * k0.y));
;       S[2] = fmaf(sa, b0.z, fmaf(S[2], d0.z, vv * k0.z)); S[3] = fmaf(sa, b0.w, fmaf(S[3], d0.w, vv * k0.w));
;       S[4] = fmaf(sa, b1.x, fmaf(S[4], d1.x, vv * k1.x)); S[5] = fmaf(sa, b1.y, fmaf(S[5], d1.y, vv * k1.y));
;       S[6] = fmaf(sa, b1.z, fmaf(S[6], d1.z, vv * k1.z)); S[7] = fmaf(sa, b1.w, fmaf(S[7], d1.w, vv * k1.w));
;       float y0 = S[0] * r0.x, y1 = S[1] * r0.y;
;       y0 = fmaf(S[2], r0.z, y0); y1 = fmaf(S[3], r0.w, y1);
;       y0 = fmaf(S[4], r1.x, y0); y1 = fmaf(S[5], r1.y, y1);
;       y0 = fmaf(S[6], r1.z, y0); y1 = fmaf(S[7], r1.w, y1);
;       float y = red8(y0 + y1);
;       Yst[t * 32 + row32] = y;
;       d0 = xd0; d1 = xd1; n0 = xn0; n1 = xn1; b0 = xb0; b1 = xb1; k0 = xk0; k1 = xk1; r0 = xr0; r1 = xr1; vv = xvv;
	v_pk_fma_f32 v[64:65], v[118:119], v[68:69], v[64:65]
	v_pk_fma_f32 v[120:121], v[24:25], v[38:39], v[8:9] op_sel_hi:[0,1,1]
	v_pk_mul_f32 v[8:9], v[48:49], v[114:115]
	v_pk_fma_f32 v[8:9], v[116:117], v[50:51], v[8:9]
	v_pk_fma_f32 v[64:65], v[120:121], v[70:71], v[64:65]
	v_pk_fma_f32 v[8:9], v[118:119], v[52:53], v[8:9]
	v_add_f32_e32 v64, v65, v64
	v_pk_fma_f32 v[8:9], v[120:121], v[54:55], v[8:9]
	s_nop 0
	v_add_f32_dpp v64, v64, v64 quad_perm:[1,0,3,2] row_mask:0xf bank_mask:0xf bound_ctrl:1
	v_add_f32_e32 v8, v8, v9
	s_waitcnt lgkmcnt(0)
	v_pk_mul_f32 v[66:67], v[80:81], v[124:125] op_sel_hi:[1,0]
	v_add_f32_dpp v64, v64, v64 quad_perm:[2,3,0,1] row_mask:0xf bank_mask:0xf bound_ctrl:1
	v_add_f32_dpp v8, v8, v8 quad_perm:[1,0,3,2] row_mask:0xf bank_mask:0xf bound_ctrl:1
	v_pk_fma_f32 v[56:57], v[114:115], v[56:57], v[66:67]
	v_add_f32_dpp v64, v64, v64 row_half_mirror row_mask:0xf bank_mask:0xf bound_ctrl:1
	v_add_f32_dpp v8, v8, v8 quad_perm:[2,3,0,1] row_mask:0xf bank_mask:0xf bound_ctrl:1
	v_pk_fma_f32 v[114:115], v[64:65], v[72:73], v[56:57] op_sel_hi:[0,1,1]
	v_pk_mul_f32 v[56:57], v[82:83], v[124:125] op_sel_hi:[1,0]
	v_add_f32_dpp v8, v8, v8 row_half_mirror row_mask:0xf bank_mask:0xf bound_ctrl:1
	v_pk_fma_f32 v[56:57], v[116:117], v[58:59], v[56:57]
	ds_write_b32 v151, v8 offset:1536
	v_pk_fma_f32 v[116:117], v[64:65], v[74:75], v[56:57] op_sel_hi:[0,1,1]
	v_pk_mul_f32 v[56:57], v[84:85], v[124:125] op_sel_hi:[1,0]
	ds_read_b128 v[8:11], v149 offset:17920
	ds_read_b128 v[12:15], v149 offset:17936
	ds_read_b128 v[24:27], v149 offset:18176
	ds_read_b128 v[28:31], v149 offset:18192
	ds_read_b128 v[32:35], v149 offset:18432
	ds_read_b128 v[36:39], v149 offset:18448
	ds_read_b128 v[40:43], v149 offset:18688
	ds_read_b128 v[44:47], v149 offset:18704
	ds_read_b128 v[48:51], v149 offset:18944
	ds_read_b128 v[52:55], v149 offset:18960
	v_pk_fma_f32 v[56:57], v[118:119], v[60:61], v[56:57]
	s_waitcnt lgkmcnt(7)
	v_pk_mul_f32 v[24:25], v[24:25], v[114:115]
	v_pk_fma_f32 v[76:77], v[64:65], v[76:77], v[56:57] op_sel_hi:[0,1,1]
	v_pk_mul_f32 v[56:57], v[86:87], v[124:125] op_sel_hi:[1,0]
	v_pk_fma_f32 v[24:25], v[116:117], v[26:27], v[24:25]
	v_pk_fma_f32 v[56:57], v[120:121], v[62:63], v[56:57]
	s_waitcnt lgkmcnt(6)
	v_pk_fma_f32 v[24:25], v[76:77], v[28:29], v[24:25]
	v_pk_fma_f32 v[86:87], v[64:65], v[78:79], v[56:57] op_sel_hi:[0,1,1]
	v_pk_mul_f32 v[56:57], v[106:107], v[114:115]
	v_pk_fma_f32 v[24:25], v[86:87], v[30:31], v[24:25]
	v_pk_fma_f32 v[56:57], v[116:117], v[108:109], v[56:57]
	v_add_f32_e32 v24, v25, v24
	v_pk_fma_f32 v[56:57], v[76:77], v[110:111], v[56:57]
	s_nop 0
	v_add_f32_dpp v24, v24, v24 quad_perm:[1,0,3,2] row_mask:0xf bank_mask:0xf bound_ctrl:1
	v_mov_b32_e32 v26, v125
	v_pk_fma_f32 v[56:57], v[86:87], v[112:113], v[56:57]
	v_add_f32_dpp v24, v24, v24 quad_perm:[2,3,0,1] row_mask:0xf bank_mask:0xf bound_ctrl:1
	s_waitcnt lgkmcnt(3)
	v_pk_mul_f32 v[28:29], v[40:41], v[26:27] op_sel_hi:[1,0]
	v_add_f32_e32 v56, v56, v57
	v_add_f32_dpp v24, v24, v24 row_half_mirror row_mask:0xf bank_mask:0xf bound_ctrl:1
	v_pk_fma_f32 v[8:9], v[114:115], v[8:9], v[28:29]
	v_add_f32_dpp v56, v56, v56 quad_perm:[1,0,3,2] row_mask:0xf bank_mask:0xf bound_ctrl:1
	v_pk_fma_f32 v[114:115], v[24:25], v[32:33], v[8:9] op_sel_hi:[0,1,1]
	v_pk_mul_f32 v[8:9], v[42:43], v[26:27] op_sel_hi:[1,0]
	v_add_f32_dpp v56, v56, v56 quad_perm:[2,3,0,1] row_mask:0xf bank_mask:0xf bound_ctrl:1
	v_pk_fma_f32 v[8:9], v[116:117], v[10:11], v[8:9]
	v_add_u32_e32 v122, 0x600, v150
	v_add_f32_dpp v56, v56, v56 row_half_mirror row_mask:0xf bank_mask:0xf bound_ctrl:1
	v_pk_fma_f32 v[116:117], v[24:25], v[34:35], v[8:9] op_sel_hi:[0,1,1]
	s_waitcnt lgkmcnt(2)
	v_pk_mul_f32 v[8:9], v[44:45], v[26:27] op_sel_hi:[1,0]
	ds_write_b32 v151, v56 offset:1664
	v_pk_fma_f32 v[8:9], v[76:77], v[12:13], v[8:9]
	ds_read_b128 v[56:59], v149 offset:19200
	ds_read_b128 v[60:63], v149 offset:19216
	ds_read_b128 v[64:67], v149 offset:19456
	ds_read_b128 v[68:71], v149 offset:19472
	ds_read_b128 v[72:75], v149 offset:19712
	ds_read_b128 v[78:81], v149 offset:19728
	ds_read_b128 v[82:85], v149 offset:19968
	ds_read_b128 v[106:109], v149 offset:19984
	ds_read_b128 v[110:113], v149 offset:20224
	ds_read_b128 v[118:121], v149 offset:20240
	v_pk_fma_f32 v[76:77], v[24:25], v[36:37], v[8:9] op_sel_hi:[0,1,1]
	v_pk_mul_f32 v[8:9], v[46:47], v[26:27] op_sel_hi:[1,0]
	s_waitcnt lgkmcnt(7)
	v_pk_mul_f32 v[64:65], v[64:65], v[114:115]
	v_pk_fma_f32 v[8:9], v[86:87], v[14:15], v[8:9]
	ds_read2_b32 v[122:123], v122 offset0:96 offset1:128
	v_pk_fma_f32 v[86:87], v[24:25], v[38:39], v[8:9] op_sel_hi:[0,1,1]
	v_pk_mul_f32 v[8:9], v[48:49], v[114:115]
	v_pk_fma_f32 v[64:65], v[116:117], v[66:67], v[64:65]
	v_pk_fma_f32 v[8:9], v[116:117], v[50:51], v[8:9]
	s_waitcnt lgkmcnt(7)
	v_pk_fma_f32 v[64:65], v[76:77], v[68:69], v[64:65]
	v_pk_fma_f32 v[8:9], v[76:77], v[52:53], v[8:9]
	v_pk_fma_f32 v[64:65], v[86:87], v[70:71], v[64:65]
	v_pk_fma_f32 v[8:9], v[86:87], v[54:55], v[8:9]
	v_add_f32_e32 v64, v65, v64
	v_add_f32_e32 v8, v8, v9
	s_waitcnt lgkmcnt(0)
; DI float ex2(float x) { return __builtin_amdgcn_exp2f(x); }
; DI void scan_item(const Params& p, int L, int c, int item, char* smem, bool dry) {
;     ...
;   auto prep4 = [&](float* PA, float* BON) {
;     float lw[8], la[8];
;     {
;       float4 t0 = *(const float4*)(LO + (0 * 32 + tt) * 64 + cs * 8), t1 = *(const float4*)(LO + (0 * 32 + tt) * 64 + cs * 8 + 4);
;       lw[0] = t0.x; lw[1] = t0.y; lw[2] = t0.z; lw[3] = t0.w; lw[4] = t1.x; lw[5] = t1.y; lw[6] = t1.z; lw[7] = t1.w;
;       t0 = *(const float4*)(LO + (1 * 32 + tt) * 64 + cs * 8); t1 = *(const float4*)(LO + (1 * 32 + tt) * 64 + cs * 8 + 4);
;       la[0] = t0.x; la[1] = t0.y; la[2] = t0.z; la[3] = t0.w; la[4] = t1.x; la[5] = t1.y; la[6] = t1.z; la[7] = t1.w;
;     }
;     float dec[8], kk[8], av[8], kp[8];
;     float ssq = 0.f, bon = 0.f;
; #pragma unroll
;     for (int e = 0; e < 8; ++e) {
;       const int ch = cs * 8 + e;
;       const float sg = frcp(1.f + fexp(-(lw[e] + PRM[4 * 64 + ch])));
;       dec[e] = ex2(-0.8750340f * sg);
;       float a = frcp(1.f + fexp(-(la[e] + PRM[5 * 64 + ch])));
;       av[e] = a;
;       kk[e] = km[e] * PRM[6 * 64 + ch];
;       ssq += kk[e] * kk[e];
;       kp[e] = km[e] * (1.f + (a - 1.f) * PRM[7 * 64 + ch]);
;       bon += rm[e] * kp[e] * PRM[8 * 64 + ch];
;     }
;     ...
;   auto steps8 = [&](const float* PA, const float* Vst, float* Yst, int t0) {
; #pragma unroll
;     for (int t8 = 0; t8 < 8; ++t8) {
;       const int t = t0 + t8;
;       const float* pa = PA + (t + 1) * 320 + ks * 8;
;       const float4 xd0 = *(const float4*)(pa), xd1 = *(const float4*)(pa + 4);
;       const float4 xn0 = *(const float4*)(pa + 64), xn1 = *(const float4*)(pa + 68);
;       const float4 xb0 = *(const float4*)(pa + 128), xb1 = *(const float4*)(pa + 132);
;       const float4 xk0 = *(const float4*)(pa + 192), xk1 = *(const float4*)(pa + 196);
;       const float4 xr0 = *(const float4*)(pa + 256), xr1 = *(const float4*)(pa + 260);
;       const float xvv = Vst[(t + 1) * 32 + row32];
;       float sa0 = S[0] * n0.x, sa1 = S[1] * n0.y;
;       sa0 = fmaf(S[2], n0.z, sa0); sa1 = fmaf(S[3], n0.w, sa1);
;       sa0 = fmaf(S[4], n1.x, sa0); sa1 = fmaf(S[5], n1.y, sa1);
;       sa0 = fmaf(S[6], n1.z, sa0); sa1 = fmaf(S[7], n1.w, sa1);
;       float sa = red8(sa0 + sa1);
;       S[0] = fmaf(sa, b0.x, fmaf(S[0], d0.x, vv * k0.x)); S[1] = fmaf(sa, b0.y, fmaf(S[1], d0.y, vv * k0.y));
	v_pk_mul_f32 v[66:67], v[82:83], v[122:123] op_sel_hi:[1,0]
	v_add_f32_dpp v64, v64, v64 quad_perm:[1,0,3,2] row_mask:0xf bank_mask:0xf bound_ctrl:1
	v_add_f32_dpp v8, v8, v8 quad_perm:[1,0,3,2] row_mask:0xf bank_mask:0xf bound_ctrl:1
	v_pk_fma_f32 v[56:57], v[114:115], v[56:57], v[66:67]
	v_add_f32_dpp v64, v64, v64 quad_perm:[2,3,0,1] row_mask:0xf bank_mask:0xf bound_ctrl:1
	v_add_f32_dpp v8, v8, v8 quad_perm:[2,3,0,1] row_mask:0xf bank_mask:0xf bound_ctrl:1
	v_pk_mul_f32 v[66:67], v[84:85], v[122:123] op_sel_hi:[1,0]
	v_add_f32_dpp v64, v64, v64 row_half_mirror row_mask:0xf bank_mask:0xf bound_ctrl:1
	v_add_f32_dpp v8, v8, v8 row_half_mirror row_mask:0xf bank_mask:0xf bound_ctrl:1
	v_pk_fma_f32 v[72:73], v[64:65], v[72:73], v[56:57] op_sel_hi:[0,1,1]
	ds_write_b32 v151, v8 offset:1792
	v_pk_fma_f32 v[58:59], v[116:117], v[58:59], v[66:67]
	v_mul_f32_e32 v65, v111, v73
	ds_read_b128 v[40:43], v149 offset:20480
	ds_read_b128 v[44:47], v149 offset:20496
	ds_read_b128 v[36:39], v149 offset:20736
	ds_read_b128 v[32:35], v149 offset:20752
	ds_read_b128 v[28:31], v149 offset:20992
	ds_read_b128 v[24:27], v149 offset:21008
	ds_read_b128 v[48:51], v149 offset:21248
	ds_read_b128 v[52:55], v149 offset:21264
	ds_read_b128 v[12:15], v149 offset:21504
	ds_read_b128 v[8:11], v149 offset:21520
	v_pk_mul_f32 v[66:67], v[106:107], v[122:123] op_sel_hi:[1,0]
	v_pk_fma_f32 v[74:75], v[64:65], v[74:75], v[58:59] op_sel_hi:[0,1,1]
	v_pk_fma_f32 v[60:61], v[76:77], v[60:61], v[66:67]
	v_mul_f32_e32 v57, v110, v72
	v_mov_b32_e32 v56, v123
	v_fmac_f32_e32 v65, v75, v113
	v_pk_mul_f32 v[66:67], v[108:109], v[122:123] op_sel_hi:[1,0]
	s_waitcnt lgkmcnt(3)
	v_pk_mul_f32 v[48:49], v[48:49], v[56:57] op_sel_hi:[1,0]
	v_pk_fma_f32 v[78:79], v[64:65], v[78:79], v[60:61] op_sel_hi:[0,1,1]
	v_pk_fma_f32 v[62:63], v[86:87], v[62:63], v[66:67]
	v_pk_fma_f32 v[68:69], v[72:73], v[40:41], v[48:49]
	v_pk_mul_f32 v[40:41], v[50:51], v[56:57] op_sel_hi:[1,0]
	v_fmac_f32_e32 v57, v74, v112
	v_fmac_f32_e32 v65, v79, v119
	v_pk_fma_f32 v[70:71], v[74:75], v[42:43], v[40:41]
	s_waitcnt lgkmcnt(2)
	v_pk_mul_f32 v[40:41], v[52:53], v[56:57] op_sel_hi:[1,0]
	v_fmac_f32_e32 v57, v78, v118
	v_pk_fma_f32 v[82:83], v[64:65], v[80:81], v[62:63] op_sel_hi:[0,1,1]
	v_pk_fma_f32 v[76:77], v[78:79], v[44:45], v[40:41]
	v_pk_mul_f32 v[40:41], v[54:55], v[56:57] op_sel_hi:[1,0]
	v_fmac_f32_e32 v57, v82, v120
	v_fmac_f32_e32 v65, v83, v121
	v_pk_fma_f32 v[80:81], v[82:83], v[46:47], v[40:41]
	v_add_f32_e32 v40, v57, v65
	v_pk_mul_f32 v[36:37], v[36:37], v[72:73]
	v_lshl_add_u32 v116, s34, 7, v147
	v_add_f32_dpp v40, v40, v40 quad_perm:[1,0,3,2] row_mask:0xf bank_mask:0xf bound_ctrl:1
	v_pk_fma_f32 v[36:37], v[74:75], v[38:39], v[36:37]
	s_nop 0
	v_add_f32_dpp v40, v40, v40 quad_perm:[2,3,0,1] row_mask:0xf bank_mask:0xf bound_ctrl:1
	v_pk_fma_f32 v[32:33], v[78:79], v[32:33], v[36:37]
	s_nop 0
	v_add_f32_dpp v40, v40, v40 row_half_mirror row_mask:0xf bank_mask:0xf bound_ctrl:1
	ds_write_b32 v151, v40 offset:1920
	s_waitcnt lgkmcnt(0)
	s_barrier
	ds_read_b128 v[40:43], v145
	ds_read_b128 v[44:47], v145 offset:16
	ds_read_b128 v[60:63], v145 offset:8192
	ds_read_b128 v[52:55], v145 offset:8208
	v_accvgpr_read_b32 v64, a56
	v_accvgpr_read_b32 v65, a57
	v_accvgpr_read_b32 v66, a58
	v_accvgpr_read_b32 v67, a59
	v_accvgpr_read_b32 v56, a60
	v_accvgpr_read_b32 v57, a61
	v_accvgpr_read_b32 v58, a62
	v_accvgpr_read_b32 v59, a63
	v_accvgpr_read_b32 v108, a64
	v_accvgpr_read_b32 v109, a65
	v_accvgpr_read_b32 v110, a66
	v_accvgpr_read_b32 v111, a67
	v_accvgpr_read_b32 v84, a68
	v_accvgpr_read_b32 v85, a69
	v_accvgpr_read_b32 v86, a70
	v_accvgpr_read_b32 v87, a71
	v_accvgpr_read_b32 v118, a72
	v_accvgpr_read_b32 v119, a73
	v_accvgpr_read_b32 v120, a74
	v_accvgpr_read_b32 v121, a75
	s_waitcnt lgkmcnt(3)
	v_add_f32_e32 v40, v40, v64
	v_add_f32_e32 v41, v41, v65
	v_add_f32_e32 v42, v42, v66
	v_add_f32_e32 v43, v43, v67
	v_accvgpr_read_b32 v64, a76
	v_accvgpr_read_b32 v65, a77
	v_accvgpr_read_b32 v66, a78
	v_accvgpr_read_b32 v67, a79
	s_waitcnt lgkmcnt(2)
	v_add_f32_e32 v46, v46, v58
	v_pk_mul_f32 v[106:107], v[94:95], v[108:109]
	s_waitcnt lgkmcnt(1)
	v_add_f32_e32 v48, v60, v84
	v_pk_mul_f32 v[108:109], v[106:107], v[106:107]
	s_waitcnt lgkmcnt(0)
; DI float ex2(float x) { return __builtin_amdgcn_exp2f(x); }
; DI float fexp(float x) { return __builtin_amdgcn_exp2f(x * 1.4426950408889634f); }
; DI float frcp(float x) { return __builtin_amdgcn_rcpf(x); }
; DI float red8(float x) { x += dppf(x, 0); x += dppf(x, 1); x += dppf(x, 2); return x; }
; DI void scan_item(const Params& p, int L, int c, int item, char* smem, bool dry) {
;     ...
;     float dec[8], kk[8], av[8], kp[8];
;     float ssq = 0.f, bon = 0.f;
; #pragma unroll
;     for (int e = 0; e < 8; ++e) {
;       const int ch = cs * 8 + e;
;       const float sg = frcp(1.f + fexp(-(lw[e] + PRM[4 * 64 + ch])));
;       dec[e] = ex2(-0.8750340f * sg);
;       float a = frcp(1.f + fexp(-(la[e] + PRM[5 * 64 + ch])));
;       av[e] = a;
;       kk[e] = km[e] * PRM[6 * 64 + ch];
;       ssq += kk[e] * kk[e];
;       kp[e] = km[e] * (1.f + (a - 1.f) * PRM[7 * 64 + ch]);
;       bon += rm[e] * kp[e] * PRM[8 * 64 + ch];
;     }
;     ssq = red8(ssq); bon = red8(bon);
;     const float inv = fminf(__builtin_amdgcn_rsqf(ssq), 1e12f);
	v_add_f32_e32 v54, v54, v66
	v_mul_f32_e32 v54, 0xbfb8aa3b, v54
	v_exp_f32_e32 v54, v54
	v_add_f32_e32 v60, v61, v85
	v_pk_mul_f32 v[110:111], v[92:93], v[110:111]
	v_mul_f32_e32 v60, 0xbfb8aa3b, v60
	v_add_f32_e32 v54, 1.0, v54
	v_rcp_f32_e32 v58, v54
	v_add_f32_e32 v54, v55, v67
	v_mul_f32_e32 v54, 0xbfb8aa3b, v54
	v_exp_f32_e32 v54, v54
	v_pk_mul_f32 v[112:113], v[110:111], v[110:111]
	v_add_f32_e32 v52, v52, v64
	v_add_f32_e32 v64, v108, v109
	v_exp_f32_e32 v60, v60
	v_pk_mul_f32 v[114:115], v[90:91], v[118:119]
	v_add_f32_e32 v64, v64, v112
	v_add_f32_e32 v44, v44, v56
	v_add_f32_e32 v45, v45, v57
	v_pk_mul_f32 v[56:57], v[114:115], v[114:115]
	v_add_f32_e32 v64, v64, v113
	v_pk_mul_f32 v[118:119], v[88:89], v[120:121]
	v_add_f32_e32 v54, 1.0, v54
	v_add_f32_e32 v56, v64, v56
	v_add_f32_e32 v47, v47, v59
	v_rcp_f32_e32 v59, v54
	v_pk_mul_f32 v[54:55], v[118:119], v[118:119]
	v_add_f32_e32 v56, v56, v57
	v_add_f32_e32 v60, 1.0, v60
	v_add_f32_e32 v54, v56, v54
	v_rcp_f32_e32 v85, v60
	v_add_f32_e32 v60, v62, v86
	v_add_f32_e32 v54, v54, v55
	v_mul_f32_e32 v60, 0xbfb8aa3b, v60
	v_exp_f32_e32 v60, v60
	v_add_f32_dpp v54, v54, v54 quad_perm:[1,0,3,2] row_mask:0xf bank_mask:0xf bound_ctrl:1
	v_mul_f32_e32 v48, 0xbfb8aa3b, v48
	v_exp_f32_e32 v48, v48
	v_add_f32_dpp v54, v54, v54 quad_perm:[2,3,0,1] row_mask:0xf bank_mask:0xf bound_ctrl:1
	v_add_f32_e32 v60, 1.0, v60
	v_rcp_f32_e32 v86, v60
	v_add_f32_dpp v54, v54, v54 row_half_mirror row_mask:0xf bank_mask:0xf bound_ctrl:1
	v_rsq_f32_e32 v54, v54
	v_add_f32_e32 v60, v63, v87
	v_add_f32_e32 v48, 1.0, v48
	v_mul_f32_e32 v60, 0xbfb8aa3b, v60
	v_min_f32_e32 v66, 0x5368d4a5, v54
	v_rcp_f32_e32 v84, v48
	v_exp_f32_e32 v60, v60
	v_pk_mul_f32 v[112:113], v[118:119], v[66:67] op_sel_hi:[1,0]
	v_accvgpr_read_b32 v118, a80
	v_accvgpr_read_b32 v119, a81
	v_accvgpr_read_b32 v120, a82
	v_accvgpr_read_b32 v121, a83
	v_accvgpr_read_b32 v48, a84
	v_accvgpr_read_b32 v49, a85
	v_accvgpr_read_b32 v50, a86
	v_accvgpr_read_b32 v51, a87
	v_pk_mul_f32 v[106:107], v[106:107], v[66:67] op_sel_hi:[1,0]
	v_add_f32_e32 v60, 1.0, v60
	v_xor_b32_e32 v55, 0x80000000, v107
	v_xor_b32_e32 v54, 0x80000000, v106
	v_pk_mul_f32 v[106:107], v[84:85], v[106:107]
	v_pk_add_f32 v[84:85], v[84:85], -1.0 op_sel_hi:[1,0]
	v_rcp_f32_e32 v87, v60
	v_pk_fma_f32 v[84:85], v[118:119], v[84:85], 1.0 op_sel_hi:[1,1,0]
	v_add_f32_e32 v53, v53, v65
	v_pk_mul_f32 v[84:85], v[94:95], v[84:85]
	v_mul_f32_e32 v52, 0xbfb8aa3b, v52
	v_pk_mul_f32 v[94:95], v[20:21], v[84:85]
	v_mul_f32_e32 v53, 0xbfb8aa3b, v53
	v_fma_f32 v94, v48, v94, 0
	v_exp_f32_e32 v52, v52
	v_exp_f32_e32 v53, v53
	v_fmac_f32_e32 v94, v49, v95
	v_pk_add_f32 v[48:49], v[86:87], -1.0 op_sel_hi:[1,0]
	v_pk_mul_f32 v[108:109], v[110:111], v[66:67] op_sel_hi:[1,0]
	v_pk_fma_f32 v[48:49], v[120:121], v[48:49], 1.0 op_sel_hi:[1,1,0]
	v_xor_b32_e32 v57, 0x80000000, v109
	v_xor_b32_e32 v56, 0x80000000, v108
	v_pk_mul_f32 v[108:109], v[86:87], v[108:109]
	v_pk_mul_f32 v[86:87], v[92:93], v[48:49]
	v_add_f32_e32 v52, 1.0, v52
	v_pk_mul_f32 v[48:49], v[22:23], v[86:87]
	v_add_f32_e32 v53, 1.0, v53
	v_fmac_f32_e32 v94, v50, v48
	v_rcp_f32_e32 v52, v52
	v_rcp_f32_e32 v53, v53
	v_fmac_f32_e32 v94, v51, v49
	v_accvgpr_read_b32 v48, a88
	v_accvgpr_read_b32 v49, a89
	v_accvgpr_read_b32 v50, a90
	v_accvgpr_read_b32 v51, a91
	v_mul_f32_e32 v40, 0xbfb8aa3b, v40
	v_mul_f32_e32 v41, 0xbfb8aa3b, v41
	v_mul_f32_e32 v42, 0xbfb8aa3b, v42
	v_mul_f32_e32 v43, 0xbfb8aa3b, v43
	v_exp_f32_e32 v40, v40
	v_exp_f32_e32 v41, v41
	v_exp_f32_e32 v42, v42
	v_exp_f32_e32 v43, v43
	v_mul_f32_e32 v44, 0xbfb8aa3b, v44
	v_accvgpr_read_b32 v60, a92
	v_accvgpr_read_b32 v61, a93
	v_accvgpr_read_b32 v62, a94
	v_accvgpr_read_b32 v63, a95
	v_mul_f32_e32 v45, 0xbfb8aa3b, v45
	v_mul_f32_e32 v46, 0xbfb8aa3b, v46
	v_mul_f32_e32 v47, 0xbfb8aa3b, v47
	v_pk_mul_f32 v[110:111], v[114:115], v[66:67] op_sel_hi:[1,0]
	v_exp_f32_e32 v44, v44
	v_exp_f32_e32 v45, v45
	v_exp_f32_e32 v46, v46
	v_exp_f32_e32 v47, v47
	v_xor_b32_e32 v65, 0x80000000, v111
	v_xor_b32_e32 v64, 0x80000000, v110
	v_pk_mul_f32 v[110:111], v[52:53], v[110:111]
	v_pk_add_f32 v[52:53], v[52:53], -1.0 op_sel_hi:[1,0]
	v_add_f32_e32 v40, 1.0, v40
	v_pk_fma_f32 v[48:49], v[48:49], v[52:53], 1.0 op_sel_hi:[1,1,0]
	v_add_f32_e32 v41, 1.0, v41
	v_pk_mul_f32 v[48:49], v[90:91], v[48:49]
	v_add_f32_e32 v42, 1.0, v42
	v_add_f32_e32 v43, 1.0, v43
	v_pk_mul_f32 v[52:53], v[16:17], v[48:49]
	v_rcp_f32_e32 v40, v40
	v_rcp_f32_e32 v41, v41
	v_rcp_f32_e32 v42, v42
	v_rcp_f32_e32 v43, v43
	v_add_f32_e32 v44, 1.0, v44
	v_add_f32_e32 v45, 1.0, v45
	v_add_f32_e32 v46, 1.0, v46
	v_add_f32_e32 v47, 1.0, v47
	v_fmac_f32_e32 v94, v60, v52
	v_rcp_f32_e32 v44, v44
	v_rcp_f32_e32 v45, v45
	v_rcp_f32_e32 v46, v46
	v_rcp_f32_e32 v47, v47
	v_fmac_f32_e32 v94, v61, v53
	v_pk_add_f32 v[52:53], v[58:59], -1.0 op_sel_hi:[1,0]
	v_mul_f32_e32 v40, 0xbf60023a, v40
	v_pk_fma_f32 v[50:51], v[50:51], v[52:53], 1.0 op_sel_hi:[1,1,0]
	v_mul_f32_e32 v41, 0xbf60023a, v41
	v_pk_mul_f32 v[50:51], v[88:89], v[50:51]
	v_mul_f32_e32 v42, 0xbf60023a, v42
	v_mul_f32_e32 v43, 0xbf60023a, v43
	v_pk_mul_f32 v[52:53], v[18:19], v[50:51]
	v_exp_f32_e32 v40, v40
	v_exp_f32_e32 v41, v41
	v_exp_f32_e32 v42, v42
	v_exp_f32_e32 v43, v43
	v_mul_f32_e32 v44, 0xbf60023a, v44
	v_mul_f32_e32 v45, 0xbf60023a, v45
	v_mul_f32_e32 v46, 0xbf60023a, v46
	v_mul_f32_e32 v47, 0xbf60023a, v47
	v_fmac_f32_e32 v94, v62, v52
	v_pk_fma_f32 v[32:33], v[82:83], v[34:35], v[32:33]
	v_exp_f32_e32 v44, v44
	v_exp_f32_e32 v45, v45
	v_exp_f32_e32 v46, v46
	v_exp_f32_e32 v47, v47
	v_fmac_f32_e32 v94, v63, v53
	v_add_f32_e32 v32, v32, v33
; DI void scan_item(const Params& p, int L, int c, int item, char* smem, bool dry) {
;     ...
;     for (int e = 0; e < 8; ++e) { float kn = kk[e] * inv; nk[e] = -kn; bb[e] = kn * av[e]; }
;     float* pa = PA + tt * 320 + cs * 8;
;     *(float4*)(pa) = make_float4(dec[0], dec[1], dec[2], dec[3]); *(float4*)(pa + 4) = make_float4(dec[4], dec[5], dec[6], dec[7]);
;     *(float4*)(pa + 64) = make_float4(nk[0], nk[1], nk[2], nk[3]); *(float4*)(pa + 68) = make_float4(nk[4], nk[5], nk[6], nk[7]);
;     *(float4*)(pa + 128) = make_float4(bb[0], bb[1], bb[2], bb[3]); *(float4*)(pa + 132) = make_float4(bb[4], bb[5], bb[6], bb[7]);
;     *(float4*)(pa + 192) = make_float4(kp[0], kp[1], kp[2], kp[3]); *(float4*)(pa + 196) = make_float4(kp[4], kp[5], kp[6], kp[7]);
;     *(float4*)(pa + 256) = make_float4(rm[0], rm[1], rm[2], rm[3]); *(float4*)(pa + 260) = make_float4(rm[4], rm[5], rm[6], rm[7]);
;     BON[tt] = bon;
;     ...
;   auto steps8 = [&](const float* PA, const float* Vst, float* Yst, int t0) {
; #pragma unroll
;     for (int t8 = 0; t8 < 8; ++t8) {
;       const int t = t0 + t8;
;       const float* pa = PA + (t + 1) * 320 + ks * 8;
;       const float4 xd0 = *(const float4*)(pa), xd1 = *(const float4*)(pa + 4);
;       const float4 xn0 = *(const float4*)(pa + 64), xn1 = *(const float4*)(pa + 68);
;       const float4 xb0 = *(const float4*)(pa + 128), xb1 = *(const float4*)(pa + 132);
;       const float4 xk0 = *(const float4*)(pa + 192), xk1 = *(const float4*)(pa + 196);
;       const float4 xr0 = *(const float4*)(pa + 256), xr1 = *(const float4*)(pa + 260);
;       const float xvv = Vst[(t + 1) * 32 + row32];
;       float sa0 = S[0] * n0.x, sa1 = S[1] * n0.y;
;       sa0 = fmaf(S[2], n0.z, sa0); sa1 = fmaf(S[3], n0.w, sa1);
;       sa0 = fmaf(S[4], n1.x, sa0); sa1 = fmaf(S[5], n1.y, sa1);
;       sa0 = fmaf(S[6], n1.z, sa0); sa1 = fmaf(S[7], n1.w, sa1);
;       float sa = red8(sa0 + sa1);
;       S[0] = fmaf(sa, b0.x, fmaf(S[0], d0.x, vv * k0.x)); S[1] = fmaf(sa, b0.y, fmaf(S[1], d0.y, vv * k0.y));
;       S[2] = fmaf(sa, b0.z, fmaf(S[2], d0.z, vv * k0.z)); S[3] = fmaf(sa, b0.w, fmaf(S[3], d0.w, vv * k0.w));
;       S[4] = fmaf(sa, b1.x, fmaf(S[4], d1.x, vv * k1.x)); S[5] = fmaf(sa, b1.y, fmaf(S[5], d1.y, vv * k1.y));
;       S[6] = fmaf(sa, b1.z, fmaf(S[6], d1.z, vv * k1.z)); S[7] = fmaf(sa, b1.w, fmaf(S[7], d1.w, vv * k1.w));
	v_xor_b32_e32 v67, 0x80000000, v113
	v_add_f32_dpp v52, v94, v94 quad_perm:[1,0,3,2] row_mask:0xf bank_mask:0xf bound_ctrl:1
	v_add_f32_dpp v32, v32, v32 quad_perm:[1,0,3,2] row_mask:0xf bank_mask:0xf bound_ctrl:1
	v_xor_b32_e32 v66, 0x80000000, v112
	v_add_f32_dpp v52, v52, v52 quad_perm:[2,3,0,1] row_mask:0xf bank_mask:0xf bound_ctrl:1
	v_add_f32_dpp v32, v32, v32 quad_perm:[2,3,0,1] row_mask:0xf bank_mask:0xf bound_ctrl:1
	v_pk_mul_f32 v[112:113], v[58:59], v[112:113]
	v_add_f32_dpp v52, v52, v52 row_half_mirror row_mask:0xf bank_mask:0xf bound_ctrl:1
	ds_write_b128 v153, v[40:43]
	ds_write_b128 v153, v[44:47] offset:16
	ds_write_b128 v153, v[54:57] offset:256
	ds_write_b128 v153, v[64:67] offset:272
	ds_write_b128 v153, v[106:109] offset:512
	ds_write_b128 v153, v[110:113] offset:528
	ds_write_b128 v153, v[84:87] offset:768
	ds_write_b128 v153, v[48:51] offset:784
	ds_write_b128 v153, v[20:23] offset:1024
	ds_write_b128 v153, v[16:19] offset:1040
	ds_write_b32 v116, v52
	v_add_f32_dpp v32, v32, v32 row_half_mirror row_mask:0xf bank_mask:0xf bound_ctrl:1
	ds_read_b128 v[16:19], v149 offset:21760
	ds_read_b128 v[20:23], v149 offset:21776
	ds_read_b128 v[40:43], v149 offset:22016
	ds_read_b128 v[44:47], v149 offset:22032
	ds_read_b128 v[48:51], v149 offset:22272
	ds_read_b128 v[52:55], v149 offset:22288
	ds_read_b128 v[56:59], v149 offset:22528
	ds_read_b128 v[60:63], v149 offset:22544
	ds_read_b128 v[64:67], v149 offset:22784
	ds_read_b128 v[84:87], v149 offset:22800
	v_pk_fma_f32 v[90:91], v[32:33], v[28:29], v[68:69] op_sel_hi:[0,1,1]
	v_add_u32_e32 v110, 0x800, v150
	v_pk_fma_f32 v[92:93], v[32:33], v[30:31], v[70:71] op_sel_hi:[0,1,1]
	s_waitcnt lgkmcnt(7)
	v_pk_mul_f32 v[40:41], v[40:41], v[90:91]
	ds_read2_b32 v[88:89], v110 offset0:32 offset1:64
	v_pk_fma_f32 v[94:95], v[32:33], v[24:25], v[76:77] op_sel_hi:[0,1,1]
	v_pk_fma_f32 v[40:41], v[92:93], v[42:43], v[40:41]
	v_pk_fma_f32 v[106:107], v[32:33], v[26:27], v[80:81] op_sel_hi:[0,1,1]
	v_pk_mul_f32 v[12:13], v[12:13], v[90:91]
	s_waitcnt lgkmcnt(7)
	v_pk_fma_f32 v[40:41], v[94:95], v[44:45], v[40:41]
	v_pk_fma_f32 v[12:13], v[92:93], v[14:15], v[12:13]
	v_pk_fma_f32 v[40:41], v[106:107], v[46:47], v[40:41]
	v_pk_fma_f32 v[12:13], v[94:95], v[8:9], v[12:13]
	v_add_f32_e32 v40, v41, v40
	v_pk_fma_f32 v[12:13], v[106:107], v[10:11], v[12:13]
	s_nop 0
	v_add_f32_dpp v40, v40, v40 quad_perm:[1,0,3,2] row_mask:0xf bank_mask:0xf bound_ctrl:1
	v_add_f32_e32 v8, v12, v13
	s_waitcnt lgkmcnt(0)
	v_pk_mul_f32 v[42:43], v[56:57], v[88:89] op_sel_hi:[1,0]
	v_add_f32_dpp v40, v40, v40 quad_perm:[2,3,0,1] row_mask:0xf bank_mask:0xf bound_ctrl:1
	v_add_f32_dpp v8, v8, v8 quad_perm:[1,0,3,2] row_mask:0xf bank_mask:0xf bound_ctrl:1
	v_pk_fma_f32 v[16:17], v[90:91], v[16:17], v[42:43]
	v_add_f32_dpp v40, v40, v40 row_half_mirror row_mask:0xf bank_mask:0xf bound_ctrl:1
	v_add_f32_dpp v8, v8, v8 quad_perm:[2,3,0,1] row_mask:0xf bank_mask:0xf bound_ctrl:1
	v_pk_fma_f32 v[90:91], v[40:41], v[48:49], v[16:17] op_sel_hi:[0,1,1]
	v_pk_mul_f32 v[16:17], v[58:59], v[88:89] op_sel_hi:[1,0]
	v_add_f32_dpp v8, v8, v8 row_half_mirror row_mask:0xf bank_mask:0xf bound_ctrl:1
	v_pk_fma_f32 v[16:17], v[92:93], v[18:19], v[16:17]
	ds_write_b32 v151, v8 offset:2048
	v_pk_fma_f32 v[92:93], v[40:41], v[50:51], v[16:17] op_sel_hi:[0,1,1]
	v_pk_mul_f32 v[16:17], v[60:61], v[88:89] op_sel_hi:[1,0]
	ds_read_b128 v[8:11], v149 offset:23040
	ds_read_b128 v[12:15], v149 offset:23056
	ds_read_b128 v[24:27], v149 offset:23296
	ds_read_b128 v[28:31], v149 offset:23312
	ds_read_b128 v[32:35], v149 offset:23552
	ds_read_b128 v[36:39], v149 offset:23568
	ds_read_b128 v[68:71], v149 offset:23808
	ds_read_b128 v[72:75], v149 offset:23824
	ds_read_b128 v[76:79], v149 offset:24064
	ds_read_b128 v[80:83], v149 offset:24080
	v_pk_fma_f32 v[16:17], v[94:95], v[20:21], v[16:17]
	s_waitcnt lgkmcnt(7)
	v_pk_mul_f32 v[24:25], v[24:25], v[90:91]
	v_pk_fma_f32 v[94:95], v[40:41], v[52:53], v[16:17] op_sel_hi:[0,1,1]
	v_pk_mul_f32 v[16:17], v[62:63], v[88:89] op_sel_hi:[1,0]
	v_pk_fma_f32 v[24:25], v[92:93], v[26:27], v[24:25]
	v_pk_fma_f32 v[16:17], v[106:107], v[22:23], v[16:17]
	s_waitcnt lgkmcnt(6)
	v_pk_fma_f32 v[24:25], v[94:95], v[28:29], v[24:25]
	v_pk_fma_f32 v[106:107], v[40:41], v[54:55], v[16:17] op_sel_hi:[0,1,1]
	v_pk_mul_f32 v[16:17], v[64:65], v[90:91]
	v_pk_fma_f32 v[16:17], v[92:93], v[66:67], v[16:17]
	v_pk_fma_f32 v[24:25], v[106:107], v[30:31], v[24:25]
	v_pk_fma_f32 v[16:17], v[94:95], v[84:85], v[16:17]
	v_add_f32_e32 v24, v25, v24
	v_pk_fma_f32 v[16:17], v[106:107], v[86:87], v[16:17]
	s_nop 0
	v_add_f32_dpp v24, v24, v24 quad_perm:[1,0,3,2] row_mask:0xf bank_mask:0xf bound_ctrl:1
	v_mov_b32_e32 v26, v89
	v_add_f32_e32 v16, v16, v17
	v_add_f32_dpp v24, v24, v24 quad_perm:[2,3,0,1] row_mask:0xf bank_mask:0xf bound_ctrl:1
	s_waitcnt lgkmcnt(3)
	v_pk_mul_f32 v[28:29], v[68:69], v[26:27] op_sel_hi:[1,0]
	v_add_f32_dpp v16, v16, v16 quad_perm:[1,0,3,2] row_mask:0xf bank_mask:0xf bound_ctrl:1
	v_add_f32_dpp v24, v24, v24 row_half_mirror row_mask:0xf bank_mask:0xf bound_ctrl:1
	v_pk_fma_f32 v[8:9], v[90:91], v[8:9], v[28:29]
	v_add_f32_dpp v16, v16, v16 quad_perm:[2,3,0,1] row_mask:0xf bank_mask:0xf bound_ctrl:1
	v_pk_fma_f32 v[88:89], v[24:25], v[32:33], v[8:9] op_sel_hi:[0,1,1]
	v_pk_mul_f32 v[8:9], v[70:71], v[26:27] op_sel_hi:[1,0]
	v_add_f32_dpp v16, v16, v16 row_half_mirror row_mask:0xf bank_mask:0xf bound_ctrl:1
	v_pk_fma_f32 v[8:9], v[92:93], v[10:11], v[8:9]
	ds_write_b32 v151, v16 offset:2176
	v_pk_fma_f32 v[90:91], v[24:25], v[34:35], v[8:9] op_sel_hi:[0,1,1]
	s_waitcnt lgkmcnt(3)
; DI float red8(float x) { x += dppf(x, 0); x += dppf(x, 1); x += dppf(x, 2); return x; }
; DI void scan_item(const Params& p, int L, int c, int item, char* smem, bool dry) {
;     ...
;   auto steps8 = [&](const float* PA, const float* Vst, float* Yst, int t0) {
; #pragma unroll
;     for (int t8 = 0; t8 < 8; ++t8) {
;       const int t = t0 + t8;
;       const float* pa = PA + (t + 1) * 320 + ks * 8;
;       const float4 xd0 = *(const float4*)(pa), xd1 = *(const float4*)(pa + 4);
;       const float4 xn0 = *(const float4*)(pa + 64), xn1 = *(const float4*)(pa + 68);
;       const float4 xb0 = *(const float4*)(pa + 128), xb1 = *(const float4*)(pa + 132);
;       const float4 xk0 = *(const float4*)(pa + 192), xk1 = *(const float4*)(pa + 196);
;       const float4 xr0 = *(const float4*)(pa + 256), xr1 = *(const float4*)(pa + 260);
;       const float xvv = Vst[(t + 1) * 32 + row32];
;       float sa0 = S[0] * n0.x, sa1 = S[1] * n0.y;
;       sa0 = fmaf(S[2], n0.z, sa0); sa1 = fmaf(S[3], n0.w, sa1);
;       sa0 = fmaf(S[4], n1.x, sa0); sa1 = fmaf(S[5], n1.y, sa1);
;       sa0 = fmaf(S[6], n1.z, sa0); sa1 = fmaf(S[7], n1.w, sa1);
;       float sa = red8(sa0 + sa1);
;       S[0] = fmaf(sa, b0.x, fmaf(S[0], d0.x, vv * k0.x)); S[1] = fmaf(sa, b0.y, fmaf(S[1], d0.y, vv * k0.y));
;       S[2] = fmaf(sa, b0.z, fmaf(S[2], d0.z, vv * k0.z)); S[3] = fmaf(sa, b0.w, fmaf(S[3], d0.w, vv * k0.w));
;       S[4] = fmaf(sa, b1.x, fmaf(S[4], d1.x, vv * k1.x)); S[5] = fmaf(sa, b1.y, fmaf(S[5], d1.y, vv * k1.y));
;       S[6] = fmaf(sa, b1.z, fmaf(S[6], d1.z, vv * k1.z)); S[7] = fmaf(sa, b1.w, fmaf(S[7], d1.w, vv * k1.w));
;       float y0 = S[0] * r0.x, y1 = S[1] * r0.y;
;       y0 = fmaf(S[2], r0.z, y0); y1 = fmaf(S[3], r0.w, y1);
;       y0 = fmaf(S[4], r1.x, y0); y1 = fmaf(S[5], r1.y, y1);
;       y0 = fmaf(S[6], r1.z, y0); y1 = fmaf(S[7], r1.w, y1);
;       float y = red8(y0 + y1);
;       Yst[t * 32 + row32] = y;
;       d0 = xd0; d1 = xd1; n0 = xn0; n1 = xn1; b0 = xb0; b1 = xb1; k0 = xk0; k1 = xk1; r0 = xr0; r1 = xr1; vv = xvv;
	v_pk_mul_f32 v[8:9], v[72:73], v[26:27] op_sel_hi:[1,0]
	ds_read_b128 v[16:19], v149 offset:24320
	ds_read_b128 v[20:23], v149 offset:24336
	ds_read_b128 v[40:43], v149 offset:24576
	ds_read_b128 v[44:47], v149 offset:24592
	ds_read_b128 v[48:51], v149 offset:24832
	ds_read_b128 v[52:55], v149 offset:24848
	ds_read_b128 v[56:59], v149 offset:25088
	ds_read_b128 v[60:63], v149 offset:25104
	ds_read_b128 v[64:67], v149 offset:25344
	ds_read_b128 v[84:87], v149 offset:25360
	ds_read2_b32 v[108:109], v110 offset0:96 offset1:128
	v_pk_fma_f32 v[8:9], v[94:95], v[12:13], v[8:9]
	s_waitcnt lgkmcnt(8)
	v_pk_mul_f32 v[40:41], v[40:41], v[88:89]
	v_pk_fma_f32 v[92:93], v[24:25], v[36:37], v[8:9] op_sel_hi:[0,1,1]
	v_pk_mul_f32 v[8:9], v[74:75], v[26:27] op_sel_hi:[1,0]
	v_pk_fma_f32 v[40:41], v[90:91], v[42:43], v[40:41]
	v_pk_fma_f32 v[8:9], v[106:107], v[14:15], v[8:9]
	s_waitcnt lgkmcnt(7)
	v_pk_fma_f32 v[40:41], v[92:93], v[44:45], v[40:41]
	v_pk_fma_f32 v[94:95], v[24:25], v[38:39], v[8:9] op_sel_hi:[0,1,1]
	v_pk_mul_f32 v[8:9], v[76:77], v[88:89]
	v_pk_fma_f32 v[8:9], v[90:91], v[78:79], v[8:9]
	v_pk_fma_f32 v[40:41], v[94:95], v[46:47], v[40:41]
	v_pk_fma_f32 v[8:9], v[92:93], v[80:81], v[8:9]
	v_add_f32_e32 v40, v41, v40
	v_pk_fma_f32 v[8:9], v[94:95], v[82:83], v[8:9]
	s_nop 0
	v_add_f32_dpp v40, v40, v40 quad_perm:[1,0,3,2] row_mask:0xf bank_mask:0xf bound_ctrl:1
	v_add_f32_e32 v8, v8, v9
	s_waitcnt lgkmcnt(0)
	v_pk_mul_f32 v[42:43], v[56:57], v[108:109] op_sel_hi:[1,0]
	v_add_f32_dpp v40, v40, v40 quad_perm:[2,3,0,1] row_mask:0xf bank_mask:0xf bound_ctrl:1
	v_add_f32_dpp v8, v8, v8 quad_perm:[1,0,3,2] row_mask:0xf bank_mask:0xf bound_ctrl:1
	v_pk_fma_f32 v[16:17], v[88:89], v[16:17], v[42:43]
	v_add_f32_dpp v40, v40, v40 row_half_mirror row_mask:0xf bank_mask:0xf bound_ctrl:1
	v_add_f32_dpp v8, v8, v8 quad_perm:[2,3,0,1] row_mask:0xf bank_mask:0xf bound_ctrl:1
	v_pk_fma_f32 v[88:89], v[40:41], v[48:49], v[16:17] op_sel_hi:[0,1,1]
	v_pk_mul_f32 v[16:17], v[58:59], v[108:109] op_sel_hi:[1,0]
	v_add_f32_dpp v8, v8, v8 row_half_mirror row_mask:0xf bank_mask:0xf bound_ctrl:1
	v_pk_fma_f32 v[16:17], v[90:91], v[18:19], v[16:17]
	ds_write_b32 v151, v8 offset:2304
	v_pk_fma_f32 v[90:91], v[40:41], v[50:51], v[16:17] op_sel_hi:[0,1,1]
	v_pk_mul_f32 v[16:17], v[60:61], v[108:109] op_sel_hi:[1,0]
	ds_read_b128 v[8:11], v149 offset:25600
	ds_read_b128 v[12:15], v149 offset:25616
	ds_read_b128 v[24:27], v149 offset:25856
	ds_read_b128 v[28:31], v149 offset:25872
	ds_read_b128 v[32:35], v149 offset:26112
	ds_read_b128 v[36:39], v149 offset:26128
	ds_read_b128 v[68:71], v149 offset:26368
	ds_read_b128 v[72:75], v149 offset:26384
	ds_read_b128 v[76:79], v149 offset:26624
	ds_read_b128 v[80:83], v149 offset:26640
	v_pk_fma_f32 v[16:17], v[92:93], v[20:21], v[16:17]
	s_waitcnt lgkmcnt(7)
	v_pk_mul_f32 v[24:25], v[24:25], v[88:89]
	v_pk_fma_f32 v[92:93], v[40:41], v[52:53], v[16:17] op_sel_hi:[0,1,1]
	v_pk_mul_f32 v[16:17], v[62:63], v[108:109] op_sel_hi:[1,0]
	v_pk_fma_f32 v[24:25], v[90:91], v[26:27], v[24:25]
	v_pk_fma_f32 v[16:17], v[94:95], v[22:23], v[16:17]
	s_waitcnt lgkmcnt(6)
	v_pk_fma_f32 v[24:25], v[92:93], v[28:29], v[24:25]
	v_pk_fma_f32 v[94:95], v[40:41], v[54:55], v[16:17] op_sel_hi:[0,1,1]
	v_pk_fma_f32 v[24:25], v[94:95], v[30:31], v[24:25]
	v_mov_b32_e32 v26, v109
	v_add_f32_e32 v24, v25, v24
	v_pk_mul_f32 v[16:17], v[64:65], v[88:89]
	s_nop 0
	v_add_f32_dpp v24, v24, v24 quad_perm:[1,0,3,2] row_mask:0xf bank_mask:0xf bound_ctrl:1
	s_waitcnt lgkmcnt(3)
	v_pk_mul_f32 v[28:29], v[68:69], v[26:27] op_sel_hi:[1,0]
	v_add_f32_dpp v24, v24, v24 quad_perm:[2,3,0,1] row_mask:0xf bank_mask:0xf bound_ctrl:1
	v_pk_fma_f32 v[16:17], v[90:91], v[66:67], v[16:17]
	v_pk_fma_f32 v[8:9], v[88:89], v[8:9], v[28:29]
	v_add_f32_dpp v24, v24, v24 row_half_mirror row_mask:0xf bank_mask:0xf bound_ctrl:1
	v_pk_fma_f32 v[16:17], v[92:93], v[84:85], v[16:17]
	v_pk_fma_f32 v[88:89], v[24:25], v[32:33], v[8:9] op_sel_hi:[0,1,1]
	v_pk_mul_f32 v[8:9], v[70:71], v[26:27] op_sel_hi:[1,0]
	v_pk_fma_f32 v[16:17], v[94:95], v[86:87], v[16:17]
	v_pk_fma_f32 v[8:9], v[90:91], v[10:11], v[8:9]
	v_add_f32_e32 v16, v16, v17
	v_pk_fma_f32 v[90:91], v[24:25], v[34:35], v[8:9] op_sel_hi:[0,1,1]
	s_waitcnt lgkmcnt(2)
	v_pk_mul_f32 v[8:9], v[72:73], v[26:27] op_sel_hi:[1,0]
	v_add_f32_dpp v16, v16, v16 quad_perm:[1,0,3,2] row_mask:0xf bank_mask:0xf bound_ctrl:1
	v_pk_fma_f32 v[8:9], v[92:93], v[12:13], v[8:9]
	s_nop 0
	v_add_f32_dpp v16, v16, v16 quad_perm:[2,3,0,1] row_mask:0xf bank_mask:0xf bound_ctrl:1
	v_pk_fma_f32 v[92:93], v[24:25], v[36:37], v[8:9] op_sel_hi:[0,1,1]
	v_pk_mul_f32 v[8:9], v[74:75], v[26:27] op_sel_hi:[1,0]
	v_add_f32_dpp v16, v16, v16 row_half_mirror row_mask:0xf bank_mask:0xf bound_ctrl:1
	v_pk_fma_f32 v[8:9], v[94:95], v[14:15], v[8:9]
	ds_write_b32 v151, v16 offset:2432
	v_pk_fma_f32 v[94:95], v[24:25], v[38:39], v[8:9] op_sel_hi:[0,1,1]
	s_waitcnt lgkmcnt(2)
	v_pk_mul_f32 v[8:9], v[76:77], v[88:89]
	ds_read_b128 v[16:19], v149 offset:26880
	ds_read_b128 v[20:23], v149 offset:26896
	ds_read_b128 v[40:43], v149 offset:27136
	ds_read_b128 v[44:47], v149 offset:27152
	ds_read_b128 v[48:51], v149 offset:27392
	ds_read_b128 v[52:55], v149 offset:27408
	ds_read_b128 v[56:59], v149 offset:27648
	ds_read_b128 v[60:63], v149 offset:27664
	ds_read_b128 v[64:67], v149 offset:27904
	ds_read_b128 v[84:87], v149 offset:27920
	ds_read2_b32 v[106:107], v110 offset0:160 offset1:192
	v_pk_fma_f32 v[8:9], v[90:91], v[78:79], v[8:9]
	s_waitcnt lgkmcnt(12)
	v_pk_fma_f32 v[8:9], v[92:93], v[80:81], v[8:9]
	s_waitcnt lgkmcnt(8)
; DI float red8(float x) { x += dppf(x, 0); x += dppf(x, 1); x += dppf(x, 2); return x; }
; DI void scan_item(const Params& p, int L, int c, int item, char* smem, bool dry) {
;     ...
;   auto steps8 = [&](const float* PA, const float* Vst, float* Yst, int t0) {
; #pragma unroll
;     for (int t8 = 0; t8 < 8; ++t8) {
;       const int t = t0 + t8;
;       const float* pa = PA + (t + 1) * 320 + ks * 8;
;       const float4 xd0 = *(const float4*)(pa), xd1 = *(const float4*)(pa + 4);
;       const float4 xn0 = *(const float4*)(pa + 64), xn1 = *(const float4*)(pa + 68);
;       const float4 xb0 = *(const float4*)(pa + 128), xb1 = *(const float4*)(pa + 132);
;       const float4 xk0 = *(const float4*)(pa + 192), xk1 = *(const float4*)(pa + 196);
;       const float4 xr0 = *(const float4*)(pa + 256), xr1 = *(const float4*)(pa + 260);
;       const float xvv = Vst[(t + 1) * 32 + row32];
;       float sa0 = S[0] * n0.x, sa1 = S[1] * n0.y;
;       sa0 = fmaf(S[2], n0.z, sa0); sa1 = fmaf(S[3], n0.w, sa1);
;       sa0 = fmaf(S[4], n1.x, sa0); sa1 = fmaf(S[5], n1.y, sa1);
;       sa0 = fmaf(S[6], n1.z, sa0); sa1 = fmaf(S[7], n1.w, sa1);
;       float sa = red8(sa0 + sa1);
;       S[0] = fmaf(sa, b0.x, fmaf(S[0], d0.x, vv * k0.x)); S[1] = fmaf(sa, b0.y, fmaf(S[1], d0.y, vv * k0.y));
;       S[2] = fmaf(sa, b0.z, fmaf(S[2], d0.z, vv * k0.z)); S[3] = fmaf(sa, b0.w, fmaf(S[3], d0.w, vv * k0.w));
;       S[4] = fmaf(sa, b1.x, fmaf(S[4], d1.x, vv * k1.x)); S[5] = fmaf(sa, b1.y, fmaf(S[5], d1.y, vv * k1.y));
;       S[6] = fmaf(sa, b1.z, fmaf(S[6], d1.z, vv * k1.z)); S[7] = fmaf(sa, b1.w, fmaf(S[7], d1.w, vv * k1.w));
;       float y0 = S[0] * r0.x, y1 = S[1] * r0.y;
;       y0 = fmaf(S[2], r0.z, y0); y1 = fmaf(S[3], r0.w, y1);
;       y0 = fmaf(S[4], r1.x, y0); y1 = fmaf(S[5], r1.y, y1);
;       y0 = fmaf(S[6], r1.z, y0); y1 = fmaf(S[7], r1.w, y1);
;       float y = red8(y0 + y1);
;       Yst[t * 32 + row32] = y;
;       d0 = xd0; d1 = xd1; n0 = xn0; n1 = xn1; b0 = xb0; b1 = xb1; k0 = xk0; k1 = xk1; r0 = xr0; r1 = xr1; vv = xvv;
	v_pk_mul_f32 v[40:41], v[40:41], v[88:89]
	v_pk_fma_f32 v[8:9], v[94:95], v[82:83], v[8:9]
	v_pk_fma_f32 v[40:41], v[90:91], v[42:43], v[40:41]
	v_add_f32_e32 v8, v8, v9
	s_waitcnt lgkmcnt(7)
	v_pk_fma_f32 v[40:41], v[92:93], v[44:45], v[40:41]
	s_waitcnt lgkmcnt(0)
	v_pk_mul_f32 v[42:43], v[56:57], v[106:107] op_sel_hi:[1,0]
	v_add_f32_dpp v8, v8, v8 quad_perm:[1,0,3,2] row_mask:0xf bank_mask:0xf bound_ctrl:1
	v_pk_fma_f32 v[40:41], v[94:95], v[46:47], v[40:41]
	v_pk_mul_f32 v[56:57], v[62:63], v[106:107] op_sel_hi:[1,0]
	v_add_f32_dpp v8, v8, v8 quad_perm:[2,3,0,1] row_mask:0xf bank_mask:0xf bound_ctrl:1
	v_add_f32_e32 v40, v41, v40
	v_pk_mul_f32 v[44:45], v[58:59], v[106:107] op_sel_hi:[1,0]
	v_add_f32_dpp v8, v8, v8 row_half_mirror row_mask:0xf bank_mask:0xf bound_ctrl:1
	v_add_f32_dpp v40, v40, v40 quad_perm:[1,0,3,2] row_mask:0xf bank_mask:0xf bound_ctrl:1
	ds_write_b32 v151, v8 offset:2560
	ds_read_b128 v[8:11], v149 offset:28160
	ds_read_b128 v[12:15], v149 offset:28176
	ds_read_b128 v[24:27], v149 offset:28416
	ds_read_b128 v[28:31], v149 offset:28432
	ds_read_b128 v[32:35], v149 offset:28672
	ds_read_b128 v[36:39], v149 offset:28688
	ds_read_b128 v[68:71], v149 offset:28928
	ds_read_b128 v[72:75], v149 offset:28944
	ds_read_b128 v[76:79], v149 offset:29184
	ds_read_b128 v[80:83], v149 offset:29200
	v_add_f32_dpp v40, v40, v40 quad_perm:[2,3,0,1] row_mask:0xf bank_mask:0xf bound_ctrl:1
	v_pk_fma_f32 v[22:23], v[94:95], v[22:23], v[56:57]
	v_pk_fma_f32 v[18:19], v[90:91], v[18:19], v[44:45]
	v_add_f32_dpp v40, v40, v40 row_half_mirror row_mask:0xf bank_mask:0xf bound_ctrl:1
	v_pk_fma_f32 v[56:57], v[40:41], v[54:55], v[22:23] op_sel_hi:[0,1,1]
	v_mov_b32_e32 v22, v107
	v_pk_fma_f32 v[16:17], v[88:89], v[16:17], v[42:43]
	v_pk_mul_f32 v[46:47], v[60:61], v[106:107] op_sel_hi:[1,0]
	v_pk_fma_f32 v[60:61], v[40:41], v[50:51], v[18:19] op_sel_hi:[0,1,1]
	s_waitcnt lgkmcnt(3)
	v_pk_mul_f32 v[18:19], v[70:71], v[22:23] op_sel_hi:[1,0]
	v_pk_fma_f32 v[62:63], v[40:41], v[48:49], v[16:17] op_sel_hi:[0,1,1]
	v_pk_fma_f32 v[20:21], v[92:93], v[20:21], v[46:47]
	v_pk_fma_f32 v[10:11], v[60:61], v[10:11], v[18:19]
	v_pk_mul_f32 v[18:19], v[64:65], v[62:63]
	v_pk_mul_f32 v[24:25], v[24:25], v[62:63]
	v_pk_fma_f32 v[58:59], v[40:41], v[52:53], v[20:21] op_sel_hi:[0,1,1]
	v_pk_fma_f32 v[18:19], v[60:61], v[66:67], v[18:19]
	v_pk_fma_f32 v[24:25], v[60:61], v[26:27], v[24:25]
	v_pk_fma_f32 v[18:19], v[58:59], v[84:85], v[18:19]
	v_pk_fma_f32 v[24:25], v[58:59], v[28:29], v[24:25]
	v_pk_mul_f32 v[16:17], v[68:69], v[22:23] op_sel_hi:[1,0]
	v_pk_fma_f32 v[18:19], v[56:57], v[86:87], v[18:19]
	v_pk_fma_f32 v[24:25], v[56:57], v[30:31], v[24:25]
	v_pk_fma_f32 v[8:9], v[62:63], v[8:9], v[16:17]
	v_add_f32_e32 v16, v18, v19
	v_add_f32_e32 v24, v25, v24
	s_waitcnt lgkmcnt(2)
	v_pk_mul_f32 v[54:55], v[74:75], v[22:23] op_sel_hi:[1,0]
	v_add_f32_dpp v16, v16, v16 quad_perm:[1,0,3,2] row_mask:0xf bank_mask:0xf bound_ctrl:1
	v_add_f32_dpp v24, v24, v24 quad_perm:[1,0,3,2] row_mask:0xf bank_mask:0xf bound_ctrl:1
	v_pk_mul_f32 v[20:21], v[72:73], v[22:23] op_sel_hi:[1,0]
	v_add_f32_dpp v16, v16, v16 quad_perm:[2,3,0,1] row_mask:0xf bank_mask:0xf bound_ctrl:1
	v_add_f32_dpp v24, v24, v24 quad_perm:[2,3,0,1] row_mask:0xf bank_mask:0xf bound_ctrl:1
	v_pk_fma_f32 v[14:15], v[56:57], v[14:15], v[54:55]
	v_add_f32_dpp v16, v16, v16 row_half_mirror row_mask:0xf bank_mask:0xf bound_ctrl:1
	v_add_f32_dpp v24, v24, v24 row_half_mirror row_mask:0xf bank_mask:0xf bound_ctrl:1
	ds_write_b32 v151, v16 offset:2688
	v_pk_fma_f32 v[26:27], v[24:25], v[32:33], v[8:9] op_sel_hi:[0,1,1]
	v_pk_fma_f32 v[12:13], v[58:59], v[12:13], v[20:21]
	ds_read_b128 v[16:19], v149 offset:29440
	ds_read_b128 v[20:23], v149 offset:29456
	ds_read_b128 v[40:43], v149 offset:29696
	ds_read_b128 v[44:47], v149 offset:29712
	ds_read_b128 v[48:51], v149 offset:29952
	ds_read_b128 v[52:55], v149 offset:29968
	ds_read_b128 v[88:91], v149 offset:30208
	ds_read_b128 v[92:95], v149 offset:30224
	ds_read_b128 v[108:111], v149 offset:30464
	ds_read_b128 v[112:115], v149 offset:30480
	ds_read_b32 v106, v150 offset:2944
	v_pk_fma_f32 v[28:29], v[24:25], v[34:35], v[10:11] op_sel_hi:[0,1,1]
	s_waitcnt lgkmcnt(8)
; DI float red8(float x) { x += dppf(x, 0); x += dppf(x, 1); x += dppf(x, 2); return x; }
; DI void scan_item(const Params& p, int L, int c, int item, char* smem, bool dry) {
;     ...
;   auto load_raw = [&](int tc) {
;     const int lr = b * 4096 + tc * 32 + tt;
;     const int s = c * 4096 + tc * 32 + tt;
;     const u16* cur = U + (size_t)lr * LDU_R;
;     const u16* prv = (s == 0) ? (BND + (size_t)4 * SHIFTW) : ((s == 4096 && c == 1) ? (BND + (size_t)b * SHIFTW) : (cur - LDU_R));
;     ...
;   auto steps8 = [&](const float* PA, const float* Vst, float* Yst, int t0) {
; #pragma unroll
;     for (int t8 = 0; t8 < 8; ++t8) {
;       const int t = t0 + t8;
;       const float* pa = PA + (t + 1) * 320 + ks * 8;
;       const float4 xd0 = *(const float4*)(pa), xd1 = *(const float4*)(pa + 4);
;       const float4 xn0 = *(const float4*)(pa + 64), xn1 = *(const float4*)(pa + 68);
;       const float4 xb0 = *(const float4*)(pa + 128), xb1 = *(const float4*)(pa + 132);
;       const float4 xk0 = *(const float4*)(pa + 192), xk1 = *(const float4*)(pa + 196);
;       const float4 xr0 = *(const float4*)(pa + 256), xr1 = *(const float4*)(pa + 260);
;       const float xvv = Vst[(t + 1) * 32 + row32];
;       float sa0 = S[0] * n0.x, sa1 = S[1] * n0.y;
;       sa0 = fmaf(S[2], n0.z, sa0); sa1 = fmaf(S[3], n0.w, sa1);
;       sa0 = fmaf(S[4], n1.x, sa0); sa1 = fmaf(S[5], n1.y, sa1);
;       sa0 = fmaf(S[6], n1.z, sa0); sa1 = fmaf(S[7], n1.w, sa1);
;       float sa = red8(sa0 + sa1);
;       S[0] = fmaf(sa, b0.x, fmaf(S[0], d0.x, vv * k0.x)); S[1] = fmaf(sa, b0.y, fmaf(S[1], d0.y, vv * k0.y));
;       S[2] = fmaf(sa, b0.z, fmaf(S[2], d0.z, vv * k0.z)); S[3] = fmaf(sa, b0.w, fmaf(S[3], d0.w, vv * k0.w));
;       S[4] = fmaf(sa, b1.x, fmaf(S[4], d1.x, vv * k1.x)); S[5] = fmaf(sa, b1.y, fmaf(S[5], d1.y, vv * k1.y));
;       S[6] = fmaf(sa, b1.z, fmaf(S[6], d1.z, vv * k1.z)); S[7] = fmaf(sa, b1.w, fmaf(S[7], d1.w, vv * k1.w));
;       float y0 = S[0] * r0.x, y1 = S[1] * r0.y;
;       y0 = fmaf(S[2], r0.z, y0); y1 = fmaf(S[3], r0.w, y1);
;       y0 = fmaf(S[4], r1.x, y0); y1 = fmaf(S[5], r1.y, y1);
;       y0 = fmaf(S[6], r1.z, y0); y1 = fmaf(S[7], r1.w, y1);
;       float y = red8(y0 + y1);
;       Yst[t * 32 + row32] = y;
;       d0 = xd0; d1 = xd1; n0 = xn0; n1 = xn1; b0 = xb0; b1 = xb1; k0 = xk0; k1 = xk1; r0 = xr0; r1 = xr1; vv = xvv;
	v_pk_mul_f32 v[32:33], v[40:41], v[26:27]
	v_pk_fma_f32 v[30:31], v[24:25], v[36:37], v[12:13] op_sel_hi:[0,1,1]
	v_pk_fma_f32 v[32:33], v[28:29], v[42:43], v[32:33]
	v_pk_fma_f32 v[24:25], v[24:25], v[38:39], v[14:15] op_sel_hi:[0,1,1]
	v_pk_mul_f32 v[8:9], v[76:77], v[26:27]
	s_waitcnt lgkmcnt(7)
	v_pk_fma_f32 v[32:33], v[30:31], v[44:45], v[32:33]
	v_pk_fma_f32 v[8:9], v[28:29], v[78:79], v[8:9]
	v_pk_fma_f32 v[32:33], v[24:25], v[46:47], v[32:33]
	v_pk_fma_f32 v[8:9], v[30:31], v[80:81], v[8:9]
	v_add_f32_e32 v32, v33, v32
	v_pk_fma_f32 v[8:9], v[24:25], v[82:83], v[8:9]
	s_nop 0
	v_add_f32_dpp v32, v32, v32 quad_perm:[1,0,3,2] row_mask:0xf bank_mask:0xf bound_ctrl:1
	v_add_f32_e32 v8, v8, v9
	s_waitcnt lgkmcnt(0)
	v_pk_mul_f32 v[34:35], v[88:89], v[106:107] op_sel_hi:[1,0]
	v_add_f32_dpp v32, v32, v32 quad_perm:[2,3,0,1] row_mask:0xf bank_mask:0xf bound_ctrl:1
	v_add_f32_dpp v8, v8, v8 quad_perm:[1,0,3,2] row_mask:0xf bank_mask:0xf bound_ctrl:1
	v_pk_fma_f32 v[16:17], v[26:27], v[16:17], v[34:35]
	v_add_f32_dpp v32, v32, v32 row_half_mirror row_mask:0xf bank_mask:0xf bound_ctrl:1
	v_add_f32_dpp v8, v8, v8 quad_perm:[2,3,0,1] row_mask:0xf bank_mask:0xf bound_ctrl:1
	v_pk_fma_f32 v[88:89], v[32:33], v[48:49], v[16:17] op_sel_hi:[0,1,1]
	v_pk_mul_f32 v[16:17], v[90:91], v[106:107] op_sel_hi:[1,0]
	v_add_f32_dpp v8, v8, v8 row_half_mirror row_mask:0xf bank_mask:0xf bound_ctrl:1
	v_pk_fma_f32 v[16:17], v[28:29], v[18:19], v[16:17]
	ds_write_b32 v151, v8 offset:2816
	v_pk_fma_f32 v[90:91], v[32:33], v[50:51], v[16:17] op_sel_hi:[0,1,1]
	v_pk_mul_f32 v[16:17], v[92:93], v[106:107] op_sel_hi:[1,0]
	ds_read_b128 v[56:59], v149 offset:30720
	ds_read_b128 v[68:71], v149 offset:30736
	ds_read_b128 v[84:87], v149 offset:30976
	ds_read_b128 v[80:83], v149 offset:30992
	ds_read_b128 v[60:63], v149 offset:31232
	ds_read_b128 v[72:75], v149 offset:31248
	ds_read_b128 v[64:67], v149 offset:31488
	ds_read_b128 v[76:79], v149 offset:31504
	ds_read_b128 v[12:15], v149 offset:31744
	ds_read_b128 v[8:11], v149 offset:31760
	v_pk_fma_f32 v[16:17], v[30:31], v[20:21], v[16:17]
	s_nop 0
	v_pk_fma_f32 v[92:93], v[32:33], v[52:53], v[16:17] op_sel_hi:[0,1,1]
	v_pk_mul_f32 v[16:17], v[94:95], v[106:107] op_sel_hi:[1,0]
	ds_read_b32 v94, v150 offset:3072
	v_pk_fma_f32 v[16:17], v[24:25], v[22:23], v[16:17]
	s_nop 0
	v_pk_fma_f32 v[106:107], v[32:33], v[54:55], v[16:17] op_sel_hi:[0,1,1]
	v_pk_mul_f32 v[16:17], v[108:109], v[88:89]
	v_pk_fma_f32 v[16:17], v[90:91], v[110:111], v[16:17]
	v_pk_fma_f32 v[16:17], v[92:93], v[112:113], v[16:17]
	v_pk_fma_f32 v[16:17], v[106:107], v[114:115], v[16:17]
	v_add_f32_e32 v16, v16, v17
	s_nop 1
	v_add_f32_dpp v16, v16, v16 quad_perm:[1,0,3,2] row_mask:0xf bank_mask:0xf bound_ctrl:1
	s_nop 1
	v_add_f32_dpp v16, v16, v16 quad_perm:[2,3,0,1] row_mask:0xf bank_mask:0xf bound_ctrl:1
	s_nop 1
	v_add_f32_dpp v16, v16, v16 row_half_mirror row_mask:0xf bank_mask:0xf bound_ctrl:1
	ds_write_b32 v151, v16 offset:2944
	v_add_u32_e32 v16, s29, v99
	v_cmp_lt_i32_e32 vcc, s69, v16
	s_and_saveexec_b64 s[22:23], vcc
	s_xor_b64 s[22:23], exec, s[22:23]
	s_cbranch_execz .LBB0_160
	v_cmp_eq_u32_e32 vcc, s73, v16
	s_mov_b64 s[18:19], -1
	s_and_saveexec_b64 s[24:25], vcc
	s_cbranch_execz .LBB0_159
	v_readlane_b32 s18, v254, 23
	v_readlane_b32 s19, v254, 24
	s_orn2_b64 s[18:19], s[18:19], exec

; DI float red8(float x) { x += dppf(x, 0); x += dppf(x, 1); x += dppf(x, 2); return x; }
; DI void scan_item(const Params& p, int L, int c, int item, char* smem, bool dry) {
;     ...
;   auto steps8 = [&](const float* PA, const float* Vst, float* Yst, int t0) {
; #pragma unroll
;     for (int t8 = 0; t8 < 8; ++t8) {
;       const int t = t0 + t8;
;       const float* pa = PA + (t + 1) * 320 + ks * 8;
;       const float4 xd0 = *(const float4*)(pa), xd1 = *(const float4*)(pa + 4);
;       const float4 xn0 = *(const float4*)(pa + 64), xn1 = *(const float4*)(pa + 68);
;       const float4 xb0 = *(const float4*)(pa + 128), xb1 = *(const float4*)(pa + 132);
;       const float4 xk0 = *(const float4*)(pa + 192), xk1 = *(const float4*)(pa + 196);
;       const float4 xr0 = *(const float4*)(pa + 256), xr1 = *(const float4*)(pa + 260);
;       const float xvv = Vst[(t + 1) * 32 + row32];
;       float sa0 = S[0] * n0.x, sa1 = S[1] * n0.y;
;       sa0 = fmaf(S[2], n0.z, sa0); sa1 = fmaf(S[3], n0.w, sa1);
;       sa0 = fmaf(S[4], n1.x, sa0); sa1 = fmaf(S[5], n1.y, sa1);
;       sa0 = fmaf(S[6], n1.z, sa0); sa1 = fmaf(S[7], n1.w, sa1);
;       float sa = red8(sa0 + sa1);
;       S[0] = fmaf(sa, b0.x, fmaf(S[0], d0.x, vv * k0.x)); S[1] = fmaf(sa, b0.y, fmaf(S[1], d0.y, vv * k0.y));
;       S[2] = fmaf(sa, b0.z, fmaf(S[2], d0.z, vv * k0.z)); S[3] = fmaf(sa, b0.w, fmaf(S[3], d0.w, vv * k0.w));
;       S[4] = fmaf(sa, b1.x, fmaf(S[4], d1.x, vv * k1.x)); S[5] = fmaf(sa, b1.y, fmaf(S[5], d1.y, vv * k1.y));
;       S[6] = fmaf(sa, b1.z, fmaf(S[6], d1.z, vv * k1.z)); S[7] = fmaf(sa, b1.w, fmaf(S[7], d1.w, vv * k1.w));
;       float y0 = S[0] * r0.x, y1 = S[1] * r0.y;
;       y0 = fmaf(S[2], r0.z, y0); y1 = fmaf(S[3], r0.w, y1);
;       y0 = fmaf(S[4], r1.x, y0); y1 = fmaf(S[5], r1.y, y1);
;       y0 = fmaf(S[6], r1.z, y0); y1 = fmaf(S[7], r1.w, y1);
;       float y = red8(y0 + y1);
;       Yst[t * 32 + row32] = y;
;       d0 = xd0; d1 = xd1; n0 = xn0; n1 = xn1; b0 = xb0; b1 = xb1; k0 = xk0; k1 = xk1; r0 = xr0; r1 = xr1; vv = xvv;
.LBB0_167:
	s_or_b64 exec, exec, s[18:19]
	s_waitcnt lgkmcnt(9)
	v_pk_mul_f32 v[84:85], v[84:85], v[88:89]
	v_add_u32_e32 v166, 0xc00, v150
	v_pk_fma_f32 v[84:85], v[90:91], v[86:87], v[84:85]
	ds_read_b128 v[0:3], v149 offset:32000
	ds_read_b128 v[4:7], v149 offset:32016
	ds_read_b128 v[108:111], v149 offset:32256
	ds_read_b128 v[112:115], v149 offset:32272
	ds_read_b128 v[116:119], v149 offset:32512
	ds_read_b128 v[120:123], v149 offset:32528
	ds_read_b128 v[124:127], v149 offset:32768
	ds_read_b128 v[128:131], v149 offset:32784
	ds_read_b128 v[152:155], v149 offset:33024
	ds_read_b128 v[156:159], v149 offset:33040
	s_waitcnt lgkmcnt(14)
	v_pk_fma_f32 v[80:81], v[92:93], v[80:81], v[84:85]
	ds_read2_b32 v[132:133], v166 offset0:32 offset1:64
	v_pk_fma_f32 v[80:81], v[106:107], v[82:83], v[80:81]
	s_waitcnt lgkmcnt(12)
	v_pk_mul_f32 v[78:79], v[78:79], v[94:95] op_sel_hi:[1,0]
	v_add_f32_e32 v80, v80, v81
	v_pk_fma_f32 v[70:71], v[106:107], v[70:71], v[78:79]
	s_add_i32 s29, s29, 32
	v_add_f32_dpp v80, v80, v80 quad_perm:[1,0,3,2] row_mask:0xf bank_mask:0xf bound_ctrl:1
	s_add_i32 s30, s30, 1
	s_cmpk_eq_i32 s29, 0x1000
	v_add_f32_dpp v80, v80, v80 quad_perm:[2,3,0,1] row_mask:0xf bank_mask:0xf bound_ctrl:1
	s_nop 1
	v_add_f32_dpp v80, v80, v80 row_half_mirror row_mask:0xf bank_mask:0xf bound_ctrl:1
	v_pk_fma_f32 v[82:83], v[80:81], v[74:75], v[70:71] op_sel_hi:[0,1,1]
	s_waitcnt lgkmcnt(0)
	v_pk_mul_f32 v[70:71], v[130:131], v[132:133] op_sel_hi:[1,0]
	s_nop 0
	v_pk_fma_f32 v[84:85], v[82:83], v[6:7], v[70:71]
	v_pk_mul_f32 v[6:7], v[76:77], v[94:95] op_sel_hi:[1,0]
	s_nop 0
	v_pk_fma_f32 v[6:7], v[92:93], v[68:69], v[6:7]
	s_nop 0
	v_pk_fma_f32 v[86:87], v[80:81], v[72:73], v[6:7] op_sel_hi:[0,1,1]
	v_pk_mul_f32 v[6:7], v[128:129], v[132:133] op_sel_hi:[1,0]
	s_nop 0
	v_pk_fma_f32 v[92:93], v[86:87], v[4:5], v[6:7]
	v_pk_mul_f32 v[4:5], v[66:67], v[94:95] op_sel_hi:[1,0]
	s_nop 0
	v_pk_fma_f32 v[4:5], v[90:91], v[58:59], v[4:5]
	s_nop 0
	v_pk_fma_f32 v[90:91], v[80:81], v[62:63], v[4:5] op_sel_hi:[0,1,1]
	v_pk_mul_f32 v[4:5], v[126:127], v[132:133] op_sel_hi:[1,0]
	s_nop 0
	v_pk_fma_f32 v[104:105], v[90:91], v[2:3], v[4:5]
	v_pk_mul_f32 v[2:3], v[64:65], v[94:95] op_sel_hi:[1,0]
	s_nop 0
	v_pk_fma_f32 v[2:3], v[88:89], v[56:57], v[2:3]
	s_nop 0
	v_pk_fma_f32 v[80:81], v[80:81], v[60:61], v[2:3] op_sel_hi:[0,1,1]
	v_pk_mul_f32 v[2:3], v[124:125], v[132:133] op_sel_hi:[1,0]
	v_pk_mul_f32 v[4:5], v[12:13], v[80:81]
	v_pk_fma_f32 v[88:89], v[80:81], v[0:1], v[2:3]
	v_pk_mul_f32 v[80:81], v[108:109], v[80:81]
	v_pk_fma_f32 v[80:81], v[90:91], v[110:111], v[80:81]
	v_pk_fma_f32 v[4:5], v[90:91], v[14:15], v[4:5]
	v_pk_fma_f32 v[80:81], v[86:87], v[112:113], v[80:81]
	v_pk_fma_f32 v[80:81], v[82:83], v[114:115], v[80:81]
	v_pk_fma_f32 v[4:5], v[86:87], v[8:9], v[4:5]
	v_add_f32_e32 v80, v81, v80
	v_pk_fma_f32 v[4:5], v[82:83], v[10:11], v[4:5]
	s_nop 0
	v_add_f32_dpp v80, v80, v80 quad_perm:[1,0,3,2] row_mask:0xf bank_mask:0xf bound_ctrl:1
	v_add_f32_e32 v0, v4, v5
	s_nop 0
	v_add_f32_dpp v80, v80, v80 quad_perm:[2,3,0,1] row_mask:0xf bank_mask:0xf bound_ctrl:1
	v_add_f32_dpp v0, v0, v0 quad_perm:[1,0,3,2] row_mask:0xf bank_mask:0xf bound_ctrl:1
	s_nop 0
	v_add_f32_dpp v80, v80, v80 row_half_mirror row_mask:0xf bank_mask:0xf bound_ctrl:1
	v_pk_fma_f32 v[160:161], v[80:81], v[116:117], v[88:89] op_sel_hi:[0,1,1]
	v_add_f32_dpp v0, v0, v0 quad_perm:[2,3,0,1] row_mask:0xf bank_mask:0xf bound_ctrl:1
	v_pk_fma_f32 v[162:163], v[80:81], v[118:119], v[104:105] op_sel_hi:[0,1,1]
	v_pk_fma_f32 v[92:93], v[80:81], v[120:121], v[92:93] op_sel_hi:[0,1,1]
	v_pk_fma_f32 v[164:165], v[80:81], v[122:123], v[84:85] op_sel_hi:[0,1,1]
	v_pk_mul_f32 v[80:81], v[152:153], v[160:161]
	v_add_f32_dpp v0, v0, v0 row_half_mirror row_mask:0xf bank_mask:0xf bound_ctrl:1
	v_pk_fma_f32 v[80:81], v[162:163], v[154:155], v[80:81]
	s_nop 0
	ds_write_b32 v151, v0 offset:3072
	v_pk_fma_f32 v[80:81], v[92:93], v[156:157], v[80:81]
	ds_read_b128 v[0:3], v149 offset:33280
	ds_read_b128 v[4:7], v149 offset:33296
	ds_read_b128 v[8:11], v149 offset:33536
	ds_read_b128 v[12:15], v149 offset:33552
	ds_read_b128 v[56:59], v149 offset:33792
	ds_read_b128 v[60:63], v149 offset:33808
	ds_read_b128 v[64:67], v149 offset:34048
	ds_read_b128 v[68:71], v149 offset:34064
	ds_read_b128 v[72:75], v149 offset:34304
	ds_read_b128 v[76:79], v149 offset:34320
	v_pk_fma_f32 v[80:81], v[164:165], v[158:159], v[80:81]
	v_add_f32_e32 v80, v80, v81
	s_waitcnt lgkmcnt(7)
	v_pk_mul_f32 v[8:9], v[8:9], v[160:161]
	v_add_f32_dpp v80, v80, v80 quad_perm:[1,0,3,2] row_mask:0xf bank_mask:0xf bound_ctrl:1
	v_pk_fma_f32 v[8:9], v[162:163], v[10:11], v[8:9]
	v_mov_b32_e32 v10, v133
	v_add_f32_dpp v80, v80, v80 quad_perm:[2,3,0,1] row_mask:0xf bank_mask:0xf bound_ctrl:1
	s_waitcnt lgkmcnt(6)
	v_pk_fma_f32 v[8:9], v[92:93], v[12:13], v[8:9]
	s_waitcnt lgkmcnt(3)
	v_pk_mul_f32 v[12:13], v[64:65], v[10:11] op_sel_hi:[1,0]
	v_add_f32_dpp v80, v80, v80 row_half_mirror row_mask:0xf bank_mask:0xf bound_ctrl:1
	v_pk_fma_f32 v[8:9], v[164:165], v[14:15], v[8:9]
	ds_write_b32 v151, v80 offset:3200
	v_add_f32_e32 v8, v9, v8
	ds_read_b128 v[80:83], v149 offset:34560
	ds_read_b128 v[84:87], v149 offset:34576
	ds_read_b128 v[88:91], v149 offset:34816
	ds_read_b128 v[104:107], v149 offset:34832
	ds_read_b128 v[108:111], v149 offset:35072
	ds_read_b128 v[112:115], v149 offset:35088
	ds_read_b128 v[116:119], v149 offset:35328
	ds_read_b128 v[120:123], v149 offset:35344
	ds_read_b128 v[124:127], v149 offset:35584
	ds_read_b128 v[128:131], v149 offset:35600
	ds_read2_b32 v[152:153], v166 offset0:96 offset1:128
	v_add_f32_dpp v8, v8, v8 quad_perm:[1,0,3,2] row_mask:0xf bank_mask:0xf bound_ctrl:1
	v_pk_fma_f32 v[0:1], v[160:161], v[0:1], v[12:13]
	v_pk_mul_f32 v[12:13], v[66:67], v[10:11] op_sel_hi:[1,0]
	v_add_f32_dpp v8, v8, v8 quad_perm:[2,3,0,1] row_mask:0xf bank_mask:0xf bound_ctrl:1
	v_pk_fma_f32 v[2:3], v[162:163], v[2:3], v[12:13]
	s_waitcnt lgkmcnt(14)
; DI float red8(float x) { x += dppf(x, 0); x += dppf(x, 1); x += dppf(x, 2); return x; }
; DI void scan_item(const Params& p, int L, int c, int item, char* smem, bool dry) {
;     ...
;   auto steps8 = [&](const float* PA, const float* Vst, float* Yst, int t0) {
; #pragma unroll
;     for (int t8 = 0; t8 < 8; ++t8) {
;       const int t = t0 + t8;
;       const float* pa = PA + (t + 1) * 320 + ks * 8;
;       const float4 xd0 = *(const float4*)(pa), xd1 = *(const float4*)(pa + 4);
;       const float4 xn0 = *(const float4*)(pa + 64), xn1 = *(const float4*)(pa + 68);
;       const float4 xb0 = *(const float4*)(pa + 128), xb1 = *(const float4*)(pa + 132);
;       const float4 xk0 = *(const float4*)(pa + 192), xk1 = *(const float4*)(pa + 196);
;       const float4 xr0 = *(const float4*)(pa + 256), xr1 = *(const float4*)(pa + 260);
;       const float xvv = Vst[(t + 1) * 32 + row32];
;       float sa0 = S[0] * n0.x, sa1 = S[1] * n0.y;
;       sa0 = fmaf(S[2], n0.z, sa0); sa1 = fmaf(S[3], n0.w, sa1);
;       sa0 = fmaf(S[4], n1.x, sa0); sa1 = fmaf(S[5], n1.y, sa1);
;       sa0 = fmaf(S[6], n1.z, sa0); sa1 = fmaf(S[7], n1.w, sa1);
;       float sa = red8(sa0 + sa1);
;       S[0] = fmaf(sa, b0.x, fmaf(S[0], d0.x, vv * k0.x)); S[1] = fmaf(sa, b0.y, fmaf(S[1], d0.y, vv * k0.y));
;       S[2] = fmaf(sa, b0.z, fmaf(S[2], d0.z, vv * k0.z)); S[3] = fmaf(sa, b0.w, fmaf(S[3], d0.w, vv * k0.w));
;       S[4] = fmaf(sa, b1.x, fmaf(S[4], d1.x, vv * k1.x)); S[5] = fmaf(sa, b1.y, fmaf(S[5], d1.y, vv * k1.y));
;       S[6] = fmaf(sa, b1.z, fmaf(S[6], d1.z, vv * k1.z)); S[7] = fmaf(sa, b1.w, fmaf(S[7], d1.w, vv * k1.w));
;       float y0 = S[0] * r0.x, y1 = S[1] * r0.y;
;       y0 = fmaf(S[2], r0.z, y0); y1 = fmaf(S[3], r0.w, y1);
;       y0 = fmaf(S[4], r1.x, y0); y1 = fmaf(S[5], r1.y, y1);
;       y0 = fmaf(S[6], r1.z, y0); y1 = fmaf(S[7], r1.w, y1);
;       float y = red8(y0 + y1);
;       Yst[t * 32 + row32] = y;
;       d0 = xd0; d1 = xd1; n0 = xn0; n1 = xn1; b0 = xb0; b1 = xb1; k0 = xk0; k1 = xk1; r0 = xr0; r1 = xr1; vv = xvv;
	v_pk_mul_f32 v[12:13], v[68:69], v[10:11] op_sel_hi:[1,0]
	v_add_f32_dpp v8, v8, v8 row_half_mirror row_mask:0xf bank_mask:0xf bound_ctrl:1
	v_pk_fma_f32 v[4:5], v[92:93], v[4:5], v[12:13]
	v_pk_fma_f32 v[92:93], v[8:9], v[56:57], v[0:1] op_sel_hi:[0,1,1]
	s_waitcnt lgkmcnt(13)
	v_mul_f32_e32 v9, v72, v92
	s_waitcnt lgkmcnt(0)
	v_pk_mul_f32 v[0:1], v[116:117], v[152:153] op_sel_hi:[1,0]
	v_pk_fma_f32 v[116:117], v[8:9], v[58:59], v[2:3] op_sel_hi:[0,1,1]
	v_pk_mul_f32 v[10:11], v[70:71], v[10:11] op_sel_hi:[1,0]
	v_fmac_f32_e32 v9, v116, v74
	v_pk_fma_f32 v[6:7], v[164:165], v[6:7], v[10:11]
	v_mul_f32_e32 v10, v73, v93
	v_pk_fma_f32 v[80:81], v[92:93], v[80:81], v[0:1]
	v_pk_mul_f32 v[0:1], v[118:119], v[152:153] op_sel_hi:[1,0]
	v_pk_fma_f32 v[118:119], v[8:9], v[60:61], v[4:5] op_sel_hi:[0,1,1]
	v_fmac_f32_e32 v10, v117, v75
	v_fmac_f32_e32 v9, v118, v76
	v_pk_mul_f32 v[88:89], v[88:89], v[92:93]
	v_pk_fma_f32 v[82:83], v[116:117], v[82:83], v[0:1]
	v_pk_mul_f32 v[0:1], v[120:121], v[152:153] op_sel_hi:[1,0]
	v_fmac_f32_e32 v10, v119, v77
	v_pk_fma_f32 v[120:121], v[8:9], v[62:63], v[6:7] op_sel_hi:[0,1,1]
	v_pk_fma_f32 v[88:89], v[116:117], v[90:91], v[88:89]
	v_pk_fma_f32 v[84:85], v[118:119], v[84:85], v[0:1]
	v_pk_mul_f32 v[0:1], v[122:123], v[152:153] op_sel_hi:[1,0]
	v_fmac_f32_e32 v9, v120, v78
	v_fmac_f32_e32 v10, v121, v79
	v_pk_fma_f32 v[88:89], v[118:119], v[104:105], v[88:89]
	v_pk_fma_f32 v[86:87], v[120:121], v[86:87], v[0:1]
	v_add_f32_e32 v0, v9, v10
	v_pk_fma_f32 v[88:89], v[120:121], v[106:107], v[88:89]
	s_nop 0
	v_add_f32_dpp v0, v0, v0 quad_perm:[1,0,3,2] row_mask:0xf bank_mask:0xf bound_ctrl:1
	v_add_f32_e32 v88, v89, v88
	s_nop 0
	v_add_f32_dpp v0, v0, v0 quad_perm:[2,3,0,1] row_mask:0xf bank_mask:0xf bound_ctrl:1
	v_add_f32_dpp v88, v88, v88 quad_perm:[1,0,3,2] row_mask:0xf bank_mask:0xf bound_ctrl:1
	s_nop 0
	v_add_f32_dpp v0, v0, v0 row_half_mirror row_mask:0xf bank_mask:0xf bound_ctrl:1
	v_add_f32_dpp v88, v88, v88 quad_perm:[2,3,0,1] row_mask:0xf bank_mask:0xf bound_ctrl:1
	ds_write_b32 v151, v0 offset:3328
	ds_read_b128 v[0:3], v149 offset:35840
	ds_read_b128 v[4:7], v149 offset:35856
	ds_read_b128 v[8:11], v149 offset:36096
	ds_read_b128 v[12:15], v149 offset:36112
	ds_read_b128 v[56:59], v149 offset:36352
	ds_read_b128 v[60:63], v149 offset:36368
	ds_read_b128 v[64:67], v149 offset:36608
	ds_read_b128 v[68:71], v149 offset:36624
	ds_read_b128 v[72:75], v149 offset:36864
	ds_read_b128 v[76:79], v149 offset:36880
	v_add_f32_dpp v88, v88, v88 row_half_mirror row_mask:0xf bank_mask:0xf bound_ctrl:1
	v_pk_fma_f32 v[92:93], v[88:89], v[108:109], v[80:81] op_sel_hi:[0,1,1]
	v_pk_fma_f32 v[132:133], v[88:89], v[110:111], v[82:83] op_sel_hi:[0,1,1]
	s_waitcnt lgkmcnt(7)
	v_pk_mul_f32 v[8:9], v[8:9], v[92:93]
	v_pk_fma_f32 v[154:155], v[88:89], v[112:113], v[84:85] op_sel_hi:[0,1,1]
	v_pk_fma_f32 v[8:9], v[132:133], v[10:11], v[8:9]
	v_pk_fma_f32 v[156:157], v[88:89], v[114:115], v[86:87] op_sel_hi:[0,1,1]
	v_pk_mul_f32 v[80:81], v[124:125], v[92:93]
	s_waitcnt lgkmcnt(6)
	v_pk_fma_f32 v[8:9], v[154:155], v[12:13], v[8:9]
	v_pk_fma_f32 v[80:81], v[132:133], v[126:127], v[80:81]
	v_pk_fma_f32 v[8:9], v[156:157], v[14:15], v[8:9]
	v_pk_fma_f32 v[80:81], v[154:155], v[128:129], v[80:81]
	v_add_f32_e32 v8, v9, v8
	v_pk_fma_f32 v[80:81], v[156:157], v[130:131], v[80:81]
	s_nop 0
	v_add_f32_dpp v8, v8, v8 quad_perm:[1,0,3,2] row_mask:0xf bank_mask:0xf bound_ctrl:1
	v_mov_b32_e32 v10, v153
	v_add_f32_e32 v80, v80, v81
	v_add_f32_dpp v8, v8, v8 quad_perm:[2,3,0,1] row_mask:0xf bank_mask:0xf bound_ctrl:1
	s_waitcnt lgkmcnt(3)
	v_pk_mul_f32 v[12:13], v[64:65], v[10:11] op_sel_hi:[1,0]
	v_add_f32_dpp v80, v80, v80 quad_perm:[1,0,3,2] row_mask:0xf bank_mask:0xf bound_ctrl:1
	v_add_f32_dpp v8, v8, v8 row_half_mirror row_mask:0xf bank_mask:0xf bound_ctrl:1
	v_pk_fma_f32 v[0:1], v[92:93], v[0:1], v[12:13]
	v_add_f32_dpp v80, v80, v80 quad_perm:[2,3,0,1] row_mask:0xf bank_mask:0xf bound_ctrl:1
	v_pk_fma_f32 v[92:93], v[8:9], v[56:57], v[0:1] op_sel_hi:[0,1,1]
	v_pk_mul_f32 v[0:1], v[66:67], v[10:11] op_sel_hi:[1,0]
	v_add_f32_dpp v80, v80, v80 row_half_mirror row_mask:0xf bank_mask:0xf bound_ctrl:1
	v_pk_fma_f32 v[0:1], v[132:133], v[2:3], v[0:1]
	ds_write_b32 v151, v80 offset:3456
	v_pk_fma_f32 v[132:133], v[8:9], v[58:59], v[0:1] op_sel_hi:[0,1,1]
	s_waitcnt lgkmcnt(3)
	v_pk_mul_f32 v[0:1], v[68:69], v[10:11] op_sel_hi:[1,0]
	ds_read_b128 v[80:83], v149 offset:37120
	ds_read_b128 v[84:87], v149 offset:37136
	ds_read_b128 v[88:91], v149 offset:37376
	ds_read_b128 v[104:107], v149 offset:37392
	ds_read_b128 v[108:111], v149 offset:37632
	ds_read_b128 v[112:115], v149 offset:37648
	ds_read_b128 v[116:119], v149 offset:37888
	ds_read_b128 v[120:123], v149 offset:37904
	ds_read_b128 v[124:127], v149 offset:38144
	ds_read_b128 v[128:131], v149 offset:38160
	ds_read2_b32 v[158:159], v166 offset0:160 offset1:192
	v_pk_fma_f32 v[0:1], v[154:155], v[4:5], v[0:1]
	s_waitcnt lgkmcnt(8)
	v_pk_mul_f32 v[88:89], v[88:89], v[92:93]
	v_pk_fma_f32 v[152:153], v[8:9], v[60:61], v[0:1] op_sel_hi:[0,1,1]
	v_pk_mul_f32 v[0:1], v[70:71], v[10:11] op_sel_hi:[1,0]
	v_pk_fma_f32 v[88:89], v[132:133], v[90:91], v[88:89]
	v_pk_fma_f32 v[0:1], v[156:157], v[6:7], v[0:1]
	s_waitcnt lgkmcnt(7)
	v_pk_fma_f32 v[88:89], v[152:153], v[104:105], v[88:89]
	v_pk_fma_f32 v[154:155], v[8:9], v[62:63], v[0:1] op_sel_hi:[0,1,1]
	v_pk_mul_f32 v[0:1], v[72:73], v[92:93]
	v_pk_fma_f32 v[0:1], v[132:133], v[74:75], v[0:1]
	v_pk_fma_f32 v[88:89], v[154:155], v[106:107], v[88:89]
	v_pk_fma_f32 v[0:1], v[152:153], v[76:77], v[0:1]
	v_add_f32_e32 v88, v89, v88
	v_pk_fma_f32 v[0:1], v[154:155], v[78:79], v[0:1]
	s_nop 0
	v_add_f32_dpp v88, v88, v88 quad_perm:[1,0,3,2] row_mask:0xf bank_mask:0xf bound_ctrl:1
	v_add_f32_e32 v0, v0, v1
	s_waitcnt lgkmcnt(0)
; DI float red8(float x) { x += dppf(x, 0); x += dppf(x, 1); x += dppf(x, 2); return x; }
; DI void scan_item(const Params& p, int L, int c, int item, char* smem, bool dry) {
;     ...
;   auto steps8 = [&](const float* PA, const float* Vst, float* Yst, int t0) {
; #pragma unroll
;     for (int t8 = 0; t8 < 8; ++t8) {
;       const int t = t0 + t8;
;       const float* pa = PA + (t + 1) * 320 + ks * 8;
;       const float4 xd0 = *(const float4*)(pa), xd1 = *(const float4*)(pa + 4);
;       const float4 xn0 = *(const float4*)(pa + 64), xn1 = *(const float4*)(pa + 68);
;       const float4 xb0 = *(const float4*)(pa + 128), xb1 = *(const float4*)(pa + 132);
;       const float4 xk0 = *(const float4*)(pa + 192), xk1 = *(const float4*)(pa + 196);
;       const float4 xr0 = *(const float4*)(pa + 256), xr1 = *(const float4*)(pa + 260);
;       const float xvv = Vst[(t + 1) * 32 + row32];
;       float sa0 = S[0] * n0.x, sa1 = S[1] * n0.y;
;       sa0 = fmaf(S[2], n0.z, sa0); sa1 = fmaf(S[3], n0.w, sa1);
;       sa0 = fmaf(S[4], n1.x, sa0); sa1 = fmaf(S[5], n1.y, sa1);
;       sa0 = fmaf(S[6], n1.z, sa0); sa1 = fmaf(S[7], n1.w, sa1);
;       float sa = red8(sa0 + sa1);
;       S[0] = fmaf(sa, b0.x, fmaf(S[0], d0.x, vv * k0.x)); S[1] = fmaf(sa, b0.y, fmaf(S[1], d0.y, vv * k0.y));
;       S[2] = fmaf(sa, b0.z, fmaf(S[2], d0.z, vv * k0.z)); S[3] = fmaf(sa, b0.w, fmaf(S[3], d0.w, vv * k0.w));
;       S[4] = fmaf(sa, b1.x, fmaf(S[4], d1.x, vv * k1.x)); S[5] = fmaf(sa, b1.y, fmaf(S[5], d1.y, vv * k1.y));
;       S[6] = fmaf(sa, b1.z, fmaf(S[6], d1.z, vv * k1.z)); S[7] = fmaf(sa, b1.w, fmaf(S[7], d1.w, vv * k1.w));
;       float y0 = S[0] * r0.x, y1 = S[1] * r0.y;
;       y0 = fmaf(S[2], r0.z, y0); y1 = fmaf(S[3], r0.w, y1);
;       y0 = fmaf(S[4], r1.x, y0); y1 = fmaf(S[5], r1.y, y1);
;       y0 = fmaf(S[6], r1.z, y0); y1 = fmaf(S[7], r1.w, y1);
;       float y = red8(y0 + y1);
;       Yst[t * 32 + row32] = y;
;       d0 = xd0; d1 = xd1; n0 = xn0; n1 = xn1; b0 = xb0; b1 = xb1; k0 = xk0; k1 = xk1; r0 = xr0; r1 = xr1; vv = xvv;
	v_pk_mul_f32 v[90:91], v[116:117], v[158:159] op_sel_hi:[1,0]
	v_add_f32_dpp v88, v88, v88 quad_perm:[2,3,0,1] row_mask:0xf bank_mask:0xf bound_ctrl:1
	v_add_f32_dpp v0, v0, v0 quad_perm:[1,0,3,2] row_mask:0xf bank_mask:0xf bound_ctrl:1
	v_pk_fma_f32 v[80:81], v[92:93], v[80:81], v[90:91]
	v_add_f32_dpp v88, v88, v88 row_half_mirror row_mask:0xf bank_mask:0xf bound_ctrl:1
	v_add_f32_dpp v0, v0, v0 quad_perm:[2,3,0,1] row_mask:0xf bank_mask:0xf bound_ctrl:1
	v_pk_fma_f32 v[92:93], v[88:89], v[108:109], v[80:81] op_sel_hi:[0,1,1]
	v_pk_mul_f32 v[80:81], v[118:119], v[158:159] op_sel_hi:[1,0]
	v_add_f32_dpp v0, v0, v0 row_half_mirror row_mask:0xf bank_mask:0xf bound_ctrl:1
	v_pk_fma_f32 v[80:81], v[132:133], v[82:83], v[80:81]
	ds_write_b32 v151, v0 offset:3584
	v_pk_fma_f32 v[132:133], v[88:89], v[110:111], v[80:81] op_sel_hi:[0,1,1]
	v_pk_mul_f32 v[80:81], v[120:121], v[158:159] op_sel_hi:[1,0]
	ds_read_b128 v[0:3], v149 offset:38400
	ds_read_b128 v[4:7], v149 offset:38416
	ds_read_b128 v[8:11], v149 offset:38656
	ds_read_b128 v[12:15], v149 offset:38672
	ds_read_b128 v[56:59], v149 offset:38912
	ds_read_b128 v[60:63], v149 offset:38928
	ds_read_b128 v[64:67], v149 offset:39168
	ds_read_b128 v[68:71], v149 offset:39184
	ds_read_b128 v[72:75], v149 offset:39424
	ds_read_b128 v[76:79], v149 offset:39440
	v_pk_fma_f32 v[80:81], v[152:153], v[84:85], v[80:81]
	s_waitcnt lgkmcnt(7)
	v_pk_mul_f32 v[8:9], v[8:9], v[92:93]
	v_pk_fma_f32 v[152:153], v[88:89], v[112:113], v[80:81] op_sel_hi:[0,1,1]
	v_pk_mul_f32 v[80:81], v[122:123], v[158:159] op_sel_hi:[1,0]
	v_pk_fma_f32 v[8:9], v[132:133], v[10:11], v[8:9]
	v_pk_fma_f32 v[80:81], v[154:155], v[86:87], v[80:81]
	s_waitcnt lgkmcnt(6)
	v_pk_fma_f32 v[8:9], v[152:153], v[12:13], v[8:9]
	v_pk_fma_f32 v[154:155], v[88:89], v[114:115], v[80:81] op_sel_hi:[0,1,1]
	v_pk_fma_f32 v[8:9], v[154:155], v[14:15], v[8:9]
	v_mov_b32_e32 v10, v159
	v_add_f32_e32 v8, v9, v8
	s_waitcnt lgkmcnt(3)
	v_pk_mul_f32 v[12:13], v[64:65], v[10:11] op_sel_hi:[1,0]
	v_add_f32_dpp v8, v8, v8 quad_perm:[1,0,3,2] row_mask:0xf bank_mask:0xf bound_ctrl:1
	v_pk_fma_f32 v[0:1], v[92:93], v[0:1], v[12:13]
	v_pk_mul_f32 v[12:13], v[66:67], v[10:11] op_sel_hi:[1,0]
	v_add_f32_dpp v8, v8, v8 quad_perm:[2,3,0,1] row_mask:0xf bank_mask:0xf bound_ctrl:1
	v_pk_mul_f32 v[80:81], v[124:125], v[92:93]
	v_pk_fma_f32 v[2:3], v[132:133], v[2:3], v[12:13]
	v_add_f32_dpp v8, v8, v8 row_half_mirror row_mask:0xf bank_mask:0xf bound_ctrl:1
	s_waitcnt lgkmcnt(2)
	v_pk_mul_f32 v[12:13], v[68:69], v[10:11] op_sel_hi:[1,0]
	v_pk_mul_f32 v[10:11], v[70:71], v[10:11] op_sel_hi:[1,0]
	v_pk_fma_f32 v[80:81], v[132:133], v[126:127], v[80:81]
	v_pk_fma_f32 v[0:1], v[8:9], v[56:57], v[0:1] op_sel_hi:[0,1,1]
	v_pk_fma_f32 v[4:5], v[152:153], v[4:5], v[12:13]
	v_pk_fma_f32 v[6:7], v[154:155], v[6:7], v[10:11]
	v_pk_fma_f32 v[80:81], v[152:153], v[128:129], v[80:81]
	v_pk_fma_f32 v[2:3], v[8:9], v[58:59], v[2:3] op_sel_hi:[0,1,1]
	v_pk_fma_f32 v[4:5], v[8:9], v[60:61], v[4:5] op_sel_hi:[0,1,1]
	v_pk_fma_f32 v[6:7], v[8:9], v[62:63], v[6:7] op_sel_hi:[0,1,1]
	s_waitcnt lgkmcnt(1)
	v_pk_mul_f32 v[8:9], v[72:73], v[0:1]
	v_pk_fma_f32 v[80:81], v[154:155], v[130:131], v[80:81]
	v_pk_fma_f32 v[8:9], v[2:3], v[74:75], v[8:9]
	v_add_f32_e32 v80, v80, v81
	s_waitcnt lgkmcnt(0)
	v_pk_fma_f32 v[8:9], v[4:5], v[76:77], v[8:9]
	v_add_f32_dpp v80, v80, v80 quad_perm:[1,0,3,2] row_mask:0xf bank_mask:0xf bound_ctrl:1
	v_pk_fma_f32 v[8:9], v[6:7], v[78:79], v[8:9]
	s_nop 0
	v_add_f32_dpp v80, v80, v80 quad_perm:[2,3,0,1] row_mask:0xf bank_mask:0xf bound_ctrl:1
	v_add_f32_e32 v8, v8, v9
	s_nop 0
	v_add_f32_dpp v80, v80, v80 row_half_mirror row_mask:0xf bank_mask:0xf bound_ctrl:1
	v_add_f32_dpp v8, v8, v8 quad_perm:[1,0,3,2] row_mask:0xf bank_mask:0xf bound_ctrl:1
	ds_write_b32 v151, v80 offset:3712
	ds_read_b128 v[80:83], v149 offset:39680
	ds_read_b128 v[84:87], v149 offset:39696
	ds_read_b128 v[88:91], v149 offset:39936
	ds_read_b128 v[104:107], v149 offset:39952
	ds_read_b128 v[108:111], v149 offset:40192
	ds_read_b128 v[112:115], v149 offset:40208
	ds_read_b128 v[116:119], v149 offset:40448
	ds_read_b128 v[120:123], v149 offset:40464
	ds_read_b128 v[124:127], v149 offset:40704
	ds_read_b128 v[128:131], v149 offset:40720
	ds_read_b32 v94, v150 offset:3968
	v_add_f32_dpp v8, v8, v8 quad_perm:[2,3,0,1] row_mask:0xf bank_mask:0xf bound_ctrl:1
	s_nop 1
	v_add_f32_dpp v56, v8, v8 row_half_mirror row_mask:0xf bank_mask:0xf bound_ctrl:1
	s_waitcnt lgkmcnt(8)
	v_pk_mul_f32 v[8:9], v[88:89], v[0:1]
	s_nop 0
	v_pk_fma_f32 v[8:9], v[2:3], v[90:91], v[8:9]
	s_waitcnt lgkmcnt(7)
	v_pk_fma_f32 v[8:9], v[4:5], v[104:105], v[8:9]
	s_nop 0
	v_pk_fma_f32 v[8:9], v[6:7], v[106:107], v[8:9]
	s_nop 0
	v_add_f32_e32 v8, v9, v8
	s_nop 1
	v_add_f32_dpp v8, v8, v8 quad_perm:[1,0,3,2] row_mask:0xf bank_mask:0xf bound_ctrl:1
	s_nop 1
	v_add_f32_dpp v8, v8, v8 quad_perm:[2,3,0,1] row_mask:0xf bank_mask:0xf bound_ctrl:1
	s_nop 1
	v_add_f32_dpp v14, v8, v8 row_half_mirror row_mask:0xf bank_mask:0xf bound_ctrl:1
	s_waitcnt lgkmcnt(0)
	v_pk_mul_f32 v[8:9], v[116:117], v[94:95] op_sel_hi:[1,0]
	s_nop 0
	v_pk_fma_f32 v[0:1], v[0:1], v[80:81], v[8:9]
	s_nop 0
	v_pk_fma_f32 v[8:9], v[14:15], v[108:109], v[0:1] op_sel_hi:[0,1,1]
	v_pk_mul_f32 v[0:1], v[118:119], v[94:95] op_sel_hi:[1,0]
	s_nop 0
	v_pk_fma_f32 v[0:1], v[2:3], v[82:83], v[0:1]
	s_nop 0
	v_pk_fma_f32 v[10:11], v[14:15], v[110:111], v[0:1] op_sel_hi:[0,1,1]
	v_pk_mul_f32 v[0:1], v[120:121], v[94:95] op_sel_hi:[1,0]
	s_nop 0
	v_pk_fma_f32 v[0:1], v[4:5], v[84:85], v[0:1]
	v_add3_u32 v4, s36, v148, v139
	v_pk_fma_f32 v[12:13], v[14:15], v[112:113], v[0:1] op_sel_hi:[0,1,1]
	v_pk_mul_f32 v[0:1], v[122:123], v[94:95] op_sel_hi:[1,0]
	s_nop 0
	v_pk_fma_f32 v[0:1], v[6:7], v[86:87], v[0:1]
	s_nop 0
	v_pk_fma_f32 v[14:15], v[14:15], v[114:115], v[0:1] op_sel_hi:[0,1,1]
	v_pk_mul_f32 v[0:1], v[124:125], v[8:9]
	v_pk_fma_f32 v[0:1], v[10:11], v[126:127], v[0:1]
	v_pk_fma_f32 v[0:1], v[12:13], v[128:129], v[0:1]
	v_pk_fma_f32 v[0:1], v[14:15], v[130:131], v[0:1]
	v_add_f32_e32 v0, v0, v1
	v_add_u32_e32 v1, 0xc00, v151
	s_nop 0
	v_add_f32_dpp v0, v0, v0 quad_perm:[1,0,3,2] row_mask:0xf bank_mask:0xf bound_ctrl:1
	s_nop 1
	v_add_f32_dpp v0, v0, v0 quad_perm:[2,3,0,1] row_mask:0xf bank_mask:0xf bound_ctrl:1
	s_nop 1
	v_add_f32_dpp v0, v0, v0 row_half_mirror row_mask:0xf bank_mask:0xf bound_ctrl:1
	ds_write2_b32 v1, v56, v0 offset0:192 offset1:224
	s_waitcnt lgkmcnt(0)
	s_barrier
; DI float red4(float x) { x += dppf(x, 0); x += dppf(x, 1); return x; }
; DI uint4 pack8(const float* f) { uint4 v; v.x = pack2(f[0], f[1]); v.y = pack2(f[2], f[3]); v.z = pack2(f[4], f[5]); v.w = pack2(f[6], f[7]); return v; }
; DI void scan_item(const Params& p, int L, int c, int item, char* smem, bool dry) {
;     ...
;     {
;       float y8[8], v8[8];
;       float4 t0 = *(const float4*)(Yc + tt * 32 + c4 * 8), t1 = *(const float4*)(Yc + tt * 32 + c4 * 8 + 4);
;       y8[0] = t0.x; y8[1] = t0.y; y8[2] = t0.z; y8[3] = t0.w; y8[4] = t1.x; y8[5] = t1.y; y8[6] = t1.z; y8[7] = t1.w;
;       float sm = 0.f, sq = 0.f;
; #pragma unroll
;       for (int e = 0; e < 8; ++e) { sm += y8[e]; sq += y8[e] * y8[e]; }
;       sm = red4(sm); sq = red4(sq);
;       const float bon = Bc[tt];
;       t0 = *(const float4*)(Vc + tt * 32 + c4 * 8); t1 = *(const float4*)(Vc + tt * 32 + c4 * 8 + 4);
;       v8[0] = t0.x * bon; v8[1] = t0.y * bon; v8[2] = t0.z * bon; v8[3] = t0.w * bon; v8[4] = t1.x * bon; v8[5] = t1.y * bon; v8[6] = t1.z * bon; v8[7] = t1.w * bon;
;       d_y = pack8(y8); d_v = pack8(v8); d_sm = sm; d_sq = sq; d_lr = lr;
;     }
;     v3 = v3n;
	ds_read_b128 v[0:3], v4
	ds_read_b128 v[56:59], v4 offset:16
	s_waitcnt lgkmcnt(1)
	v_add_f32_e32 v4, 0, v0
	v_add_f32_e32 v4, v4, v1
	v_add_f32_e32 v6, v4, v2
	v_mov_b32_e32 v4, v0
	v_mov_b32_e32 v5, v2
	v_pk_mul_f32 v[4:5], v[4:5], v[4:5]
	v_add_f32_e32 v6, v6, v3
	s_waitcnt lgkmcnt(0)
	v_add_f32_e32 v60, v6, v56
	v_pk_mov_b32 v[6:7], v[2:3], v[56:57] op_sel:[1,0]
	v_fma_f32 v4, v1, v1, v4
	v_pk_mul_f32 v[6:7], v[6:7], v[6:7]
	v_add_f32_e32 v4, v4, v5
	v_add_f32_e32 v4, v4, v6
	v_add_f32_e32 v4, v4, v7
	v_pk_mov_b32 v[62:63], v[56:57], v[58:59] op_sel:[1,0]
	v_fmac_f32_e32 v4, v57, v57
	v_add_f32_e32 v60, v60, v57
	v_pk_fma_f32 v[4:5], v[62:63], v[62:63], v[4:5] op_sel_hi:[1,1,0]
	v_pk_mul_f32 v[6:7], v[58:59], v[58:59]
	v_add_f32_e32 v60, v60, v58
	v_mov_b32_e32 v61, v7
	v_mov_b32_e32 v4, v59
	v_pk_add_f32 v[4:5], v[60:61], v[4:5]
	v_add3_u32 v60, s35, v148, v139
	s_nop 0
	v_mov_b32_dpp v6, v4 quad_perm:[1,0,3,2] row_mask:0xf bank_mask:0xf bound_ctrl:1
	v_mov_b32_dpp v7, v5 quad_perm:[1,0,3,2] row_mask:0xf bank_mask:0xf bound_ctrl:1
	v_pk_add_f32 v[64:65], v[4:5], v[6:7]
	v_lshl_add_u32 v4, s31, 7, v147
	ds_read_b32 v66, v4
	ds_read_b128 v[4:7], v60
	ds_read_b128 v[60:63], v60 offset:16
	v_mov_b32_dpp v68, v64 quad_perm:[2,3,0,1] row_mask:0xf bank_mask:0xf bound_ctrl:1
	v_mov_b32_dpp v69, v65 quad_perm:[2,3,0,1] row_mask:0xf bank_mask:0xf bound_ctrl:1
	v_pk_add_f32 v[104:105], v[64:65], v[68:69]
	s_waitcnt lgkmcnt(1)
	v_pk_mul_f32 v[64:65], v[66:67], v[4:5] op_sel_hi:[0,1]
	v_pk_mul_f32 v[68:69], v[66:67], v[6:7] op_sel_hi:[0,1]
	s_waitcnt lgkmcnt(0)
	v_pk_mul_f32 v[60:61], v[66:67], v[60:61] op_sel_hi:[0,1]
	v_pk_mul_f32 v[62:63], v[66:67], v[62:63] op_sel_hi:[0,1]
	v_cvt_pk_bf16_f32 v4, v0, v1
	v_cvt_pk_bf16_f32 v5, v2, v3
	v_cvt_pk_bf16_f32 v6, v56, v57
	v_cvt_pk_bf16_f32 v7, v58, v59
	v_cvt_pk_bf16_f32 v0, v64, v65
	v_cvt_pk_bf16_f32 v1, v68, v69
	v_cvt_pk_bf16_f32 v2, v60, v61
	v_cvt_pk_bf16_f32 v3, v62, v63
	s_cbranch_scc1 .LBB0_175
	s_mov_b32 s31, s34
	v_mov_b32_e32 v152, v95
	s_branch .LBB0_156

; #define MFMA32(a, b, c) __builtin_amdgcn_mfma_f32_32x32x16_bf16((a), (b), (c), 0, 0, 0)
; DI unsigned pack2(float a, float b) { f2_t v = {a, b}; bf2_t r = __builtin_convertvector(v, bf2_t); return __builtin_bit_cast(unsigned, r); }
; DI float ex2(float x) { return __builtin_amdgcn_exp2f(x); }
; template <int DQK>
; DI void attn_item(const u16* __restrict__ Qp, int ldq, const u16* __restrict__ Kp, const u16* __restrict__ Vtp, int ldv,
;                   int nkt, int q0, bool causal, float c, u16* Yp, int ldy, char* smem, bool dry) {
;     ...
;       const float mc = m * c;
;       float ps = 0.f;
; #pragma unroll
;       for (int e = 0; e < 16; ++e) { s0[e] = ex2(fmaf(s0[e], c, -mc)); s1[e] = ex2(fmaf(s1[e], c, -mc)); ps += s0[e] + s1[e]; }
;       l += ps;
;       bf16x8 pf[4];
;       {
;         u32x4 t;
;         t.x = pack2(s0[0], s0[1]); t.y = pack2(s0[2], s0[3]); t.z = pack2(s0[4], s0[5]); t.w = pack2(s0[6], s0[7]); pf[0] = __builtin_bit_cast(bf16x8, t);
;         t.x = pack2(s0[8], s0[9]); t.y = pack2(s0[10], s0[11]); t.z = pack2(s0[12], s0[13]); t.w = pack2(s0[14], s0[15]); pf[1] = __builtin_bit_cast(bf16x8, t);
;         t.x = pack2(s1[0], s1[1]); t.y = pack2(s1[2], s1[3]); t.z = pack2(s1[4], s1[5]); t.w = pack2(s1[6], s1[7]); pf[2] = __builtin_bit_cast(bf16x8, t);
;         t.x = pack2(s1[8], s1[9]); t.y = pack2(s1[10], s1[11]); t.z = pack2(s1[12], s1[13]); t.w = pack2(s1[14], s1[15]); pf[3] = __builtin_bit_cast(bf16x8, t);
;       }
; #pragma unroll
;       for (int kk = 0; kk < 4; ++kk) {
;         if (kk < 3) {
; #pragma unroll
;           for (int dt = 0; dt < 4; ++dt) va[(kk + 1) & 1][dt] = *(const bf16x8*)(v0 + (32 * dt) * 72 + 16 * (kk + 1));
;         }
;         __builtin_amdgcn_sched_barrier(0);
; #pragma unroll
;         for (int dt = 0; dt < 4; ++dt) o[dt] = MFMA32(va[kk & 1][dt], pf[kk], o[dt]);
;         __builtin_amdgcn_sched_barrier(0);
;       }
;     }
;     __syncthreads();
.LBB0_194:
	v_fmamk_f32 v0, v112, 0x3e0293ee, v149
	v_fmamk_f32 v1, v113, 0x3e0293ee, v149
	v_exp_f32_e32 v0, v0
	v_exp_f32_e32 v8, v1
	v_fmamk_f32 v2, v111, 0x3e0293ee, v149
	v_fmamk_f32 v3, v110, 0x3e0293ee, v149
	v_exp_f32_e32 v2, v2
	v_exp_f32_e32 v9, v3
	v_add_f32_e32 v1, v0, v8
	v_add_f32_e32 v1, 0, v1
	v_fmamk_f32 v4, v108, 0x3e0293ee, v149
	v_add_f32_e32 v3, v2, v9
	v_add_f32_e32 v1, v3, v1
	v_fmamk_f32 v3, v109, 0x3e0293ee, v149
	v_exp_f32_e32 v3, v3
	v_exp_f32_e32 v10, v4
	v_fmamk_f32 v5, v106, 0x3e0293ee, v149
	v_exp_f32_e32 v11, v5
	v_fmamk_f32 v6, v104, 0x3e0293ee, v149
	v_add_f32_e32 v4, v3, v10
	v_add_f32_e32 v1, v4, v1
	v_fmamk_f32 v4, v107, 0x3e0293ee, v149
	v_exp_f32_e32 v4, v4
	v_exp_f32_e32 v12, v6
	v_fmamk_f32 v7, v102, 0x3e0293ee, v149
	v_exp_f32_e32 v13, v7
	v_add_f32_e32 v5, v4, v11
	v_add_f32_e32 v1, v5, v1
	v_fmamk_f32 v5, v105, 0x3e0293ee, v149
	v_exp_f32_e32 v5, v5
	v_fmamk_f32 v14, v100, 0x3e0293ee, v149
	v_exp_f32_e32 v14, v14
	v_fmamk_f32 v16, v98, 0x3e0293ee, v149
	v_add_f32_e32 v6, v5, v12
	v_add_f32_e32 v1, v6, v1
	v_fmamk_f32 v6, v103, 0x3e0293ee, v149
	v_exp_f32_e32 v6, v6
	v_exp_f32_e32 v16, v16
	v_fmamk_f32 v18, v94, 0x3e0293ee, v149
	v_exp_f32_e32 v18, v18
	v_add_f32_e32 v7, v6, v13
	v_add_f32_e32 v1, v7, v1
	v_fmamk_f32 v7, v101, 0x3e0293ee, v149
	v_exp_f32_e32 v7, v7
	v_fmamk_f32 v20, v92, 0x3e0293ee, v149
	v_exp_f32_e32 v20, v20
	v_fmamk_f32 v22, v90, 0x3e0293ee, v149
	v_add_f32_e32 v15, v7, v14
	v_add_f32_e32 v1, v15, v1
	v_fmamk_f32 v15, v99, 0x3e0293ee, v149
	v_exp_f32_e32 v15, v15
	v_exp_f32_e32 v22, v22
	v_fmamk_f32 v24, v88, 0x3e0293ee, v149
	v_exp_f32_e32 v24, v24
	v_add_f32_e32 v17, v15, v16
	v_add_f32_e32 v1, v17, v1
	v_fmamk_f32 v17, v95, 0x3e0293ee, v149
	v_exp_f32_e32 v17, v17
	v_fmamk_f32 v26, v86, 0x3e0293ee, v149
	v_exp_f32_e32 v26, v26
	v_fmamk_f32 v28, v84, 0x3e0293ee, v149
	v_add_f32_e32 v19, v17, v18
	v_add_f32_e32 v1, v19, v1
	v_fmamk_f32 v19, v93, 0x3e0293ee, v149
	v_exp_f32_e32 v19, v19
	v_exp_f32_e32 v28, v28
	v_fmamk_f32 v30, v82, 0x3e0293ee, v149
	v_exp_f32_e32 v30, v30
	v_add_f32_e32 v21, v19, v20
	v_add_f32_e32 v1, v21, v1
	v_fmamk_f32 v21, v91, 0x3e0293ee, v149
	v_exp_f32_e32 v21, v21
	v_cvt_pk_bf16_f32 v0, v0, v2
	v_cvt_pk_bf16_f32 v2, v5, v6
	v_cvt_pk_bf16_f32 v8, v8, v9
	v_add_f32_e32 v23, v21, v22
	v_add_f32_e32 v1, v23, v1
	v_fmamk_f32 v23, v89, 0x3e0293ee, v149
	v_exp_f32_e32 v23, v23
	v_cvt_pk_bf16_f32 v9, v10, v11
	v_cvt_pk_bf16_f32 v10, v12, v13
	v_cvt_pk_bf16_f32 v11, v14, v16
	v_add_f32_e32 v25, v23, v24
	v_add_f32_e32 v1, v25, v1
	v_fmamk_f32 v25, v87, 0x3e0293ee, v149
	v_exp_f32_e32 v25, v25
	v_cvt_pk_bf16_f32 v5, v21, v23
	v_cvt_pk_bf16_f32 v12, v18, v20
	v_cvt_pk_bf16_f32 v13, v22, v24
	v_add_f32_e32 v27, v25, v26
	v_add_f32_e32 v1, v27, v1
	v_fmamk_f32 v27, v85, 0x3e0293ee, v149
	v_exp_f32_e32 v27, v27
	v_cvt_pk_bf16_f32 v14, v26, v28
	v_add_f32_e32 v29, v27, v28
	v_add_f32_e32 v1, v29, v1
	v_fmamk_f32 v29, v83, 0x3e0293ee, v149
	v_exp_f32_e32 v29, v29
	v_cvt_pk_bf16_f32 v6, v25, v27
	v_add_f32_e32 v31, v29, v30
	v_add_f32_e32 v1, v31, v1
	v_fmamk_f32 v31, v81, 0x3e0293ee, v149
	v_fmac_f32_e32 v149, 0x3e0293ee, v80
	v_exp_f32_e32 v31, v31
	v_exp_f32_e32 v32, v149
	s_nop 0
	v_add_f32_e32 v33, v31, v32
	v_add_f32_e32 v44, v33, v1
	v_cvt_pk_bf16_f32 v1, v3, v4
	v_cvt_pk_bf16_f32 v3, v7, v15
	v_cvt_pk_bf16_f32 v4, v17, v19
	v_cvt_pk_bf16_f32 v7, v29, v31
	v_cvt_pk_bf16_f32 v15, v30, v32
	ds_read_b128 v[16:19], v152 offset:53280
	ds_read_b128 v[20:23], v152 offset:57888
	ds_read_b128 v[24:27], v152 offset:62496
	ds_read_b128 v[28:31], v153 offset:13856
	s_waitcnt lgkmcnt(7)
	v_mfma_f32_32x32x16_bf16 a[16:31], v[76:79], v[0:3], a[16:31]
	s_waitcnt lgkmcnt(6)
	v_mfma_f32_32x32x16_bf16 a[32:47], v[72:75], v[0:3], a[32:47]
	s_waitcnt lgkmcnt(5)
	v_mfma_f32_32x32x16_bf16 a[48:63], v[68:71], v[0:3], a[48:63]
	s_waitcnt lgkmcnt(4)
	v_mfma_f32_32x32x16_bf16 a[0:15], v[64:67], v[0:3], a[0:15]
	ds_read_b128 v[0:3], v152 offset:53312
	ds_read_b128 v[32:35], v152 offset:57920
	ds_read_b128 v[36:39], v152 offset:62528
	ds_read_b128 v[40:43], v153 offset:13888
	s_waitcnt lgkmcnt(7)
	v_mfma_f32_32x32x16_bf16 a[16:31], v[16:19], v[4:7], a[16:31]
	s_waitcnt lgkmcnt(6)
	v_mfma_f32_32x32x16_bf16 a[32:47], v[20:23], v[4:7], a[32:47]
	s_waitcnt lgkmcnt(5)
	v_mfma_f32_32x32x16_bf16 a[48:63], v[24:27], v[4:7], a[48:63]
	s_waitcnt lgkmcnt(4)
	v_mfma_f32_32x32x16_bf16 a[0:15], v[28:31], v[4:7], a[0:15]
	ds_read_b128 v[4:7], v152 offset:53344
	ds_read_b128 v[16:19], v152 offset:57952
	ds_read_b128 v[20:23], v152 offset:62560
	ds_read_b128 v[24:27], v153 offset:13920
	s_waitcnt lgkmcnt(7)
	v_mfma_f32_32x32x16_bf16 a[16:31], v[0:3], v[8:11], a[16:31]
	s_waitcnt lgkmcnt(6)
	v_mfma_f32_32x32x16_bf16 a[32:47], v[32:35], v[8:11], a[32:47]
	s_waitcnt lgkmcnt(5)
	v_mfma_f32_32x32x16_bf16 a[48:63], v[36:39], v[8:11], a[48:63]
	s_waitcnt lgkmcnt(4)
	v_mfma_f32_32x32x16_bf16 a[0:15], v[40:43], v[8:11], a[0:15]
	s_waitcnt lgkmcnt(3)
	v_mfma_f32_32x32x16_bf16 a[16:31], v[4:7], v[12:15], a[16:31]
	s_waitcnt lgkmcnt(2)
	v_mfma_f32_32x32x16_bf16 a[32:47], v[16:19], v[12:15], a[32:47]
	s_waitcnt lgkmcnt(1)
	v_mfma_f32_32x32x16_bf16 a[48:63], v[20:23], v[12:15], a[48:63]
	s_waitcnt lgkmcnt(0)
	v_mfma_f32_32x32x16_bf16 a[0:15], v[24:27], v[12:15], a[0:15]
	v_add_f32_e32 v64, v96, v44
	ds_bpermute_b32 v65, v151, v64
	v_readlane_b32 s6, v255, 20
	v_readlane_b32 s7, v255, 21
	s_andn2_b64 vcc, exec, s[6:7]
	s_waitcnt lgkmcnt(0)
	s_barrier
	s_cbranch_vccnz .LBB0_181
; DI float bf2f(unsigned v) { return __uint_as_float(v << 16); }
; DI unsigned pack2(float a, float b) { f2_t v = {a, b}; bf2_t r = __builtin_convertvector(v, bf2_t); return __builtin_bit_cast(unsigned, r); }
; DI float silu(float g) { return g * frcp(1.f + fexp(-g)); }
; template <int DQK>
; DI void attn_item(const u16* __restrict__ Qp, int ldq, const u16* __restrict__ Kp, const u16* __restrict__ Vtp, int ldv,
;                   int nkt, int q0, bool causal, float c, u16* Yp, int ldy, char* smem, bool dry) {
;     ...
;   const float lt = l + __shfl_xor(l, 32);
;   const float inv = 1.f / lt;
;   if (dry) return;
;   u16* yrow = Yp + (size_t)(32 * w + r) * ldy;
; #pragma unroll
;   for (int dt = 0; dt < 4; ++dt)
; #pragma unroll
;     for (int g = 0; g < 4; ++g) {
;       const int d = 32 * dt + 8 * g + 4 * h;
;       uint2 gv = *(const uint2*)(yrow + d);
;       float g0 = bf2f(gv.x & 0xffffu), g1 = bf2f(gv.x >> 16), g2 = bf2f(gv.y & 0xffffu), g3 = bf2f(gv.y >> 16);
;       uint2 ov;
;       ov.x = pack2(o[dt][4 * g] * inv * silu(g0), o[dt][4 * g + 1] * inv * silu(g1));
;       ov.y = pack2(o[dt][4 * g + 2] * inv * silu(g2), o[dt][4 * g + 3] * inv * silu(g3));
;       *(uint2*)(yrow + d) = ov;
;     }
	v_readlane_b32 s7, v254, 30
	s_lshl_b32 s6, s10, 7
	s_lshl_b32 s7, s7, 1
	s_add_u32 s7, s11, s7
	s_addc_u32 s8, s12, 0
	s_lshl_b32 s6, s6, 1
	s_add_u32 s6, s7, s6
	v_add_f32_e32 v64, v64, v65
	s_addc_u32 s7, s8, 0
	v_div_scale_f32 v65, s[8:9], v64, v64, 1.0
	v_rcp_f32_e32 v66, v65
	v_lshlrev_b32_e32 v198, 3, v150
	v_accvgpr_read_b32 v63, a31
	v_accvgpr_read_b32 v49, a17
	v_fma_f32 v67, -v65, v66, 1.0
	v_fmac_f32_e32 v66, v67, v66
	v_div_scale_f32 v67, vcc, 1.0, v64, 1.0
	v_mul_f32_e32 v68, v67, v66
	v_fma_f32 v69, -v65, v68, v67
	v_fmac_f32_e32 v68, v69, v66
	v_fma_f32 v65, -v65, v68, v67
	v_div_fmas_f32 v65, v65, v66, v68
	v_lshl_add_u64 v[66:67], v[146:147], 1, s[6:7]
	v_lshl_add_u64 v[66:67], v[66:67], 0, v[198:199]
	global_load_dwordx2 v[98:99], v[66:67], off offset:3072
	global_load_dwordx2 v[100:101], v[66:67], off offset:3088
	global_load_dwordx2 v[102:103], v[66:67], off offset:3104
	global_load_dwordx2 v[104:105], v[66:67], off offset:3120
	global_load_dwordx2 v[106:107], v[66:67], off offset:3136
	global_load_dwordx2 v[108:109], v[66:67], off offset:3152
	global_load_dwordx2 v[110:111], v[66:67], off offset:3168
	global_load_dwordx2 v[112:113], v[66:67], off offset:3184
	global_load_dwordx2 v[114:115], v[66:67], off offset:3200
	global_load_dwordx2 v[116:117], v[66:67], off offset:3216
	global_load_dwordx2 v[118:119], v[66:67], off offset:3232
	global_load_dwordx2 v[120:121], v[66:67], off offset:3248
	global_load_dwordx2 v[122:123], v[66:67], off offset:3264
	global_load_dwordx2 v[124:125], v[66:67], off offset:3280
	global_load_dwordx2 v[126:127], v[66:67], off offset:3296
	global_load_dwordx2 v[128:129], v[66:67], off offset:3312
	v_div_fixup_f32 v64, v65, v64, 1.0
	v_accvgpr_read_b32 v48, a16
	v_accvgpr_read_b32 v51, a19
	v_accvgpr_read_b32 v50, a18
	v_accvgpr_read_b32 v53, a21
	v_accvgpr_read_b32 v52, a20
	v_accvgpr_read_b32 v55, a23
	v_accvgpr_read_b32 v54, a22
	v_accvgpr_read_b32 v57, a25
	v_accvgpr_read_b32 v56, a24
	v_accvgpr_read_b32 v59, a27
	v_accvgpr_read_b32 v58, a26
	v_accvgpr_read_b32 v61, a29
	v_accvgpr_read_b32 v60, a28
	v_accvgpr_read_b32 v62, a30
	v_accvgpr_read_b32 v32, a32
	v_accvgpr_read_b32 v33, a33
	v_accvgpr_read_b32 v34, a34
	v_accvgpr_read_b32 v35, a35
	v_accvgpr_read_b32 v36, a36
	v_accvgpr_read_b32 v37, a37
	v_accvgpr_read_b32 v38, a38
	v_accvgpr_read_b32 v39, a39
	v_accvgpr_read_b32 v40, a40
	v_accvgpr_read_b32 v41, a41
	v_accvgpr_read_b32 v42, a42
	v_accvgpr_read_b32 v43, a43
	v_accvgpr_read_b32 v44, a44
	v_accvgpr_read_b32 v45, a45
	v_accvgpr_read_b32 v46, a46
	v_accvgpr_read_b32 v47, a47
	v_accvgpr_read_b32 v16, a48
	v_accvgpr_read_b32 v17, a49
	v_accvgpr_read_b32 v18, a50
	v_accvgpr_read_b32 v19, a51
	v_accvgpr_read_b32 v20, a52
	v_accvgpr_read_b32 v21, a53
	v_accvgpr_read_b32 v22, a54
	v_accvgpr_read_b32 v23, a55
	v_accvgpr_read_b32 v24, a56
	v_accvgpr_read_b32 v25, a57
	v_accvgpr_read_b32 v26, a58
	v_accvgpr_read_b32 v27, a59
	v_accvgpr_read_b32 v28, a60
	v_accvgpr_read_b32 v29, a61
	v_accvgpr_read_b32 v30, a62
	v_accvgpr_read_b32 v31, a63
	v_accvgpr_read_b32 v0, a0
	v_accvgpr_read_b32 v1, a1
	v_accvgpr_read_b32 v2, a2
	v_accvgpr_read_b32 v3, a3
	v_accvgpr_read_b32 v4, a4
	v_accvgpr_read_b32 v5, a5
	v_accvgpr_read_b32 v6, a6
	v_accvgpr_read_b32 v7, a7
	v_accvgpr_read_b32 v8, a8
	v_accvgpr_read_b32 v9, a9
	v_accvgpr_read_b32 v10, a10
	v_accvgpr_read_b32 v11, a11
	v_accvgpr_read_b32 v12, a12
	v_accvgpr_read_b32 v13, a13
	v_accvgpr_read_b32 v14, a14
	v_accvgpr_read_b32 v15, a15
	s_waitcnt vmcnt(0)
	v_lshlrev_b32_e32 v70, 16, v98
	v_mul_f32_e32 v65, 0xbfb8aa3b, v70
	v_exp_f32_e32 v65, v65
	v_and_b32_e32 v71, 0xffff0000, v98
	v_lshlrev_b32_e32 v68, 16, v99
	v_and_b32_e32 v69, 0xffff0000, v99
	v_add_f32_e32 v65, 1.0, v65
	v_rcp_f32_e32 v72, v65
	v_pk_mul_f32 v[48:49], v[48:49], v[64:65] op_sel_hi:[1,0]
	v_mul_f32_e32 v65, 0xbfb8aa3b, v71
	v_exp_f32_e32 v65, v65
	s_nop 0
	v_add_f32_e32 v65, 1.0, v65
	v_rcp_f32_e32 v73, v65
	v_pk_mul_f32 v[50:51], v[50:51], v[64:65] op_sel_hi:[1,0]
	v_pk_mul_f32 v[70:71], v[72:73], v[70:71]
	s_nop 0
	v_pk_mul_f32 v[48:49], v[48:49], v[70:71]
	s_nop 0
	v_cvt_pk_bf16_f32 v48, v48, v49
	v_mul_f32_e32 v49, 0xbfb8aa3b, v68
	v_exp_f32_e32 v49, v49
	s_nop 0
	v_add_f32_e32 v49, 1.0, v49
	v_rcp_f32_e32 v70, v49
	v_mul_f32_e32 v49, 0xbfb8aa3b, v69
	v_exp_f32_e32 v49, v49
	s_nop 0
	v_add_f32_e32 v49, 1.0, v49
	v_rcp_f32_e32 v71, v49
	s_nop 0
	v_pk_mul_f32 v[68:69], v[70:71], v[68:69]
	s_nop 0
	v_pk_mul_f32 v[50:51], v[50:51], v[68:69]
	s_nop 0
	v_cvt_pk_bf16_f32 v49, v50, v51
	global_store_dwordx2 v[66:67], v[48:49], off offset:3072
	v_lshlrev_b32_e32 v50, 16, v100
	v_mul_f32_e32 v65, 0xbfb8aa3b, v50
	v_exp_f32_e32 v65, v65
	v_and_b32_e32 v51, 0xffff0000, v100
	v_lshlrev_b32_e32 v48, 16, v101
	v_and_b32_e32 v49, 0xffff0000, v101
	v_add_f32_e32 v65, 1.0, v65
	v_rcp_f32_e32 v68, v65
	v_pk_mul_f32 v[52:53], v[52:53], v[64:65] op_sel_hi:[1,0]
	v_mul_f32_e32 v65, 0xbfb8aa3b, v51
	v_exp_f32_e32 v65, v65
	s_nop 0
	v_add_f32_e32 v65, 1.0, v65
	v_rcp_f32_e32 v69, v65
	v_pk_mul_f32 v[54:55], v[54:55], v[64:65] op_sel_hi:[1,0]
	v_pk_mul_f32 v[32:33], v[32:33], v[64:65] op_sel_hi:[1,0]
	v_pk_mul_f32 v[34:35], v[34:35], v[64:65] op_sel_hi:[1,0]
	v_pk_mul_f32 v[50:51], v[68:69], v[50:51]
	v_pk_mul_f32 v[36:37], v[36:37], v[64:65] op_sel_hi:[1,0]
	v_pk_mul_f32 v[50:51], v[52:53], v[50:51]
	v_pk_mul_f32 v[38:39], v[38:39], v[64:65] op_sel_hi:[1,0]
	v_cvt_pk_bf16_f32 v50, v50, v51
	v_mul_f32_e32 v51, 0xbfb8aa3b, v48
	v_exp_f32_e32 v51, v51
	v_pk_mul_f32 v[16:17], v[16:17], v[64:65] op_sel_hi:[1,0]
	v_pk_mul_f32 v[18:19], v[18:19], v[64:65] op_sel_hi:[1,0]
	v_pk_mul_f32 v[20:21], v[20:21], v[64:65] op_sel_hi:[1,0]
; DI float bf2f(unsigned v) { return __uint_as_float(v << 16); }
; DI unsigned pack2(float a, float b) { f2_t v = {a, b}; bf2_t r = __builtin_convertvector(v, bf2_t); return __builtin_bit_cast(unsigned, r); }
; DI float silu(float g) { return g * frcp(1.f + fexp(-g)); }
; template <int DQK>
; DI void attn_item(const u16* __restrict__ Qp, int ldq, const u16* __restrict__ Kp, const u16* __restrict__ Vtp, int ldv,
;                   int nkt, int q0, bool causal, float c, u16* Yp, int ldy, char* smem, bool dry) {
;     ...
;   for (int dt = 0; dt < 4; ++dt)
; #pragma unroll
;     for (int g = 0; g < 4; ++g) {
;       const int d = 32 * dt + 8 * g + 4 * h;
;       uint2 gv = *(const uint2*)(yrow + d);
;       float g0 = bf2f(gv.x & 0xffffu), g1 = bf2f(gv.x >> 16), g2 = bf2f(gv.y & 0xffffu), g3 = bf2f(gv.y >> 16);
;       uint2 ov;
;       ov.x = pack2(o[dt][4 * g] * inv * silu(g0), o[dt][4 * g + 1] * inv * silu(g1));
;       ov.y = pack2(o[dt][4 * g + 2] * inv * silu(g2), o[dt][4 * g + 3] * inv * silu(g3));
;       *(uint2*)(yrow + d) = ov;
;     }
	v_add_f32_e32 v51, 1.0, v51
	v_rcp_f32_e32 v52, v51
	v_mul_f32_e32 v51, 0xbfb8aa3b, v49
	v_exp_f32_e32 v51, v51
	v_pk_mul_f32 v[22:23], v[22:23], v[64:65] op_sel_hi:[1,0]
	v_pk_mul_f32 v[0:1], v[0:1], v[64:65] op_sel_hi:[1,0]
	v_pk_mul_f32 v[2:3], v[2:3], v[64:65] op_sel_hi:[1,0]
	v_add_f32_e32 v51, 1.0, v51
	v_rcp_f32_e32 v53, v51
	v_pk_mul_f32 v[4:5], v[4:5], v[64:65] op_sel_hi:[1,0]
	v_pk_mul_f32 v[6:7], v[6:7], v[64:65] op_sel_hi:[1,0]
	v_pk_mul_f32 v[48:49], v[52:53], v[48:49]
	s_nop 0
	v_pk_mul_f32 v[48:49], v[54:55], v[48:49]
	v_pk_mul_f32 v[54:55], v[56:57], v[64:65] op_sel_hi:[1,0]
	v_cvt_pk_bf16_f32 v51, v48, v49
	s_nop 0
	global_store_dwordx2 v[66:67], v[50:51], off offset:3088
	v_lshlrev_b32_e32 v50, 16, v102
	v_and_b32_e32 v51, 0xffff0000, v102
	v_mul_f32_e32 v52, 0xbfb8aa3b, v50
	v_mul_f32_e32 v53, 0xbfb8aa3b, v51
	v_exp_f32_e32 v52, v52
	v_exp_f32_e32 v53, v53
	v_lshlrev_b32_e32 v48, 16, v103
	v_and_b32_e32 v49, 0xffff0000, v103
	v_add_f32_e32 v52, 1.0, v52
	v_add_f32_e32 v53, 1.0, v53
	v_rcp_f32_e32 v52, v52
	v_rcp_f32_e32 v53, v53
	s_nop 0
	v_pk_mul_f32 v[50:51], v[52:53], v[50:51]
	s_nop 0
	v_pk_mul_f32 v[50:51], v[54:55], v[50:51]
	v_pk_mul_f32 v[54:55], v[58:59], v[64:65] op_sel_hi:[1,0]
	v_cvt_pk_bf16_f32 v50, v50, v51
	v_mul_f32_e32 v51, 0xbfb8aa3b, v48
	v_exp_f32_e32 v51, v51
	s_nop 0
	v_add_f32_e32 v51, 1.0, v51
	v_rcp_f32_e32 v52, v51
	v_mul_f32_e32 v51, 0xbfb8aa3b, v49
	v_exp_f32_e32 v51, v51
	s_nop 0
	v_add_f32_e32 v51, 1.0, v51
	v_rcp_f32_e32 v53, v51
	s_nop 0
	v_pk_mul_f32 v[48:49], v[52:53], v[48:49]
	s_nop 0
	v_pk_mul_f32 v[48:49], v[54:55], v[48:49]
	v_pk_mul_f32 v[54:55], v[60:61], v[64:65] op_sel_hi:[1,0]
	v_cvt_pk_bf16_f32 v51, v48, v49
	s_nop 0
	global_store_dwordx2 v[66:67], v[50:51], off offset:3104
	v_lshlrev_b32_e32 v50, 16, v104
	v_and_b32_e32 v51, 0xffff0000, v104
	v_mul_f32_e32 v52, 0xbfb8aa3b, v50
	v_mul_f32_e32 v53, 0xbfb8aa3b, v51
	v_exp_f32_e32 v52, v52
	v_exp_f32_e32 v53, v53
	v_lshlrev_b32_e32 v48, 16, v105
	v_and_b32_e32 v49, 0xffff0000, v105
	v_add_f32_e32 v52, 1.0, v52
	v_add_f32_e32 v53, 1.0, v53
	v_rcp_f32_e32 v52, v52
	v_rcp_f32_e32 v53, v53
	s_nop 0
	v_pk_mul_f32 v[50:51], v[52:53], v[50:51]
	s_nop 0
	v_pk_mul_f32 v[50:51], v[54:55], v[50:51]
	v_pk_mul_f32 v[54:55], v[62:63], v[64:65] op_sel_hi:[1,0]
	v_cvt_pk_bf16_f32 v50, v50, v51
	v_mul_f32_e32 v51, 0xbfb8aa3b, v48
	v_exp_f32_e32 v51, v51
	s_nop 0
	v_add_f32_e32 v51, 1.0, v51
	v_rcp_f32_e32 v52, v51
	v_mul_f32_e32 v51, 0xbfb8aa3b, v49
	v_exp_f32_e32 v51, v51
	s_nop 0
	v_add_f32_e32 v51, 1.0, v51
	v_rcp_f32_e32 v53, v51
	s_nop 0
	v_pk_mul_f32 v[48:49], v[52:53], v[48:49]
	s_nop 0
	v_pk_mul_f32 v[48:49], v[54:55], v[48:49]
	s_nop 0
	v_cvt_pk_bf16_f32 v51, v48, v49
	s_nop 0
	global_store_dwordx2 v[66:67], v[50:51], off offset:3120
	v_lshlrev_b32_e32 v50, 16, v106
	v_and_b32_e32 v51, 0xffff0000, v106
	v_mul_f32_e32 v52, 0xbfb8aa3b, v50
	v_mul_f32_e32 v53, 0xbfb8aa3b, v51
	v_exp_f32_e32 v52, v52
	v_exp_f32_e32 v53, v53
	v_lshlrev_b32_e32 v48, 16, v107
	v_and_b32_e32 v49, 0xffff0000, v107
	v_add_f32_e32 v52, 1.0, v52
	v_add_f32_e32 v53, 1.0, v53
	v_rcp_f32_e32 v52, v52
	v_rcp_f32_e32 v53, v53
	s_nop 0
	v_pk_mul_f32 v[50:51], v[52:53], v[50:51]
	s_nop 0
	v_pk_mul_f32 v[32:33], v[32:33], v[50:51]
	s_nop 0
	v_cvt_pk_bf16_f32 v32, v32, v33
	v_mul_f32_e32 v33, 0xbfb8aa3b, v48
	v_exp_f32_e32 v33, v33
	s_nop 0
	v_add_f32_e32 v33, 1.0, v33
	v_rcp_f32_e32 v50, v33
	v_mul_f32_e32 v33, 0xbfb8aa3b, v49
	v_exp_f32_e32 v33, v33
	s_nop 0
	v_add_f32_e32 v33, 1.0, v33
	v_rcp_f32_e32 v51, v33
	s_nop 0
	v_pk_mul_f32 v[48:49], v[50:51], v[48:49]
	s_nop 0
	v_pk_mul_f32 v[34:35], v[34:35], v[48:49]
	s_nop 0
	v_cvt_pk_bf16_f32 v33, v34, v35
	global_store_dwordx2 v[66:67], v[32:33], off offset:3136
	v_lshlrev_b32_e32 v34, 16, v108
	v_and_b32_e32 v35, 0xffff0000, v108
	v_mul_f32_e32 v48, 0xbfb8aa3b, v34
	v_mul_f32_e32 v49, 0xbfb8aa3b, v35
	v_exp_f32_e32 v48, v48
	v_exp_f32_e32 v49, v49
	v_lshlrev_b32_e32 v32, 16, v109
	v_and_b32_e32 v33, 0xffff0000, v109
	v_add_f32_e32 v48, 1.0, v48
	v_add_f32_e32 v49, 1.0, v49
	v_rcp_f32_e32 v48, v48
	v_rcp_f32_e32 v49, v49
	s_nop 0
	v_pk_mul_f32 v[34:35], v[48:49], v[34:35]
	s_nop 0
	v_pk_mul_f32 v[34:35], v[36:37], v[34:35]
	s_nop 0
	v_cvt_pk_bf16_f32 v34, v34, v35
	v_mul_f32_e32 v35, 0xbfb8aa3b, v32
	v_exp_f32_e32 v35, v35
	s_nop 0
	v_add_f32_e32 v35, 1.0, v35
	v_rcp_f32_e32 v36, v35
	v_mul_f32_e32 v35, 0xbfb8aa3b, v33
	v_exp_f32_e32 v35, v35
	s_nop 0
	v_add_f32_e32 v35, 1.0, v35
	v_rcp_f32_e32 v37, v35
	s_nop 0
	v_pk_mul_f32 v[32:33], v[36:37], v[32:33]
	s_nop 0
	v_pk_mul_f32 v[32:33], v[38:39], v[32:33]
	v_pk_mul_f32 v[38:39], v[40:41], v[64:65] op_sel_hi:[1,0]
	v_cvt_pk_bf16_f32 v35, v32, v33
	s_nop 0
	global_store_dwordx2 v[66:67], v[34:35], off offset:3152
	v_lshlrev_b32_e32 v34, 16, v110
	v_and_b32_e32 v35, 0xffff0000, v110
	v_mul_f32_e32 v36, 0xbfb8aa3b, v34
	v_mul_f32_e32 v37, 0xbfb8aa3b, v35
	v_exp_f32_e32 v36, v36
	v_exp_f32_e32 v37, v37
	v_lshlrev_b32_e32 v32, 16, v111
	v_and_b32_e32 v33, 0xffff0000, v111
	v_add_f32_e32 v36, 1.0, v36
	v_add_f32_e32 v37, 1.0, v37
	v_rcp_f32_e32 v36, v36
	v_rcp_f32_e32 v37, v37
	s_nop 0
	v_pk_mul_f32 v[34:35], v[36:37], v[34:35]
	s_nop 0
	v_pk_mul_f32 v[34:35], v[38:39], v[34:35]
	v_pk_mul_f32 v[38:39], v[42:43], v[64:65] op_sel_hi:[1,0]
	v_cvt_pk_bf16_f32 v34, v34, v35
	v_mul_f32_e32 v35, 0xbfb8aa3b, v32
	v_exp_f32_e32 v35, v35
	s_nop 0
	v_add_f32_e32 v35, 1.0, v35
	v_rcp_f32_e32 v36, v35
	v_mul_f32_e32 v35, 0xbfb8aa3b, v33
	v_exp_f32_e32 v35, v35
	s_nop 0
	v_add_f32_e32 v35, 1.0, v35
	v_rcp_f32_e32 v37, v35
	s_nop 0
	v_pk_mul_f32 v[32:33], v[36:37], v[32:33]
	s_nop 0
; DI float bf2f(unsigned v) { return __uint_as_float(v << 16); }
; DI unsigned pack2(float a, float b) { f2_t v = {a, b}; bf2_t r = __builtin_convertvector(v, bf2_t); return __builtin_bit_cast(unsigned, r); }
; DI float silu(float g) { return g * frcp(1.f + fexp(-g)); }
; template <int DQK>
; DI void attn_item(const u16* __restrict__ Qp, int ldq, const u16* __restrict__ Kp, const u16* __restrict__ Vtp, int ldv,
;                   int nkt, int q0, bool causal, float c, u16* Yp, int ldy, char* smem, bool dry) {
;     ...
;   for (int dt = 0; dt < 4; ++dt)
; #pragma unroll
;     for (int g = 0; g < 4; ++g) {
;       const int d = 32 * dt + 8 * g + 4 * h;
;       uint2 gv = *(const uint2*)(yrow + d);
;       float g0 = bf2f(gv.x & 0xffffu), g1 = bf2f(gv.x >> 16), g2 = bf2f(gv.y & 0xffffu), g3 = bf2f(gv.y >> 16);
;       uint2 ov;
;       ov.x = pack2(o[dt][4 * g] * inv * silu(g0), o[dt][4 * g + 1] * inv * silu(g1));
;       ov.y = pack2(o[dt][4 * g + 2] * inv * silu(g2), o[dt][4 * g + 3] * inv * silu(g3));
;       *(uint2*)(yrow + d) = ov;
;     }
	v_pk_mul_f32 v[32:33], v[38:39], v[32:33]
	v_pk_mul_f32 v[38:39], v[44:45], v[64:65] op_sel_hi:[1,0]
	v_cvt_pk_bf16_f32 v35, v32, v33
	s_nop 0
	global_store_dwordx2 v[66:67], v[34:35], off offset:3168
	v_lshlrev_b32_e32 v34, 16, v112
	v_and_b32_e32 v35, 0xffff0000, v112
	v_mul_f32_e32 v36, 0xbfb8aa3b, v34
	v_mul_f32_e32 v37, 0xbfb8aa3b, v35
	v_exp_f32_e32 v36, v36
	v_exp_f32_e32 v37, v37
	v_lshlrev_b32_e32 v32, 16, v113
	v_and_b32_e32 v33, 0xffff0000, v113
	v_add_f32_e32 v36, 1.0, v36
	v_add_f32_e32 v37, 1.0, v37
	v_rcp_f32_e32 v36, v36
	v_rcp_f32_e32 v37, v37
	s_nop 0
	v_pk_mul_f32 v[34:35], v[36:37], v[34:35]
	s_nop 0
	v_pk_mul_f32 v[34:35], v[38:39], v[34:35]
	v_pk_mul_f32 v[38:39], v[46:47], v[64:65] op_sel_hi:[1,0]
	v_cvt_pk_bf16_f32 v34, v34, v35
	v_mul_f32_e32 v35, 0xbfb8aa3b, v32
	v_exp_f32_e32 v35, v35
	s_nop 0
	v_add_f32_e32 v35, 1.0, v35
	v_rcp_f32_e32 v36, v35
	v_mul_f32_e32 v35, 0xbfb8aa3b, v33
	v_exp_f32_e32 v35, v35
	s_nop 0
	v_add_f32_e32 v35, 1.0, v35
	v_rcp_f32_e32 v37, v35
	s_nop 0
	v_pk_mul_f32 v[32:33], v[36:37], v[32:33]
	s_nop 0
	v_pk_mul_f32 v[32:33], v[38:39], v[32:33]
	s_nop 0
	v_cvt_pk_bf16_f32 v35, v32, v33
	s_nop 0
	global_store_dwordx2 v[66:67], v[34:35], off offset:3184
	v_lshlrev_b32_e32 v34, 16, v114
	v_and_b32_e32 v35, 0xffff0000, v114
	v_mul_f32_e32 v36, 0xbfb8aa3b, v34
	v_mul_f32_e32 v37, 0xbfb8aa3b, v35
	v_exp_f32_e32 v36, v36
	v_exp_f32_e32 v37, v37
	v_lshlrev_b32_e32 v32, 16, v115
	v_and_b32_e32 v33, 0xffff0000, v115
	v_add_f32_e32 v36, 1.0, v36
	v_add_f32_e32 v37, 1.0, v37
	v_rcp_f32_e32 v36, v36
	v_rcp_f32_e32 v37, v37
	s_nop 0
	v_pk_mul_f32 v[34:35], v[36:37], v[34:35]
	s_nop 0
	v_pk_mul_f32 v[16:17], v[16:17], v[34:35]
	s_nop 0
	v_cvt_pk_bf16_f32 v16, v16, v17
	v_mul_f32_e32 v17, 0xbfb8aa3b, v32
	v_exp_f32_e32 v17, v17
	s_nop 0
	v_add_f32_e32 v17, 1.0, v17
	v_rcp_f32_e32 v34, v17
	v_mul_f32_e32 v17, 0xbfb8aa3b, v33
	v_exp_f32_e32 v17, v17
	s_nop 0
	v_add_f32_e32 v17, 1.0, v17
	v_rcp_f32_e32 v35, v17
	s_nop 0
	v_pk_mul_f32 v[32:33], v[34:35], v[32:33]
	s_nop 0
	v_pk_mul_f32 v[18:19], v[18:19], v[32:33]
	s_nop 0
	v_cvt_pk_bf16_f32 v17, v18, v19
	global_store_dwordx2 v[66:67], v[16:17], off offset:3200
	v_lshlrev_b32_e32 v18, 16, v116
	v_and_b32_e32 v19, 0xffff0000, v116
	v_mul_f32_e32 v32, 0xbfb8aa3b, v18
	v_mul_f32_e32 v33, 0xbfb8aa3b, v19
	v_exp_f32_e32 v32, v32
	v_exp_f32_e32 v33, v33
	v_lshlrev_b32_e32 v16, 16, v117
	v_and_b32_e32 v17, 0xffff0000, v117
	v_add_f32_e32 v32, 1.0, v32
	v_add_f32_e32 v33, 1.0, v33
	v_rcp_f32_e32 v32, v32
	v_rcp_f32_e32 v33, v33
	s_nop 0
	v_pk_mul_f32 v[18:19], v[32:33], v[18:19]
	s_nop 0
	v_pk_mul_f32 v[18:19], v[20:21], v[18:19]
	s_nop 0
	v_cvt_pk_bf16_f32 v18, v18, v19
	v_mul_f32_e32 v19, 0xbfb8aa3b, v16
	v_exp_f32_e32 v19, v19
	s_nop 0
	v_add_f32_e32 v19, 1.0, v19
	v_rcp_f32_e32 v20, v19
	v_mul_f32_e32 v19, 0xbfb8aa3b, v17
	v_exp_f32_e32 v19, v19
	s_nop 0
	v_add_f32_e32 v19, 1.0, v19
	v_rcp_f32_e32 v21, v19
	s_nop 0
	v_pk_mul_f32 v[16:17], v[20:21], v[16:17]
	s_nop 0
	v_pk_mul_f32 v[16:17], v[22:23], v[16:17]
	v_pk_mul_f32 v[22:23], v[24:25], v[64:65] op_sel_hi:[1,0]
	v_cvt_pk_bf16_f32 v19, v16, v17
	s_nop 0
	global_store_dwordx2 v[66:67], v[18:19], off offset:3216
	v_lshlrev_b32_e32 v18, 16, v118
	v_and_b32_e32 v19, 0xffff0000, v118
	v_mul_f32_e32 v20, 0xbfb8aa3b, v18
	v_mul_f32_e32 v21, 0xbfb8aa3b, v19
	v_exp_f32_e32 v20, v20
	v_exp_f32_e32 v21, v21
	v_lshlrev_b32_e32 v16, 16, v119
	v_and_b32_e32 v17, 0xffff0000, v119
	v_add_f32_e32 v20, 1.0, v20
	v_add_f32_e32 v21, 1.0, v21
	v_rcp_f32_e32 v20, v20
	v_rcp_f32_e32 v21, v21
	s_nop 0
	v_pk_mul_f32 v[18:19], v[20:21], v[18:19]
	s_nop 0
	v_pk_mul_f32 v[18:19], v[22:23], v[18:19]
	v_pk_mul_f32 v[22:23], v[26:27], v[64:65] op_sel_hi:[1,0]
	v_cvt_pk_bf16_f32 v18, v18, v19
	v_mul_f32_e32 v19, 0xbfb8aa3b, v16
	v_exp_f32_e32 v19, v19
	s_nop 0
	v_add_f32_e32 v19, 1.0, v19
	v_rcp_f32_e32 v20, v19
	v_mul_f32_e32 v19, 0xbfb8aa3b, v17
	v_exp_f32_e32 v19, v19
	s_nop 0
	v_add_f32_e32 v19, 1.0, v19
	v_rcp_f32_e32 v21, v19
	s_nop 0
	v_pk_mul_f32 v[16:17], v[20:21], v[16:17]
	s_nop 0
	v_pk_mul_f32 v[16:17], v[22:23], v[16:17]
	v_pk_mul_f32 v[22:23], v[28:29], v[64:65] op_sel_hi:[1,0]
	v_cvt_pk_bf16_f32 v19, v16, v17
	s_nop 0
	global_store_dwordx2 v[66:67], v[18:19], off offset:3232
	v_lshlrev_b32_e32 v18, 16, v120
	v_and_b32_e32 v19, 0xffff0000, v120
	v_mul_f32_e32 v20, 0xbfb8aa3b, v18
	v_mul_f32_e32 v21, 0xbfb8aa3b, v19
	v_exp_f32_e32 v20, v20
	v_exp_f32_e32 v21, v21
	v_lshlrev_b32_e32 v16, 16, v121
	v_and_b32_e32 v17, 0xffff0000, v121
	v_add_f32_e32 v20, 1.0, v20
; DI float bf2f(unsigned v) { return __uint_as_float(v << 16); }
; DI unsigned pack2(float a, float b) { f2_t v = {a, b}; bf2_t r = __builtin_convertvector(v, bf2_t); return __builtin_bit_cast(unsigned, r); }
; DI float silu(float g) { return g * frcp(1.f + fexp(-g)); }
; template <int DQK>
; DI void attn_item(const u16* __restrict__ Qp, int ldq, const u16* __restrict__ Kp, const u16* __restrict__ Vtp, int ldv,
;                   int nkt, int q0, bool causal, float c, u16* Yp, int ldy, char* smem, bool dry) {
;     ...
;   for (int dt = 0; dt < 4; ++dt)
; #pragma unroll
;     for (int g = 0; g < 4; ++g) {
;       const int d = 32 * dt + 8 * g + 4 * h;
;       uint2 gv = *(const uint2*)(yrow + d);
;       float g0 = bf2f(gv.x & 0xffffu), g1 = bf2f(gv.x >> 16), g2 = bf2f(gv.y & 0xffffu), g3 = bf2f(gv.y >> 16);
;       uint2 ov;
;       ov.x = pack2(o[dt][4 * g] * inv * silu(g0), o[dt][4 * g + 1] * inv * silu(g1));
;       ov.y = pack2(o[dt][4 * g + 2] * inv * silu(g2), o[dt][4 * g + 3] * inv * silu(g3));
;       *(uint2*)(yrow + d) = ov;
;     }
	v_add_f32_e32 v21, 1.0, v21
	v_rcp_f32_e32 v20, v20
	v_rcp_f32_e32 v21, v21
	s_nop 0
	v_pk_mul_f32 v[18:19], v[20:21], v[18:19]
	s_nop 0
	v_pk_mul_f32 v[18:19], v[22:23], v[18:19]
	v_pk_mul_f32 v[22:23], v[30:31], v[64:65] op_sel_hi:[1,0]
	v_cvt_pk_bf16_f32 v18, v18, v19
	v_mul_f32_e32 v19, 0xbfb8aa3b, v16
	v_exp_f32_e32 v19, v19
	s_nop 0
	v_add_f32_e32 v19, 1.0, v19
	v_rcp_f32_e32 v20, v19
	v_mul_f32_e32 v19, 0xbfb8aa3b, v17
	v_exp_f32_e32 v19, v19
	s_nop 0
	v_add_f32_e32 v19, 1.0, v19
	v_rcp_f32_e32 v21, v19
	s_nop 0
	v_pk_mul_f32 v[16:17], v[20:21], v[16:17]
	s_nop 0
	v_pk_mul_f32 v[16:17], v[22:23], v[16:17]
	s_nop 0
	v_cvt_pk_bf16_f32 v19, v16, v17
	s_nop 0
	global_store_dwordx2 v[66:67], v[18:19], off offset:3248
	v_lshlrev_b32_e32 v18, 16, v122
	v_and_b32_e32 v19, 0xffff0000, v122
	v_mul_f32_e32 v20, 0xbfb8aa3b, v18
	v_mul_f32_e32 v21, 0xbfb8aa3b, v19
	v_exp_f32_e32 v20, v20
	v_exp_f32_e32 v21, v21
	v_lshlrev_b32_e32 v16, 16, v123
	v_and_b32_e32 v17, 0xffff0000, v123
	v_add_f32_e32 v20, 1.0, v20
	v_add_f32_e32 v21, 1.0, v21
	v_rcp_f32_e32 v20, v20
	v_rcp_f32_e32 v21, v21
	s_nop 0
	v_pk_mul_f32 v[18:19], v[20:21], v[18:19]
	s_nop 0
	v_pk_mul_f32 v[0:1], v[0:1], v[18:19]
	s_nop 0
	v_cvt_pk_bf16_f32 v0, v0, v1
	v_mul_f32_e32 v1, 0xbfb8aa3b, v16
	v_exp_f32_e32 v1, v1
	s_nop 0
	v_add_f32_e32 v1, 1.0, v1
	v_rcp_f32_e32 v18, v1
	v_mul_f32_e32 v1, 0xbfb8aa3b, v17
	v_exp_f32_e32 v1, v1
	s_nop 0
	v_add_f32_e32 v1, 1.0, v1
	v_rcp_f32_e32 v19, v1
	s_nop 0
	v_pk_mul_f32 v[16:17], v[18:19], v[16:17]
	s_nop 0
	v_pk_mul_f32 v[2:3], v[2:3], v[16:17]
	s_nop 0
	v_cvt_pk_bf16_f32 v1, v2, v3
	global_store_dwordx2 v[66:67], v[0:1], off offset:3264
	v_lshlrev_b32_e32 v2, 16, v124
	v_and_b32_e32 v3, 0xffff0000, v124
	v_mul_f32_e32 v16, 0xbfb8aa3b, v2
	v_mul_f32_e32 v17, 0xbfb8aa3b, v3
	v_exp_f32_e32 v16, v16
	v_exp_f32_e32 v17, v17
	v_lshlrev_b32_e32 v0, 16, v125
	v_and_b32_e32 v1, 0xffff0000, v125
	v_add_f32_e32 v16, 1.0, v16
	v_add_f32_e32 v17, 1.0, v17
	v_rcp_f32_e32 v16, v16
	v_rcp_f32_e32 v17, v17
	s_nop 0
	v_pk_mul_f32 v[2:3], v[16:17], v[2:3]
	s_nop 0
	v_pk_mul_f32 v[2:3], v[4:5], v[2:3]
	s_nop 0
	v_cvt_pk_bf16_f32 v2, v2, v3
	v_mul_f32_e32 v3, 0xbfb8aa3b, v0
	v_exp_f32_e32 v3, v3
	s_nop 0
	v_add_f32_e32 v3, 1.0, v3
	v_rcp_f32_e32 v4, v3
	v_mul_f32_e32 v3, 0xbfb8aa3b, v1
	v_exp_f32_e32 v3, v3
	s_nop 0
	v_add_f32_e32 v3, 1.0, v3
	v_rcp_f32_e32 v5, v3
	s_nop 0
	v_pk_mul_f32 v[0:1], v[4:5], v[0:1]
	s_nop 0
	v_pk_mul_f32 v[0:1], v[6:7], v[0:1]
	v_pk_mul_f32 v[6:7], v[8:9], v[64:65] op_sel_hi:[1,0]
	v_cvt_pk_bf16_f32 v3, v0, v1
	s_nop 0
	global_store_dwordx2 v[66:67], v[2:3], off offset:3280
	v_lshlrev_b32_e32 v2, 16, v126
	v_and_b32_e32 v3, 0xffff0000, v126
	v_mul_f32_e32 v4, 0xbfb8aa3b, v2
	v_mul_f32_e32 v5, 0xbfb8aa3b, v3
	v_exp_f32_e32 v4, v4
	v_exp_f32_e32 v5, v5
	v_lshlrev_b32_e32 v0, 16, v127
	v_and_b32_e32 v1, 0xffff0000, v127
	v_add_f32_e32 v4, 1.0, v4
	v_add_f32_e32 v5, 1.0, v5
	v_rcp_f32_e32 v4, v4
	v_rcp_f32_e32 v5, v5
	s_nop 0
	v_pk_mul_f32 v[2:3], v[4:5], v[2:3]
	s_nop 0
	v_pk_mul_f32 v[2:3], v[6:7], v[2:3]
	v_pk_mul_f32 v[6:7], v[10:11], v[64:65] op_sel_hi:[1,0]
	v_cvt_pk_bf16_f32 v2, v2, v3
	v_mul_f32_e32 v3, 0xbfb8aa3b, v0
	v_exp_f32_e32 v3, v3
	s_nop 0
	v_add_f32_e32 v3, 1.0, v3
	v_rcp_f32_e32 v4, v3
	v_mul_f32_e32 v3, 0xbfb8aa3b, v1
	v_exp_f32_e32 v3, v3
	s_nop 0
	v_add_f32_e32 v3, 1.0, v3
	v_rcp_f32_e32 v5, v3
	s_nop 0
	v_pk_mul_f32 v[0:1], v[4:5], v[0:1]
	s_nop 0
	v_pk_mul_f32 v[0:1], v[6:7], v[0:1]
	v_pk_mul_f32 v[6:7], v[12:13], v[64:65] op_sel_hi:[1,0]
	v_cvt_pk_bf16_f32 v3, v0, v1
	s_nop 0
	global_store_dwordx2 v[66:67], v[2:3], off offset:3296
	v_lshlrev_b32_e32 v2, 16, v128
	v_and_b32_e32 v3, 0xffff0000, v128
	v_mul_f32_e32 v4, 0xbfb8aa3b, v2
	v_mul_f32_e32 v5, 0xbfb8aa3b, v3
	v_exp_f32_e32 v4, v4
	v_exp_f32_e32 v5, v5
	v_lshlrev_b32_e32 v0, 16, v129
	v_and_b32_e32 v1, 0xffff0000, v129
	v_add_f32_e32 v4, 1.0, v4
	v_add_f32_e32 v5, 1.0, v5
	v_rcp_f32_e32 v4, v4
	v_rcp_f32_e32 v5, v5
	s_nop 0
	v_pk_mul_f32 v[2:3], v[4:5], v[2:3]
	s_nop 0
	v_pk_mul_f32 v[2:3], v[6:7], v[2:3]
	v_pk_mul_f32 v[6:7], v[14:15], v[64:65] op_sel_hi:[1,0]
	v_cvt_pk_bf16_f32 v2, v2, v3
	v_mul_f32_e32 v3, 0xbfb8aa3b, v0
	v_exp_f32_e32 v3, v3
	s_nop 0
	v_add_f32_e32 v3, 1.0, v3
	v_rcp_f32_e32 v4, v3
	v_mul_f32_e32 v3, 0xbfb8aa3b, v1
	v_exp_f32_e32 v3, v3
	s_nop 0
	v_add_f32_e32 v3, 1.0, v3
	v_rcp_f32_e32 v5, v3
	s_nop 0
	v_pk_mul_f32 v[0:1], v[4:5], v[0:1]
	s_nop 0
	v_pk_mul_f32 v[0:1], v[6:7], v[0:1]
	s_nop 0
	v_cvt_pk_bf16_f32 v3, v0, v1
	global_store_dwordx2 v[66:67], v[2:3], off offset:3312
	s_branch .LBB0_181

; DI float bf2f(unsigned v) { return __uint_as_float(v << 16); }
; DI unsigned pack2(float a, float b) { f2_t v = {a, b}; bf2_t r = __builtin_convertvector(v, bf2_t); return __builtin_bit_cast(unsigned, r); }
; DI float silu(float g) { return g * frcp(1.f + fexp(-g)); }
; template <int DQK>
; DI void attn_item_c(const u16* __restrict__ Qp, int ldq, const u16* __restrict__ Kp, const u16* __restrict__ Vtp, int ldv,
;                     int nkt, int q0, float c, u16* Yp, int ldy, char* smem, bool dry) {
;     ...
;   const float lt = l + __shfl_xor(l, 32);
;   const float inv = 1.f / lt;
;   if (dry) return;
;   u16* yrow = Yp + (size_t)(32 * w + r) * ldy;
; #pragma unroll
;   for (int dt = 0; dt < 4; ++dt)
; #pragma unroll
;     for (int g = 0; g < 4; ++g) {
;       const int d = 32 * dt + 8 * g + 4 * h;
;       uint2 gv = *(const uint2*)(yrow + d);
;       float g0 = bf2f(gv.x & 0xffffu), g1 = bf2f(gv.x >> 16), g2 = bf2f(gv.y & 0xffffu), g3 = bf2f(gv.y >> 16);
;       uint2 ov;
;       ov.x = pack2(o[dt][4 * g] * inv * silu(g0), o[dt][4 * g + 1] * inv * silu(g1));
;       ov.y = pack2(o[dt][4 * g + 2] * inv * silu(g2), o[dt][4 * g + 3] * inv * silu(g3));
;       *(uint2*)(yrow + d) = ov;
;     }
.LBB0_248:
	ds_bpermute_b32 v64, v232, v190
	v_readlane_b32 s0, v255, 20
	v_readlane_b32 s1, v255, 21
	s_and_b64 vcc, exec, s[0:1]
	v_accvgpr_read_b32 v199, a197
	s_cbranch_vccz .LBB0_199
	s_mul_hi_i32 s0, s92, 0x2aaaaaab
	s_lshr_b32 s1, s0, 31
	s_ashr_i32 s0, s0, 1
	s_add_i32 s6, s0, s1
	s_lshl_b32 s0, s6, 13
	s_waitcnt lgkmcnt(0)
	v_add_f32_e32 v64, v190, v64
	s_or_b32 s7, s0, s62
	v_div_scale_f32 v65, s[0:1], v64, v64, 1.0
	v_rcp_f32_e32 v66, v65
	s_mul_i32 s0, s6, -12
	s_add_i32 s0, s0, s92
	s_lshl_b32 s0, s0, 7
	v_fma_f32 v67, -v65, v66, 1.0
	v_fmac_f32_e32 v66, v67, v66
	v_div_scale_f32 v67, vcc, 1.0, v64, 1.0
	v_mul_f32_e32 v68, v67, v66
	s_mul_hi_i32 s8, s7, 0x1980
	s_mulk_i32 s7, 0x1980
	s_ashr_i32 s1, s0, 31
	v_fma_f32 v69, -v65, v68, v67
	s_add_u32 s6, s2, s7
	v_fmac_f32_e32 v68, v69, v66
	s_addc_u32 s7, s3, s8
	s_lshl_b64 s[0:1], s[0:1], 1
	v_fma_f32 v65, -v65, v68, v67
	s_add_u32 s0, s6, s0
	v_div_fmas_f32 v65, v65, v66, v68
	s_addc_u32 s1, s7, s1
	v_div_fixup_f32 v64, v65, v64, 1.0
	v_mov_b64_e32 v[66:67], s[0:1]
	s_movk_i32 s0, 0x1980
	v_accvgpr_read_b32 v68, a228
	v_accvgpr_read_b32 v65, a237
	v_mad_i64_i32 v[66:67], s[0:1], v68, s0, v[66:67]
	v_lshlrev_b32_e32 v198, 1, v65
	v_lshl_add_u64 v[66:67], v[66:67], 0, v[198:199]
	global_load_dwordx2 v[96:97], v[66:67], off offset:2432
	global_load_dwordx2 v[98:99], v[66:67], off offset:2448
	global_load_dwordx2 v[100:101], v[66:67], off offset:2464
	global_load_dwordx2 v[102:103], v[66:67], off offset:2480
	global_load_dwordx2 v[104:105], v[66:67], off offset:2496
	global_load_dwordx2 v[106:107], v[66:67], off offset:2512
	global_load_dwordx2 v[108:109], v[66:67], off offset:2528
	global_load_dwordx2 v[110:111], v[66:67], off offset:2544
	global_load_dwordx2 v[112:113], v[66:67], off offset:2560
	global_load_dwordx2 v[114:115], v[66:67], off offset:2576
	global_load_dwordx2 v[116:117], v[66:67], off offset:2592
	global_load_dwordx2 v[118:119], v[66:67], off offset:2608
	global_load_dwordx2 v[120:121], v[66:67], off offset:2624
	global_load_dwordx2 v[122:123], v[66:67], off offset:2640
	global_load_dwordx2 v[124:125], v[66:67], off offset:2656
	global_load_dwordx2 v[126:127], v[66:67], off offset:2672
	v_accvgpr_read_b32 v63, a15
	v_accvgpr_read_b32 v49, a1
	v_accvgpr_read_b32 v48, a0
	v_accvgpr_read_b32 v51, a3
	v_accvgpr_read_b32 v50, a2
	v_accvgpr_read_b32 v53, a5
	v_accvgpr_read_b32 v52, a4
	v_accvgpr_read_b32 v55, a7
	v_accvgpr_read_b32 v54, a6
	v_accvgpr_read_b32 v57, a9
	v_accvgpr_read_b32 v56, a8
	v_accvgpr_read_b32 v59, a11
	v_accvgpr_read_b32 v58, a10
	v_accvgpr_read_b32 v61, a13
	v_accvgpr_read_b32 v60, a12
	v_accvgpr_read_b32 v62, a14
	v_accvgpr_read_b32 v47, a31
	v_accvgpr_read_b32 v33, a17
	v_accvgpr_read_b32 v32, a16
	v_accvgpr_read_b32 v35, a19
	v_accvgpr_read_b32 v34, a18
	v_accvgpr_read_b32 v37, a21
	v_accvgpr_read_b32 v36, a20
	v_accvgpr_read_b32 v39, a23
	v_accvgpr_read_b32 v38, a22
	v_accvgpr_read_b32 v41, a25
	v_accvgpr_read_b32 v40, a24
	v_accvgpr_read_b32 v43, a27
	v_accvgpr_read_b32 v42, a26
	v_accvgpr_read_b32 v45, a29
	v_accvgpr_read_b32 v44, a28
	v_accvgpr_read_b32 v46, a30
	v_accvgpr_read_b32 v16, a32
	v_accvgpr_read_b32 v17, a33
	v_accvgpr_read_b32 v18, a34
	v_accvgpr_read_b32 v19, a35
	v_accvgpr_read_b32 v20, a36
	v_accvgpr_read_b32 v21, a37
	v_accvgpr_read_b32 v22, a38
	v_accvgpr_read_b32 v23, a39
	v_accvgpr_read_b32 v24, a40
	v_accvgpr_read_b32 v25, a41
	v_accvgpr_read_b32 v26, a42
	v_accvgpr_read_b32 v27, a43
	v_accvgpr_read_b32 v28, a44
	v_accvgpr_read_b32 v29, a45
	v_accvgpr_read_b32 v30, a46
	v_accvgpr_read_b32 v31, a47
	v_accvgpr_read_b32 v0, a48
	v_accvgpr_read_b32 v1, a49
	v_accvgpr_read_b32 v2, a50
	v_accvgpr_read_b32 v3, a51
	v_accvgpr_read_b32 v4, a52
	v_accvgpr_read_b32 v5, a53
	v_accvgpr_read_b32 v6, a54
	v_accvgpr_read_b32 v7, a55
	v_accvgpr_read_b32 v8, a56
	v_accvgpr_read_b32 v9, a57
	v_accvgpr_read_b32 v10, a58
	v_accvgpr_read_b32 v11, a59
	v_accvgpr_read_b32 v12, a60
	v_accvgpr_read_b32 v13, a61
	v_accvgpr_read_b32 v14, a62
	v_accvgpr_read_b32 v15, a63
	s_waitcnt vmcnt(0)
	v_lshlrev_b32_e32 v70, 16, v96
	v_mul_f32_e32 v65, 0xbfb8aa3b, v70
	v_exp_f32_e32 v65, v65
	v_and_b32_e32 v71, 0xffff0000, v96
	v_lshlrev_b32_e32 v68, 16, v97
	v_and_b32_e32 v69, 0xffff0000, v97
	v_add_f32_e32 v65, 1.0, v65
	v_rcp_f32_e32 v72, v65
	v_pk_mul_f32 v[48:49], v[48:49], v[64:65] op_sel_hi:[1,0]
	v_mul_f32_e32 v65, 0xbfb8aa3b, v71
	v_exp_f32_e32 v65, v65
	s_nop 0
	v_add_f32_e32 v65, 1.0, v65
	v_rcp_f32_e32 v73, v65
	v_pk_mul_f32 v[50:51], v[50:51], v[64:65] op_sel_hi:[1,0]
	v_pk_mul_f32 v[70:71], v[72:73], v[70:71]
	s_nop 0
	v_pk_mul_f32 v[48:49], v[48:49], v[70:71]
	s_nop 0
	v_cvt_pk_bf16_f32 v48, v48, v49
	v_mul_f32_e32 v49, 0xbfb8aa3b, v68
	v_exp_f32_e32 v49, v49
	s_nop 0
	v_add_f32_e32 v49, 1.0, v49
	v_rcp_f32_e32 v70, v49
	v_mul_f32_e32 v49, 0xbfb8aa3b, v69
	v_exp_f32_e32 v49, v49
	s_nop 0
	v_add_f32_e32 v49, 1.0, v49
	v_rcp_f32_e32 v71, v49
	s_nop 0
	v_pk_mul_f32 v[68:69], v[70:71], v[68:69]
	s_nop 0
	v_pk_mul_f32 v[50:51], v[50:51], v[68:69]
	s_nop 0
	v_cvt_pk_bf16_f32 v49, v50, v51
	global_store_dwordx2 v[66:67], v[48:49], off offset:2432
	v_lshlrev_b32_e32 v50, 16, v98
	v_mul_f32_e32 v65, 0xbfb8aa3b, v50
	v_exp_f32_e32 v65, v65
	v_and_b32_e32 v51, 0xffff0000, v98
	v_lshlrev_b32_e32 v48, 16, v99
	v_and_b32_e32 v49, 0xffff0000, v99
	v_add_f32_e32 v65, 1.0, v65
	v_rcp_f32_e32 v68, v65
	v_pk_mul_f32 v[52:53], v[52:53], v[64:65] op_sel_hi:[1,0]
	v_mul_f32_e32 v65, 0xbfb8aa3b, v51
	v_exp_f32_e32 v65, v65
	s_nop 0
	v_add_f32_e32 v65, 1.0, v65
	v_rcp_f32_e32 v69, v65
	v_pk_mul_f32 v[54:55], v[54:55], v[64:65] op_sel_hi:[1,0]
; DI float bf2f(unsigned v) { return __uint_as_float(v << 16); }
; DI unsigned pack2(float a, float b) { f2_t v = {a, b}; bf2_t r = __builtin_convertvector(v, bf2_t); return __builtin_bit_cast(unsigned, r); }
; DI float silu(float g) { return g * frcp(1.f + fexp(-g)); }
; template <int DQK>
; DI void attn_item_c(const u16* __restrict__ Qp, int ldq, const u16* __restrict__ Kp, const u16* __restrict__ Vtp, int ldv,
;                     int nkt, int q0, float c, u16* Yp, int ldy, char* smem, bool dry) {
;     ...
; #pragma unroll
;     for (int g = 0; g < 4; ++g) {
;       const int d = 32 * dt + 8 * g + 4 * h;
;       uint2 gv = *(const uint2*)(yrow + d);
;       float g0 = bf2f(gv.x & 0xffffu), g1 = bf2f(gv.x >> 16), g2 = bf2f(gv.y & 0xffffu), g3 = bf2f(gv.y >> 16);
;       uint2 ov;
;       ov.x = pack2(o[dt][4 * g] * inv * silu(g0), o[dt][4 * g + 1] * inv * silu(g1));
;       ov.y = pack2(o[dt][4 * g + 2] * inv * silu(g2), o[dt][4 * g + 3] * inv * silu(g3));
;       *(uint2*)(yrow + d) = ov;
;     }
	v_pk_mul_f32 v[32:33], v[32:33], v[64:65] op_sel_hi:[1,0]
	v_pk_mul_f32 v[34:35], v[34:35], v[64:65] op_sel_hi:[1,0]
	v_pk_mul_f32 v[50:51], v[68:69], v[50:51]
	v_pk_mul_f32 v[36:37], v[36:37], v[64:65] op_sel_hi:[1,0]
	v_pk_mul_f32 v[50:51], v[52:53], v[50:51]
	v_pk_mul_f32 v[38:39], v[38:39], v[64:65] op_sel_hi:[1,0]
	v_cvt_pk_bf16_f32 v50, v50, v51
	v_mul_f32_e32 v51, 0xbfb8aa3b, v48
	v_exp_f32_e32 v51, v51
	v_pk_mul_f32 v[16:17], v[16:17], v[64:65] op_sel_hi:[1,0]
	v_pk_mul_f32 v[18:19], v[18:19], v[64:65] op_sel_hi:[1,0]
	v_pk_mul_f32 v[20:21], v[20:21], v[64:65] op_sel_hi:[1,0]
	v_add_f32_e32 v51, 1.0, v51
	v_rcp_f32_e32 v52, v51
	v_mul_f32_e32 v51, 0xbfb8aa3b, v49
	v_exp_f32_e32 v51, v51
	v_pk_mul_f32 v[22:23], v[22:23], v[64:65] op_sel_hi:[1,0]
	v_pk_mul_f32 v[0:1], v[0:1], v[64:65] op_sel_hi:[1,0]
	v_pk_mul_f32 v[2:3], v[2:3], v[64:65] op_sel_hi:[1,0]
	v_add_f32_e32 v51, 1.0, v51
	v_rcp_f32_e32 v53, v51
	v_pk_mul_f32 v[4:5], v[4:5], v[64:65] op_sel_hi:[1,0]
	v_pk_mul_f32 v[6:7], v[6:7], v[64:65] op_sel_hi:[1,0]
	v_pk_mul_f32 v[48:49], v[52:53], v[48:49]
	s_nop 0
	v_pk_mul_f32 v[48:49], v[54:55], v[48:49]
	v_pk_mul_f32 v[54:55], v[56:57], v[64:65] op_sel_hi:[1,0]
	v_cvt_pk_bf16_f32 v51, v48, v49
	s_nop 0
	global_store_dwordx2 v[66:67], v[50:51], off offset:2448
	v_lshlrev_b32_e32 v50, 16, v100
	v_and_b32_e32 v51, 0xffff0000, v100
	v_mul_f32_e32 v52, 0xbfb8aa3b, v50
	v_mul_f32_e32 v53, 0xbfb8aa3b, v51
	v_exp_f32_e32 v52, v52
	v_exp_f32_e32 v53, v53
	v_lshlrev_b32_e32 v48, 16, v101
	v_and_b32_e32 v49, 0xffff0000, v101
	v_add_f32_e32 v52, 1.0, v52
	v_add_f32_e32 v53, 1.0, v53
	v_rcp_f32_e32 v52, v52
	v_rcp_f32_e32 v53, v53
	s_nop 0
	v_pk_mul_f32 v[50:51], v[52:53], v[50:51]
	s_nop 0
	v_pk_mul_f32 v[50:51], v[54:55], v[50:51]
	v_pk_mul_f32 v[54:55], v[58:59], v[64:65] op_sel_hi:[1,0]
	v_cvt_pk_bf16_f32 v50, v50, v51
	v_mul_f32_e32 v51, 0xbfb8aa3b, v48
	v_exp_f32_e32 v51, v51
	s_nop 0
	v_add_f32_e32 v51, 1.0, v51
	v_rcp_f32_e32 v52, v51
	v_mul_f32_e32 v51, 0xbfb8aa3b, v49
	v_exp_f32_e32 v51, v51
	s_nop 0
	v_add_f32_e32 v51, 1.0, v51
	v_rcp_f32_e32 v53, v51
	s_nop 0
	v_pk_mul_f32 v[48:49], v[52:53], v[48:49]
	s_nop 0
	v_pk_mul_f32 v[48:49], v[54:55], v[48:49]
	v_pk_mul_f32 v[54:55], v[60:61], v[64:65] op_sel_hi:[1,0]
	v_cvt_pk_bf16_f32 v51, v48, v49
	s_nop 0
	global_store_dwordx2 v[66:67], v[50:51], off offset:2464
	v_lshlrev_b32_e32 v50, 16, v102
	v_and_b32_e32 v51, 0xffff0000, v102
	v_mul_f32_e32 v52, 0xbfb8aa3b, v50
	v_mul_f32_e32 v53, 0xbfb8aa3b, v51
	v_exp_f32_e32 v52, v52
	v_exp_f32_e32 v53, v53
	v_lshlrev_b32_e32 v48, 16, v103
	v_and_b32_e32 v49, 0xffff0000, v103
	v_add_f32_e32 v52, 1.0, v52
	v_add_f32_e32 v53, 1.0, v53
	v_rcp_f32_e32 v52, v52
	v_rcp_f32_e32 v53, v53
	s_nop 0
	v_pk_mul_f32 v[50:51], v[52:53], v[50:51]
	s_nop 0
	v_pk_mul_f32 v[50:51], v[54:55], v[50:51]
	v_pk_mul_f32 v[54:55], v[62:63], v[64:65] op_sel_hi:[1,0]
	v_cvt_pk_bf16_f32 v50, v50, v51
	v_mul_f32_e32 v51, 0xbfb8aa3b, v48
	v_exp_f32_e32 v51, v51
	s_nop 0
	v_add_f32_e32 v51, 1.0, v51
	v_rcp_f32_e32 v52, v51
	v_mul_f32_e32 v51, 0xbfb8aa3b, v49
	v_exp_f32_e32 v51, v51
	s_nop 0
	v_add_f32_e32 v51, 1.0, v51
	v_rcp_f32_e32 v53, v51
	s_nop 0
	v_pk_mul_f32 v[48:49], v[52:53], v[48:49]
	s_nop 0
	v_pk_mul_f32 v[48:49], v[54:55], v[48:49]
	s_nop 0
	v_cvt_pk_bf16_f32 v51, v48, v49
	s_nop 0
	global_store_dwordx2 v[66:67], v[50:51], off offset:2480
	v_lshlrev_b32_e32 v50, 16, v104
	v_and_b32_e32 v51, 0xffff0000, v104
	v_mul_f32_e32 v52, 0xbfb8aa3b, v50
	v_mul_f32_e32 v53, 0xbfb8aa3b, v51
	v_exp_f32_e32 v52, v52
	v_exp_f32_e32 v53, v53
	v_lshlrev_b32_e32 v48, 16, v105
	v_and_b32_e32 v49, 0xffff0000, v105
	v_add_f32_e32 v52, 1.0, v52
	v_add_f32_e32 v53, 1.0, v53
	v_rcp_f32_e32 v52, v52
	v_rcp_f32_e32 v53, v53
	s_nop 0
	v_pk_mul_f32 v[50:51], v[52:53], v[50:51]
	s_nop 0
	v_pk_mul_f32 v[32:33], v[32:33], v[50:51]
	s_nop 0
	v_cvt_pk_bf16_f32 v32, v32, v33
	v_mul_f32_e32 v33, 0xbfb8aa3b, v48
	v_exp_f32_e32 v33, v33
	s_nop 0
	v_add_f32_e32 v33, 1.0, v33
	v_rcp_f32_e32 v50, v33
	v_mul_f32_e32 v33, 0xbfb8aa3b, v49
	v_exp_f32_e32 v33, v33
	s_nop 0
	v_add_f32_e32 v33, 1.0, v33
	v_rcp_f32_e32 v51, v33
	s_nop 0
	v_pk_mul_f32 v[48:49], v[50:51], v[48:49]
	s_nop 0
	v_pk_mul_f32 v[34:35], v[34:35], v[48:49]
	s_nop 0
	v_cvt_pk_bf16_f32 v33, v34, v35
	global_store_dwordx2 v[66:67], v[32:33], off offset:2496
	v_lshlrev_b32_e32 v34, 16, v106
	v_and_b32_e32 v35, 0xffff0000, v106
	v_mul_f32_e32 v48, 0xbfb8aa3b, v34
	v_mul_f32_e32 v49, 0xbfb8aa3b, v35
	v_exp_f32_e32 v48, v48
	v_exp_f32_e32 v49, v49
	v_lshlrev_b32_e32 v32, 16, v107
	v_and_b32_e32 v33, 0xffff0000, v107
	v_add_f32_e32 v48, 1.0, v48
	v_add_f32_e32 v49, 1.0, v49
	v_rcp_f32_e32 v48, v48
	v_rcp_f32_e32 v49, v49
	s_nop 0
	v_pk_mul_f32 v[34:35], v[48:49], v[34:35]
	s_nop 0
	v_pk_mul_f32 v[34:35], v[36:37], v[34:35]
	s_nop 0
	v_cvt_pk_bf16_f32 v34, v34, v35
	v_mul_f32_e32 v35, 0xbfb8aa3b, v32
	v_exp_f32_e32 v35, v35
	s_nop 0
	v_add_f32_e32 v35, 1.0, v35
	v_rcp_f32_e32 v36, v35
	v_mul_f32_e32 v35, 0xbfb8aa3b, v33
	v_exp_f32_e32 v35, v35
	s_nop 0
	v_add_f32_e32 v35, 1.0, v35
	v_rcp_f32_e32 v37, v35
	s_nop 0
	v_pk_mul_f32 v[32:33], v[36:37], v[32:33]
	s_nop 0
	v_pk_mul_f32 v[32:33], v[38:39], v[32:33]
	v_pk_mul_f32 v[38:39], v[40:41], v[64:65] op_sel_hi:[1,0]
	v_cvt_pk_bf16_f32 v35, v32, v33
	s_nop 0
	global_store_dwordx2 v[66:67], v[34:35], off offset:2512
	v_lshlrev_b32_e32 v34, 16, v108
	v_and_b32_e32 v35, 0xffff0000, v108
	v_mul_f32_e32 v36, 0xbfb8aa3b, v34
	v_mul_f32_e32 v37, 0xbfb8aa3b, v35
	v_exp_f32_e32 v36, v36
	v_exp_f32_e32 v37, v37
	v_lshlrev_b32_e32 v32, 16, v109
	v_and_b32_e32 v33, 0xffff0000, v109
	v_add_f32_e32 v36, 1.0, v36
; DI float bf2f(unsigned v) { return __uint_as_float(v << 16); }
; DI unsigned pack2(float a, float b) { f2_t v = {a, b}; bf2_t r = __builtin_convertvector(v, bf2_t); return __builtin_bit_cast(unsigned, r); }
; DI float silu(float g) { return g * frcp(1.f + fexp(-g)); }
; template <int DQK>
; DI void attn_item_c(const u16* __restrict__ Qp, int ldq, const u16* __restrict__ Kp, const u16* __restrict__ Vtp, int ldv,
;                     int nkt, int q0, float c, u16* Yp, int ldy, char* smem, bool dry) {
;     ...
; #pragma unroll
;     for (int g = 0; g < 4; ++g) {
;       const int d = 32 * dt + 8 * g + 4 * h;
;       uint2 gv = *(const uint2*)(yrow + d);
;       float g0 = bf2f(gv.x & 0xffffu), g1 = bf2f(gv.x >> 16), g2 = bf2f(gv.y & 0xffffu), g3 = bf2f(gv.y >> 16);
;       uint2 ov;
;       ov.x = pack2(o[dt][4 * g] * inv * silu(g0), o[dt][4 * g + 1] * inv * silu(g1));
;       ov.y = pack2(o[dt][4 * g + 2] * inv * silu(g2), o[dt][4 * g + 3] * inv * silu(g3));
;       *(uint2*)(yrow + d) = ov;
;     }
	v_add_f32_e32 v37, 1.0, v37
	v_rcp_f32_e32 v36, v36
	v_rcp_f32_e32 v37, v37
	s_nop 0
	v_pk_mul_f32 v[34:35], v[36:37], v[34:35]
	s_nop 0
	v_pk_mul_f32 v[34:35], v[38:39], v[34:35]
	v_pk_mul_f32 v[38:39], v[42:43], v[64:65] op_sel_hi:[1,0]
	v_cvt_pk_bf16_f32 v34, v34, v35
	v_mul_f32_e32 v35, 0xbfb8aa3b, v32
	v_exp_f32_e32 v35, v35
	s_nop 0
	v_add_f32_e32 v35, 1.0, v35
	v_rcp_f32_e32 v36, v35
	v_mul_f32_e32 v35, 0xbfb8aa3b, v33
	v_exp_f32_e32 v35, v35
	s_nop 0
	v_add_f32_e32 v35, 1.0, v35
	v_rcp_f32_e32 v37, v35
	s_nop 0
	v_pk_mul_f32 v[32:33], v[36:37], v[32:33]
	s_nop 0
	v_pk_mul_f32 v[32:33], v[38:39], v[32:33]
	v_pk_mul_f32 v[38:39], v[44:45], v[64:65] op_sel_hi:[1,0]
	v_cvt_pk_bf16_f32 v35, v32, v33
	s_nop 0
	global_store_dwordx2 v[66:67], v[34:35], off offset:2528
	v_lshlrev_b32_e32 v34, 16, v110
	v_and_b32_e32 v35, 0xffff0000, v110
	v_mul_f32_e32 v36, 0xbfb8aa3b, v34
	v_mul_f32_e32 v37, 0xbfb8aa3b, v35
	v_exp_f32_e32 v36, v36
	v_exp_f32_e32 v37, v37
	v_lshlrev_b32_e32 v32, 16, v111
	v_and_b32_e32 v33, 0xffff0000, v111
	v_add_f32_e32 v36, 1.0, v36
	v_add_f32_e32 v37, 1.0, v37
	v_rcp_f32_e32 v36, v36
	v_rcp_f32_e32 v37, v37
	s_nop 0
	v_pk_mul_f32 v[34:35], v[36:37], v[34:35]
	s_nop 0
	v_pk_mul_f32 v[34:35], v[38:39], v[34:35]
	v_pk_mul_f32 v[38:39], v[46:47], v[64:65] op_sel_hi:[1,0]
	v_cvt_pk_bf16_f32 v34, v34, v35
	v_mul_f32_e32 v35, 0xbfb8aa3b, v32
	v_exp_f32_e32 v35, v35
	s_nop 0
	v_add_f32_e32 v35, 1.0, v35
	v_rcp_f32_e32 v36, v35
	v_mul_f32_e32 v35, 0xbfb8aa3b, v33
	v_exp_f32_e32 v35, v35
	s_nop 0
	v_add_f32_e32 v35, 1.0, v35
	v_rcp_f32_e32 v37, v35
	s_nop 0
	v_pk_mul_f32 v[32:33], v[36:37], v[32:33]
	s_nop 0
	v_pk_mul_f32 v[32:33], v[38:39], v[32:33]
	s_nop 0
	v_cvt_pk_bf16_f32 v35, v32, v33
	s_nop 0
	global_store_dwordx2 v[66:67], v[34:35], off offset:2544
	v_lshlrev_b32_e32 v34, 16, v112
	v_and_b32_e32 v35, 0xffff0000, v112
	v_mul_f32_e32 v36, 0xbfb8aa3b, v34
	v_mul_f32_e32 v37, 0xbfb8aa3b, v35
	v_exp_f32_e32 v36, v36
	v_exp_f32_e32 v37, v37
	v_lshlrev_b32_e32 v32, 16, v113
	v_and_b32_e32 v33, 0xffff0000, v113
	v_add_f32_e32 v36, 1.0, v36
	v_add_f32_e32 v37, 1.0, v37
	v_rcp_f32_e32 v36, v36
	v_rcp_f32_e32 v37, v37
	s_nop 0
	v_pk_mul_f32 v[34:35], v[36:37], v[34:35]
	s_nop 0
	v_pk_mul_f32 v[16:17], v[16:17], v[34:35]
	s_nop 0
	v_cvt_pk_bf16_f32 v16, v16, v17
	v_mul_f32_e32 v17, 0xbfb8aa3b, v32
	v_exp_f32_e32 v17, v17
	s_nop 0
	v_add_f32_e32 v17, 1.0, v17
	v_rcp_f32_e32 v34, v17
	v_mul_f32_e32 v17, 0xbfb8aa3b, v33
	v_exp_f32_e32 v17, v17
	s_nop 0
	v_add_f32_e32 v17, 1.0, v17
	v_rcp_f32_e32 v35, v17
	s_nop 0
	v_pk_mul_f32 v[32:33], v[34:35], v[32:33]
	s_nop 0
	v_pk_mul_f32 v[18:19], v[18:19], v[32:33]
	s_nop 0
	v_cvt_pk_bf16_f32 v17, v18, v19
	global_store_dwordx2 v[66:67], v[16:17], off offset:2560
	v_lshlrev_b32_e32 v18, 16, v114
	v_and_b32_e32 v19, 0xffff0000, v114
	v_mul_f32_e32 v32, 0xbfb8aa3b, v18
	v_mul_f32_e32 v33, 0xbfb8aa3b, v19
	v_exp_f32_e32 v32, v32
	v_exp_f32_e32 v33, v33
	v_lshlrev_b32_e32 v16, 16, v115
	v_and_b32_e32 v17, 0xffff0000, v115
	v_add_f32_e32 v32, 1.0, v32
	v_add_f32_e32 v33, 1.0, v33
	v_rcp_f32_e32 v32, v32
	v_rcp_f32_e32 v33, v33
	s_nop 0
	v_pk_mul_f32 v[18:19], v[32:33], v[18:19]
	s_nop 0
	v_pk_mul_f32 v[18:19], v[20:21], v[18:19]
	s_nop 0
	v_cvt_pk_bf16_f32 v18, v18, v19
	v_mul_f32_e32 v19, 0xbfb8aa3b, v16
	v_exp_f32_e32 v19, v19
	s_nop 0
	v_add_f32_e32 v19, 1.0, v19
	v_rcp_f32_e32 v20, v19
	v_mul_f32_e32 v19, 0xbfb8aa3b, v17
	v_exp_f32_e32 v19, v19
	s_nop 0
	v_add_f32_e32 v19, 1.0, v19
	v_rcp_f32_e32 v21, v19
	s_nop 0
	v_pk_mul_f32 v[16:17], v[20:21], v[16:17]
	s_nop 0
	v_pk_mul_f32 v[16:17], v[22:23], v[16:17]
	v_pk_mul_f32 v[22:23], v[24:25], v[64:65] op_sel_hi:[1,0]
	v_cvt_pk_bf16_f32 v19, v16, v17
	s_nop 0
	global_store_dwordx2 v[66:67], v[18:19], off offset:2576
	v_lshlrev_b32_e32 v18, 16, v116
	v_and_b32_e32 v19, 0xffff0000, v116
	v_mul_f32_e32 v20, 0xbfb8aa3b, v18
	v_mul_f32_e32 v21, 0xbfb8aa3b, v19
	v_exp_f32_e32 v20, v20
	v_exp_f32_e32 v21, v21
	v_lshlrev_b32_e32 v16, 16, v117
	v_and_b32_e32 v17, 0xffff0000, v117
	v_add_f32_e32 v20, 1.0, v20
	v_add_f32_e32 v21, 1.0, v21
	v_rcp_f32_e32 v20, v20
	v_rcp_f32_e32 v21, v21
	s_nop 0
	v_pk_mul_f32 v[18:19], v[20:21], v[18:19]
	s_nop 0
	v_pk_mul_f32 v[18:19], v[22:23], v[18:19]
	v_pk_mul_f32 v[22:23], v[26:27], v[64:65] op_sel_hi:[1,0]
	v_cvt_pk_bf16_f32 v18, v18, v19
	v_mul_f32_e32 v19, 0xbfb8aa3b, v16
	v_exp_f32_e32 v19, v19
	s_nop 0
	v_add_f32_e32 v19, 1.0, v19
	v_rcp_f32_e32 v20, v19
	v_mul_f32_e32 v19, 0xbfb8aa3b, v17
	v_exp_f32_e32 v19, v19
	s_nop 0
	v_add_f32_e32 v19, 1.0, v19
	v_rcp_f32_e32 v21, v19
	s_nop 0
	v_pk_mul_f32 v[16:17], v[20:21], v[16:17]
	s_nop 0
	v_pk_mul_f32 v[16:17], v[22:23], v[16:17]
	v_pk_mul_f32 v[22:23], v[28:29], v[64:65] op_sel_hi:[1,0]
	v_cvt_pk_bf16_f32 v19, v16, v17
	s_nop 0
	global_store_dwordx2 v[66:67], v[18:19], off offset:2592
; DI float bf2f(unsigned v) { return __uint_as_float(v << 16); }
; DI unsigned pack2(float a, float b) { f2_t v = {a, b}; bf2_t r = __builtin_convertvector(v, bf2_t); return __builtin_bit_cast(unsigned, r); }
; DI float silu(float g) { return g * frcp(1.f + fexp(-g)); }
; template <int DQK>
; DI void attn_item_c(const u16* __restrict__ Qp, int ldq, const u16* __restrict__ Kp, const u16* __restrict__ Vtp, int ldv,
;                     int nkt, int q0, float c, u16* Yp, int ldy, char* smem, bool dry) {
;     ...
; #pragma unroll
;     for (int g = 0; g < 4; ++g) {
;       const int d = 32 * dt + 8 * g + 4 * h;
;       uint2 gv = *(const uint2*)(yrow + d);
;       float g0 = bf2f(gv.x & 0xffffu), g1 = bf2f(gv.x >> 16), g2 = bf2f(gv.y & 0xffffu), g3 = bf2f(gv.y >> 16);
;       uint2 ov;
;       ov.x = pack2(o[dt][4 * g] * inv * silu(g0), o[dt][4 * g + 1] * inv * silu(g1));
;       ov.y = pack2(o[dt][4 * g + 2] * inv * silu(g2), o[dt][4 * g + 3] * inv * silu(g3));
;       *(uint2*)(yrow + d) = ov;
;     }
	v_lshlrev_b32_e32 v18, 16, v118
	v_and_b32_e32 v19, 0xffff0000, v118
	v_mul_f32_e32 v20, 0xbfb8aa3b, v18
	v_mul_f32_e32 v21, 0xbfb8aa3b, v19
	v_exp_f32_e32 v20, v20
	v_exp_f32_e32 v21, v21
	v_lshlrev_b32_e32 v16, 16, v119
	v_and_b32_e32 v17, 0xffff0000, v119
	v_add_f32_e32 v20, 1.0, v20
	v_add_f32_e32 v21, 1.0, v21
	v_rcp_f32_e32 v20, v20
	v_rcp_f32_e32 v21, v21
	s_nop 0
	v_pk_mul_f32 v[18:19], v[20:21], v[18:19]
	s_nop 0
	v_pk_mul_f32 v[18:19], v[22:23], v[18:19]
	v_pk_mul_f32 v[22:23], v[30:31], v[64:65] op_sel_hi:[1,0]
	v_cvt_pk_bf16_f32 v18, v18, v19
	v_mul_f32_e32 v19, 0xbfb8aa3b, v16
	v_exp_f32_e32 v19, v19
	s_nop 0
	v_add_f32_e32 v19, 1.0, v19
	v_rcp_f32_e32 v20, v19
	v_mul_f32_e32 v19, 0xbfb8aa3b, v17
	v_exp_f32_e32 v19, v19
	s_nop 0
	v_add_f32_e32 v19, 1.0, v19
	v_rcp_f32_e32 v21, v19
	s_nop 0
	v_pk_mul_f32 v[16:17], v[20:21], v[16:17]
	s_nop 0
	v_pk_mul_f32 v[16:17], v[22:23], v[16:17]
	s_nop 0
	v_cvt_pk_bf16_f32 v19, v16, v17
	s_nop 0
	global_store_dwordx2 v[66:67], v[18:19], off offset:2608
	v_lshlrev_b32_e32 v18, 16, v120
	v_and_b32_e32 v19, 0xffff0000, v120
	v_mul_f32_e32 v20, 0xbfb8aa3b, v18
	v_mul_f32_e32 v21, 0xbfb8aa3b, v19
	v_exp_f32_e32 v20, v20
	v_exp_f32_e32 v21, v21
	v_lshlrev_b32_e32 v16, 16, v121
	v_and_b32_e32 v17, 0xffff0000, v121
	v_add_f32_e32 v20, 1.0, v20
	v_add_f32_e32 v21, 1.0, v21
	v_rcp_f32_e32 v20, v20
	v_rcp_f32_e32 v21, v21
	s_nop 0
	v_pk_mul_f32 v[18:19], v[20:21], v[18:19]
	s_nop 0
	v_pk_mul_f32 v[0:1], v[0:1], v[18:19]
	s_nop 0
	v_cvt_pk_bf16_f32 v0, v0, v1
	v_mul_f32_e32 v1, 0xbfb8aa3b, v16
	v_exp_f32_e32 v1, v1
	s_nop 0
	v_add_f32_e32 v1, 1.0, v1
	v_rcp_f32_e32 v18, v1
	v_mul_f32_e32 v1, 0xbfb8aa3b, v17
	v_exp_f32_e32 v1, v1
	s_nop 0
	v_add_f32_e32 v1, 1.0, v1
	v_rcp_f32_e32 v19, v1
	s_nop 0
	v_pk_mul_f32 v[16:17], v[18:19], v[16:17]
	s_nop 0
	v_pk_mul_f32 v[2:3], v[2:3], v[16:17]
	s_nop 0
	v_cvt_pk_bf16_f32 v1, v2, v3
	global_store_dwordx2 v[66:67], v[0:1], off offset:2624
	v_lshlrev_b32_e32 v2, 16, v122
	v_and_b32_e32 v3, 0xffff0000, v122
	v_mul_f32_e32 v16, 0xbfb8aa3b, v2
	v_mul_f32_e32 v17, 0xbfb8aa3b, v3
	v_exp_f32_e32 v16, v16
	v_exp_f32_e32 v17, v17
	v_lshlrev_b32_e32 v0, 16, v123
	v_and_b32_e32 v1, 0xffff0000, v123
	v_add_f32_e32 v16, 1.0, v16
	v_add_f32_e32 v17, 1.0, v17
	v_rcp_f32_e32 v16, v16
	v_rcp_f32_e32 v17, v17
	s_nop 0
	v_pk_mul_f32 v[2:3], v[16:17], v[2:3]
	s_nop 0
	v_pk_mul_f32 v[2:3], v[4:5], v[2:3]
	s_nop 0
	v_cvt_pk_bf16_f32 v2, v2, v3
	v_mul_f32_e32 v3, 0xbfb8aa3b, v0
	v_exp_f32_e32 v3, v3
	s_nop 0
	v_add_f32_e32 v3, 1.0, v3
	v_rcp_f32_e32 v4, v3
	v_mul_f32_e32 v3, 0xbfb8aa3b, v1
	v_exp_f32_e32 v3, v3
	s_nop 0
	v_add_f32_e32 v3, 1.0, v3
	v_rcp_f32_e32 v5, v3
	s_nop 0
	v_pk_mul_f32 v[0:1], v[4:5], v[0:1]
	s_nop 0
	v_pk_mul_f32 v[0:1], v[6:7], v[0:1]
	v_pk_mul_f32 v[6:7], v[8:9], v[64:65] op_sel_hi:[1,0]
	v_cvt_pk_bf16_f32 v3, v0, v1
	s_nop 0
	global_store_dwordx2 v[66:67], v[2:3], off offset:2640
	v_lshlrev_b32_e32 v2, 16, v124
	v_and_b32_e32 v3, 0xffff0000, v124
	v_mul_f32_e32 v4, 0xbfb8aa3b, v2
	v_mul_f32_e32 v5, 0xbfb8aa3b, v3
	v_exp_f32_e32 v4, v4
	v_exp_f32_e32 v5, v5
	v_lshlrev_b32_e32 v0, 16, v125
	v_and_b32_e32 v1, 0xffff0000, v125
	v_add_f32_e32 v4, 1.0, v4
	v_add_f32_e32 v5, 1.0, v5
	v_rcp_f32_e32 v4, v4
	v_rcp_f32_e32 v5, v5
	s_nop 0
	v_pk_mul_f32 v[2:3], v[4:5], v[2:3]
	s_nop 0
	v_pk_mul_f32 v[2:3], v[6:7], v[2:3]
	v_pk_mul_f32 v[6:7], v[10:11], v[64:65] op_sel_hi:[1,0]
	v_cvt_pk_bf16_f32 v2, v2, v3
	v_mul_f32_e32 v3, 0xbfb8aa3b, v0
	v_exp_f32_e32 v3, v3
	s_nop 0
	v_add_f32_e32 v3, 1.0, v3
	v_rcp_f32_e32 v4, v3
	v_mul_f32_e32 v3, 0xbfb8aa3b, v1
	v_exp_f32_e32 v3, v3
	s_nop 0
	v_add_f32_e32 v3, 1.0, v3
	v_rcp_f32_e32 v5, v3
	s_nop 0
	v_pk_mul_f32 v[0:1], v[4:5], v[0:1]
	s_nop 0
	v_pk_mul_f32 v[0:1], v[6:7], v[0:1]
	v_pk_mul_f32 v[6:7], v[12:13], v[64:65] op_sel_hi:[1,0]
	v_cvt_pk_bf16_f32 v3, v0, v1
	s_nop 0
	global_store_dwordx2 v[66:67], v[2:3], off offset:2656
	v_lshlrev_b32_e32 v2, 16, v126
	v_and_b32_e32 v3, 0xffff0000, v126
	v_mul_f32_e32 v4, 0xbfb8aa3b, v2
	v_mul_f32_e32 v5, 0xbfb8aa3b, v3
	v_exp_f32_e32 v4, v4
	v_exp_f32_e32 v5, v5
	v_lshlrev_b32_e32 v0, 16, v127
	v_and_b32_e32 v1, 0xffff0000, v127
	v_add_f32_e32 v4, 1.0, v4
	v_add_f32_e32 v5, 1.0, v5
	v_rcp_f32_e32 v4, v4
	v_rcp_f32_e32 v5, v5
	s_nop 0
	v_pk_mul_f32 v[2:3], v[4:5], v[2:3]
	s_nop 0
	v_pk_mul_f32 v[2:3], v[6:7], v[2:3]
	v_pk_mul_f32 v[6:7], v[14:15], v[64:65] op_sel_hi:[1,0]
	v_cvt_pk_bf16_f32 v2, v2, v3
	v_mul_f32_e32 v3, 0xbfb8aa3b, v0
	v_exp_f32_e32 v3, v3
	s_nop 0
	v_add_f32_e32 v3, 1.0, v3
	v_rcp_f32_e32 v4, v3
	v_mul_f32_e32 v3, 0xbfb8aa3b, v1
	v_exp_f32_e32 v3, v3
	s_nop 0
	v_add_f32_e32 v3, 1.0, v3
	v_rcp_f32_e32 v5, v3
	s_nop 0
	v_pk_mul_f32 v[0:1], v[4:5], v[0:1]
	s_nop 0
	v_pk_mul_f32 v[0:1], v[6:7], v[0:1]
	s_nop 0
	v_cvt_pk_bf16_f32 v3, v0, v1
	global_store_dwordx2 v[66:67], v[2:3], off offset:2672
	s_branch .LBB0_199

; template <int DQK>
; DI void attn_item_c(const u16* __restrict__ Qp, int ldq, const u16* __restrict__ Kp, const u16* __restrict__ Vtp, int ldv,
;                     int nkt, int q0, float c, u16* Yp, int ldy, char* smem, bool dry) {
;     ...
;   const float lt = l + __shfl_xor(l, 32);
;   const float inv = 1.f / lt;
;   if (dry) return;
;   u16* yrow = Yp + (size_t)(32 * w + r) * ldy;
; #pragma unroll
.LBB0_303:
	ds_bpermute_b32 v64, v232, v190
	v_readlane_b32 s0, v255, 20
	v_readlane_b32 s1, v255, 21
	v_accvgpr_read_b32 v215, a209
	v_accvgpr_read_b32 v219, a211
	v_accvgpr_read_b32 v221, a213
	v_accvgpr_read_b32 v223, a215
	v_accvgpr_read_b32 v225, a217
	v_accvgpr_read_b32 v227, a219
	v_accvgpr_read_b32 v229, a221
	v_accvgpr_read_b32 v231, a223
	v_accvgpr_read_b32 v233, a225
	s_and_b64 vcc, exec, s[0:1]
	v_accvgpr_read_b32 v197, a196
	v_accvgpr_read_b32 v199, a197
	v_mov_b32_e32 v206, 0x358637bd
	v_mov_b32_e32 v207, 0x24804
	v_accvgpr_read_b32 v209, a199
	v_accvgpr_read_b32 v210, a200
	v_accvgpr_read_b32 v211, a201
	v_accvgpr_read_b32 v213, a202
	v_accvgpr_read_b32 v214, a208
	v_accvgpr_read_b32 v218, a210
	v_accvgpr_read_b32 v220, a212
	v_accvgpr_read_b32 v222, a214
	v_accvgpr_read_b32 v224, a216
	v_accvgpr_read_b32 v226, a218
	v_accvgpr_read_b32 v228, a220
	v_accvgpr_read_b32 v230, a222
	v_accvgpr_read_b32 v232, a224
	s_cbranch_vccz .LBB0_251
	s_mul_hi_i32 s0, s92, 0x2aaaaaab
	s_lshr_b32 s1, s0, 31
	s_ashr_i32 s0, s0, 1
	s_add_i32 s6, s0, s1
	s_lshl_b32 s0, s6, 13
	s_waitcnt lgkmcnt(0)
	v_add_f32_e32 v64, v190, v64
	s_or_b32 s7, s0, s63
	v_div_scale_f32 v65, s[0:1], v64, v64, 1.0
	v_rcp_f32_e32 v66, v65
	s_mul_i32 s0, s6, -12
	s_add_i32 s0, s0, s92
	s_lshl_b32 s0, s0, 7
	v_fma_f32 v67, -v65, v66, 1.0
	v_fmac_f32_e32 v66, v67, v66
	v_div_scale_f32 v67, vcc, 1.0, v64, 1.0
	v_mul_f32_e32 v68, v67, v66
	s_mul_hi_i32 s8, s7, 0x1980
	s_mulk_i32 s7, 0x1980
	s_ashr_i32 s1, s0, 31
	v_fma_f32 v69, -v65, v68, v67
	s_add_u32 s6, s2, s7
	v_fmac_f32_e32 v68, v69, v66
	s_addc_u32 s7, s3, s8
	s_lshl_b64 s[0:1], s[0:1], 1
	v_fma_f32 v65, -v65, v68, v67
	s_add_u32 s0, s6, s0
	v_div_fmas_f32 v65, v65, v66, v68
	s_addc_u32 s1, s7, s1
	v_div_fixup_f32 v64, v65, v64, 1.0
	v_mov_b64_e32 v[66:67], s[0:1]
	s_movk_i32 s0, 0x1980
	v_accvgpr_read_b32 v68, a228
	v_accvgpr_read_b32 v65, a237
	v_mad_i64_i32 v[66:67], s[0:1], v68, s0, v[66:67]
	v_lshlrev_b32_e32 v198, 1, v65
	v_lshl_add_u64 v[66:67], v[66:67], 0, v[198:199]
	global_load_dwordx2 v[96:97], v[66:67], off offset:2432
	global_load_dwordx2 v[98:99], v[66:67], off offset:2448
	global_load_dwordx2 v[100:101], v[66:67], off offset:2464
	global_load_dwordx2 v[102:103], v[66:67], off offset:2480
	global_load_dwordx2 v[104:105], v[66:67], off offset:2496
	global_load_dwordx2 v[106:107], v[66:67], off offset:2512
	global_load_dwordx2 v[108:109], v[66:67], off offset:2528
	global_load_dwordx2 v[110:111], v[66:67], off offset:2544
	global_load_dwordx2 v[112:113], v[66:67], off offset:2560
	global_load_dwordx2 v[114:115], v[66:67], off offset:2576
	global_load_dwordx2 v[116:117], v[66:67], off offset:2592
	global_load_dwordx2 v[118:119], v[66:67], off offset:2608
	global_load_dwordx2 v[120:121], v[66:67], off offset:2624
	global_load_dwordx2 v[122:123], v[66:67], off offset:2640
	global_load_dwordx2 v[124:125], v[66:67], off offset:2656
	global_load_dwordx2 v[126:127], v[66:67], off offset:2672
	v_accvgpr_read_b32 v63, a15
	v_accvgpr_read_b32 v49, a1
	v_accvgpr_read_b32 v48, a0
	v_accvgpr_read_b32 v51, a3
	v_accvgpr_read_b32 v50, a2
	v_accvgpr_read_b32 v53, a5
	v_accvgpr_read_b32 v52, a4
	v_accvgpr_read_b32 v55, a7
	v_accvgpr_read_b32 v54, a6
	v_accvgpr_read_b32 v57, a9
	v_accvgpr_read_b32 v56, a8
	v_accvgpr_read_b32 v59, a11
	v_accvgpr_read_b32 v58, a10
	v_accvgpr_read_b32 v61, a13
	v_accvgpr_read_b32 v60, a12
	v_accvgpr_read_b32 v62, a14
	v_accvgpr_read_b32 v47, a31
	v_accvgpr_read_b32 v33, a17
	v_accvgpr_read_b32 v32, a16
	v_accvgpr_read_b32 v35, a19
	v_accvgpr_read_b32 v34, a18
	v_accvgpr_read_b32 v37, a21
	v_accvgpr_read_b32 v36, a20
	v_accvgpr_read_b32 v39, a23
	v_accvgpr_read_b32 v38, a22
	v_accvgpr_read_b32 v41, a25
	v_accvgpr_read_b32 v40, a24
	v_accvgpr_read_b32 v43, a27
	v_accvgpr_read_b32 v42, a26
	v_accvgpr_read_b32 v45, a29
	v_accvgpr_read_b32 v44, a28
	v_accvgpr_read_b32 v46, a30
	v_accvgpr_read_b32 v16, a32
	v_accvgpr_read_b32 v17, a33
	v_accvgpr_read_b32 v18, a34
	v_accvgpr_read_b32 v19, a35
	v_accvgpr_read_b32 v20, a36
	v_accvgpr_read_b32 v21, a37
	v_accvgpr_read_b32 v22, a38
	v_accvgpr_read_b32 v23, a39
	v_accvgpr_read_b32 v24, a40
	v_accvgpr_read_b32 v25, a41
	v_accvgpr_read_b32 v26, a42
	v_accvgpr_read_b32 v27, a43
	v_accvgpr_read_b32 v28, a44
	v_accvgpr_read_b32 v29, a45
	v_accvgpr_read_b32 v30, a46
	v_accvgpr_read_b32 v31, a47
	v_accvgpr_read_b32 v0, a48
	v_accvgpr_read_b32 v1, a49
	v_accvgpr_read_b32 v2, a50
	v_accvgpr_read_b32 v3, a51
	v_accvgpr_read_b32 v4, a52
	v_accvgpr_read_b32 v5, a53
	v_accvgpr_read_b32 v6, a54
	v_accvgpr_read_b32 v7, a55
	v_accvgpr_read_b32 v8, a56
	v_accvgpr_read_b32 v9, a57
	v_accvgpr_read_b32 v10, a58
	v_accvgpr_read_b32 v11, a59
	v_accvgpr_read_b32 v12, a60
	v_accvgpr_read_b32 v13, a61
	v_accvgpr_read_b32 v14, a62
	v_accvgpr_read_b32 v15, a63
	s_waitcnt vmcnt(0)
; DI float bf2f(unsigned v) { return __uint_as_float(v << 16); }
; DI unsigned pack2(float a, float b) { f2_t v = {a, b}; bf2_t r = __builtin_convertvector(v, bf2_t); return __builtin_bit_cast(unsigned, r); }
; DI float silu(float g) { return g * frcp(1.f + fexp(-g)); }
; template <int DQK>
; DI void attn_item_c(const u16* __restrict__ Qp, int ldq, const u16* __restrict__ Kp, const u16* __restrict__ Vtp, int ldv,
;                     int nkt, int q0, float c, u16* Yp, int ldy, char* smem, bool dry) {
;     ...
; #pragma unroll
;     for (int g = 0; g < 4; ++g) {
;       const int d = 32 * dt + 8 * g + 4 * h;
;       uint2 gv = *(const uint2*)(yrow + d);
;       float g0 = bf2f(gv.x & 0xffffu), g1 = bf2f(gv.x >> 16), g2 = bf2f(gv.y & 0xffffu), g3 = bf2f(gv.y >> 16);
;       uint2 ov;
;       ov.x = pack2(o[dt][4 * g] * inv * silu(g0), o[dt][4 * g + 1] * inv * silu(g1));
;       ov.y = pack2(o[dt][4 * g + 2] * inv * silu(g2), o[dt][4 * g + 3] * inv * silu(g3));
;       *(uint2*)(yrow + d) = ov;
;     }
	v_lshlrev_b32_e32 v70, 16, v96
	v_mul_f32_e32 v65, 0xbfb8aa3b, v70
	v_exp_f32_e32 v65, v65
	v_and_b32_e32 v71, 0xffff0000, v96
	v_lshlrev_b32_e32 v68, 16, v97
	v_and_b32_e32 v69, 0xffff0000, v97
	v_add_f32_e32 v65, 1.0, v65
	v_rcp_f32_e32 v72, v65
	v_pk_mul_f32 v[48:49], v[48:49], v[64:65] op_sel_hi:[1,0]
	v_mul_f32_e32 v65, 0xbfb8aa3b, v71
	v_exp_f32_e32 v65, v65
	s_nop 0
	v_add_f32_e32 v65, 1.0, v65
	v_rcp_f32_e32 v73, v65
	v_pk_mul_f32 v[50:51], v[50:51], v[64:65] op_sel_hi:[1,0]
	v_pk_mul_f32 v[70:71], v[72:73], v[70:71]
	s_nop 0
	v_pk_mul_f32 v[48:49], v[48:49], v[70:71]
	s_nop 0
	v_cvt_pk_bf16_f32 v48, v48, v49
	v_mul_f32_e32 v49, 0xbfb8aa3b, v68
	v_exp_f32_e32 v49, v49
	s_nop 0
	v_add_f32_e32 v49, 1.0, v49
	v_rcp_f32_e32 v70, v49
	v_mul_f32_e32 v49, 0xbfb8aa3b, v69
	v_exp_f32_e32 v49, v49
	s_nop 0
	v_add_f32_e32 v49, 1.0, v49
	v_rcp_f32_e32 v71, v49
	s_nop 0
	v_pk_mul_f32 v[68:69], v[70:71], v[68:69]
	s_nop 0
	v_pk_mul_f32 v[50:51], v[50:51], v[68:69]
	s_nop 0
	v_cvt_pk_bf16_f32 v49, v50, v51
	global_store_dwordx2 v[66:67], v[48:49], off offset:2432
	v_lshlrev_b32_e32 v50, 16, v98
	v_mul_f32_e32 v65, 0xbfb8aa3b, v50
	v_exp_f32_e32 v65, v65
	v_and_b32_e32 v51, 0xffff0000, v98
	v_lshlrev_b32_e32 v48, 16, v99
	v_and_b32_e32 v49, 0xffff0000, v99
	v_add_f32_e32 v65, 1.0, v65
	v_rcp_f32_e32 v68, v65
	v_pk_mul_f32 v[52:53], v[52:53], v[64:65] op_sel_hi:[1,0]
	v_mul_f32_e32 v65, 0xbfb8aa3b, v51
	v_exp_f32_e32 v65, v65
	s_nop 0
	v_add_f32_e32 v65, 1.0, v65
	v_rcp_f32_e32 v69, v65
	v_pk_mul_f32 v[54:55], v[54:55], v[64:65] op_sel_hi:[1,0]
	v_pk_mul_f32 v[32:33], v[32:33], v[64:65] op_sel_hi:[1,0]
	v_pk_mul_f32 v[34:35], v[34:35], v[64:65] op_sel_hi:[1,0]
	v_pk_mul_f32 v[50:51], v[68:69], v[50:51]
	v_pk_mul_f32 v[36:37], v[36:37], v[64:65] op_sel_hi:[1,0]
	v_pk_mul_f32 v[50:51], v[52:53], v[50:51]
	v_pk_mul_f32 v[38:39], v[38:39], v[64:65] op_sel_hi:[1,0]
	v_cvt_pk_bf16_f32 v50, v50, v51
	v_mul_f32_e32 v51, 0xbfb8aa3b, v48
	v_exp_f32_e32 v51, v51
	v_pk_mul_f32 v[16:17], v[16:17], v[64:65] op_sel_hi:[1,0]
	v_pk_mul_f32 v[18:19], v[18:19], v[64:65] op_sel_hi:[1,0]
	v_pk_mul_f32 v[20:21], v[20:21], v[64:65] op_sel_hi:[1,0]
	v_add_f32_e32 v51, 1.0, v51
	v_rcp_f32_e32 v52, v51
	v_mul_f32_e32 v51, 0xbfb8aa3b, v49
	v_exp_f32_e32 v51, v51
	v_pk_mul_f32 v[22:23], v[22:23], v[64:65] op_sel_hi:[1,0]
	v_pk_mul_f32 v[0:1], v[0:1], v[64:65] op_sel_hi:[1,0]
	v_pk_mul_f32 v[2:3], v[2:3], v[64:65] op_sel_hi:[1,0]
	v_add_f32_e32 v51, 1.0, v51
	v_rcp_f32_e32 v53, v51
	v_pk_mul_f32 v[4:5], v[4:5], v[64:65] op_sel_hi:[1,0]
	v_pk_mul_f32 v[6:7], v[6:7], v[64:65] op_sel_hi:[1,0]
	v_pk_mul_f32 v[48:49], v[52:53], v[48:49]
	s_nop 0
	v_pk_mul_f32 v[48:49], v[54:55], v[48:49]
	v_pk_mul_f32 v[54:55], v[56:57], v[64:65] op_sel_hi:[1,0]
	v_cvt_pk_bf16_f32 v51, v48, v49
	s_nop 0
	global_store_dwordx2 v[66:67], v[50:51], off offset:2448
	v_lshlrev_b32_e32 v50, 16, v100
	v_and_b32_e32 v51, 0xffff0000, v100
	v_mul_f32_e32 v52, 0xbfb8aa3b, v50
	v_mul_f32_e32 v53, 0xbfb8aa3b, v51
	v_exp_f32_e32 v52, v52
	v_exp_f32_e32 v53, v53
	v_lshlrev_b32_e32 v48, 16, v101
	v_and_b32_e32 v49, 0xffff0000, v101
	v_add_f32_e32 v52, 1.0, v52
	v_add_f32_e32 v53, 1.0, v53
	v_rcp_f32_e32 v52, v52
	v_rcp_f32_e32 v53, v53
	s_nop 0
	v_pk_mul_f32 v[50:51], v[52:53], v[50:51]
	s_nop 0
	v_pk_mul_f32 v[50:51], v[54:55], v[50:51]
	v_pk_mul_f32 v[54:55], v[58:59], v[64:65] op_sel_hi:[1,0]
	v_cvt_pk_bf16_f32 v50, v50, v51
	v_mul_f32_e32 v51, 0xbfb8aa3b, v48
	v_exp_f32_e32 v51, v51
	s_nop 0
	v_add_f32_e32 v51, 1.0, v51
	v_rcp_f32_e32 v52, v51
	v_mul_f32_e32 v51, 0xbfb8aa3b, v49
	v_exp_f32_e32 v51, v51
	s_nop 0
	v_add_f32_e32 v51, 1.0, v51
	v_rcp_f32_e32 v53, v51
	s_nop 0
	v_pk_mul_f32 v[48:49], v[52:53], v[48:49]
	s_nop 0
	v_pk_mul_f32 v[48:49], v[54:55], v[48:49]
	v_pk_mul_f32 v[54:55], v[60:61], v[64:65] op_sel_hi:[1,0]
	v_cvt_pk_bf16_f32 v51, v48, v49
	s_nop 0
	global_store_dwordx2 v[66:67], v[50:51], off offset:2464
	v_lshlrev_b32_e32 v50, 16, v102
	v_and_b32_e32 v51, 0xffff0000, v102
	v_mul_f32_e32 v52, 0xbfb8aa3b, v50
	v_mul_f32_e32 v53, 0xbfb8aa3b, v51
	v_exp_f32_e32 v52, v52
	v_exp_f32_e32 v53, v53
	v_lshlrev_b32_e32 v48, 16, v103
	v_and_b32_e32 v49, 0xffff0000, v103
	v_add_f32_e32 v52, 1.0, v52
	v_add_f32_e32 v53, 1.0, v53
	v_rcp_f32_e32 v52, v52
	v_rcp_f32_e32 v53, v53
	s_nop 0
	v_pk_mul_f32 v[50:51], v[52:53], v[50:51]
	s_nop 0
	v_pk_mul_f32 v[50:51], v[54:55], v[50:51]
	v_pk_mul_f32 v[54:55], v[62:63], v[64:65] op_sel_hi:[1,0]
	v_cvt_pk_bf16_f32 v50, v50, v51
	v_mul_f32_e32 v51, 0xbfb8aa3b, v48
	v_exp_f32_e32 v51, v51
	s_nop 0
	v_add_f32_e32 v51, 1.0, v51
	v_rcp_f32_e32 v52, v51
	v_mul_f32_e32 v51, 0xbfb8aa3b, v49
	v_exp_f32_e32 v51, v51
	s_nop 0
	v_add_f32_e32 v51, 1.0, v51
	v_rcp_f32_e32 v53, v51
	s_nop 0
	v_pk_mul_f32 v[48:49], v[52:53], v[48:49]
	s_nop 0
	v_pk_mul_f32 v[48:49], v[54:55], v[48:49]
	s_nop 0
	v_cvt_pk_bf16_f32 v51, v48, v49
	s_nop 0
	global_store_dwordx2 v[66:67], v[50:51], off offset:2480
	v_lshlrev_b32_e32 v50, 16, v104
	v_and_b32_e32 v51, 0xffff0000, v104
	v_mul_f32_e32 v52, 0xbfb8aa3b, v50
	v_mul_f32_e32 v53, 0xbfb8aa3b, v51
	v_exp_f32_e32 v52, v52
	v_exp_f32_e32 v53, v53
	v_lshlrev_b32_e32 v48, 16, v105
	v_and_b32_e32 v49, 0xffff0000, v105
	v_add_f32_e32 v52, 1.0, v52
	v_add_f32_e32 v53, 1.0, v53
	v_rcp_f32_e32 v52, v52
	v_rcp_f32_e32 v53, v53
	s_nop 0
	v_pk_mul_f32 v[50:51], v[52:53], v[50:51]
	s_nop 0
	v_pk_mul_f32 v[32:33], v[32:33], v[50:51]
	s_nop 0
	v_cvt_pk_bf16_f32 v32, v32, v33
	v_mul_f32_e32 v33, 0xbfb8aa3b, v48
	v_exp_f32_e32 v33, v33
	s_nop 0
	v_add_f32_e32 v33, 1.0, v33
	v_rcp_f32_e32 v50, v33
	v_mul_f32_e32 v33, 0xbfb8aa3b, v49
	v_exp_f32_e32 v33, v33
; DI float bf2f(unsigned v) { return __uint_as_float(v << 16); }
; DI unsigned pack2(float a, float b) { f2_t v = {a, b}; bf2_t r = __builtin_convertvector(v, bf2_t); return __builtin_bit_cast(unsigned, r); }
; DI float silu(float g) { return g * frcp(1.f + fexp(-g)); }
; template <int DQK>
; DI void attn_item_c(const u16* __restrict__ Qp, int ldq, const u16* __restrict__ Kp, const u16* __restrict__ Vtp, int ldv,
;                     int nkt, int q0, float c, u16* Yp, int ldy, char* smem, bool dry) {
;     ...
; #pragma unroll
;     for (int g = 0; g < 4; ++g) {
;       const int d = 32 * dt + 8 * g + 4 * h;
;       uint2 gv = *(const uint2*)(yrow + d);
;       float g0 = bf2f(gv.x & 0xffffu), g1 = bf2f(gv.x >> 16), g2 = bf2f(gv.y & 0xffffu), g3 = bf2f(gv.y >> 16);
;       uint2 ov;
;       ov.x = pack2(o[dt][4 * g] * inv * silu(g0), o[dt][4 * g + 1] * inv * silu(g1));
;       ov.y = pack2(o[dt][4 * g + 2] * inv * silu(g2), o[dt][4 * g + 3] * inv * silu(g3));
;       *(uint2*)(yrow + d) = ov;
;     }
	s_nop 0
	v_add_f32_e32 v33, 1.0, v33
	v_rcp_f32_e32 v51, v33
	s_nop 0
	v_pk_mul_f32 v[48:49], v[50:51], v[48:49]
	s_nop 0
	v_pk_mul_f32 v[34:35], v[34:35], v[48:49]
	s_nop 0
	v_cvt_pk_bf16_f32 v33, v34, v35
	global_store_dwordx2 v[66:67], v[32:33], off offset:2496
	v_lshlrev_b32_e32 v34, 16, v106
	v_and_b32_e32 v35, 0xffff0000, v106
	v_mul_f32_e32 v48, 0xbfb8aa3b, v34
	v_mul_f32_e32 v49, 0xbfb8aa3b, v35
	v_exp_f32_e32 v48, v48
	v_exp_f32_e32 v49, v49
	v_lshlrev_b32_e32 v32, 16, v107
	v_and_b32_e32 v33, 0xffff0000, v107
	v_add_f32_e32 v48, 1.0, v48
	v_add_f32_e32 v49, 1.0, v49
	v_rcp_f32_e32 v48, v48
	v_rcp_f32_e32 v49, v49
	s_nop 0
	v_pk_mul_f32 v[34:35], v[48:49], v[34:35]
	s_nop 0
	v_pk_mul_f32 v[34:35], v[36:37], v[34:35]
	s_nop 0
	v_cvt_pk_bf16_f32 v34, v34, v35
	v_mul_f32_e32 v35, 0xbfb8aa3b, v32
	v_exp_f32_e32 v35, v35
	s_nop 0
	v_add_f32_e32 v35, 1.0, v35
	v_rcp_f32_e32 v36, v35
	v_mul_f32_e32 v35, 0xbfb8aa3b, v33
	v_exp_f32_e32 v35, v35
	s_nop 0
	v_add_f32_e32 v35, 1.0, v35
	v_rcp_f32_e32 v37, v35
	s_nop 0
	v_pk_mul_f32 v[32:33], v[36:37], v[32:33]
	s_nop 0
	v_pk_mul_f32 v[32:33], v[38:39], v[32:33]
	v_pk_mul_f32 v[38:39], v[40:41], v[64:65] op_sel_hi:[1,0]
	v_cvt_pk_bf16_f32 v35, v32, v33
	s_nop 0
	global_store_dwordx2 v[66:67], v[34:35], off offset:2512
	v_lshlrev_b32_e32 v34, 16, v108
	v_and_b32_e32 v35, 0xffff0000, v108
	v_mul_f32_e32 v36, 0xbfb8aa3b, v34
	v_mul_f32_e32 v37, 0xbfb8aa3b, v35
	v_exp_f32_e32 v36, v36
	v_exp_f32_e32 v37, v37
	v_lshlrev_b32_e32 v32, 16, v109
	v_and_b32_e32 v33, 0xffff0000, v109
	v_add_f32_e32 v36, 1.0, v36
	v_add_f32_e32 v37, 1.0, v37
	v_rcp_f32_e32 v36, v36
	v_rcp_f32_e32 v37, v37
	s_nop 0
	v_pk_mul_f32 v[34:35], v[36:37], v[34:35]
	s_nop 0
	v_pk_mul_f32 v[34:35], v[38:39], v[34:35]
	v_pk_mul_f32 v[38:39], v[42:43], v[64:65] op_sel_hi:[1,0]
	v_cvt_pk_bf16_f32 v34, v34, v35
	v_mul_f32_e32 v35, 0xbfb8aa3b, v32
	v_exp_f32_e32 v35, v35
	s_nop 0
	v_add_f32_e32 v35, 1.0, v35
	v_rcp_f32_e32 v36, v35
	v_mul_f32_e32 v35, 0xbfb8aa3b, v33
	v_exp_f32_e32 v35, v35
	s_nop 0
	v_add_f32_e32 v35, 1.0, v35
	v_rcp_f32_e32 v37, v35
	s_nop 0
	v_pk_mul_f32 v[32:33], v[36:37], v[32:33]
	s_nop 0
	v_pk_mul_f32 v[32:33], v[38:39], v[32:33]
	v_pk_mul_f32 v[38:39], v[44:45], v[64:65] op_sel_hi:[1,0]
	v_cvt_pk_bf16_f32 v35, v32, v33
	s_nop 0
	global_store_dwordx2 v[66:67], v[34:35], off offset:2528
	v_lshlrev_b32_e32 v34, 16, v110
	v_and_b32_e32 v35, 0xffff0000, v110
	v_mul_f32_e32 v36, 0xbfb8aa3b, v34
	v_mul_f32_e32 v37, 0xbfb8aa3b, v35
	v_exp_f32_e32 v36, v36
	v_exp_f32_e32 v37, v37
	v_lshlrev_b32_e32 v32, 16, v111
	v_and_b32_e32 v33, 0xffff0000, v111
	v_add_f32_e32 v36, 1.0, v36
	v_add_f32_e32 v37, 1.0, v37
	v_rcp_f32_e32 v36, v36
	v_rcp_f32_e32 v37, v37
	s_nop 0
	v_pk_mul_f32 v[34:35], v[36:37], v[34:35]
	s_nop 0
	v_pk_mul_f32 v[34:35], v[38:39], v[34:35]
	v_pk_mul_f32 v[38:39], v[46:47], v[64:65] op_sel_hi:[1,0]
	v_cvt_pk_bf16_f32 v34, v34, v35
	v_mul_f32_e32 v35, 0xbfb8aa3b, v32
	v_exp_f32_e32 v35, v35
	s_nop 0
	v_add_f32_e32 v35, 1.0, v35
	v_rcp_f32_e32 v36, v35
	v_mul_f32_e32 v35, 0xbfb8aa3b, v33
	v_exp_f32_e32 v35, v35
	s_nop 0
	v_add_f32_e32 v35, 1.0, v35
	v_rcp_f32_e32 v37, v35
	s_nop 0
	v_pk_mul_f32 v[32:33], v[36:37], v[32:33]
	s_nop 0
	v_pk_mul_f32 v[32:33], v[38:39], v[32:33]
	s_nop 0
	v_cvt_pk_bf16_f32 v35, v32, v33
	s_nop 0
	global_store_dwordx2 v[66:67], v[34:35], off offset:2544
	v_lshlrev_b32_e32 v34, 16, v112
	v_and_b32_e32 v35, 0xffff0000, v112
	v_mul_f32_e32 v36, 0xbfb8aa3b, v34
	v_mul_f32_e32 v37, 0xbfb8aa3b, v35
	v_exp_f32_e32 v36, v36
	v_exp_f32_e32 v37, v37
	v_lshlrev_b32_e32 v32, 16, v113
	v_and_b32_e32 v33, 0xffff0000, v113
	v_add_f32_e32 v36, 1.0, v36
	v_add_f32_e32 v37, 1.0, v37
	v_rcp_f32_e32 v36, v36
	v_rcp_f32_e32 v37, v37
	s_nop 0
	v_pk_mul_f32 v[34:35], v[36:37], v[34:35]
	s_nop 0
	v_pk_mul_f32 v[16:17], v[16:17], v[34:35]
	s_nop 0
	v_cvt_pk_bf16_f32 v16, v16, v17
	v_mul_f32_e32 v17, 0xbfb8aa3b, v32
	v_exp_f32_e32 v17, v17
	s_nop 0
	v_add_f32_e32 v17, 1.0, v17
	v_rcp_f32_e32 v34, v17
	v_mul_f32_e32 v17, 0xbfb8aa3b, v33
	v_exp_f32_e32 v17, v17
	s_nop 0
	v_add_f32_e32 v17, 1.0, v17
	v_rcp_f32_e32 v35, v17
	s_nop 0
	v_pk_mul_f32 v[32:33], v[34:35], v[32:33]
	s_nop 0
	v_pk_mul_f32 v[18:19], v[18:19], v[32:33]
	s_nop 0
	v_cvt_pk_bf16_f32 v17, v18, v19
	global_store_dwordx2 v[66:67], v[16:17], off offset:2560
	v_lshlrev_b32_e32 v18, 16, v114
	v_and_b32_e32 v19, 0xffff0000, v114
	v_mul_f32_e32 v32, 0xbfb8aa3b, v18
	v_mul_f32_e32 v33, 0xbfb8aa3b, v19
	v_exp_f32_e32 v32, v32
	v_exp_f32_e32 v33, v33
	v_lshlrev_b32_e32 v16, 16, v115
	v_and_b32_e32 v17, 0xffff0000, v115
	v_add_f32_e32 v32, 1.0, v32
	v_add_f32_e32 v33, 1.0, v33
	v_rcp_f32_e32 v32, v32
	v_rcp_f32_e32 v33, v33
	s_nop 0
	v_pk_mul_f32 v[18:19], v[32:33], v[18:19]
	s_nop 0
	v_pk_mul_f32 v[18:19], v[20:21], v[18:19]
	s_nop 0
	v_cvt_pk_bf16_f32 v18, v18, v19
	v_mul_f32_e32 v19, 0xbfb8aa3b, v16
	v_exp_f32_e32 v19, v19
	s_nop 0
	v_add_f32_e32 v19, 1.0, v19
	v_rcp_f32_e32 v20, v19
	v_mul_f32_e32 v19, 0xbfb8aa3b, v17
	v_exp_f32_e32 v19, v19
	s_nop 0
	v_add_f32_e32 v19, 1.0, v19
	v_rcp_f32_e32 v21, v19
	s_nop 0
	v_pk_mul_f32 v[16:17], v[20:21], v[16:17]
	s_nop 0
	v_pk_mul_f32 v[16:17], v[22:23], v[16:17]
	v_pk_mul_f32 v[22:23], v[24:25], v[64:65] op_sel_hi:[1,0]
	v_cvt_pk_bf16_f32 v19, v16, v17
	s_nop 0
	global_store_dwordx2 v[66:67], v[18:19], off offset:2576
	v_lshlrev_b32_e32 v18, 16, v116
	v_and_b32_e32 v19, 0xffff0000, v116
	v_mul_f32_e32 v20, 0xbfb8aa3b, v18
	v_mul_f32_e32 v21, 0xbfb8aa3b, v19
	v_exp_f32_e32 v20, v20
	v_exp_f32_e32 v21, v21
	v_lshlrev_b32_e32 v16, 16, v117
	v_and_b32_e32 v17, 0xffff0000, v117
	v_add_f32_e32 v20, 1.0, v20
; DI float bf2f(unsigned v) { return __uint_as_float(v << 16); }
; DI unsigned pack2(float a, float b) { f2_t v = {a, b}; bf2_t r = __builtin_convertvector(v, bf2_t); return __builtin_bit_cast(unsigned, r); }
; DI float silu(float g) { return g * frcp(1.f + fexp(-g)); }
; template <int DQK>
; DI void attn_item_c(const u16* __restrict__ Qp, int ldq, const u16* __restrict__ Kp, const u16* __restrict__ Vtp, int ldv,
;                     int nkt, int q0, float c, u16* Yp, int ldy, char* smem, bool dry) {
;     ...
; #pragma unroll
;     for (int g = 0; g < 4; ++g) {
;       const int d = 32 * dt + 8 * g + 4 * h;
;       uint2 gv = *(const uint2*)(yrow + d);
;       float g0 = bf2f(gv.x & 0xffffu), g1 = bf2f(gv.x >> 16), g2 = bf2f(gv.y & 0xffffu), g3 = bf2f(gv.y >> 16);
;       uint2 ov;
;       ov.x = pack2(o[dt][4 * g] * inv * silu(g0), o[dt][4 * g + 1] * inv * silu(g1));
;       ov.y = pack2(o[dt][4 * g + 2] * inv * silu(g2), o[dt][4 * g + 3] * inv * silu(g3));
;       *(uint2*)(yrow + d) = ov;
;     }
	v_add_f32_e32 v21, 1.0, v21
	v_rcp_f32_e32 v20, v20
	v_rcp_f32_e32 v21, v21
	s_nop 0
	v_pk_mul_f32 v[18:19], v[20:21], v[18:19]
	s_nop 0
	v_pk_mul_f32 v[18:19], v[22:23], v[18:19]
	v_pk_mul_f32 v[22:23], v[26:27], v[64:65] op_sel_hi:[1,0]
	v_cvt_pk_bf16_f32 v18, v18, v19
	v_mul_f32_e32 v19, 0xbfb8aa3b, v16
	v_exp_f32_e32 v19, v19
	s_nop 0
	v_add_f32_e32 v19, 1.0, v19
	v_rcp_f32_e32 v20, v19
	v_mul_f32_e32 v19, 0xbfb8aa3b, v17
	v_exp_f32_e32 v19, v19
	s_nop 0
	v_add_f32_e32 v19, 1.0, v19
	v_rcp_f32_e32 v21, v19
	s_nop 0
	v_pk_mul_f32 v[16:17], v[20:21], v[16:17]
	s_nop 0
	v_pk_mul_f32 v[16:17], v[22:23], v[16:17]
	v_pk_mul_f32 v[22:23], v[28:29], v[64:65] op_sel_hi:[1,0]
	v_cvt_pk_bf16_f32 v19, v16, v17
	s_nop 0
	global_store_dwordx2 v[66:67], v[18:19], off offset:2592
	v_lshlrev_b32_e32 v18, 16, v118
	v_and_b32_e32 v19, 0xffff0000, v118
	v_mul_f32_e32 v20, 0xbfb8aa3b, v18
	v_mul_f32_e32 v21, 0xbfb8aa3b, v19
	v_exp_f32_e32 v20, v20
	v_exp_f32_e32 v21, v21
	v_lshlrev_b32_e32 v16, 16, v119
	v_and_b32_e32 v17, 0xffff0000, v119
	v_add_f32_e32 v20, 1.0, v20
	v_add_f32_e32 v21, 1.0, v21
	v_rcp_f32_e32 v20, v20
	v_rcp_f32_e32 v21, v21
	s_nop 0
	v_pk_mul_f32 v[18:19], v[20:21], v[18:19]
	s_nop 0
	v_pk_mul_f32 v[18:19], v[22:23], v[18:19]
	v_pk_mul_f32 v[22:23], v[30:31], v[64:65] op_sel_hi:[1,0]
	v_cvt_pk_bf16_f32 v18, v18, v19
	v_mul_f32_e32 v19, 0xbfb8aa3b, v16
	v_exp_f32_e32 v19, v19
	s_nop 0
	v_add_f32_e32 v19, 1.0, v19
	v_rcp_f32_e32 v20, v19
	v_mul_f32_e32 v19, 0xbfb8aa3b, v17
	v_exp_f32_e32 v19, v19
	s_nop 0
	v_add_f32_e32 v19, 1.0, v19
	v_rcp_f32_e32 v21, v19
	s_nop 0
	v_pk_mul_f32 v[16:17], v[20:21], v[16:17]
	s_nop 0
	v_pk_mul_f32 v[16:17], v[22:23], v[16:17]
	s_nop 0
	v_cvt_pk_bf16_f32 v19, v16, v17
	s_nop 0
	global_store_dwordx2 v[66:67], v[18:19], off offset:2608
	v_lshlrev_b32_e32 v18, 16, v120
	v_and_b32_e32 v19, 0xffff0000, v120
	v_mul_f32_e32 v20, 0xbfb8aa3b, v18
	v_mul_f32_e32 v21, 0xbfb8aa3b, v19
	v_exp_f32_e32 v20, v20
	v_exp_f32_e32 v21, v21
	v_lshlrev_b32_e32 v16, 16, v121
	v_and_b32_e32 v17, 0xffff0000, v121
	v_add_f32_e32 v20, 1.0, v20
	v_add_f32_e32 v21, 1.0, v21
	v_rcp_f32_e32 v20, v20
	v_rcp_f32_e32 v21, v21
	s_nop 0
	v_pk_mul_f32 v[18:19], v[20:21], v[18:19]
	s_nop 0
	v_pk_mul_f32 v[0:1], v[0:1], v[18:19]
	s_nop 0
	v_cvt_pk_bf16_f32 v0, v0, v1
	v_mul_f32_e32 v1, 0xbfb8aa3b, v16
	v_exp_f32_e32 v1, v1
	s_nop 0
	v_add_f32_e32 v1, 1.0, v1
	v_rcp_f32_e32 v18, v1
	v_mul_f32_e32 v1, 0xbfb8aa3b, v17
	v_exp_f32_e32 v1, v1
	s_nop 0
	v_add_f32_e32 v1, 1.0, v1
	v_rcp_f32_e32 v19, v1
	s_nop 0
	v_pk_mul_f32 v[16:17], v[18:19], v[16:17]
	s_nop 0
	v_pk_mul_f32 v[2:3], v[2:3], v[16:17]
	s_nop 0
	v_cvt_pk_bf16_f32 v1, v2, v3
	global_store_dwordx2 v[66:67], v[0:1], off offset:2624
	v_lshlrev_b32_e32 v2, 16, v122
	v_and_b32_e32 v3, 0xffff0000, v122
	v_mul_f32_e32 v16, 0xbfb8aa3b, v2
	v_mul_f32_e32 v17, 0xbfb8aa3b, v3
	v_exp_f32_e32 v16, v16
	v_exp_f32_e32 v17, v17
	v_lshlrev_b32_e32 v0, 16, v123
	v_and_b32_e32 v1, 0xffff0000, v123
	v_add_f32_e32 v16, 1.0, v16
	v_add_f32_e32 v17, 1.0, v17
	v_rcp_f32_e32 v16, v16
	v_rcp_f32_e32 v17, v17
	s_nop 0
	v_pk_mul_f32 v[2:3], v[16:17], v[2:3]
	s_nop 0
	v_pk_mul_f32 v[2:3], v[4:5], v[2:3]
	s_nop 0
	v_cvt_pk_bf16_f32 v2, v2, v3
	v_mul_f32_e32 v3, 0xbfb8aa3b, v0
	v_exp_f32_e32 v3, v3
	s_nop 0
	v_add_f32_e32 v3, 1.0, v3
	v_rcp_f32_e32 v4, v3
	v_mul_f32_e32 v3, 0xbfb8aa3b, v1
	v_exp_f32_e32 v3, v3
	s_nop 0
	v_add_f32_e32 v3, 1.0, v3
	v_rcp_f32_e32 v5, v3
	s_nop 0
	v_pk_mul_f32 v[0:1], v[4:5], v[0:1]
	s_nop 0
	v_pk_mul_f32 v[0:1], v[6:7], v[0:1]
	v_pk_mul_f32 v[6:7], v[8:9], v[64:65] op_sel_hi:[1,0]
	v_cvt_pk_bf16_f32 v3, v0, v1
	s_nop 0
	global_store_dwordx2 v[66:67], v[2:3], off offset:2640
	v_lshlrev_b32_e32 v2, 16, v124
	v_and_b32_e32 v3, 0xffff0000, v124
	v_mul_f32_e32 v4, 0xbfb8aa3b, v2
	v_mul_f32_e32 v5, 0xbfb8aa3b, v3
	v_exp_f32_e32 v4, v4
	v_exp_f32_e32 v5, v5
	v_lshlrev_b32_e32 v0, 16, v125
	v_and_b32_e32 v1, 0xffff0000, v125
	v_add_f32_e32 v4, 1.0, v4
	v_add_f32_e32 v5, 1.0, v5
	v_rcp_f32_e32 v4, v4
	v_rcp_f32_e32 v5, v5
	s_nop 0
	v_pk_mul_f32 v[2:3], v[4:5], v[2:3]
	s_nop 0
	v_pk_mul_f32 v[2:3], v[6:7], v[2:3]
	v_pk_mul_f32 v[6:7], v[10:11], v[64:65] op_sel_hi:[1,0]
	v_cvt_pk_bf16_f32 v2, v2, v3
	v_mul_f32_e32 v3, 0xbfb8aa3b, v0
	v_exp_f32_e32 v3, v3
	s_nop 0
	v_add_f32_e32 v3, 1.0, v3
	v_rcp_f32_e32 v4, v3
	v_mul_f32_e32 v3, 0xbfb8aa3b, v1
	v_exp_f32_e32 v3, v3
	s_nop 0
	v_add_f32_e32 v3, 1.0, v3
	v_rcp_f32_e32 v5, v3
	s_nop 0
	v_pk_mul_f32 v[0:1], v[4:5], v[0:1]
	s_nop 0
	v_pk_mul_f32 v[0:1], v[6:7], v[0:1]
	v_pk_mul_f32 v[6:7], v[12:13], v[64:65] op_sel_hi:[1,0]
	v_cvt_pk_bf16_f32 v3, v0, v1
	s_nop 0
	global_store_dwordx2 v[66:67], v[2:3], off offset:2656
	v_lshlrev_b32_e32 v2, 16, v126
	v_and_b32_e32 v3, 0xffff0000, v126
	v_mul_f32_e32 v4, 0xbfb8aa3b, v2
	v_mul_f32_e32 v5, 0xbfb8aa3b, v3
	v_exp_f32_e32 v4, v4
	v_exp_f32_e32 v5, v5
	v_lshlrev_b32_e32 v0, 16, v127
	v_and_b32_e32 v1, 0xffff0000, v127
	v_add_f32_e32 v4, 1.0, v4
	v_add_f32_e32 v5, 1.0, v5
	v_rcp_f32_e32 v4, v4
	v_rcp_f32_e32 v5, v5
	s_nop 0
	v_pk_mul_f32 v[2:3], v[4:5], v[2:3]
	s_nop 0
	v_pk_mul_f32 v[2:3], v[6:7], v[2:3]
	v_pk_mul_f32 v[6:7], v[14:15], v[64:65] op_sel_hi:[1,0]
	v_cvt_pk_bf16_f32 v2, v2, v3
	v_mul_f32_e32 v3, 0xbfb8aa3b, v0
	v_exp_f32_e32 v3, v3
	s_nop 0
	v_add_f32_e32 v3, 1.0, v3
	v_rcp_f32_e32 v4, v3
	v_mul_f32_e32 v3, 0xbfb8aa3b, v1
	v_exp_f32_e32 v3, v3
	s_nop 0
	v_add_f32_e32 v3, 1.0, v3
	v_rcp_f32_e32 v5, v3
	s_nop 0
	v_pk_mul_f32 v[0:1], v[4:5], v[0:1]
	s_nop 0
	v_pk_mul_f32 v[0:1], v[6:7], v[0:1]
	s_nop 0
	v_cvt_pk_bf16_f32 v3, v0, v1
	global_store_dwordx2 v[66:67], v[2:3], off offset:2672
	s_branch .LBB0_251

; #define MFMA32(a, b, c) __builtin_amdgcn_mfma_f32_32x32x16_bf16((a), (b), (c), 0, 0, 0)
; DI unsigned pack2(float a, float b) { f2_t v = {a, b}; bf2_t r = __builtin_convertvector(v, bf2_t); return __builtin_bit_cast(unsigned, r); }
; DI float ex2(float x) { return __builtin_amdgcn_exp2f(x); }
; template <int DQK>
; DI void attn_item(const u16* __restrict__ Qp, int ldq, const u16* __restrict__ Kp, const u16* __restrict__ Vtp, int ldv,
;                   int nkt, int q0, bool causal, float c, u16* Yp, int ldy, char* smem, bool dry) {
;     ...
;       const float mc = m * c;
;       float ps = 0.f;
; #pragma unroll
;       for (int e = 0; e < 16; ++e) { s0[e] = ex2(fmaf(s0[e], c, -mc)); s1[e] = ex2(fmaf(s1[e], c, -mc)); ps += s0[e] + s1[e]; }
;       l += ps;
;       bf16x8 pf[4];
;       {
;         u32x4 t;
;         t.x = pack2(s0[0], s0[1]); t.y = pack2(s0[2], s0[3]); t.z = pack2(s0[4], s0[5]); t.w = pack2(s0[6], s0[7]); pf[0] = __builtin_bit_cast(bf16x8, t);
;         t.x = pack2(s0[8], s0[9]); t.y = pack2(s0[10], s0[11]); t.z = pack2(s0[12], s0[13]); t.w = pack2(s0[14], s0[15]); pf[1] = __builtin_bit_cast(bf16x8, t);
;         t.x = pack2(s1[0], s1[1]); t.y = pack2(s1[2], s1[3]); t.z = pack2(s1[4], s1[5]); t.w = pack2(s1[6], s1[7]); pf[2] = __builtin_bit_cast(bf16x8, t);
;         t.x = pack2(s1[8], s1[9]); t.y = pack2(s1[10], s1[11]); t.z = pack2(s1[12], s1[13]); t.w = pack2(s1[14], s1[15]); pf[3] = __builtin_bit_cast(bf16x8, t);
;       }
; #pragma unroll
;       for (int kk = 0; kk < 4; ++kk) {
;         if (kk < 3) {
; #pragma unroll
;           for (int dt = 0; dt < 4; ++dt) va[(kk + 1) & 1][dt] = *(const bf16x8*)(v0 + (32 * dt) * 72 + 16 * (kk + 1));
;         }
;         __builtin_amdgcn_sched_barrier(0);
; #pragma unroll
;         for (int dt = 0; dt < 4; ++dt) o[dt] = MFMA32(va[kk & 1][dt], pf[kk], o[dt]);
;         __builtin_amdgcn_sched_barrier(0);
;       }
;     }
;     __syncthreads();
;   }
.LBB0_318:
	v_fmamk_f32 v0, v112, 0x3e0293ee, v149
	v_fmamk_f32 v1, v113, 0x3e0293ee, v149
	v_exp_f32_e32 v0, v0
	v_exp_f32_e32 v8, v1
	v_fmamk_f32 v2, v111, 0x3e0293ee, v149
	v_fmamk_f32 v3, v110, 0x3e0293ee, v149
	v_exp_f32_e32 v2, v2
	v_exp_f32_e32 v9, v3
	v_add_f32_e32 v1, v0, v8
	v_add_f32_e32 v1, 0, v1
	v_fmamk_f32 v4, v108, 0x3e0293ee, v149
	v_add_f32_e32 v3, v2, v9
	v_add_f32_e32 v1, v3, v1
	v_fmamk_f32 v3, v109, 0x3e0293ee, v149
	v_exp_f32_e32 v3, v3
	v_exp_f32_e32 v10, v4
	v_fmamk_f32 v5, v106, 0x3e0293ee, v149
	v_exp_f32_e32 v11, v5
	v_fmamk_f32 v6, v104, 0x3e0293ee, v149
	v_add_f32_e32 v4, v3, v10
	v_add_f32_e32 v1, v4, v1
	v_fmamk_f32 v4, v107, 0x3e0293ee, v149
	v_exp_f32_e32 v4, v4
	v_exp_f32_e32 v12, v6
	v_fmamk_f32 v7, v102, 0x3e0293ee, v149
	v_exp_f32_e32 v13, v7
	v_add_f32_e32 v5, v4, v11
	v_add_f32_e32 v1, v5, v1
	v_fmamk_f32 v5, v105, 0x3e0293ee, v149
	v_exp_f32_e32 v5, v5
	v_fmamk_f32 v14, v100, 0x3e0293ee, v149
	v_exp_f32_e32 v14, v14
	v_fmamk_f32 v16, v98, 0x3e0293ee, v149
	v_add_f32_e32 v6, v5, v12
	v_add_f32_e32 v1, v6, v1
	v_fmamk_f32 v6, v103, 0x3e0293ee, v149
	v_exp_f32_e32 v6, v6
	v_exp_f32_e32 v16, v16
	v_fmamk_f32 v18, v94, 0x3e0293ee, v149
	v_exp_f32_e32 v18, v18
	v_add_f32_e32 v7, v6, v13
	v_add_f32_e32 v1, v7, v1
	v_fmamk_f32 v7, v101, 0x3e0293ee, v149
	v_exp_f32_e32 v7, v7
	v_fmamk_f32 v20, v92, 0x3e0293ee, v149
	v_exp_f32_e32 v20, v20
	v_fmamk_f32 v22, v90, 0x3e0293ee, v149
	v_add_f32_e32 v15, v7, v14
	v_add_f32_e32 v1, v15, v1
	v_fmamk_f32 v15, v99, 0x3e0293ee, v149
	v_exp_f32_e32 v15, v15
	v_exp_f32_e32 v22, v22
	v_fmamk_f32 v24, v88, 0x3e0293ee, v149
	v_exp_f32_e32 v24, v24
	v_add_f32_e32 v17, v15, v16
	v_add_f32_e32 v1, v17, v1
	v_fmamk_f32 v17, v95, 0x3e0293ee, v149
	v_exp_f32_e32 v17, v17
	v_fmamk_f32 v26, v86, 0x3e0293ee, v149
	v_exp_f32_e32 v26, v26
	v_fmamk_f32 v28, v84, 0x3e0293ee, v149
	v_add_f32_e32 v19, v17, v18
	v_add_f32_e32 v1, v19, v1
	v_fmamk_f32 v19, v93, 0x3e0293ee, v149
	v_exp_f32_e32 v19, v19
	v_exp_f32_e32 v28, v28
	v_fmamk_f32 v30, v82, 0x3e0293ee, v149
	v_exp_f32_e32 v30, v30
	v_add_f32_e32 v21, v19, v20
	v_add_f32_e32 v1, v21, v1
	v_fmamk_f32 v21, v91, 0x3e0293ee, v149
	v_exp_f32_e32 v21, v21
	v_cvt_pk_bf16_f32 v0, v0, v2
	v_cvt_pk_bf16_f32 v2, v5, v6
	v_cvt_pk_bf16_f32 v8, v8, v9
	v_add_f32_e32 v23, v21, v22
	v_add_f32_e32 v1, v23, v1
	v_fmamk_f32 v23, v89, 0x3e0293ee, v149
	v_exp_f32_e32 v23, v23
	v_cvt_pk_bf16_f32 v9, v10, v11
	v_cvt_pk_bf16_f32 v10, v12, v13
	v_cvt_pk_bf16_f32 v11, v14, v16
	v_add_f32_e32 v25, v23, v24
	v_add_f32_e32 v1, v25, v1
	v_fmamk_f32 v25, v87, 0x3e0293ee, v149
	v_exp_f32_e32 v25, v25
	v_cvt_pk_bf16_f32 v5, v21, v23
	v_cvt_pk_bf16_f32 v12, v18, v20
	v_cvt_pk_bf16_f32 v13, v22, v24
	v_add_f32_e32 v27, v25, v26
	v_add_f32_e32 v1, v27, v1
	v_fmamk_f32 v27, v85, 0x3e0293ee, v149
	v_exp_f32_e32 v27, v27
	v_cvt_pk_bf16_f32 v14, v26, v28
	v_add_f32_e32 v29, v27, v28
	v_add_f32_e32 v1, v29, v1
	v_fmamk_f32 v29, v83, 0x3e0293ee, v149
	v_exp_f32_e32 v29, v29
	v_cvt_pk_bf16_f32 v6, v25, v27
	v_add_f32_e32 v31, v29, v30
	v_add_f32_e32 v1, v31, v1
	v_fmamk_f32 v31, v81, 0x3e0293ee, v149
	v_fmac_f32_e32 v149, 0x3e0293ee, v80
	v_exp_f32_e32 v31, v31
	v_exp_f32_e32 v32, v149
	s_nop 0
	v_add_f32_e32 v33, v31, v32
	v_add_f32_e32 v44, v33, v1
	v_cvt_pk_bf16_f32 v1, v3, v4
	v_cvt_pk_bf16_f32 v3, v7, v15
	v_cvt_pk_bf16_f32 v4, v17, v19
	v_cvt_pk_bf16_f32 v7, v29, v31
	v_cvt_pk_bf16_f32 v15, v30, v32
	ds_read_b128 v[16:19], v152 offset:53280
	ds_read_b128 v[20:23], v152 offset:57888
	ds_read_b128 v[24:27], v152 offset:62496
	ds_read_b128 v[28:31], v153 offset:13856
	s_waitcnt lgkmcnt(7)
	v_mfma_f32_32x32x16_bf16 a[16:31], v[76:79], v[0:3], a[16:31]
	s_waitcnt lgkmcnt(6)
	v_mfma_f32_32x32x16_bf16 a[32:47], v[72:75], v[0:3], a[32:47]
	s_waitcnt lgkmcnt(5)
	v_mfma_f32_32x32x16_bf16 a[48:63], v[68:71], v[0:3], a[48:63]
	s_waitcnt lgkmcnt(4)
	v_mfma_f32_32x32x16_bf16 a[0:15], v[64:67], v[0:3], a[0:15]
	ds_read_b128 v[0:3], v152 offset:53312
	ds_read_b128 v[32:35], v152 offset:57920
	ds_read_b128 v[36:39], v152 offset:62528
	ds_read_b128 v[40:43], v153 offset:13888
	s_waitcnt lgkmcnt(7)
	v_mfma_f32_32x32x16_bf16 a[16:31], v[16:19], v[4:7], a[16:31]
	s_waitcnt lgkmcnt(6)
	v_mfma_f32_32x32x16_bf16 a[32:47], v[20:23], v[4:7], a[32:47]
	s_waitcnt lgkmcnt(5)
	v_mfma_f32_32x32x16_bf16 a[48:63], v[24:27], v[4:7], a[48:63]
	s_waitcnt lgkmcnt(4)
	v_mfma_f32_32x32x16_bf16 a[0:15], v[28:31], v[4:7], a[0:15]
	ds_read_b128 v[4:7], v152 offset:53344
	ds_read_b128 v[16:19], v152 offset:57952
	ds_read_b128 v[20:23], v152 offset:62560
	ds_read_b128 v[24:27], v153 offset:13920
	s_waitcnt lgkmcnt(7)
	v_mfma_f32_32x32x16_bf16 a[16:31], v[0:3], v[8:11], a[16:31]
	s_waitcnt lgkmcnt(6)
	v_mfma_f32_32x32x16_bf16 a[32:47], v[32:35], v[8:11], a[32:47]
	s_waitcnt lgkmcnt(5)
	v_mfma_f32_32x32x16_bf16 a[48:63], v[36:39], v[8:11], a[48:63]
	s_waitcnt lgkmcnt(4)
	v_mfma_f32_32x32x16_bf16 a[0:15], v[40:43], v[8:11], a[0:15]
	s_waitcnt lgkmcnt(3)
	v_mfma_f32_32x32x16_bf16 a[16:31], v[4:7], v[12:15], a[16:31]
	s_waitcnt lgkmcnt(2)
	v_mfma_f32_32x32x16_bf16 a[32:47], v[16:19], v[12:15], a[32:47]
	s_waitcnt lgkmcnt(1)
	v_mfma_f32_32x32x16_bf16 a[48:63], v[20:23], v[12:15], a[48:63]
	s_waitcnt lgkmcnt(0)
	v_mfma_f32_32x32x16_bf16 a[0:15], v[24:27], v[12:15], a[0:15]
	v_add_f32_e32 v64, v96, v44
	ds_bpermute_b32 v65, v151, v64
	v_readlane_b32 s0, v255, 20
	v_readlane_b32 s1, v255, 21
	s_andn2_b64 vcc, exec, s[0:1]
	s_waitcnt lgkmcnt(0)
	s_barrier
	s_cbranch_vccnz .LBB0_305
; DI float bf2f(unsigned v) { return __uint_as_float(v << 16); }
; DI unsigned pack2(float a, float b) { f2_t v = {a, b}; bf2_t r = __builtin_convertvector(v, bf2_t); return __builtin_bit_cast(unsigned, r); }
; DI float silu(float g) { return g * frcp(1.f + fexp(-g)); }
; template <int DQK>
; DI void attn_item(const u16* __restrict__ Qp, int ldq, const u16* __restrict__ Kp, const u16* __restrict__ Vtp, int ldv,
;                   int nkt, int q0, bool causal, float c, u16* Yp, int ldy, char* smem, bool dry) {
;     ...
;   const float lt = l + __shfl_xor(l, 32);
;   const float inv = 1.f / lt;
;   if (dry) return;
;   u16* yrow = Yp + (size_t)(32 * w + r) * ldy;
; #pragma unroll
;   for (int dt = 0; dt < 4; ++dt)
; #pragma unroll
;     for (int g = 0; g < 4; ++g) {
;       const int d = 32 * dt + 8 * g + 4 * h;
;       uint2 gv = *(const uint2*)(yrow + d);
;       float g0 = bf2f(gv.x & 0xffffu), g1 = bf2f(gv.x >> 16), g2 = bf2f(gv.y & 0xffffu), g3 = bf2f(gv.y >> 16);
;       uint2 ov;
;       ov.x = pack2(o[dt][4 * g] * inv * silu(g0), o[dt][4 * g + 1] * inv * silu(g1));
;       ov.y = pack2(o[dt][4 * g + 2] * inv * silu(g2), o[dt][4 * g + 3] * inv * silu(g3));
;       *(uint2*)(yrow + d) = ov;
;     }
	v_readlane_b32 s1, v254, 30
	s_lshl_b32 s0, s8, 7
	s_lshl_b32 s1, s1, 1
	s_add_u32 s1, s9, s1
	s_addc_u32 s6, s10, 0
	s_lshl_b32 s0, s0, 1
	s_add_u32 s0, s1, s0
	v_add_f32_e32 v64, v64, v65
	s_addc_u32 s1, s6, 0
	v_div_scale_f32 v65, s[6:7], v64, v64, 1.0
	v_rcp_f32_e32 v66, v65
	v_lshlrev_b32_e32 v198, 3, v150
	v_accvgpr_read_b32 v63, a31
	v_accvgpr_read_b32 v49, a17
	v_fma_f32 v67, -v65, v66, 1.0
	v_fmac_f32_e32 v66, v67, v66
	v_div_scale_f32 v67, vcc, 1.0, v64, 1.0
	v_mul_f32_e32 v68, v67, v66
	v_fma_f32 v69, -v65, v68, v67
	v_fmac_f32_e32 v68, v69, v66
	v_fma_f32 v65, -v65, v68, v67
	v_div_fmas_f32 v65, v65, v66, v68
	v_lshl_add_u64 v[66:67], v[146:147], 1, s[0:1]
	v_lshl_add_u64 v[66:67], v[66:67], 0, v[198:199]
	global_load_dwordx2 v[98:99], v[66:67], off offset:3072
	global_load_dwordx2 v[100:101], v[66:67], off offset:3088
	global_load_dwordx2 v[102:103], v[66:67], off offset:3104
	global_load_dwordx2 v[104:105], v[66:67], off offset:3120
	global_load_dwordx2 v[106:107], v[66:67], off offset:3136
	global_load_dwordx2 v[108:109], v[66:67], off offset:3152
	global_load_dwordx2 v[110:111], v[66:67], off offset:3168
	global_load_dwordx2 v[112:113], v[66:67], off offset:3184
	global_load_dwordx2 v[114:115], v[66:67], off offset:3200
	global_load_dwordx2 v[116:117], v[66:67], off offset:3216
	global_load_dwordx2 v[118:119], v[66:67], off offset:3232
	global_load_dwordx2 v[120:121], v[66:67], off offset:3248
	global_load_dwordx2 v[122:123], v[66:67], off offset:3264
	global_load_dwordx2 v[124:125], v[66:67], off offset:3280
	global_load_dwordx2 v[126:127], v[66:67], off offset:3296
	global_load_dwordx2 v[128:129], v[66:67], off offset:3312
	v_div_fixup_f32 v64, v65, v64, 1.0
	v_accvgpr_read_b32 v48, a16
	v_accvgpr_read_b32 v51, a19
	v_accvgpr_read_b32 v50, a18
	v_accvgpr_read_b32 v53, a21
	v_accvgpr_read_b32 v52, a20
	v_accvgpr_read_b32 v55, a23
	v_accvgpr_read_b32 v54, a22
	v_accvgpr_read_b32 v57, a25
	v_accvgpr_read_b32 v56, a24
	v_accvgpr_read_b32 v59, a27
	v_accvgpr_read_b32 v58, a26
	v_accvgpr_read_b32 v61, a29
	v_accvgpr_read_b32 v60, a28
	v_accvgpr_read_b32 v62, a30
	v_accvgpr_read_b32 v32, a32
	v_accvgpr_read_b32 v33, a33
	v_accvgpr_read_b32 v34, a34
	v_accvgpr_read_b32 v35, a35
	v_accvgpr_read_b32 v36, a36
	v_accvgpr_read_b32 v37, a37
	v_accvgpr_read_b32 v38, a38
	v_accvgpr_read_b32 v39, a39
	v_accvgpr_read_b32 v40, a40
	v_accvgpr_read_b32 v41, a41
	v_accvgpr_read_b32 v42, a42
	v_accvgpr_read_b32 v43, a43
	v_accvgpr_read_b32 v44, a44
	v_accvgpr_read_b32 v45, a45
	v_accvgpr_read_b32 v46, a46
	v_accvgpr_read_b32 v47, a47
	v_accvgpr_read_b32 v16, a48
	v_accvgpr_read_b32 v17, a49
	v_accvgpr_read_b32 v18, a50
	v_accvgpr_read_b32 v19, a51
	v_accvgpr_read_b32 v20, a52
	v_accvgpr_read_b32 v21, a53
	v_accvgpr_read_b32 v22, a54
	v_accvgpr_read_b32 v23, a55
	v_accvgpr_read_b32 v24, a56
	v_accvgpr_read_b32 v25, a57
	v_accvgpr_read_b32 v26, a58
	v_accvgpr_read_b32 v27, a59
	v_accvgpr_read_b32 v28, a60
	v_accvgpr_read_b32 v29, a61
	v_accvgpr_read_b32 v30, a62
	v_accvgpr_read_b32 v31, a63
	v_accvgpr_read_b32 v0, a0
	v_accvgpr_read_b32 v1, a1
	v_accvgpr_read_b32 v2, a2
	v_accvgpr_read_b32 v3, a3
	v_accvgpr_read_b32 v4, a4
	v_accvgpr_read_b32 v5, a5
	v_accvgpr_read_b32 v6, a6
	v_accvgpr_read_b32 v7, a7
	v_accvgpr_read_b32 v8, a8
	v_accvgpr_read_b32 v9, a9
	v_accvgpr_read_b32 v10, a10
	v_accvgpr_read_b32 v11, a11
	v_accvgpr_read_b32 v12, a12
	v_accvgpr_read_b32 v13, a13
	v_accvgpr_read_b32 v14, a14
	v_accvgpr_read_b32 v15, a15
	s_waitcnt vmcnt(0)
	v_lshlrev_b32_e32 v70, 16, v98
	v_mul_f32_e32 v65, 0xbfb8aa3b, v70
	v_exp_f32_e32 v65, v65
	v_and_b32_e32 v71, 0xffff0000, v98
	v_lshlrev_b32_e32 v68, 16, v99
	v_and_b32_e32 v69, 0xffff0000, v99
	v_add_f32_e32 v65, 1.0, v65
	v_rcp_f32_e32 v72, v65
	v_pk_mul_f32 v[48:49], v[48:49], v[64:65] op_sel_hi:[1,0]
	v_mul_f32_e32 v65, 0xbfb8aa3b, v71
	v_exp_f32_e32 v65, v65
	s_nop 0
	v_add_f32_e32 v65, 1.0, v65
	v_rcp_f32_e32 v73, v65
	v_pk_mul_f32 v[50:51], v[50:51], v[64:65] op_sel_hi:[1,0]
	v_pk_mul_f32 v[70:71], v[72:73], v[70:71]
	s_nop 0
	v_pk_mul_f32 v[48:49], v[48:49], v[70:71]
	s_nop 0
	v_cvt_pk_bf16_f32 v48, v48, v49
	v_mul_f32_e32 v49, 0xbfb8aa3b, v68
	v_exp_f32_e32 v49, v49
	s_nop 0
	v_add_f32_e32 v49, 1.0, v49
	v_rcp_f32_e32 v70, v49
	v_mul_f32_e32 v49, 0xbfb8aa3b, v69
	v_exp_f32_e32 v49, v49
	s_nop 0
	v_add_f32_e32 v49, 1.0, v49
	v_rcp_f32_e32 v71, v49
	s_nop 0
	v_pk_mul_f32 v[68:69], v[70:71], v[68:69]
	s_nop 0
	v_pk_mul_f32 v[50:51], v[50:51], v[68:69]
	s_nop 0
	v_cvt_pk_bf16_f32 v49, v50, v51
	global_store_dwordx2 v[66:67], v[48:49], off offset:3072
	v_lshlrev_b32_e32 v50, 16, v100
	v_mul_f32_e32 v65, 0xbfb8aa3b, v50
	v_exp_f32_e32 v65, v65
	v_and_b32_e32 v51, 0xffff0000, v100
	v_lshlrev_b32_e32 v48, 16, v101
	v_and_b32_e32 v49, 0xffff0000, v101
	v_add_f32_e32 v65, 1.0, v65
	v_rcp_f32_e32 v68, v65
	v_pk_mul_f32 v[52:53], v[52:53], v[64:65] op_sel_hi:[1,0]
	v_mul_f32_e32 v65, 0xbfb8aa3b, v51
	v_exp_f32_e32 v65, v65
	s_nop 0
	v_add_f32_e32 v65, 1.0, v65
	v_rcp_f32_e32 v69, v65
	v_pk_mul_f32 v[54:55], v[54:55], v[64:65] op_sel_hi:[1,0]
	v_pk_mul_f32 v[32:33], v[32:33], v[64:65] op_sel_hi:[1,0]
	v_pk_mul_f32 v[34:35], v[34:35], v[64:65] op_sel_hi:[1,0]
	v_pk_mul_f32 v[50:51], v[68:69], v[50:51]
	v_pk_mul_f32 v[36:37], v[36:37], v[64:65] op_sel_hi:[1,0]
	v_pk_mul_f32 v[50:51], v[52:53], v[50:51]
	v_pk_mul_f32 v[38:39], v[38:39], v[64:65] op_sel_hi:[1,0]
	v_cvt_pk_bf16_f32 v50, v50, v51
	v_mul_f32_e32 v51, 0xbfb8aa3b, v48
	v_exp_f32_e32 v51, v51
	v_pk_mul_f32 v[16:17], v[16:17], v[64:65] op_sel_hi:[1,0]
	v_pk_mul_f32 v[18:19], v[18:19], v[64:65] op_sel_hi:[1,0]
	v_pk_mul_f32 v[20:21], v[20:21], v[64:65] op_sel_hi:[1,0]
; DI float bf2f(unsigned v) { return __uint_as_float(v << 16); }
; DI unsigned pack2(float a, float b) { f2_t v = {a, b}; bf2_t r = __builtin_convertvector(v, bf2_t); return __builtin_bit_cast(unsigned, r); }
; DI float silu(float g) { return g * frcp(1.f + fexp(-g)); }
; template <int DQK>
; DI void attn_item(const u16* __restrict__ Qp, int ldq, const u16* __restrict__ Kp, const u16* __restrict__ Vtp, int ldv,
;                   int nkt, int q0, bool causal, float c, u16* Yp, int ldy, char* smem, bool dry) {
;     ...
;   for (int dt = 0; dt < 4; ++dt)
; #pragma unroll
;     for (int g = 0; g < 4; ++g) {
;       const int d = 32 * dt + 8 * g + 4 * h;
;       uint2 gv = *(const uint2*)(yrow + d);
;       float g0 = bf2f(gv.x & 0xffffu), g1 = bf2f(gv.x >> 16), g2 = bf2f(gv.y & 0xffffu), g3 = bf2f(gv.y >> 16);
;       uint2 ov;
;       ov.x = pack2(o[dt][4 * g] * inv * silu(g0), o[dt][4 * g + 1] * inv * silu(g1));
;       ov.y = pack2(o[dt][4 * g + 2] * inv * silu(g2), o[dt][4 * g + 3] * inv * silu(g3));
;       *(uint2*)(yrow + d) = ov;
;     }
	v_add_f32_e32 v51, 1.0, v51
	v_rcp_f32_e32 v52, v51
	v_mul_f32_e32 v51, 0xbfb8aa3b, v49
	v_exp_f32_e32 v51, v51
	v_pk_mul_f32 v[22:23], v[22:23], v[64:65] op_sel_hi:[1,0]
	v_pk_mul_f32 v[0:1], v[0:1], v[64:65] op_sel_hi:[1,0]
	v_pk_mul_f32 v[2:3], v[2:3], v[64:65] op_sel_hi:[1,0]
	v_add_f32_e32 v51, 1.0, v51
	v_rcp_f32_e32 v53, v51
	v_pk_mul_f32 v[4:5], v[4:5], v[64:65] op_sel_hi:[1,0]
	v_pk_mul_f32 v[6:7], v[6:7], v[64:65] op_sel_hi:[1,0]
	v_pk_mul_f32 v[48:49], v[52:53], v[48:49]
	s_nop 0
	v_pk_mul_f32 v[48:49], v[54:55], v[48:49]
	v_pk_mul_f32 v[54:55], v[56:57], v[64:65] op_sel_hi:[1,0]
	v_cvt_pk_bf16_f32 v51, v48, v49
	s_nop 0
	global_store_dwordx2 v[66:67], v[50:51], off offset:3088
	v_lshlrev_b32_e32 v50, 16, v102
	v_and_b32_e32 v51, 0xffff0000, v102
	v_mul_f32_e32 v52, 0xbfb8aa3b, v50
	v_mul_f32_e32 v53, 0xbfb8aa3b, v51
	v_exp_f32_e32 v52, v52
	v_exp_f32_e32 v53, v53
	v_lshlrev_b32_e32 v48, 16, v103
	v_and_b32_e32 v49, 0xffff0000, v103
	v_add_f32_e32 v52, 1.0, v52
	v_add_f32_e32 v53, 1.0, v53
	v_rcp_f32_e32 v52, v52
	v_rcp_f32_e32 v53, v53
	s_nop 0
	v_pk_mul_f32 v[50:51], v[52:53], v[50:51]
	s_nop 0
	v_pk_mul_f32 v[50:51], v[54:55], v[50:51]
	v_pk_mul_f32 v[54:55], v[58:59], v[64:65] op_sel_hi:[1,0]
	v_cvt_pk_bf16_f32 v50, v50, v51
	v_mul_f32_e32 v51, 0xbfb8aa3b, v48
	v_exp_f32_e32 v51, v51
	s_nop 0
	v_add_f32_e32 v51, 1.0, v51
	v_rcp_f32_e32 v52, v51
	v_mul_f32_e32 v51, 0xbfb8aa3b, v49
	v_exp_f32_e32 v51, v51
	s_nop 0
	v_add_f32_e32 v51, 1.0, v51
	v_rcp_f32_e32 v53, v51
	s_nop 0
	v_pk_mul_f32 v[48:49], v[52:53], v[48:49]
	s_nop 0
	v_pk_mul_f32 v[48:49], v[54:55], v[48:49]
	v_pk_mul_f32 v[54:55], v[60:61], v[64:65] op_sel_hi:[1,0]
	v_cvt_pk_bf16_f32 v51, v48, v49
	s_nop 0
	global_store_dwordx2 v[66:67], v[50:51], off offset:3104
	v_lshlrev_b32_e32 v50, 16, v104
	v_and_b32_e32 v51, 0xffff0000, v104
	v_mul_f32_e32 v52, 0xbfb8aa3b, v50
	v_mul_f32_e32 v53, 0xbfb8aa3b, v51
	v_exp_f32_e32 v52, v52
	v_exp_f32_e32 v53, v53
	v_lshlrev_b32_e32 v48, 16, v105
	v_and_b32_e32 v49, 0xffff0000, v105
	v_add_f32_e32 v52, 1.0, v52
	v_add_f32_e32 v53, 1.0, v53
	v_rcp_f32_e32 v52, v52
	v_rcp_f32_e32 v53, v53
	s_nop 0
	v_pk_mul_f32 v[50:51], v[52:53], v[50:51]
	s_nop 0
	v_pk_mul_f32 v[50:51], v[54:55], v[50:51]
	v_pk_mul_f32 v[54:55], v[62:63], v[64:65] op_sel_hi:[1,0]
	v_cvt_pk_bf16_f32 v50, v50, v51
	v_mul_f32_e32 v51, 0xbfb8aa3b, v48
	v_exp_f32_e32 v51, v51
	s_nop 0
	v_add_f32_e32 v51, 1.0, v51
	v_rcp_f32_e32 v52, v51
	v_mul_f32_e32 v51, 0xbfb8aa3b, v49
	v_exp_f32_e32 v51, v51
	s_nop 0
	v_add_f32_e32 v51, 1.0, v51
	v_rcp_f32_e32 v53, v51
	s_nop 0
	v_pk_mul_f32 v[48:49], v[52:53], v[48:49]
	s_nop 0
	v_pk_mul_f32 v[48:49], v[54:55], v[48:49]
	s_nop 0
	v_cvt_pk_bf16_f32 v51, v48, v49
	s_nop 0
	global_store_dwordx2 v[66:67], v[50:51], off offset:3120
	v_lshlrev_b32_e32 v50, 16, v106
	v_and_b32_e32 v51, 0xffff0000, v106
	v_mul_f32_e32 v52, 0xbfb8aa3b, v50
	v_mul_f32_e32 v53, 0xbfb8aa3b, v51
	v_exp_f32_e32 v52, v52
	v_exp_f32_e32 v53, v53
	v_lshlrev_b32_e32 v48, 16, v107
	v_and_b32_e32 v49, 0xffff0000, v107
	v_add_f32_e32 v52, 1.0, v52
	v_add_f32_e32 v53, 1.0, v53
	v_rcp_f32_e32 v52, v52
	v_rcp_f32_e32 v53, v53
	s_nop 0
	v_pk_mul_f32 v[50:51], v[52:53], v[50:51]
	s_nop 0
	v_pk_mul_f32 v[32:33], v[32:33], v[50:51]
	s_nop 0
	v_cvt_pk_bf16_f32 v32, v32, v33
	v_mul_f32_e32 v33, 0xbfb8aa3b, v48
	v_exp_f32_e32 v33, v33
	s_nop 0
	v_add_f32_e32 v33, 1.0, v33
	v_rcp_f32_e32 v50, v33
	v_mul_f32_e32 v33, 0xbfb8aa3b, v49
	v_exp_f32_e32 v33, v33
	s_nop 0
	v_add_f32_e32 v33, 1.0, v33
	v_rcp_f32_e32 v51, v33
	s_nop 0
	v_pk_mul_f32 v[48:49], v[50:51], v[48:49]
	s_nop 0
	v_pk_mul_f32 v[34:35], v[34:35], v[48:49]
	s_nop 0
	v_cvt_pk_bf16_f32 v33, v34, v35
	global_store_dwordx2 v[66:67], v[32:33], off offset:3136
	v_lshlrev_b32_e32 v34, 16, v108
	v_and_b32_e32 v35, 0xffff0000, v108
	v_mul_f32_e32 v48, 0xbfb8aa3b, v34
	v_mul_f32_e32 v49, 0xbfb8aa3b, v35
	v_exp_f32_e32 v48, v48
	v_exp_f32_e32 v49, v49
	v_lshlrev_b32_e32 v32, 16, v109
	v_and_b32_e32 v33, 0xffff0000, v109
	v_add_f32_e32 v48, 1.0, v48
	v_add_f32_e32 v49, 1.0, v49
	v_rcp_f32_e32 v48, v48
	v_rcp_f32_e32 v49, v49
	s_nop 0
	v_pk_mul_f32 v[34:35], v[48:49], v[34:35]
	s_nop 0
	v_pk_mul_f32 v[34:35], v[36:37], v[34:35]
	s_nop 0
	v_cvt_pk_bf16_f32 v34, v34, v35
	v_mul_f32_e32 v35, 0xbfb8aa3b, v32
	v_exp_f32_e32 v35, v35
	s_nop 0
	v_add_f32_e32 v35, 1.0, v35
	v_rcp_f32_e32 v36, v35
	v_mul_f32_e32 v35, 0xbfb8aa3b, v33
	v_exp_f32_e32 v35, v35
	s_nop 0
	v_add_f32_e32 v35, 1.0, v35
	v_rcp_f32_e32 v37, v35
	s_nop 0
	v_pk_mul_f32 v[32:33], v[36:37], v[32:33]
	s_nop 0
	v_pk_mul_f32 v[32:33], v[38:39], v[32:33]
	v_pk_mul_f32 v[38:39], v[40:41], v[64:65] op_sel_hi:[1,0]
	v_cvt_pk_bf16_f32 v35, v32, v33
	s_nop 0
	global_store_dwordx2 v[66:67], v[34:35], off offset:3152
	v_lshlrev_b32_e32 v34, 16, v110
	v_and_b32_e32 v35, 0xffff0000, v110
	v_mul_f32_e32 v36, 0xbfb8aa3b, v34
	v_mul_f32_e32 v37, 0xbfb8aa3b, v35
	v_exp_f32_e32 v36, v36
	v_exp_f32_e32 v37, v37
	v_lshlrev_b32_e32 v32, 16, v111
	v_and_b32_e32 v33, 0xffff0000, v111
	v_add_f32_e32 v36, 1.0, v36
	v_add_f32_e32 v37, 1.0, v37
	v_rcp_f32_e32 v36, v36
	v_rcp_f32_e32 v37, v37
	s_nop 0
	v_pk_mul_f32 v[34:35], v[36:37], v[34:35]
	s_nop 0
	v_pk_mul_f32 v[34:35], v[38:39], v[34:35]
	v_pk_mul_f32 v[38:39], v[42:43], v[64:65] op_sel_hi:[1,0]
	v_cvt_pk_bf16_f32 v34, v34, v35
	v_mul_f32_e32 v35, 0xbfb8aa3b, v32
	v_exp_f32_e32 v35, v35
	s_nop 0
	v_add_f32_e32 v35, 1.0, v35
	v_rcp_f32_e32 v36, v35
	v_mul_f32_e32 v35, 0xbfb8aa3b, v33
	v_exp_f32_e32 v35, v35
	s_nop 0
	v_add_f32_e32 v35, 1.0, v35
	v_rcp_f32_e32 v37, v35
	s_nop 0
	v_pk_mul_f32 v[32:33], v[36:37], v[32:33]
	s_nop 0
; DI float bf2f(unsigned v) { return __uint_as_float(v << 16); }
; DI unsigned pack2(float a, float b) { f2_t v = {a, b}; bf2_t r = __builtin_convertvector(v, bf2_t); return __builtin_bit_cast(unsigned, r); }
; DI float silu(float g) { return g * frcp(1.f + fexp(-g)); }
; template <int DQK>
; DI void attn_item(const u16* __restrict__ Qp, int ldq, const u16* __restrict__ Kp, const u16* __restrict__ Vtp, int ldv,
;                   int nkt, int q0, bool causal, float c, u16* Yp, int ldy, char* smem, bool dry) {
;     ...
;   for (int dt = 0; dt < 4; ++dt)
; #pragma unroll
;     for (int g = 0; g < 4; ++g) {
;       const int d = 32 * dt + 8 * g + 4 * h;
;       uint2 gv = *(const uint2*)(yrow + d);
;       float g0 = bf2f(gv.x & 0xffffu), g1 = bf2f(gv.x >> 16), g2 = bf2f(gv.y & 0xffffu), g3 = bf2f(gv.y >> 16);
;       uint2 ov;
;       ov.x = pack2(o[dt][4 * g] * inv * silu(g0), o[dt][4 * g + 1] * inv * silu(g1));
;       ov.y = pack2(o[dt][4 * g + 2] * inv * silu(g2), o[dt][4 * g + 3] * inv * silu(g3));
;       *(uint2*)(yrow + d) = ov;
;     }
	v_pk_mul_f32 v[32:33], v[38:39], v[32:33]
	v_pk_mul_f32 v[38:39], v[44:45], v[64:65] op_sel_hi:[1,0]
	v_cvt_pk_bf16_f32 v35, v32, v33
	s_nop 0
	global_store_dwordx2 v[66:67], v[34:35], off offset:3168
	v_lshlrev_b32_e32 v34, 16, v112
	v_and_b32_e32 v35, 0xffff0000, v112
	v_mul_f32_e32 v36, 0xbfb8aa3b, v34
	v_mul_f32_e32 v37, 0xbfb8aa3b, v35
	v_exp_f32_e32 v36, v36
	v_exp_f32_e32 v37, v37
	v_lshlrev_b32_e32 v32, 16, v113
	v_and_b32_e32 v33, 0xffff0000, v113
	v_add_f32_e32 v36, 1.0, v36
	v_add_f32_e32 v37, 1.0, v37
	v_rcp_f32_e32 v36, v36
	v_rcp_f32_e32 v37, v37
	s_nop 0
	v_pk_mul_f32 v[34:35], v[36:37], v[34:35]
	s_nop 0
	v_pk_mul_f32 v[34:35], v[38:39], v[34:35]
	v_pk_mul_f32 v[38:39], v[46:47], v[64:65] op_sel_hi:[1,0]
	v_cvt_pk_bf16_f32 v34, v34, v35
	v_mul_f32_e32 v35, 0xbfb8aa3b, v32
	v_exp_f32_e32 v35, v35
	s_nop 0
	v_add_f32_e32 v35, 1.0, v35
	v_rcp_f32_e32 v36, v35
	v_mul_f32_e32 v35, 0xbfb8aa3b, v33
	v_exp_f32_e32 v35, v35
	s_nop 0
	v_add_f32_e32 v35, 1.0, v35
	v_rcp_f32_e32 v37, v35
	s_nop 0
	v_pk_mul_f32 v[32:33], v[36:37], v[32:33]
	s_nop 0
	v_pk_mul_f32 v[32:33], v[38:39], v[32:33]
	s_nop 0
	v_cvt_pk_bf16_f32 v35, v32, v33
	s_nop 0
	global_store_dwordx2 v[66:67], v[34:35], off offset:3184
	v_lshlrev_b32_e32 v34, 16, v114
	v_and_b32_e32 v35, 0xffff0000, v114
	v_mul_f32_e32 v36, 0xbfb8aa3b, v34
	v_mul_f32_e32 v37, 0xbfb8aa3b, v35
	v_exp_f32_e32 v36, v36
	v_exp_f32_e32 v37, v37
	v_lshlrev_b32_e32 v32, 16, v115
	v_and_b32_e32 v33, 0xffff0000, v115
	v_add_f32_e32 v36, 1.0, v36
	v_add_f32_e32 v37, 1.0, v37
	v_rcp_f32_e32 v36, v36
	v_rcp_f32_e32 v37, v37
	s_nop 0
	v_pk_mul_f32 v[34:35], v[36:37], v[34:35]
	s_nop 0
	v_pk_mul_f32 v[16:17], v[16:17], v[34:35]
	s_nop 0
	v_cvt_pk_bf16_f32 v16, v16, v17
	v_mul_f32_e32 v17, 0xbfb8aa3b, v32
	v_exp_f32_e32 v17, v17
	s_nop 0
	v_add_f32_e32 v17, 1.0, v17
	v_rcp_f32_e32 v34, v17
	v_mul_f32_e32 v17, 0xbfb8aa3b, v33
	v_exp_f32_e32 v17, v17
	s_nop 0
	v_add_f32_e32 v17, 1.0, v17
	v_rcp_f32_e32 v35, v17
	s_nop 0
	v_pk_mul_f32 v[32:33], v[34:35], v[32:33]
	s_nop 0
	v_pk_mul_f32 v[18:19], v[18:19], v[32:33]
	s_nop 0
	v_cvt_pk_bf16_f32 v17, v18, v19
	global_store_dwordx2 v[66:67], v[16:17], off offset:3200
	v_lshlrev_b32_e32 v18, 16, v116
	v_and_b32_e32 v19, 0xffff0000, v116
	v_mul_f32_e32 v32, 0xbfb8aa3b, v18
	v_mul_f32_e32 v33, 0xbfb8aa3b, v19
	v_exp_f32_e32 v32, v32
	v_exp_f32_e32 v33, v33
	v_lshlrev_b32_e32 v16, 16, v117
	v_and_b32_e32 v17, 0xffff0000, v117
	v_add_f32_e32 v32, 1.0, v32
	v_add_f32_e32 v33, 1.0, v33
	v_rcp_f32_e32 v32, v32
	v_rcp_f32_e32 v33, v33
	s_nop 0
	v_pk_mul_f32 v[18:19], v[32:33], v[18:19]
	s_nop 0
	v_pk_mul_f32 v[18:19], v[20:21], v[18:19]
	s_nop 0
	v_cvt_pk_bf16_f32 v18, v18, v19
	v_mul_f32_e32 v19, 0xbfb8aa3b, v16
	v_exp_f32_e32 v19, v19
	s_nop 0
	v_add_f32_e32 v19, 1.0, v19
	v_rcp_f32_e32 v20, v19
	v_mul_f32_e32 v19, 0xbfb8aa3b, v17
	v_exp_f32_e32 v19, v19
	s_nop 0
	v_add_f32_e32 v19, 1.0, v19
	v_rcp_f32_e32 v21, v19
	s_nop 0
	v_pk_mul_f32 v[16:17], v[20:21], v[16:17]
	s_nop 0
	v_pk_mul_f32 v[16:17], v[22:23], v[16:17]
	v_pk_mul_f32 v[22:23], v[24:25], v[64:65] op_sel_hi:[1,0]
	v_cvt_pk_bf16_f32 v19, v16, v17
	s_nop 0
	global_store_dwordx2 v[66:67], v[18:19], off offset:3216
	v_lshlrev_b32_e32 v18, 16, v118
	v_and_b32_e32 v19, 0xffff0000, v118
	v_mul_f32_e32 v20, 0xbfb8aa3b, v18
	v_mul_f32_e32 v21, 0xbfb8aa3b, v19
	v_exp_f32_e32 v20, v20
	v_exp_f32_e32 v21, v21
	v_lshlrev_b32_e32 v16, 16, v119
	v_and_b32_e32 v17, 0xffff0000, v119
	v_add_f32_e32 v20, 1.0, v20
	v_add_f32_e32 v21, 1.0, v21
	v_rcp_f32_e32 v20, v20
	v_rcp_f32_e32 v21, v21
	s_nop 0
	v_pk_mul_f32 v[18:19], v[20:21], v[18:19]
	s_nop 0
	v_pk_mul_f32 v[18:19], v[22:23], v[18:19]
	v_pk_mul_f32 v[22:23], v[26:27], v[64:65] op_sel_hi:[1,0]
	v_cvt_pk_bf16_f32 v18, v18, v19
	v_mul_f32_e32 v19, 0xbfb8aa3b, v16
	v_exp_f32_e32 v19, v19
	s_nop 0
	v_add_f32_e32 v19, 1.0, v19
	v_rcp_f32_e32 v20, v19
	v_mul_f32_e32 v19, 0xbfb8aa3b, v17
	v_exp_f32_e32 v19, v19
	s_nop 0
	v_add_f32_e32 v19, 1.0, v19
	v_rcp_f32_e32 v21, v19
	s_nop 0
	v_pk_mul_f32 v[16:17], v[20:21], v[16:17]
	s_nop 0
	v_pk_mul_f32 v[16:17], v[22:23], v[16:17]
	v_pk_mul_f32 v[22:23], v[28:29], v[64:65] op_sel_hi:[1,0]
	v_cvt_pk_bf16_f32 v19, v16, v17
	s_nop 0
	global_store_dwordx2 v[66:67], v[18:19], off offset:3232
	v_lshlrev_b32_e32 v18, 16, v120
	v_and_b32_e32 v19, 0xffff0000, v120
	v_mul_f32_e32 v20, 0xbfb8aa3b, v18
	v_mul_f32_e32 v21, 0xbfb8aa3b, v19
	v_exp_f32_e32 v20, v20
	v_exp_f32_e32 v21, v21
	v_lshlrev_b32_e32 v16, 16, v121
	v_and_b32_e32 v17, 0xffff0000, v121
	v_add_f32_e32 v20, 1.0, v20
; DI float bf2f(unsigned v) { return __uint_as_float(v << 16); }
; DI unsigned pack2(float a, float b) { f2_t v = {a, b}; bf2_t r = __builtin_convertvector(v, bf2_t); return __builtin_bit_cast(unsigned, r); }
; DI float silu(float g) { return g * frcp(1.f + fexp(-g)); }
; template <int DQK>
; DI void attn_item(const u16* __restrict__ Qp, int ldq, const u16* __restrict__ Kp, const u16* __restrict__ Vtp, int ldv,
;                   int nkt, int q0, bool causal, float c, u16* Yp, int ldy, char* smem, bool dry) {
;     ...
;   for (int dt = 0; dt < 4; ++dt)
; #pragma unroll
;     for (int g = 0; g < 4; ++g) {
;       const int d = 32 * dt + 8 * g + 4 * h;
;       uint2 gv = *(const uint2*)(yrow + d);
;       float g0 = bf2f(gv.x & 0xffffu), g1 = bf2f(gv.x >> 16), g2 = bf2f(gv.y & 0xffffu), g3 = bf2f(gv.y >> 16);
;       uint2 ov;
;       ov.x = pack2(o[dt][4 * g] * inv * silu(g0), o[dt][4 * g + 1] * inv * silu(g1));
;       ov.y = pack2(o[dt][4 * g + 2] * inv * silu(g2), o[dt][4 * g + 3] * inv * silu(g3));
;       *(uint2*)(yrow + d) = ov;
;     }
	v_add_f32_e32 v21, 1.0, v21
	v_rcp_f32_e32 v20, v20
	v_rcp_f32_e32 v21, v21
	s_nop 0
	v_pk_mul_f32 v[18:19], v[20:21], v[18:19]
	s_nop 0
	v_pk_mul_f32 v[18:19], v[22:23], v[18:19]
	v_pk_mul_f32 v[22:23], v[30:31], v[64:65] op_sel_hi:[1,0]
	v_cvt_pk_bf16_f32 v18, v18, v19
	v_mul_f32_e32 v19, 0xbfb8aa3b, v16
	v_exp_f32_e32 v19, v19
	s_nop 0
	v_add_f32_e32 v19, 1.0, v19
	v_rcp_f32_e32 v20, v19
	v_mul_f32_e32 v19, 0xbfb8aa3b, v17
	v_exp_f32_e32 v19, v19
	s_nop 0
	v_add_f32_e32 v19, 1.0, v19
	v_rcp_f32_e32 v21, v19
	s_nop 0
	v_pk_mul_f32 v[16:17], v[20:21], v[16:17]
	s_nop 0
	v_pk_mul_f32 v[16:17], v[22:23], v[16:17]
	s_nop 0
	v_cvt_pk_bf16_f32 v19, v16, v17
	s_nop 0
	global_store_dwordx2 v[66:67], v[18:19], off offset:3248
	v_lshlrev_b32_e32 v18, 16, v122
	v_and_b32_e32 v19, 0xffff0000, v122
	v_mul_f32_e32 v20, 0xbfb8aa3b, v18
	v_mul_f32_e32 v21, 0xbfb8aa3b, v19
	v_exp_f32_e32 v20, v20
	v_exp_f32_e32 v21, v21
	v_lshlrev_b32_e32 v16, 16, v123
	v_and_b32_e32 v17, 0xffff0000, v123
	v_add_f32_e32 v20, 1.0, v20
	v_add_f32_e32 v21, 1.0, v21
	v_rcp_f32_e32 v20, v20
	v_rcp_f32_e32 v21, v21
	s_nop 0
	v_pk_mul_f32 v[18:19], v[20:21], v[18:19]
	s_nop 0
	v_pk_mul_f32 v[0:1], v[0:1], v[18:19]
	s_nop 0
	v_cvt_pk_bf16_f32 v0, v0, v1
	v_mul_f32_e32 v1, 0xbfb8aa3b, v16
	v_exp_f32_e32 v1, v1
	s_nop 0
	v_add_f32_e32 v1, 1.0, v1
	v_rcp_f32_e32 v18, v1
	v_mul_f32_e32 v1, 0xbfb8aa3b, v17
	v_exp_f32_e32 v1, v1
	s_nop 0
	v_add_f32_e32 v1, 1.0, v1
	v_rcp_f32_e32 v19, v1
	s_nop 0
	v_pk_mul_f32 v[16:17], v[18:19], v[16:17]
	s_nop 0
	v_pk_mul_f32 v[2:3], v[2:3], v[16:17]
	s_nop 0
	v_cvt_pk_bf16_f32 v1, v2, v3
	global_store_dwordx2 v[66:67], v[0:1], off offset:3264
	v_lshlrev_b32_e32 v2, 16, v124
	v_and_b32_e32 v3, 0xffff0000, v124
	v_mul_f32_e32 v16, 0xbfb8aa3b, v2
	v_mul_f32_e32 v17, 0xbfb8aa3b, v3
	v_exp_f32_e32 v16, v16
	v_exp_f32_e32 v17, v17
	v_lshlrev_b32_e32 v0, 16, v125
	v_and_b32_e32 v1, 0xffff0000, v125
	v_add_f32_e32 v16, 1.0, v16
	v_add_f32_e32 v17, 1.0, v17
	v_rcp_f32_e32 v16, v16
	v_rcp_f32_e32 v17, v17
	s_nop 0
	v_pk_mul_f32 v[2:3], v[16:17], v[2:3]
	s_nop 0
	v_pk_mul_f32 v[2:3], v[4:5], v[2:3]
	s_nop 0
	v_cvt_pk_bf16_f32 v2, v2, v3
	v_mul_f32_e32 v3, 0xbfb8aa3b, v0
	v_exp_f32_e32 v3, v3
	s_nop 0
	v_add_f32_e32 v3, 1.0, v3
	v_rcp_f32_e32 v4, v3
	v_mul_f32_e32 v3, 0xbfb8aa3b, v1
	v_exp_f32_e32 v3, v3
	s_nop 0
	v_add_f32_e32 v3, 1.0, v3
	v_rcp_f32_e32 v5, v3
	s_nop 0
	v_pk_mul_f32 v[0:1], v[4:5], v[0:1]
	s_nop 0
	v_pk_mul_f32 v[0:1], v[6:7], v[0:1]
	v_pk_mul_f32 v[6:7], v[8:9], v[64:65] op_sel_hi:[1,0]
	v_cvt_pk_bf16_f32 v3, v0, v1
	s_nop 0
	global_store_dwordx2 v[66:67], v[2:3], off offset:3280
	v_lshlrev_b32_e32 v2, 16, v126
	v_and_b32_e32 v3, 0xffff0000, v126
	v_mul_f32_e32 v4, 0xbfb8aa3b, v2
	v_mul_f32_e32 v5, 0xbfb8aa3b, v3
	v_exp_f32_e32 v4, v4
	v_exp_f32_e32 v5, v5
	v_lshlrev_b32_e32 v0, 16, v127
	v_and_b32_e32 v1, 0xffff0000, v127
	v_add_f32_e32 v4, 1.0, v4
	v_add_f32_e32 v5, 1.0, v5
	v_rcp_f32_e32 v4, v4
	v_rcp_f32_e32 v5, v5
	s_nop 0
	v_pk_mul_f32 v[2:3], v[4:5], v[2:3]
	s_nop 0
	v_pk_mul_f32 v[2:3], v[6:7], v[2:3]
	v_pk_mul_f32 v[6:7], v[10:11], v[64:65] op_sel_hi:[1,0]
	v_cvt_pk_bf16_f32 v2, v2, v3
	v_mul_f32_e32 v3, 0xbfb8aa3b, v0
	v_exp_f32_e32 v3, v3
	s_nop 0
	v_add_f32_e32 v3, 1.0, v3
	v_rcp_f32_e32 v4, v3
	v_mul_f32_e32 v3, 0xbfb8aa3b, v1
	v_exp_f32_e32 v3, v3
	s_nop 0
	v_add_f32_e32 v3, 1.0, v3
	v_rcp_f32_e32 v5, v3
	s_nop 0
	v_pk_mul_f32 v[0:1], v[4:5], v[0:1]
	s_nop 0
	v_pk_mul_f32 v[0:1], v[6:7], v[0:1]
	v_pk_mul_f32 v[6:7], v[12:13], v[64:65] op_sel_hi:[1,0]
	v_cvt_pk_bf16_f32 v3, v0, v1
	s_nop 0
	global_store_dwordx2 v[66:67], v[2:3], off offset:3296
	v_lshlrev_b32_e32 v2, 16, v128
	v_and_b32_e32 v3, 0xffff0000, v128
	v_mul_f32_e32 v4, 0xbfb8aa3b, v2
	v_mul_f32_e32 v5, 0xbfb8aa3b, v3
	v_exp_f32_e32 v4, v4
	v_exp_f32_e32 v5, v5
	v_lshlrev_b32_e32 v0, 16, v129
	v_and_b32_e32 v1, 0xffff0000, v129
	v_add_f32_e32 v4, 1.0, v4
	v_add_f32_e32 v5, 1.0, v5
	v_rcp_f32_e32 v4, v4
	v_rcp_f32_e32 v5, v5
	s_nop 0
	v_pk_mul_f32 v[2:3], v[4:5], v[2:3]
	s_nop 0
	v_pk_mul_f32 v[2:3], v[6:7], v[2:3]
	v_pk_mul_f32 v[6:7], v[14:15], v[64:65] op_sel_hi:[1,0]
	v_cvt_pk_bf16_f32 v2, v2, v3
	v_mul_f32_e32 v3, 0xbfb8aa3b, v0
	v_exp_f32_e32 v3, v3
	s_nop 0
	v_add_f32_e32 v3, 1.0, v3
	v_rcp_f32_e32 v4, v3
	v_mul_f32_e32 v3, 0xbfb8aa3b, v1
	v_exp_f32_e32 v3, v3
	s_nop 0
	v_add_f32_e32 v3, 1.0, v3
	v_rcp_f32_e32 v5, v3
	s_nop 0
	v_pk_mul_f32 v[0:1], v[4:5], v[0:1]
	s_nop 0
	v_pk_mul_f32 v[0:1], v[6:7], v[0:1]
	s_nop 0
	v_cvt_pk_bf16_f32 v3, v0, v1
	global_store_dwordx2 v[66:67], v[2:3], off offset:3312
	s_branch .LBB0_305
